# sc1 write-through on the 136 streaming dwordx4 stores of P1-P4 and P8 (on top of nt loads in P2-P4)
# speedup vs baseline: 1.0018x; 1.0018x over previous
.LBB0_192:
	s_cmp_lt_i32 s58, 2
	s_cselect_b64 s[2:3], -1, 0
	v_cndmask_b32_e64 v144, v179, 1.0, s[2:3]
	v_ashrrev_i32_e32 v0, 31, v202
	v_mul_lo_u32 v203, s56, v0
	v_lshl_add_u64 v[170:171], v[170:171], 1, s[86:87]
	v_and_b32_e32 v0, s65, v202
	v_lshlrev_b32_e32 v0, 7, v0
	v_lshl_add_u64 v[132:133], v[162:163], 0, v[0:1]
	global_load_dwordx4 v[136:139], v[132:133], off
	v_lshl_add_u64 v[132:133], v[164:165], 0, v[0:1]
	global_load_dwordx4 v[140:143], v[132:133], off
	v_or_b32_e32 v145, 16, v202
	v_and_b32_e32 v0, s65, v145
	v_lshlrev_b32_e32 v0, 7, v0
	v_lshl_add_u64 v[132:133], v[162:163], 0, v[0:1]
	global_load_dwordx4 v[208:211], v[132:133], off
	v_lshl_add_u64 v[132:133], v[164:165], 0, v[0:1]
	global_load_dwordx4 v[216:219], v[132:133], off
	v_or_b32_e32 v145, 32, v202
	v_and_b32_e32 v0, s65, v145
	v_lshlrev_b32_e32 v0, 7, v0
	v_lshl_add_u64 v[132:133], v[162:163], 0, v[0:1]
	global_load_dwordx4 v[220:223], v[132:133], off
	v_lshl_add_u64 v[132:133], v[164:165], 0, v[0:1]
	global_load_dwordx4 v[224:227], v[132:133], off
	v_or_b32_e32 v145, 48, v202
	v_and_b32_e32 v0, s65, v145
	v_lshlrev_b32_e32 v0, 7, v0
	v_lshl_add_u64 v[132:133], v[162:163], 0, v[0:1]
	global_load_dwordx4 v[228:231], v[132:133], off
	v_lshl_add_u64 v[132:133], v[164:165], 0, v[0:1]
	global_load_dwordx4 v[232:235], v[132:133], off
	v_or_b32_e32 v145, 0x80, v202
	v_and_b32_e32 v0, s65, v145
	v_lshlrev_b32_e32 v0, 7, v0
	v_lshl_add_u64 v[132:133], v[162:163], 0, v[0:1]
	global_load_dwordx4 v[236:239], v[132:133], off
	v_lshl_add_u64 v[132:133], v[164:165], 0, v[0:1]
	global_load_dwordx4 v[240:243], v[132:133], off
	v_or_b32_e32 v145, 0x90, v202
	v_and_b32_e32 v0, s65, v145
	v_lshlrev_b32_e32 v0, 7, v0
	v_lshl_add_u64 v[132:133], v[162:163], 0, v[0:1]
	global_load_dwordx4 v[174:177], v[132:133], off
	v_lshl_add_u64 v[132:133], v[164:165], 0, v[0:1]
	global_load_dwordx4 v[204:207], v[132:133], off
	v_mul_lo_u32 v0, s57, v202
	v_mad_u64_u32 v[212:213], s[2:3], s56, v202, 0
	v_add3_u32 v213, v213, v203, v0
	v_lshlrev_b64 v[212:213], 1, v[212:213]
	s_waitcnt vmcnt(10)
	v_pk_mul_f32 v[136:137], v[144:145], v[136:137] op_sel_hi:[0,1]
	v_pk_mul_f32 v[138:139], v[144:145], v[138:139] op_sel_hi:[0,1]
	v_pk_mul_f32 v[140:141], v[144:145], v[140:141] op_sel_hi:[0,1]
	v_pk_mul_f32 v[142:143], v[144:145], v[142:143] op_sel_hi:[0,1]
	v_pk_mul_f32 v[130:131], v[122:123], v[140:141]
	v_pk_mul_f32 v[132:133], v[124:125], v[142:143]
	v_pk_fma_f32 v[130:131], v[126:127], v[136:137], v[130:131] neg_lo:[0,0,1] neg_hi:[0,0,1]
	v_pk_fma_f32 v[132:133], v[128:129], v[138:139], v[132:133] neg_lo:[0,0,1] neg_hi:[0,0,1]
	v_pk_mul_f32 v[126:127], v[126:127], v[140:141]
	v_pk_mul_f32 v[128:129], v[128:129], v[142:143]
	v_pk_fma_f32 v[122:123], v[122:123], v[136:137], v[126:127]
	v_pk_fma_f32 v[124:125], v[124:125], v[138:139], v[128:129]
	v_cvt_pk_bf16_f32 v126, v130, v131
	v_cvt_pk_bf16_f32 v127, v132, v133
	v_cvt_pk_bf16_f32 v128, v122, v123
	v_cvt_pk_bf16_f32 v129, v124, v125
	v_lshl_add_u64 v[132:133], v[170:171], 0, v[212:213]
	global_store_dwordx4 v[132:133], v[126:129], off sc1
	v_pk_mul_f32 v[130:131], v[114:115], v[140:141]
	v_pk_mul_f32 v[132:133], v[116:117], v[142:143]
	v_pk_fma_f32 v[130:131], v[118:119], v[136:137], v[130:131] neg_lo:[0,0,1] neg_hi:[0,0,1]
	v_pk_fma_f32 v[132:133], v[120:121], v[138:139], v[132:133] neg_lo:[0,0,1] neg_hi:[0,0,1]
	v_pk_mul_f32 v[118:119], v[118:119], v[140:141]
	v_pk_mul_f32 v[120:121], v[120:121], v[142:143]
	v_pk_fma_f32 v[114:115], v[114:115], v[136:137], v[118:119]
	v_pk_fma_f32 v[116:117], v[116:117], v[138:139], v[120:121]
	v_cvt_pk_bf16_f32 v118, v130, v131
	v_cvt_pk_bf16_f32 v119, v132, v133
	v_cvt_pk_bf16_f32 v120, v114, v115
	v_cvt_pk_bf16_f32 v121, v116, v117
	v_lshl_add_u64 v[132:133], v[134:135], 0, v[212:213]
	global_store_dwordx4 v[132:133], v[118:121], off sc1
	v_or_b32_e32 v145, 0xa0, v202
	v_and_b32_e32 v0, s65, v145
	v_lshlrev_b32_e32 v0, 7, v0
	v_lshl_add_u64 v[132:133], v[162:163], 0, v[0:1]
	global_load_dwordx4 v[136:139], v[132:133], off
	v_lshl_add_u64 v[132:133], v[164:165], 0, v[0:1]
	global_load_dwordx4 v[140:143], v[132:133], off
	v_or_b32_e32 v145, 0x10, v202
	v_mul_lo_u32 v0, s57, v145
	v_mad_u64_u32 v[212:213], s[2:3], s56, v145, 0
	v_add3_u32 v213, v213, v203, v0
	v_lshlrev_b64 v[212:213], 1, v[212:213]
	s_waitcnt vmcnt(12)
	v_pk_mul_f32 v[208:209], v[144:145], v[208:209] op_sel_hi:[0,1]
	v_pk_mul_f32 v[210:211], v[144:145], v[210:211] op_sel_hi:[0,1]
	v_pk_mul_f32 v[216:217], v[144:145], v[216:217] op_sel_hi:[0,1]
	v_pk_mul_f32 v[218:219], v[144:145], v[218:219] op_sel_hi:[0,1]
	v_pk_mul_f32 v[130:131], v[106:107], v[216:217]
	v_pk_mul_f32 v[132:133], v[108:109], v[218:219]
	v_pk_fma_f32 v[130:131], v[110:111], v[208:209], v[130:131] neg_lo:[0,0,1] neg_hi:[0,0,1]
	v_pk_fma_f32 v[132:133], v[112:113], v[210:211], v[132:133] neg_lo:[0,0,1] neg_hi:[0,0,1]
	v_pk_mul_f32 v[110:111], v[110:111], v[216:217]
	v_pk_mul_f32 v[112:113], v[112:113], v[218:219]
	v_pk_fma_f32 v[106:107], v[106:107], v[208:209], v[110:111]
	v_pk_fma_f32 v[108:109], v[108:109], v[210:211], v[112:113]
	v_cvt_pk_bf16_f32 v110, v130, v131
	v_cvt_pk_bf16_f32 v111, v132, v133
	v_cvt_pk_bf16_f32 v112, v106, v107
	v_cvt_pk_bf16_f32 v113, v108, v109
	v_lshl_add_u64 v[132:133], v[170:171], 0, v[212:213]
	global_store_dwordx4 v[132:133], v[110:113], off sc1
	v_pk_mul_f32 v[130:131], v[98:99], v[216:217]
	v_pk_mul_f32 v[132:133], v[100:101], v[218:219]
	v_pk_fma_f32 v[130:131], v[102:103], v[208:209], v[130:131] neg_lo:[0,0,1] neg_hi:[0,0,1]
	v_pk_fma_f32 v[132:133], v[104:105], v[210:211], v[132:133] neg_lo:[0,0,1] neg_hi:[0,0,1]
	v_pk_mul_f32 v[102:103], v[102:103], v[216:217]
	v_pk_mul_f32 v[104:105], v[104:105], v[218:219]
	v_pk_fma_f32 v[98:99], v[98:99], v[208:209], v[102:103]
	v_pk_fma_f32 v[100:101], v[100:101], v[210:211], v[104:105]
	v_cvt_pk_bf16_f32 v102, v130, v131
	v_cvt_pk_bf16_f32 v103, v132, v133
	v_cvt_pk_bf16_f32 v104, v98, v99
	v_cvt_pk_bf16_f32 v105, v100, v101
	v_lshl_add_u64 v[132:133], v[134:135], 0, v[212:213]
	global_store_dwordx4 v[132:133], v[102:105], off sc1
	v_or_b32_e32 v145, 0xb0, v202
	v_and_b32_e32 v0, s65, v145
	v_lshlrev_b32_e32 v0, 7, v0
	v_lshl_add_u64 v[132:133], v[162:163], 0, v[0:1]
	global_load_dwordx4 v[208:211], v[132:133], off
	v_lshl_add_u64 v[132:133], v[164:165], 0, v[0:1]
	global_load_dwordx4 v[216:219], v[132:133], off
	v_or_b32_e32 v145, 0x20, v202
	v_mul_lo_u32 v0, s57, v145
	v_mad_u64_u32 v[212:213], s[2:3], s56, v145, 0
	v_add3_u32 v213, v213, v203, v0
	v_lshlrev_b64 v[212:213], 1, v[212:213]
	s_waitcnt vmcnt(14)
	v_pk_mul_f32 v[220:221], v[144:145], v[220:221] op_sel_hi:[0,1]
	v_pk_mul_f32 v[222:223], v[144:145], v[222:223] op_sel_hi:[0,1]
	v_pk_mul_f32 v[224:225], v[144:145], v[224:225] op_sel_hi:[0,1]
	v_pk_mul_f32 v[226:227], v[144:145], v[226:227] op_sel_hi:[0,1]
	v_pk_mul_f32 v[130:131], v[90:91], v[224:225]
	v_pk_mul_f32 v[132:133], v[92:93], v[226:227]
	v_pk_fma_f32 v[130:131], v[94:95], v[220:221], v[130:131] neg_lo:[0,0,1] neg_hi:[0,0,1]
	v_pk_fma_f32 v[132:133], v[96:97], v[222:223], v[132:133] neg_lo:[0,0,1] neg_hi:[0,0,1]
	v_pk_mul_f32 v[94:95], v[94:95], v[224:225]
	v_pk_mul_f32 v[96:97], v[96:97], v[226:227]
	v_pk_fma_f32 v[90:91], v[90:91], v[220:221], v[94:95]
	v_pk_fma_f32 v[92:93], v[92:93], v[222:223], v[96:97]
	v_cvt_pk_bf16_f32 v94, v130, v131
	v_cvt_pk_bf16_f32 v95, v132, v133
	v_cvt_pk_bf16_f32 v96, v90, v91
	v_cvt_pk_bf16_f32 v97, v92, v93
	v_lshl_add_u64 v[132:133], v[170:171], 0, v[212:213]
	global_store_dwordx4 v[132:133], v[94:97], off sc1
	v_pk_mul_f32 v[130:131], v[82:83], v[224:225]
	v_pk_mul_f32 v[132:133], v[84:85], v[226:227]
	v_pk_fma_f32 v[130:131], v[86:87], v[220:221], v[130:131] neg_lo:[0,0,1] neg_hi:[0,0,1]
	v_pk_fma_f32 v[132:133], v[88:89], v[222:223], v[132:133] neg_lo:[0,0,1] neg_hi:[0,0,1]
	v_pk_mul_f32 v[86:87], v[86:87], v[224:225]
	v_pk_mul_f32 v[88:89], v[88:89], v[226:227]
	v_pk_fma_f32 v[82:83], v[82:83], v[220:221], v[86:87]
	v_pk_fma_f32 v[84:85], v[84:85], v[222:223], v[88:89]
	v_cvt_pk_bf16_f32 v86, v130, v131
	v_cvt_pk_bf16_f32 v87, v132, v133
	v_cvt_pk_bf16_f32 v88, v82, v83
	v_cvt_pk_bf16_f32 v89, v84, v85
	v_lshl_add_u64 v[132:133], v[134:135], 0, v[212:213]
	global_store_dwordx4 v[132:133], v[86:89], off sc1
	v_or_b32_e32 v145, 0x30, v202
	v_mul_lo_u32 v0, s57, v145
	v_mad_u64_u32 v[212:213], s[2:3], s56, v145, 0
	v_add3_u32 v213, v213, v203, v0
	v_lshlrev_b64 v[212:213], 1, v[212:213]
	s_waitcnt vmcnt(14)
	v_pk_mul_f32 v[228:229], v[144:145], v[228:229] op_sel_hi:[0,1]
	v_pk_mul_f32 v[230:231], v[144:145], v[230:231] op_sel_hi:[0,1]
	v_pk_mul_f32 v[232:233], v[144:145], v[232:233] op_sel_hi:[0,1]
	v_pk_mul_f32 v[234:235], v[144:145], v[234:235] op_sel_hi:[0,1]
	v_pk_mul_f32 v[130:131], v[74:75], v[232:233]
	v_pk_mul_f32 v[132:133], v[76:77], v[234:235]
	v_pk_fma_f32 v[130:131], v[78:79], v[228:229], v[130:131] neg_lo:[0,0,1] neg_hi:[0,0,1]
	v_pk_fma_f32 v[132:133], v[80:81], v[230:231], v[132:133] neg_lo:[0,0,1] neg_hi:[0,0,1]
	v_pk_mul_f32 v[78:79], v[78:79], v[232:233]
	v_pk_mul_f32 v[80:81], v[80:81], v[234:235]
	v_pk_fma_f32 v[74:75], v[74:75], v[228:229], v[78:79]
	v_pk_fma_f32 v[76:77], v[76:77], v[230:231], v[80:81]
	v_cvt_pk_bf16_f32 v78, v130, v131
	v_cvt_pk_bf16_f32 v79, v132, v133
	v_cvt_pk_bf16_f32 v80, v74, v75
	v_cvt_pk_bf16_f32 v81, v76, v77
	v_lshl_add_u64 v[132:133], v[170:171], 0, v[212:213]
	global_store_dwordx4 v[132:133], v[78:81], off sc1
	v_pk_mul_f32 v[130:131], v[66:67], v[232:233]
	v_pk_mul_f32 v[132:133], v[68:69], v[234:235]
	v_pk_fma_f32 v[130:131], v[70:71], v[228:229], v[130:131] neg_lo:[0,0,1] neg_hi:[0,0,1]
	v_pk_fma_f32 v[132:133], v[72:73], v[230:231], v[132:133] neg_lo:[0,0,1] neg_hi:[0,0,1]
	v_pk_mul_f32 v[70:71], v[70:71], v[232:233]
	v_pk_mul_f32 v[72:73], v[72:73], v[234:235]
	v_pk_fma_f32 v[66:67], v[66:67], v[228:229], v[70:71]
	v_pk_fma_f32 v[68:69], v[68:69], v[230:231], v[72:73]
	v_cvt_pk_bf16_f32 v70, v130, v131
	v_cvt_pk_bf16_f32 v71, v132, v133
	v_cvt_pk_bf16_f32 v72, v66, v67
	v_cvt_pk_bf16_f32 v73, v68, v69
	v_lshl_add_u64 v[132:133], v[134:135], 0, v[212:213]
	global_store_dwordx4 v[132:133], v[70:73], off sc1
	v_or_b32_e32 v145, 0x80, v202
	v_mul_lo_u32 v0, s57, v145
	v_mad_u64_u32 v[212:213], s[2:3], s56, v145, 0
	v_add3_u32 v213, v213, v203, v0
	v_lshlrev_b64 v[212:213], 1, v[212:213]
	s_waitcnt vmcnt(14)
	v_pk_mul_f32 v[236:237], v[144:145], v[236:237] op_sel_hi:[0,1]
	v_pk_mul_f32 v[238:239], v[144:145], v[238:239] op_sel_hi:[0,1]
	v_pk_mul_f32 v[240:241], v[144:145], v[240:241] op_sel_hi:[0,1]
	v_pk_mul_f32 v[242:243], v[144:145], v[242:243] op_sel_hi:[0,1]
	v_pk_mul_f32 v[130:131], v[58:59], v[240:241]
	v_pk_mul_f32 v[132:133], v[60:61], v[242:243]
	v_pk_fma_f32 v[130:131], v[62:63], v[236:237], v[130:131] neg_lo:[0,0,1] neg_hi:[0,0,1]
	v_pk_fma_f32 v[132:133], v[64:65], v[238:239], v[132:133] neg_lo:[0,0,1] neg_hi:[0,0,1]
	v_pk_mul_f32 v[62:63], v[62:63], v[240:241]
	v_pk_mul_f32 v[64:65], v[64:65], v[242:243]
	v_pk_fma_f32 v[58:59], v[58:59], v[236:237], v[62:63]
	v_pk_fma_f32 v[60:61], v[60:61], v[238:239], v[64:65]
	v_cvt_pk_bf16_f32 v62, v130, v131
	v_cvt_pk_bf16_f32 v63, v132, v133
	v_cvt_pk_bf16_f32 v64, v58, v59
	v_cvt_pk_bf16_f32 v65, v60, v61
	v_lshl_add_u64 v[132:133], v[170:171], 0, v[212:213]
	global_store_dwordx4 v[132:133], v[62:65], off sc1
	v_pk_mul_f32 v[130:131], v[50:51], v[240:241]
	v_pk_mul_f32 v[132:133], v[52:53], v[242:243]
	v_pk_fma_f32 v[130:131], v[54:55], v[236:237], v[130:131] neg_lo:[0,0,1] neg_hi:[0,0,1]
	v_pk_fma_f32 v[132:133], v[56:57], v[238:239], v[132:133] neg_lo:[0,0,1] neg_hi:[0,0,1]
	v_pk_mul_f32 v[54:55], v[54:55], v[240:241]
	v_pk_mul_f32 v[56:57], v[56:57], v[242:243]
	v_pk_fma_f32 v[50:51], v[50:51], v[236:237], v[54:55]
	v_pk_fma_f32 v[52:53], v[52:53], v[238:239], v[56:57]
	v_cvt_pk_bf16_f32 v54, v130, v131
	v_cvt_pk_bf16_f32 v55, v132, v133
	v_cvt_pk_bf16_f32 v56, v50, v51
	v_cvt_pk_bf16_f32 v57, v52, v53
	v_lshl_add_u64 v[132:133], v[134:135], 0, v[212:213]
	global_store_dwordx4 v[132:133], v[54:57], off sc1
	v_or_b32_e32 v145, 0x90, v202
	v_mul_lo_u32 v0, s57, v145
	v_mad_u64_u32 v[212:213], s[2:3], s56, v145, 0
	v_add3_u32 v213, v213, v203, v0
	v_lshlrev_b64 v[212:213], 1, v[212:213]
	s_waitcnt vmcnt(14)
	v_pk_mul_f32 v[174:175], v[144:145], v[174:175] op_sel_hi:[0,1]
	v_pk_mul_f32 v[176:177], v[144:145], v[176:177] op_sel_hi:[0,1]
	v_pk_mul_f32 v[204:205], v[144:145], v[204:205] op_sel_hi:[0,1]
	v_pk_mul_f32 v[206:207], v[144:145], v[206:207] op_sel_hi:[0,1]
	v_pk_mul_f32 v[130:131], v[42:43], v[204:205]
	v_pk_mul_f32 v[132:133], v[44:45], v[206:207]
	v_pk_fma_f32 v[130:131], v[46:47], v[174:175], v[130:131] neg_lo:[0,0,1] neg_hi:[0,0,1]
	v_pk_fma_f32 v[132:133], v[48:49], v[176:177], v[132:133] neg_lo:[0,0,1] neg_hi:[0,0,1]
	v_pk_mul_f32 v[46:47], v[46:47], v[204:205]
	v_pk_mul_f32 v[48:49], v[48:49], v[206:207]
	v_pk_fma_f32 v[42:43], v[42:43], v[174:175], v[46:47]
	v_pk_fma_f32 v[44:45], v[44:45], v[176:177], v[48:49]
	v_cvt_pk_bf16_f32 v46, v130, v131
	v_cvt_pk_bf16_f32 v47, v132, v133
	v_cvt_pk_bf16_f32 v48, v42, v43
	v_cvt_pk_bf16_f32 v49, v44, v45
	v_lshl_add_u64 v[132:133], v[170:171], 0, v[212:213]
	global_store_dwordx4 v[132:133], v[46:49], off sc1
	v_pk_mul_f32 v[130:131], v[34:35], v[204:205]
	v_pk_mul_f32 v[132:133], v[36:37], v[206:207]
	v_pk_fma_f32 v[130:131], v[38:39], v[174:175], v[130:131] neg_lo:[0,0,1] neg_hi:[0,0,1]
	v_pk_fma_f32 v[132:133], v[40:41], v[176:177], v[132:133] neg_lo:[0,0,1] neg_hi:[0,0,1]
	v_pk_mul_f32 v[38:39], v[38:39], v[204:205]
	v_pk_mul_f32 v[40:41], v[40:41], v[206:207]
	v_pk_fma_f32 v[34:35], v[34:35], v[174:175], v[38:39]
	v_pk_fma_f32 v[36:37], v[36:37], v[176:177], v[40:41]
	v_cvt_pk_bf16_f32 v38, v130, v131
	v_cvt_pk_bf16_f32 v39, v132, v133
	v_cvt_pk_bf16_f32 v40, v34, v35
	v_cvt_pk_bf16_f32 v41, v36, v37
	v_lshl_add_u64 v[132:133], v[134:135], 0, v[212:213]
	global_store_dwordx4 v[132:133], v[38:41], off sc1
	v_or_b32_e32 v145, 0xa0, v202
	v_mul_lo_u32 v0, s57, v145
	v_mad_u64_u32 v[212:213], s[2:3], s56, v145, 0
	v_add3_u32 v213, v213, v203, v0
	v_lshlrev_b64 v[212:213], 1, v[212:213]
	s_waitcnt vmcnt(12)
	v_pk_mul_f32 v[136:137], v[144:145], v[136:137] op_sel_hi:[0,1]
	v_pk_mul_f32 v[138:139], v[144:145], v[138:139] op_sel_hi:[0,1]
	v_pk_mul_f32 v[140:141], v[144:145], v[140:141] op_sel_hi:[0,1]
	v_pk_mul_f32 v[142:143], v[144:145], v[142:143] op_sel_hi:[0,1]
	v_pk_mul_f32 v[130:131], v[26:27], v[140:141]
	v_pk_mul_f32 v[132:133], v[28:29], v[142:143]
	v_pk_fma_f32 v[130:131], v[30:31], v[136:137], v[130:131] neg_lo:[0,0,1] neg_hi:[0,0,1]
	v_pk_fma_f32 v[132:133], v[32:33], v[138:139], v[132:133] neg_lo:[0,0,1] neg_hi:[0,0,1]
	v_pk_mul_f32 v[30:31], v[30:31], v[140:141]
	v_pk_mul_f32 v[32:33], v[32:33], v[142:143]
	v_pk_fma_f32 v[26:27], v[26:27], v[136:137], v[30:31]
	v_pk_fma_f32 v[28:29], v[28:29], v[138:139], v[32:33]
	v_cvt_pk_bf16_f32 v30, v130, v131
	v_cvt_pk_bf16_f32 v31, v132, v133
	v_cvt_pk_bf16_f32 v32, v26, v27
	v_cvt_pk_bf16_f32 v33, v28, v29
	v_lshl_add_u64 v[132:133], v[170:171], 0, v[212:213]
	global_store_dwordx4 v[132:133], v[30:33], off sc1
	v_pk_mul_f32 v[130:131], v[18:19], v[140:141]
	v_pk_mul_f32 v[132:133], v[20:21], v[142:143]
	v_pk_fma_f32 v[130:131], v[22:23], v[136:137], v[130:131] neg_lo:[0,0,1] neg_hi:[0,0,1]
	v_pk_fma_f32 v[132:133], v[24:25], v[138:139], v[132:133] neg_lo:[0,0,1] neg_hi:[0,0,1]
	v_pk_mul_f32 v[22:23], v[22:23], v[140:141]
	v_pk_mul_f32 v[24:25], v[24:25], v[142:143]
	v_pk_fma_f32 v[18:19], v[18:19], v[136:137], v[22:23]
	v_pk_fma_f32 v[20:21], v[20:21], v[138:139], v[24:25]
	v_cvt_pk_bf16_f32 v22, v130, v131
	v_cvt_pk_bf16_f32 v23, v132, v133
	v_cvt_pk_bf16_f32 v24, v18, v19
	v_cvt_pk_bf16_f32 v25, v20, v21
	v_lshl_add_u64 v[132:133], v[134:135], 0, v[212:213]
	global_store_dwordx4 v[132:133], v[22:25], off sc1
	v_or_b32_e32 v145, 0xb0, v202
	v_mul_lo_u32 v0, s57, v145
	v_mad_u64_u32 v[176:177], s[2:3], s56, v145, 0
	v_add3_u32 v177, v177, v203, v0
	v_lshlrev_b64 v[212:213], 1, v[176:177]
	s_waitcnt vmcnt(10)
	v_pk_mul_f32 v[208:209], v[144:145], v[208:209] op_sel_hi:[0,1]
	v_pk_mul_f32 v[210:211], v[144:145], v[210:211] op_sel_hi:[0,1]
	v_pk_mul_f32 v[216:217], v[144:145], v[216:217] op_sel_hi:[0,1]
	v_pk_mul_f32 v[218:219], v[144:145], v[218:219] op_sel_hi:[0,1]
	v_pk_mul_f32 v[130:131], v[10:11], v[216:217]
	v_pk_mul_f32 v[132:133], v[12:13], v[218:219]
	v_pk_fma_f32 v[130:131], v[14:15], v[208:209], v[130:131] neg_lo:[0,0,1] neg_hi:[0,0,1]
	v_pk_fma_f32 v[132:133], v[16:17], v[210:211], v[132:133] neg_lo:[0,0,1] neg_hi:[0,0,1]
	v_pk_mul_f32 v[14:15], v[14:15], v[216:217]
	v_pk_mul_f32 v[16:17], v[16:17], v[218:219]
	v_pk_fma_f32 v[10:11], v[10:11], v[208:209], v[14:15]
	v_pk_fma_f32 v[12:13], v[12:13], v[210:211], v[16:17]
	v_cvt_pk_bf16_f32 v14, v130, v131
	v_cvt_pk_bf16_f32 v15, v132, v133
	v_cvt_pk_bf16_f32 v16, v10, v11
	v_cvt_pk_bf16_f32 v17, v12, v13
	v_lshl_add_u64 v[132:133], v[170:171], 0, v[212:213]
	global_store_dwordx4 v[132:133], v[14:17], off sc1
	v_pk_mul_f32 v[130:131], v[2:3], v[216:217]
	v_pk_mul_f32 v[132:133], v[4:5], v[218:219]
	v_pk_fma_f32 v[130:131], v[6:7], v[208:209], v[130:131] neg_lo:[0,0,1] neg_hi:[0,0,1]
	v_pk_fma_f32 v[132:133], v[8:9], v[210:211], v[132:133] neg_lo:[0,0,1] neg_hi:[0,0,1]
	v_pk_mul_f32 v[6:7], v[6:7], v[216:217]
	v_pk_mul_f32 v[8:9], v[8:9], v[218:219]
	v_pk_fma_f32 v[2:3], v[2:3], v[208:209], v[6:7]
	v_pk_fma_f32 v[4:5], v[4:5], v[210:211], v[8:9]
	v_cvt_pk_bf16_f32 v130, v130, v131
	v_cvt_pk_bf16_f32 v131, v132, v133
	v_cvt_pk_bf16_f32 v132, v2, v3
	v_mov_b32_e32 v136, v4
	v_mov_b32_e32 v137, v5
.LBB0_193:
	v_cvt_pk_bf16_f32 v133, v136, v137
	v_lshl_add_u64 v[2:3], v[176:177], 1, v[134:135]
	s_andn2_b64 vcc, exec, s[40:41]
	s_mov_b64 s[2:3], -1
	global_store_dwordx4 v[2:3], v[130:133], off sc1
	s_cbranch_vccnz .LBB0_166
	s_andn2_b64 vcc, exec, s[6:7]
	s_cbranch_vccnz .LBB0_165
	s_barrier
	s_branch .LBB0_165

.LBB0_204:
	s_cmp_lg_u64 s[42:43], 0
	s_cbranch_scc1 .Lsig_m1
	v_ashrrev_i32_e32 v0, 31, v202
	v_mul_lo_u32 v174, s57, v202
	v_mul_lo_u32 v0, s56, v0
	v_mad_u64_u32 v[176:177], s[10:11], s56, v202, 0
	v_add3_u32 v177, v177, v0, v174
	v_pk_mul_f32 v[174:175], v[128:129], s[8:9] op_sel_hi:[1,0]
	v_pk_mul_f32 v[204:205], v[126:127], s[8:9] op_sel_hi:[1,0]
	v_min_f32_e32 v174, 0x41e6d4ca, v174
	v_min_f32_e32 v203, 0x41e6d4ca, v204
	v_exp_f32_e32 v207, v203
	v_min_f32_e32 v203, 0x41e6d4ca, v205
	v_exp_f32_e32 v205, v174
	v_min_f32_e32 v174, 0x41e6d4ca, v175
	v_exp_f32_e32 v206, v203
	v_exp_f32_e32 v204, v174
	v_pk_add_f32 v[174:175], v[206:207], 1.0 op_sel_hi:[1,0]
	v_pk_add_f32 v[204:205], v[204:205], 1.0 op_sel_hi:[1,0]
	v_mul_f32_e32 v206, v175, v174
	v_mul_f32_e32 v207, v205, v204
	s_nop 0
	v_mul_f32_e32 v203, v206, v207
	v_rcp_f32_e32 v203, v203
	s_nop 0
	v_mul_f32_e32 v208, v207, v203
	v_mul_f32_e32 v206, v206, v203
	v_pk_mul_f32 v[174:175], v[174:175], v[208:209] op_sel_hi:[1,0]
	v_pk_mul_f32 v[204:205], v[204:205], v[206:207] op_sel_hi:[1,0]
	s_waitcnt vmcnt(0)
	v_pk_mul_f32 v[174:175], v[142:143], v[174:175]
	v_pk_mul_f32 v[206:207], v[122:123], s[8:9] op_sel_hi:[1,0]
	s_nop 0
	v_min_f32_e32 v203, 0x41e6d4ca, v206
	v_pk_mul_f32 v[208:209], v[144:145], v[204:205]
	v_pk_mul_f32 v[204:205], v[124:125], s[8:9] op_sel_hi:[1,0]
	v_exp_f32_e32 v211, v203
	v_min_f32_e32 v203, 0x41e6d4ca, v207
	v_exp_f32_e32 v210, v203
	v_min_f32_e32 v203, 0x41e6d4ca, v204
	v_exp_f32_e32 v207, v203
	v_min_f32_e32 v203, 0x41e6d4ca, v205
	v_exp_f32_e32 v206, v203
	v_pk_add_f32 v[204:205], v[210:211], 1.0 op_sel_hi:[1,0]
	v_pk_add_f32 v[206:207], v[206:207], 1.0 op_sel_hi:[1,0]
	v_mul_f32_e32 v210, v205, v204
	v_mul_f32_e32 v211, v207, v206
	s_nop 0
	v_mul_f32_e32 v203, v210, v211
	v_rcp_f32_e32 v203, v203
	s_nop 0
	v_mul_f32_e32 v212, v211, v203
	v_mul_f32_e32 v210, v210, v203
	v_pk_mul_f32 v[204:205], v[204:205], v[212:213] op_sel_hi:[1,0]
	v_pk_mul_f32 v[206:207], v[206:207], v[210:211] op_sel_hi:[1,0]
	v_pk_mul_f32 v[212:213], v[140:141], v[206:207]
	v_pk_mul_f32 v[206:207], v[138:139], v[204:205]
	v_cvt_pk_bf16_f32 v204, v174, v175
	v_cvt_pk_bf16_f32 v205, v208, v209
	v_lshl_add_u64 v[174:175], v[170:171], 1, s[86:87]
	v_lshlrev_b64 v[208:209], 1, v[176:177]
	v_cvt_pk_bf16_f32 v206, v206, v207
	v_cvt_pk_bf16_f32 v207, v212, v213
	v_lshl_add_u64 v[176:177], v[174:175], 0, v[208:209]
	global_store_dwordx4 v[176:177], v[204:207], off sc1
	v_pk_mul_f32 v[176:177], v[120:121], s[8:9] op_sel_hi:[1,0]
	s_nop 0
	v_pk_mul_f32 v[204:205], v[118:119], s[8:9] op_sel_hi:[1,0]
	v_min_f32_e32 v176, 0x41e6d4ca, v176
	v_min_f32_e32 v203, 0x41e6d4ca, v204
	v_exp_f32_e32 v207, v203
	v_min_f32_e32 v203, 0x41e6d4ca, v205
	v_exp_f32_e32 v205, v176
	v_min_f32_e32 v176, 0x41e6d4ca, v177
	v_exp_f32_e32 v206, v203
	v_exp_f32_e32 v204, v176
	v_pk_add_f32 v[176:177], v[206:207], 1.0 op_sel_hi:[1,0]
	v_pk_add_f32 v[204:205], v[204:205], 1.0 op_sel_hi:[1,0]
	v_mul_f32_e32 v206, v177, v176
	v_mul_f32_e32 v207, v205, v204
	s_nop 0
	v_mul_f32_e32 v203, v206, v207
	v_rcp_f32_e32 v203, v203
	s_nop 0
	v_mul_f32_e32 v210, v207, v203
	v_mul_f32_e32 v206, v206, v203
	v_pk_mul_f32 v[176:177], v[176:177], v[210:211] op_sel_hi:[1,0]
	v_pk_mul_f32 v[204:205], v[204:205], v[206:207] op_sel_hi:[1,0]
	v_pk_mul_f32 v[176:177], v[134:135], v[176:177]
	v_pk_mul_f32 v[206:207], v[114:115], s[8:9] op_sel_hi:[1,0]
	s_nop 0
	v_min_f32_e32 v203, 0x41e6d4ca, v206
	v_pk_mul_f32 v[210:211], v[136:137], v[204:205]
	v_pk_mul_f32 v[204:205], v[116:117], s[8:9] op_sel_hi:[1,0]
	v_exp_f32_e32 v213, v203
	v_min_f32_e32 v203, 0x41e6d4ca, v207
	v_exp_f32_e32 v212, v203
	v_min_f32_e32 v203, 0x41e6d4ca, v204
	v_exp_f32_e32 v207, v203
	v_min_f32_e32 v203, 0x41e6d4ca, v205
	v_exp_f32_e32 v206, v203
	v_pk_add_f32 v[204:205], v[212:213], 1.0 op_sel_hi:[1,0]
	v_pk_add_f32 v[206:207], v[206:207], 1.0 op_sel_hi:[1,0]
	v_mul_f32_e32 v212, v205, v204
	v_mul_f32_e32 v213, v207, v206
	s_nop 0
	v_mul_f32_e32 v203, v212, v213
	v_rcp_f32_e32 v203, v203
	s_nop 0
	v_mul_f32_e32 v216, v213, v203
	v_mul_f32_e32 v212, v212, v203
	v_pk_mul_f32 v[204:205], v[204:205], v[216:217] op_sel_hi:[1,0]
	v_pk_mul_f32 v[206:207], v[206:207], v[212:213] op_sel_hi:[1,0]
	v_pk_mul_f32 v[216:217], v[132:133], v[206:207]
	v_pk_mul_f32 v[206:207], v[130:131], v[204:205]
	v_cvt_pk_bf16_f32 v204, v176, v177
	v_lshl_add_u64 v[176:177], v[172:173], 1, s[86:87]
	v_cvt_pk_bf16_f32 v205, v210, v211
	v_cvt_pk_bf16_f32 v206, v206, v207
	v_cvt_pk_bf16_f32 v207, v216, v217
	v_lshl_add_u64 v[208:209], v[176:177], 0, v[208:209]
	global_store_dwordx4 v[208:209], v[204:207], off sc1
	v_or_b32_e32 v203, 16, v202
	v_mad_u64_u32 v[208:209], s[10:11], s56, v203, 0
	v_pk_mul_f32 v[206:207], v[110:111], s[8:9] op_sel_hi:[1,0]
	v_mul_lo_u32 v204, s57, v203
	v_min_f32_e32 v203, 0x41e6d4ca, v206
	v_add3_u32 v209, v209, v0, v204
	v_pk_mul_f32 v[204:205], v[112:113], s[8:9] op_sel_hi:[1,0]
	v_exp_f32_e32 v211, v203
	v_min_f32_e32 v203, 0x41e6d4ca, v207
	v_exp_f32_e32 v210, v203
	v_min_f32_e32 v203, 0x41e6d4ca, v204
	v_exp_f32_e32 v207, v203
	v_min_f32_e32 v203, 0x41e6d4ca, v205
	v_exp_f32_e32 v206, v203
	v_pk_add_f32 v[204:205], v[210:211], 1.0 op_sel_hi:[1,0]
	v_lshlrev_b64 v[208:209], 1, v[208:209]
	v_pk_add_f32 v[206:207], v[206:207], 1.0 op_sel_hi:[1,0]
	v_mul_f32_e32 v210, v205, v204
	v_mul_f32_e32 v211, v207, v206
	s_nop 0
	v_mul_f32_e32 v203, v210, v211
	v_rcp_f32_e32 v203, v203
	s_nop 0
	v_mul_f32_e32 v212, v211, v203
	v_mul_f32_e32 v210, v210, v203
	v_pk_mul_f32 v[204:205], v[204:205], v[212:213] op_sel_hi:[1,0]
	v_pk_mul_f32 v[206:207], v[206:207], v[210:211] op_sel_hi:[1,0]
	v_pk_mul_f32 v[206:207], v[144:145], v[206:207]
	v_pk_mul_f32 v[212:213], v[106:107], s[8:9] op_sel_hi:[1,0]
	s_nop 0
	v_min_f32_e32 v203, 0x41e6d4ca, v212
	v_pk_mul_f32 v[204:205], v[142:143], v[204:205]
	v_pk_mul_f32 v[210:211], v[108:109], s[8:9] op_sel_hi:[1,0]
	v_exp_f32_e32 v217, v203
	v_min_f32_e32 v203, 0x41e6d4ca, v213
	v_exp_f32_e32 v216, v203
	v_min_f32_e32 v203, 0x41e6d4ca, v210
	v_exp_f32_e32 v213, v203
	v_min_f32_e32 v203, 0x41e6d4ca, v211
	v_exp_f32_e32 v212, v203
	v_pk_add_f32 v[210:211], v[216:217], 1.0 op_sel_hi:[1,0]
	v_cvt_pk_bf16_f32 v204, v204, v205
	v_pk_add_f32 v[212:213], v[212:213], 1.0 op_sel_hi:[1,0]
	v_mul_f32_e32 v216, v211, v210
	v_mul_f32_e32 v217, v213, v212
	v_cvt_pk_bf16_f32 v205, v206, v207
	v_mul_f32_e32 v203, v216, v217
	v_rcp_f32_e32 v203, v203
	s_nop 0
	v_mul_f32_e32 v218, v217, v203
	v_mul_f32_e32 v216, v216, v203
	v_pk_mul_f32 v[210:211], v[210:211], v[218:219] op_sel_hi:[1,0]
	v_pk_mul_f32 v[212:213], v[212:213], v[216:217] op_sel_hi:[1,0]
	v_pk_mul_f32 v[212:213], v[140:141], v[212:213]
	v_pk_mul_f32 v[210:211], v[138:139], v[210:211]
	v_cvt_pk_bf16_f32 v207, v212, v213
	v_cvt_pk_bf16_f32 v206, v210, v211
	v_lshl_add_u64 v[210:211], v[174:175], 0, v[208:209]
	global_store_dwordx4 v[210:211], v[204:207], off sc1
	v_lshl_add_u64 v[208:209], v[176:177], 0, v[208:209]
	s_nop 0
	v_pk_mul_f32 v[206:207], v[102:103], s[8:9] op_sel_hi:[1,0]
	v_pk_mul_f32 v[204:205], v[104:105], s[8:9] op_sel_hi:[1,0]
	v_min_f32_e32 v203, 0x41e6d4ca, v206
	v_exp_f32_e32 v211, v203
	v_min_f32_e32 v203, 0x41e6d4ca, v207
	v_exp_f32_e32 v210, v203
	v_min_f32_e32 v203, 0x41e6d4ca, v204
	v_exp_f32_e32 v207, v203
	v_min_f32_e32 v203, 0x41e6d4ca, v205
	v_exp_f32_e32 v206, v203
	v_pk_add_f32 v[204:205], v[210:211], 1.0 op_sel_hi:[1,0]
	v_pk_add_f32 v[206:207], v[206:207], 1.0 op_sel_hi:[1,0]
	v_mul_f32_e32 v210, v205, v204
	v_mul_f32_e32 v211, v207, v206
	s_nop 0
	v_mul_f32_e32 v203, v210, v211
	v_rcp_f32_e32 v203, v203
	s_nop 0
	v_mul_f32_e32 v212, v211, v203
	v_mul_f32_e32 v210, v210, v203
	v_pk_mul_f32 v[204:205], v[204:205], v[212:213] op_sel_hi:[1,0]
	v_pk_mul_f32 v[206:207], v[206:207], v[210:211] op_sel_hi:[1,0]
	v_pk_mul_f32 v[206:207], v[136:137], v[206:207]
	v_pk_mul_f32 v[212:213], v[98:99], s[8:9] op_sel_hi:[1,0]
	s_nop 0
	v_min_f32_e32 v203, 0x41e6d4ca, v212
	v_pk_mul_f32 v[204:205], v[134:135], v[204:205]
	v_pk_mul_f32 v[210:211], v[100:101], s[8:9] op_sel_hi:[1,0]
	v_exp_f32_e32 v217, v203
	v_min_f32_e32 v203, 0x41e6d4ca, v213
	v_exp_f32_e32 v216, v203
	v_min_f32_e32 v203, 0x41e6d4ca, v210
	v_exp_f32_e32 v213, v203
	v_min_f32_e32 v203, 0x41e6d4ca, v211
	v_exp_f32_e32 v212, v203
	v_pk_add_f32 v[210:211], v[216:217], 1.0 op_sel_hi:[1,0]
	v_cvt_pk_bf16_f32 v204, v204, v205
	v_pk_add_f32 v[212:213], v[212:213], 1.0 op_sel_hi:[1,0]
	v_mul_f32_e32 v216, v211, v210
	v_mul_f32_e32 v217, v213, v212
	v_cvt_pk_bf16_f32 v205, v206, v207
	v_mul_f32_e32 v203, v216, v217
	v_rcp_f32_e32 v203, v203
	s_nop 0
	v_mul_f32_e32 v218, v217, v203
	v_mul_f32_e32 v216, v216, v203
	v_pk_mul_f32 v[210:211], v[210:211], v[218:219] op_sel_hi:[1,0]
	v_pk_mul_f32 v[212:213], v[212:213], v[216:217] op_sel_hi:[1,0]
	v_pk_mul_f32 v[212:213], v[132:133], v[212:213]
	v_pk_mul_f32 v[210:211], v[130:131], v[210:211]
	v_cvt_pk_bf16_f32 v207, v212, v213
	v_cvt_pk_bf16_f32 v206, v210, v211
	global_store_dwordx4 v[208:209], v[204:207], off sc1
	v_or_b32_e32 v203, 32, v202
	v_mad_u64_u32 v[208:209], s[10:11], s56, v203, 0
	v_pk_mul_f32 v[206:207], v[94:95], s[8:9] op_sel_hi:[1,0]
	v_mul_lo_u32 v204, s57, v203
	v_min_f32_e32 v203, 0x41e6d4ca, v206
	v_add3_u32 v209, v209, v0, v204
	v_pk_mul_f32 v[204:205], v[96:97], s[8:9] op_sel_hi:[1,0]
	v_exp_f32_e32 v211, v203
	v_min_f32_e32 v203, 0x41e6d4ca, v207
	v_exp_f32_e32 v210, v203
	v_min_f32_e32 v203, 0x41e6d4ca, v204
	v_exp_f32_e32 v207, v203
	v_min_f32_e32 v203, 0x41e6d4ca, v205
	v_exp_f32_e32 v206, v203
	v_pk_add_f32 v[204:205], v[210:211], 1.0 op_sel_hi:[1,0]
	v_lshlrev_b64 v[208:209], 1, v[208:209]
	v_pk_add_f32 v[206:207], v[206:207], 1.0 op_sel_hi:[1,0]
	v_mul_f32_e32 v210, v205, v204
	v_mul_f32_e32 v211, v207, v206
	s_nop 0
	v_mul_f32_e32 v203, v210, v211
	v_rcp_f32_e32 v203, v203
	s_nop 0
	v_mul_f32_e32 v212, v211, v203
	v_mul_f32_e32 v210, v210, v203
	v_pk_mul_f32 v[204:205], v[204:205], v[212:213] op_sel_hi:[1,0]
	v_pk_mul_f32 v[206:207], v[206:207], v[210:211] op_sel_hi:[1,0]
	v_pk_mul_f32 v[206:207], v[144:145], v[206:207]
	v_pk_mul_f32 v[212:213], v[90:91], s[8:9] op_sel_hi:[1,0]
	s_nop 0
	v_min_f32_e32 v203, 0x41e6d4ca, v212
	v_pk_mul_f32 v[204:205], v[142:143], v[204:205]
	v_pk_mul_f32 v[210:211], v[92:93], s[8:9] op_sel_hi:[1,0]
	v_exp_f32_e32 v217, v203
	v_min_f32_e32 v203, 0x41e6d4ca, v213
	v_exp_f32_e32 v216, v203
	v_min_f32_e32 v203, 0x41e6d4ca, v210
	v_exp_f32_e32 v213, v203
	v_min_f32_e32 v203, 0x41e6d4ca, v211
	v_exp_f32_e32 v212, v203
	v_pk_add_f32 v[210:211], v[216:217], 1.0 op_sel_hi:[1,0]
	v_cvt_pk_bf16_f32 v204, v204, v205
	v_pk_add_f32 v[212:213], v[212:213], 1.0 op_sel_hi:[1,0]
	v_mul_f32_e32 v216, v211, v210
	v_mul_f32_e32 v217, v213, v212
	v_cvt_pk_bf16_f32 v205, v206, v207
	v_mul_f32_e32 v203, v216, v217
	v_rcp_f32_e32 v203, v203
	s_nop 0
	v_mul_f32_e32 v218, v217, v203
	v_mul_f32_e32 v216, v216, v203
	v_pk_mul_f32 v[210:211], v[210:211], v[218:219] op_sel_hi:[1,0]
	v_pk_mul_f32 v[212:213], v[212:213], v[216:217] op_sel_hi:[1,0]
	v_pk_mul_f32 v[212:213], v[140:141], v[212:213]
	v_pk_mul_f32 v[210:211], v[138:139], v[210:211]
	v_cvt_pk_bf16_f32 v207, v212, v213
	v_cvt_pk_bf16_f32 v206, v210, v211
	v_lshl_add_u64 v[210:211], v[174:175], 0, v[208:209]
	global_store_dwordx4 v[210:211], v[204:207], off sc1
	v_lshl_add_u64 v[208:209], v[176:177], 0, v[208:209]
	s_nop 0
	v_pk_mul_f32 v[206:207], v[86:87], s[8:9] op_sel_hi:[1,0]
	v_pk_mul_f32 v[204:205], v[88:89], s[8:9] op_sel_hi:[1,0]
	v_min_f32_e32 v203, 0x41e6d4ca, v206
	v_exp_f32_e32 v211, v203
	v_min_f32_e32 v203, 0x41e6d4ca, v207
	v_exp_f32_e32 v210, v203
	v_min_f32_e32 v203, 0x41e6d4ca, v204
	v_exp_f32_e32 v207, v203
	v_min_f32_e32 v203, 0x41e6d4ca, v205
	v_exp_f32_e32 v206, v203
	v_pk_add_f32 v[204:205], v[210:211], 1.0 op_sel_hi:[1,0]
	v_pk_add_f32 v[206:207], v[206:207], 1.0 op_sel_hi:[1,0]
	v_mul_f32_e32 v210, v205, v204
	v_mul_f32_e32 v211, v207, v206
	s_nop 0
	v_mul_f32_e32 v203, v210, v211
	v_rcp_f32_e32 v203, v203
	s_nop 0
	v_mul_f32_e32 v212, v211, v203
	v_mul_f32_e32 v210, v210, v203
	v_pk_mul_f32 v[204:205], v[204:205], v[212:213] op_sel_hi:[1,0]
	v_pk_mul_f32 v[206:207], v[206:207], v[210:211] op_sel_hi:[1,0]
	v_pk_mul_f32 v[206:207], v[136:137], v[206:207]
	v_pk_mul_f32 v[212:213], v[82:83], s[8:9] op_sel_hi:[1,0]
	s_nop 0
	v_min_f32_e32 v203, 0x41e6d4ca, v212
	v_pk_mul_f32 v[204:205], v[134:135], v[204:205]
	v_pk_mul_f32 v[210:211], v[84:85], s[8:9] op_sel_hi:[1,0]
	v_exp_f32_e32 v217, v203
	v_min_f32_e32 v203, 0x41e6d4ca, v213
	v_exp_f32_e32 v216, v203
	v_min_f32_e32 v203, 0x41e6d4ca, v210
	v_exp_f32_e32 v213, v203
	v_min_f32_e32 v203, 0x41e6d4ca, v211
	v_exp_f32_e32 v212, v203
	v_pk_add_f32 v[210:211], v[216:217], 1.0 op_sel_hi:[1,0]
	v_cvt_pk_bf16_f32 v204, v204, v205
	v_pk_add_f32 v[212:213], v[212:213], 1.0 op_sel_hi:[1,0]
	v_mul_f32_e32 v216, v211, v210
	v_mul_f32_e32 v217, v213, v212
	v_cvt_pk_bf16_f32 v205, v206, v207
	v_mul_f32_e32 v203, v216, v217
	v_rcp_f32_e32 v203, v203
	s_nop 0
	v_mul_f32_e32 v218, v217, v203
	v_mul_f32_e32 v216, v216, v203
	v_pk_mul_f32 v[210:211], v[210:211], v[218:219] op_sel_hi:[1,0]
	v_pk_mul_f32 v[212:213], v[212:213], v[216:217] op_sel_hi:[1,0]
	v_pk_mul_f32 v[212:213], v[132:133], v[212:213]
	v_pk_mul_f32 v[210:211], v[130:131], v[210:211]
	v_cvt_pk_bf16_f32 v207, v212, v213
	v_cvt_pk_bf16_f32 v206, v210, v211
	v_or_b32_e32 v203, 48, v202
	global_store_dwordx4 v[208:209], v[204:207], off sc1
	v_mad_u64_u32 v[208:209], s[10:11], s56, v203, 0
	s_nop 0
	v_mul_lo_u32 v204, s57, v203
	v_pk_mul_f32 v[206:207], v[78:79], s[8:9] op_sel_hi:[1,0]
	v_add3_u32 v209, v209, v0, v204
	v_min_f32_e32 v0, 0x41e6d4ca, v206
	v_pk_mul_f32 v[204:205], v[80:81], s[8:9] op_sel_hi:[1,0]
	v_exp_f32_e32 v211, v0
	v_min_f32_e32 v0, 0x41e6d4ca, v207
	v_exp_f32_e32 v210, v0
	v_min_f32_e32 v0, 0x41e6d4ca, v204
	v_exp_f32_e32 v207, v0
	v_min_f32_e32 v0, 0x41e6d4ca, v205
	v_exp_f32_e32 v206, v0
	v_pk_add_f32 v[204:205], v[210:211], 1.0 op_sel_hi:[1,0]
	v_lshlrev_b64 v[208:209], 1, v[208:209]
	v_pk_add_f32 v[206:207], v[206:207], 1.0 op_sel_hi:[1,0]
	v_mul_f32_e32 v210, v205, v204
	v_mul_f32_e32 v211, v207, v206
	v_mul_f32_e32 v0, v210, v211
	v_rcp_f32_e32 v203, v0
	s_nop 0
	v_mul_f32_e32 v210, v210, v203
	v_pk_mul_f32 v[206:207], v[206:207], v[210:211] op_sel_hi:[1,0]
	v_mul_f32_e32 v0, v211, v203
	v_pk_mul_f32 v[206:207], v[144:145], v[206:207]
	v_pk_mul_f32 v[212:213], v[74:75], s[8:9] op_sel_hi:[1,0]
	v_pk_mul_f32 v[204:205], v[204:205], v[0:1] op_sel_hi:[1,0]
	v_min_f32_e32 v0, 0x41e6d4ca, v212
	v_pk_mul_f32 v[204:205], v[142:143], v[204:205]
	v_pk_mul_f32 v[210:211], v[76:77], s[8:9] op_sel_hi:[1,0]
	v_exp_f32_e32 v217, v0
	v_min_f32_e32 v0, 0x41e6d4ca, v213
	v_exp_f32_e32 v216, v0
	v_min_f32_e32 v0, 0x41e6d4ca, v210
	v_exp_f32_e32 v213, v0
	v_min_f32_e32 v0, 0x41e6d4ca, v211
	v_exp_f32_e32 v212, v0
	v_pk_add_f32 v[210:211], v[216:217], 1.0 op_sel_hi:[1,0]
	v_cvt_pk_bf16_f32 v204, v204, v205
	v_pk_add_f32 v[212:213], v[212:213], 1.0 op_sel_hi:[1,0]
	v_mul_f32_e32 v216, v211, v210
	v_mul_f32_e32 v217, v213, v212
	v_mul_f32_e32 v0, v216, v217
	v_rcp_f32_e32 v203, v0
	v_cvt_pk_bf16_f32 v205, v206, v207
	v_mul_f32_e32 v0, v217, v203
	v_mul_f32_e32 v216, v216, v203
	v_pk_mul_f32 v[210:211], v[210:211], v[0:1] op_sel_hi:[1,0]
	v_pk_mul_f32 v[212:213], v[212:213], v[216:217] op_sel_hi:[1,0]
	v_pk_mul_f32 v[212:213], v[140:141], v[212:213]
	v_pk_mul_f32 v[210:211], v[138:139], v[210:211]
	v_cvt_pk_bf16_f32 v207, v212, v213
	v_cvt_pk_bf16_f32 v206, v210, v211
	v_lshl_add_u64 v[210:211], v[174:175], 0, v[208:209]
	global_store_dwordx4 v[210:211], v[204:207], off sc1
	v_lshl_add_u64 v[208:209], v[176:177], 0, v[208:209]
	s_nop 0
	v_pk_mul_f32 v[206:207], v[70:71], s[8:9] op_sel_hi:[1,0]
	v_pk_mul_f32 v[204:205], v[72:73], s[8:9] op_sel_hi:[1,0]
	v_min_f32_e32 v0, 0x41e6d4ca, v206
	v_exp_f32_e32 v211, v0
	v_min_f32_e32 v0, 0x41e6d4ca, v207
	v_exp_f32_e32 v210, v0
	v_min_f32_e32 v0, 0x41e6d4ca, v204
	v_exp_f32_e32 v207, v0
	v_min_f32_e32 v0, 0x41e6d4ca, v205
	v_exp_f32_e32 v206, v0
	v_pk_add_f32 v[204:205], v[210:211], 1.0 op_sel_hi:[1,0]
	v_pk_add_f32 v[206:207], v[206:207], 1.0 op_sel_hi:[1,0]
	v_mul_f32_e32 v210, v205, v204
	v_mul_f32_e32 v211, v207, v206
	v_mul_f32_e32 v0, v210, v211
	v_rcp_f32_e32 v203, v0
	s_nop 0
	v_mul_f32_e32 v210, v210, v203
	v_pk_mul_f32 v[206:207], v[206:207], v[210:211] op_sel_hi:[1,0]
	v_mul_f32_e32 v0, v211, v203
	v_pk_mul_f32 v[206:207], v[136:137], v[206:207]
	v_pk_mul_f32 v[212:213], v[66:67], s[8:9] op_sel_hi:[1,0]
	v_pk_mul_f32 v[204:205], v[204:205], v[0:1] op_sel_hi:[1,0]
	v_min_f32_e32 v0, 0x41e6d4ca, v212
	v_pk_mul_f32 v[204:205], v[134:135], v[204:205]
	v_pk_mul_f32 v[210:211], v[68:69], s[8:9] op_sel_hi:[1,0]
	v_exp_f32_e32 v217, v0
	v_min_f32_e32 v0, 0x41e6d4ca, v213
	v_exp_f32_e32 v216, v0
	v_min_f32_e32 v0, 0x41e6d4ca, v210
	v_exp_f32_e32 v213, v0
	v_min_f32_e32 v0, 0x41e6d4ca, v211
	v_exp_f32_e32 v212, v0
	v_pk_add_f32 v[210:211], v[216:217], 1.0 op_sel_hi:[1,0]
	v_cvt_pk_bf16_f32 v204, v204, v205
	v_pk_add_f32 v[212:213], v[212:213], 1.0 op_sel_hi:[1,0]
	v_mul_f32_e32 v216, v211, v210
	v_mul_f32_e32 v217, v213, v212
	v_mul_f32_e32 v0, v216, v217
	v_rcp_f32_e32 v203, v0
	v_cvt_pk_bf16_f32 v205, v206, v207
	v_mul_f32_e32 v0, v217, v203
	v_mul_f32_e32 v216, v216, v203
	v_pk_mul_f32 v[210:211], v[210:211], v[0:1] op_sel_hi:[1,0]
	v_pk_mul_f32 v[212:213], v[212:213], v[216:217] op_sel_hi:[1,0]
	v_pk_mul_f32 v[212:213], v[132:133], v[212:213]
	v_pk_mul_f32 v[210:211], v[130:131], v[210:211]
	v_cvt_pk_bf16_f32 v207, v212, v213
	v_cvt_pk_bf16_f32 v206, v210, v211
	v_add_u32_e32 v0, 0x80, v202
	global_store_dwordx4 v[208:209], v[204:207], off sc1
	v_ashrrev_i32_e32 v203, 31, v0
	v_mul_lo_u32 v203, s56, v203
	v_pk_mul_f32 v[206:207], v[62:63], s[8:9] op_sel_hi:[1,0]
	v_mul_lo_u32 v204, s57, v0
	v_mad_u64_u32 v[208:209], s[10:11], s56, v0, 0
	v_min_f32_e32 v0, 0x41e6d4ca, v206
	v_add3_u32 v209, v209, v203, v204
	v_pk_mul_f32 v[204:205], v[64:65], s[8:9] op_sel_hi:[1,0]
	v_exp_f32_e32 v211, v0
	v_min_f32_e32 v0, 0x41e6d4ca, v207
	v_exp_f32_e32 v210, v0
	v_min_f32_e32 v0, 0x41e6d4ca, v204
	v_exp_f32_e32 v207, v0
	v_min_f32_e32 v0, 0x41e6d4ca, v205
	v_exp_f32_e32 v206, v0
	v_pk_add_f32 v[204:205], v[210:211], 1.0 op_sel_hi:[1,0]
	v_lshlrev_b64 v[208:209], 1, v[208:209]
	v_pk_add_f32 v[206:207], v[206:207], 1.0 op_sel_hi:[1,0]
	v_mul_f32_e32 v210, v205, v204
	v_mul_f32_e32 v211, v207, v206
	v_mul_f32_e32 v0, v210, v211
	v_rcp_f32_e32 v203, v0
	s_nop 0
	v_mul_f32_e32 v210, v210, v203
	v_pk_mul_f32 v[206:207], v[206:207], v[210:211] op_sel_hi:[1,0]
	v_mul_f32_e32 v0, v211, v203
	v_pk_mul_f32 v[206:207], v[144:145], v[206:207]
	v_pk_mul_f32 v[212:213], v[58:59], s[8:9] op_sel_hi:[1,0]
	v_pk_mul_f32 v[204:205], v[204:205], v[0:1] op_sel_hi:[1,0]
	v_min_f32_e32 v0, 0x41e6d4ca, v212
	v_pk_mul_f32 v[204:205], v[142:143], v[204:205]
	v_pk_mul_f32 v[210:211], v[60:61], s[8:9] op_sel_hi:[1,0]
	v_exp_f32_e32 v217, v0
	v_min_f32_e32 v0, 0x41e6d4ca, v213
	v_exp_f32_e32 v216, v0
	v_min_f32_e32 v0, 0x41e6d4ca, v210
	v_exp_f32_e32 v213, v0
	v_min_f32_e32 v0, 0x41e6d4ca, v211
	v_exp_f32_e32 v212, v0
	v_pk_add_f32 v[210:211], v[216:217], 1.0 op_sel_hi:[1,0]
	v_cvt_pk_bf16_f32 v204, v204, v205
	v_pk_add_f32 v[212:213], v[212:213], 1.0 op_sel_hi:[1,0]
	v_mul_f32_e32 v216, v211, v210
	v_mul_f32_e32 v217, v213, v212
	v_mul_f32_e32 v0, v216, v217
	v_rcp_f32_e32 v203, v0
	v_cvt_pk_bf16_f32 v205, v206, v207
	v_mul_f32_e32 v0, v217, v203
	v_mul_f32_e32 v216, v216, v203
	v_pk_mul_f32 v[210:211], v[210:211], v[0:1] op_sel_hi:[1,0]
	v_pk_mul_f32 v[212:213], v[212:213], v[216:217] op_sel_hi:[1,0]
	v_pk_mul_f32 v[212:213], v[140:141], v[212:213]
	v_pk_mul_f32 v[210:211], v[138:139], v[210:211]
	v_cvt_pk_bf16_f32 v207, v212, v213
	v_cvt_pk_bf16_f32 v206, v210, v211
	v_lshl_add_u64 v[210:211], v[174:175], 0, v[208:209]
	global_store_dwordx4 v[210:211], v[204:207], off sc1
	v_lshl_add_u64 v[208:209], v[176:177], 0, v[208:209]
	s_nop 0
	v_pk_mul_f32 v[206:207], v[54:55], s[8:9] op_sel_hi:[1,0]
	v_pk_mul_f32 v[204:205], v[56:57], s[8:9] op_sel_hi:[1,0]
	v_min_f32_e32 v0, 0x41e6d4ca, v206
	v_exp_f32_e32 v211, v0
	v_min_f32_e32 v0, 0x41e6d4ca, v207
	v_exp_f32_e32 v210, v0
	v_min_f32_e32 v0, 0x41e6d4ca, v204
	v_exp_f32_e32 v207, v0
	v_min_f32_e32 v0, 0x41e6d4ca, v205
	v_exp_f32_e32 v206, v0
	v_pk_add_f32 v[204:205], v[210:211], 1.0 op_sel_hi:[1,0]
	v_pk_add_f32 v[206:207], v[206:207], 1.0 op_sel_hi:[1,0]
	v_mul_f32_e32 v210, v205, v204
	v_mul_f32_e32 v211, v207, v206
	v_mul_f32_e32 v0, v210, v211
	v_rcp_f32_e32 v203, v0
	s_nop 0
	v_mul_f32_e32 v210, v210, v203
	v_pk_mul_f32 v[206:207], v[206:207], v[210:211] op_sel_hi:[1,0]
	v_mul_f32_e32 v0, v211, v203
	v_pk_mul_f32 v[206:207], v[136:137], v[206:207]
	v_pk_mul_f32 v[212:213], v[50:51], s[8:9] op_sel_hi:[1,0]
	v_pk_mul_f32 v[204:205], v[204:205], v[0:1] op_sel_hi:[1,0]
	v_min_f32_e32 v0, 0x41e6d4ca, v212
	v_pk_mul_f32 v[204:205], v[134:135], v[204:205]
	v_pk_mul_f32 v[210:211], v[52:53], s[8:9] op_sel_hi:[1,0]
	v_exp_f32_e32 v217, v0
	v_min_f32_e32 v0, 0x41e6d4ca, v213
	v_exp_f32_e32 v216, v0
	v_min_f32_e32 v0, 0x41e6d4ca, v210
	v_exp_f32_e32 v213, v0
	v_min_f32_e32 v0, 0x41e6d4ca, v211
	v_exp_f32_e32 v212, v0
	v_pk_add_f32 v[210:211], v[216:217], 1.0 op_sel_hi:[1,0]
	v_cvt_pk_bf16_f32 v204, v204, v205
	v_pk_add_f32 v[212:213], v[212:213], 1.0 op_sel_hi:[1,0]
	v_mul_f32_e32 v216, v211, v210
	v_mul_f32_e32 v217, v213, v212
	v_mul_f32_e32 v0, v216, v217
	v_rcp_f32_e32 v203, v0
	v_cvt_pk_bf16_f32 v205, v206, v207
	v_mul_f32_e32 v0, v217, v203
	v_mul_f32_e32 v216, v216, v203
	v_pk_mul_f32 v[210:211], v[210:211], v[0:1] op_sel_hi:[1,0]
	v_pk_mul_f32 v[212:213], v[212:213], v[216:217] op_sel_hi:[1,0]
	v_pk_mul_f32 v[212:213], v[132:133], v[212:213]
	v_pk_mul_f32 v[210:211], v[130:131], v[210:211]
	v_cvt_pk_bf16_f32 v207, v212, v213
	v_cvt_pk_bf16_f32 v206, v210, v211
	v_add_u32_e32 v0, 0x90, v202
	global_store_dwordx4 v[208:209], v[204:207], off sc1
	v_ashrrev_i32_e32 v203, 31, v0
	v_mul_lo_u32 v203, s56, v203
	v_pk_mul_f32 v[206:207], v[46:47], s[8:9] op_sel_hi:[1,0]
	v_mul_lo_u32 v204, s57, v0
	v_mad_u64_u32 v[208:209], s[10:11], s56, v0, 0
	v_min_f32_e32 v0, 0x41e6d4ca, v206
	v_add3_u32 v209, v209, v203, v204
	v_pk_mul_f32 v[204:205], v[48:49], s[8:9] op_sel_hi:[1,0]
	v_exp_f32_e32 v211, v0
	v_min_f32_e32 v0, 0x41e6d4ca, v207
	v_exp_f32_e32 v210, v0
	v_min_f32_e32 v0, 0x41e6d4ca, v204
	v_exp_f32_e32 v207, v0
	v_min_f32_e32 v0, 0x41e6d4ca, v205
	v_exp_f32_e32 v206, v0
	v_pk_add_f32 v[204:205], v[210:211], 1.0 op_sel_hi:[1,0]
	v_lshlrev_b64 v[208:209], 1, v[208:209]
	v_pk_add_f32 v[206:207], v[206:207], 1.0 op_sel_hi:[1,0]
	v_mul_f32_e32 v210, v205, v204
	v_mul_f32_e32 v211, v207, v206
	v_mul_f32_e32 v0, v210, v211
	v_rcp_f32_e32 v203, v0
	s_nop 0
	v_mul_f32_e32 v210, v210, v203
	v_pk_mul_f32 v[206:207], v[206:207], v[210:211] op_sel_hi:[1,0]
	v_mul_f32_e32 v0, v211, v203
	v_pk_mul_f32 v[206:207], v[144:145], v[206:207]
	v_pk_mul_f32 v[212:213], v[42:43], s[8:9] op_sel_hi:[1,0]
	v_pk_mul_f32 v[204:205], v[204:205], v[0:1] op_sel_hi:[1,0]
	v_min_f32_e32 v0, 0x41e6d4ca, v212
	v_pk_mul_f32 v[204:205], v[142:143], v[204:205]
	v_pk_mul_f32 v[210:211], v[44:45], s[8:9] op_sel_hi:[1,0]
	v_exp_f32_e32 v217, v0
	v_min_f32_e32 v0, 0x41e6d4ca, v213
	v_exp_f32_e32 v216, v0
	v_min_f32_e32 v0, 0x41e6d4ca, v210
	v_exp_f32_e32 v213, v0
	v_min_f32_e32 v0, 0x41e6d4ca, v211
	v_exp_f32_e32 v212, v0
	v_pk_add_f32 v[210:211], v[216:217], 1.0 op_sel_hi:[1,0]
	v_cvt_pk_bf16_f32 v204, v204, v205
	v_pk_add_f32 v[212:213], v[212:213], 1.0 op_sel_hi:[1,0]
	v_mul_f32_e32 v216, v211, v210
	v_mul_f32_e32 v217, v213, v212
	v_mul_f32_e32 v0, v216, v217
	v_rcp_f32_e32 v203, v0
	v_cvt_pk_bf16_f32 v205, v206, v207
	v_mul_f32_e32 v0, v217, v203
	v_mul_f32_e32 v216, v216, v203
	v_pk_mul_f32 v[210:211], v[210:211], v[0:1] op_sel_hi:[1,0]
	v_pk_mul_f32 v[212:213], v[212:213], v[216:217] op_sel_hi:[1,0]
	v_pk_mul_f32 v[212:213], v[140:141], v[212:213]
	v_pk_mul_f32 v[210:211], v[138:139], v[210:211]
	v_cvt_pk_bf16_f32 v207, v212, v213
	v_cvt_pk_bf16_f32 v206, v210, v211
	v_lshl_add_u64 v[210:211], v[174:175], 0, v[208:209]
	global_store_dwordx4 v[210:211], v[204:207], off sc1
	v_lshl_add_u64 v[208:209], v[176:177], 0, v[208:209]
	s_nop 0
	v_pk_mul_f32 v[206:207], v[38:39], s[8:9] op_sel_hi:[1,0]
	v_pk_mul_f32 v[204:205], v[40:41], s[8:9] op_sel_hi:[1,0]
	v_min_f32_e32 v0, 0x41e6d4ca, v206
	v_exp_f32_e32 v211, v0
	v_min_f32_e32 v0, 0x41e6d4ca, v207
	v_exp_f32_e32 v210, v0
	v_min_f32_e32 v0, 0x41e6d4ca, v204
	v_exp_f32_e32 v207, v0
	v_min_f32_e32 v0, 0x41e6d4ca, v205
	v_exp_f32_e32 v206, v0
	v_pk_add_f32 v[204:205], v[210:211], 1.0 op_sel_hi:[1,0]
	v_pk_add_f32 v[206:207], v[206:207], 1.0 op_sel_hi:[1,0]
	v_mul_f32_e32 v210, v205, v204
	v_mul_f32_e32 v211, v207, v206
	v_mul_f32_e32 v0, v210, v211
	v_rcp_f32_e32 v203, v0
	s_nop 0
	v_mul_f32_e32 v210, v210, v203
	v_pk_mul_f32 v[206:207], v[206:207], v[210:211] op_sel_hi:[1,0]
	v_mul_f32_e32 v0, v211, v203
	v_pk_mul_f32 v[206:207], v[136:137], v[206:207]
	v_pk_mul_f32 v[212:213], v[34:35], s[8:9] op_sel_hi:[1,0]
	v_pk_mul_f32 v[204:205], v[204:205], v[0:1] op_sel_hi:[1,0]
	v_min_f32_e32 v0, 0x41e6d4ca, v212
	v_pk_mul_f32 v[204:205], v[134:135], v[204:205]
	v_pk_mul_f32 v[210:211], v[36:37], s[8:9] op_sel_hi:[1,0]
	v_exp_f32_e32 v217, v0
	v_min_f32_e32 v0, 0x41e6d4ca, v213
	v_exp_f32_e32 v216, v0
	v_min_f32_e32 v0, 0x41e6d4ca, v210
	v_exp_f32_e32 v213, v0
	v_min_f32_e32 v0, 0x41e6d4ca, v211
	v_exp_f32_e32 v212, v0
	v_pk_add_f32 v[210:211], v[216:217], 1.0 op_sel_hi:[1,0]
	v_cvt_pk_bf16_f32 v204, v204, v205
	v_pk_add_f32 v[212:213], v[212:213], 1.0 op_sel_hi:[1,0]
	v_mul_f32_e32 v216, v211, v210
	v_mul_f32_e32 v217, v213, v212
	v_mul_f32_e32 v0, v216, v217
	v_rcp_f32_e32 v203, v0
	v_cvt_pk_bf16_f32 v205, v206, v207
	v_mul_f32_e32 v0, v217, v203
	v_mul_f32_e32 v216, v216, v203
	v_pk_mul_f32 v[210:211], v[210:211], v[0:1] op_sel_hi:[1,0]
	v_pk_mul_f32 v[212:213], v[212:213], v[216:217] op_sel_hi:[1,0]
	v_pk_mul_f32 v[212:213], v[132:133], v[212:213]
	v_pk_mul_f32 v[210:211], v[130:131], v[210:211]
	v_cvt_pk_bf16_f32 v207, v212, v213
	v_cvt_pk_bf16_f32 v206, v210, v211
	v_add_u32_e32 v0, 0xa0, v202
	global_store_dwordx4 v[208:209], v[204:207], off sc1
	v_ashrrev_i32_e32 v203, 31, v0
	v_mul_lo_u32 v203, s56, v203
	v_pk_mul_f32 v[206:207], v[30:31], s[8:9] op_sel_hi:[1,0]
	v_mul_lo_u32 v204, s57, v0
	v_mad_u64_u32 v[208:209], s[10:11], s56, v0, 0
	v_min_f32_e32 v0, 0x41e6d4ca, v206
	v_add3_u32 v209, v209, v203, v204
	v_pk_mul_f32 v[204:205], v[32:33], s[8:9] op_sel_hi:[1,0]
	v_exp_f32_e32 v211, v0
	v_min_f32_e32 v0, 0x41e6d4ca, v207
	v_exp_f32_e32 v210, v0
	v_min_f32_e32 v0, 0x41e6d4ca, v204
	v_exp_f32_e32 v207, v0
	v_min_f32_e32 v0, 0x41e6d4ca, v205
	v_exp_f32_e32 v206, v0
	v_pk_add_f32 v[204:205], v[210:211], 1.0 op_sel_hi:[1,0]
	v_lshlrev_b64 v[208:209], 1, v[208:209]
	v_pk_add_f32 v[206:207], v[206:207], 1.0 op_sel_hi:[1,0]
	v_mul_f32_e32 v210, v205, v204
	v_mul_f32_e32 v211, v207, v206
	v_mul_f32_e32 v0, v210, v211
	v_rcp_f32_e32 v203, v0
	v_lshl_add_u64 v[176:177], v[176:177], 0, v[208:209]
	v_mul_f32_e32 v210, v210, v203
	v_pk_mul_f32 v[206:207], v[206:207], v[210:211] op_sel_hi:[1,0]
	v_mul_f32_e32 v0, v211, v203
	v_pk_mul_f32 v[206:207], v[144:145], v[206:207]
	v_pk_mul_f32 v[212:213], v[26:27], s[8:9] op_sel_hi:[1,0]
	v_pk_mul_f32 v[204:205], v[204:205], v[0:1] op_sel_hi:[1,0]
	v_min_f32_e32 v0, 0x41e6d4ca, v212
	v_pk_mul_f32 v[204:205], v[142:143], v[204:205]
	v_pk_mul_f32 v[210:211], v[28:29], s[8:9] op_sel_hi:[1,0]
	v_exp_f32_e32 v217, v0
	v_min_f32_e32 v0, 0x41e6d4ca, v213
	v_exp_f32_e32 v216, v0
	v_min_f32_e32 v0, 0x41e6d4ca, v210
	v_exp_f32_e32 v213, v0
	v_min_f32_e32 v0, 0x41e6d4ca, v211
	v_exp_f32_e32 v212, v0
	v_pk_add_f32 v[210:211], v[216:217], 1.0 op_sel_hi:[1,0]
	v_cvt_pk_bf16_f32 v204, v204, v205
	v_pk_add_f32 v[212:213], v[212:213], 1.0 op_sel_hi:[1,0]
	v_mul_f32_e32 v216, v211, v210
	v_mul_f32_e32 v217, v213, v212
	v_mul_f32_e32 v0, v216, v217
	v_rcp_f32_e32 v203, v0
	v_cvt_pk_bf16_f32 v205, v206, v207
	v_mul_f32_e32 v0, v217, v203
	v_mul_f32_e32 v216, v216, v203
	v_pk_mul_f32 v[210:211], v[210:211], v[0:1] op_sel_hi:[1,0]
	v_pk_mul_f32 v[212:213], v[212:213], v[216:217] op_sel_hi:[1,0]
	v_pk_mul_f32 v[212:213], v[140:141], v[212:213]
	v_pk_mul_f32 v[210:211], v[138:139], v[210:211]
	v_cvt_pk_bf16_f32 v207, v212, v213
	v_cvt_pk_bf16_f32 v206, v210, v211
	v_lshl_add_u64 v[210:211], v[174:175], 0, v[208:209]
	global_store_dwordx4 v[210:211], v[204:207], off sc1
	s_nop 1
	v_pk_mul_f32 v[206:207], v[22:23], s[8:9] op_sel_hi:[1,0]
	v_pk_mul_f32 v[204:205], v[24:25], s[8:9] op_sel_hi:[1,0]
	v_min_f32_e32 v0, 0x41e6d4ca, v206
	v_exp_f32_e32 v211, v0
	v_min_f32_e32 v0, 0x41e6d4ca, v207
	v_exp_f32_e32 v210, v0
	v_min_f32_e32 v0, 0x41e6d4ca, v204
	v_exp_f32_e32 v207, v0
	v_min_f32_e32 v0, 0x41e6d4ca, v205
	v_exp_f32_e32 v206, v0
	v_pk_add_f32 v[204:205], v[210:211], 1.0 op_sel_hi:[1,0]
	v_pk_add_f32 v[206:207], v[206:207], 1.0 op_sel_hi:[1,0]
	v_mul_f32_e32 v210, v205, v204
	v_mul_f32_e32 v211, v207, v206
	v_mul_f32_e32 v0, v210, v211
	v_rcp_f32_e32 v203, v0
	s_nop 0
	v_mul_f32_e32 v210, v210, v203
	v_pk_mul_f32 v[206:207], v[206:207], v[210:211] op_sel_hi:[1,0]
	v_mul_f32_e32 v0, v211, v203
	v_pk_mul_f32 v[206:207], v[136:137], v[206:207]
	v_pk_mul_f32 v[212:213], v[18:19], s[8:9] op_sel_hi:[1,0]
	v_pk_mul_f32 v[204:205], v[204:205], v[0:1] op_sel_hi:[1,0]
	v_min_f32_e32 v0, 0x41e6d4ca, v212
	v_pk_mul_f32 v[204:205], v[134:135], v[204:205]
	v_pk_mul_f32 v[210:211], v[20:21], s[8:9] op_sel_hi:[1,0]
	v_exp_f32_e32 v217, v0
	v_min_f32_e32 v0, 0x41e6d4ca, v213
	v_exp_f32_e32 v216, v0
	v_min_f32_e32 v0, 0x41e6d4ca, v210
	v_exp_f32_e32 v213, v0
	v_min_f32_e32 v0, 0x41e6d4ca, v211
	v_exp_f32_e32 v212, v0
	v_pk_add_f32 v[210:211], v[216:217], 1.0 op_sel_hi:[1,0]
	v_cvt_pk_bf16_f32 v204, v204, v205
	v_pk_add_f32 v[212:213], v[212:213], 1.0 op_sel_hi:[1,0]
	v_mul_f32_e32 v216, v211, v210
	v_mul_f32_e32 v217, v213, v212
	v_mul_f32_e32 v0, v216, v217
	v_rcp_f32_e32 v203, v0
	v_cvt_pk_bf16_f32 v205, v206, v207
	v_mul_f32_e32 v0, v217, v203
	v_mul_f32_e32 v216, v216, v203
	v_pk_mul_f32 v[210:211], v[210:211], v[0:1] op_sel_hi:[1,0]
	v_pk_mul_f32 v[212:213], v[212:213], v[216:217] op_sel_hi:[1,0]
	v_pk_mul_f32 v[212:213], v[132:133], v[212:213]
	v_pk_mul_f32 v[210:211], v[130:131], v[210:211]
	v_cvt_pk_bf16_f32 v207, v212, v213
	v_cvt_pk_bf16_f32 v206, v210, v211
	v_add_u32_e32 v0, 0xb0, v202
	global_store_dwordx4 v[176:177], v[204:207], off sc1
	v_ashrrev_i32_e32 v176, 31, v0
	v_mul_lo_u32 v203, s56, v176
	v_pk_mul_f32 v[206:207], v[14:15], s[8:9] op_sel_hi:[1,0]
	v_mul_lo_u32 v204, s57, v0
	v_mad_u64_u32 v[176:177], s[10:11], s56, v0, 0
	v_min_f32_e32 v0, 0x41e6d4ca, v206
	v_add3_u32 v177, v177, v203, v204
	v_pk_mul_f32 v[204:205], v[16:17], s[8:9] op_sel_hi:[1,0]
	v_exp_f32_e32 v209, v0
	v_min_f32_e32 v0, 0x41e6d4ca, v207
	v_exp_f32_e32 v208, v0
	v_min_f32_e32 v0, 0x41e6d4ca, v204
	v_exp_f32_e32 v207, v0
	v_min_f32_e32 v0, 0x41e6d4ca, v205
	v_exp_f32_e32 v206, v0
	v_pk_add_f32 v[204:205], v[208:209], 1.0 op_sel_hi:[1,0]
	v_pk_add_f32 v[206:207], v[206:207], 1.0 op_sel_hi:[1,0]
	v_mul_f32_e32 v208, v205, v204
	v_mul_f32_e32 v209, v207, v206
	v_mul_f32_e32 v0, v208, v209
	v_rcp_f32_e32 v203, v0
	s_nop 0
	v_mul_f32_e32 v208, v208, v203
	v_pk_mul_f32 v[206:207], v[206:207], v[208:209] op_sel_hi:[1,0]
	v_mul_f32_e32 v0, v209, v203
	v_pk_mul_f32 v[144:145], v[144:145], v[206:207]
	v_pk_mul_f32 v[206:207], v[10:11], s[8:9] op_sel_hi:[1,0]
	v_pk_mul_f32 v[204:205], v[204:205], v[0:1] op_sel_hi:[1,0]
	v_min_f32_e32 v0, 0x41e6d4ca, v206
	v_pk_mul_f32 v[142:143], v[142:143], v[204:205]
	v_pk_mul_f32 v[204:205], v[12:13], s[8:9] op_sel_hi:[1,0]
	v_exp_f32_e32 v209, v0
	v_min_f32_e32 v0, 0x41e6d4ca, v207
	v_exp_f32_e32 v208, v0
	v_min_f32_e32 v0, 0x41e6d4ca, v204
	v_exp_f32_e32 v207, v0
	v_min_f32_e32 v0, 0x41e6d4ca, v205
	v_exp_f32_e32 v206, v0
	v_pk_add_f32 v[204:205], v[208:209], 1.0 op_sel_hi:[1,0]
	v_pk_add_f32 v[206:207], v[206:207], 1.0 op_sel_hi:[1,0]
	v_mul_f32_e32 v208, v205, v204
	s_nop 0
	v_mul_f32_e32 v209, v207, v206
	v_mul_f32_e32 v0, v208, v209
	v_rcp_f32_e32 v203, v0
	s_mov_b64 s[10:11], 0
	v_mul_f32_e32 v0, v209, v203
	v_mul_f32_e32 v208, v208, v203
	v_pk_mul_f32 v[204:205], v[204:205], v[0:1] op_sel_hi:[1,0]
	v_pk_mul_f32 v[206:207], v[206:207], v[208:209] op_sel_hi:[1,0]
	s_nop 0
	v_pk_mul_f32 v[206:207], v[140:141], v[206:207]
	v_pk_mul_f32 v[140:141], v[138:139], v[204:205]
	v_cvt_pk_bf16_f32 v138, v142, v143
	v_cvt_pk_bf16_f32 v139, v144, v145
	v_cvt_pk_bf16_f32 v140, v140, v141
	v_cvt_pk_bf16_f32 v141, v206, v207
	v_lshl_add_u64 v[142:143], v[176:177], 1, v[174:175]
	global_store_dwordx4 v[142:143], v[138:141], off sc1
	s_nop 1
	v_pk_mul_f32 v[140:141], v[6:7], s[8:9] op_sel_hi:[1,0]
	v_pk_mul_f32 v[138:139], v[8:9], s[8:9] op_sel_hi:[1,0]
	v_min_f32_e32 v0, 0x41e6d4ca, v140
	v_exp_f32_e32 v143, v0
	v_min_f32_e32 v0, 0x41e6d4ca, v141
	v_exp_f32_e32 v142, v0
	v_min_f32_e32 v0, 0x41e6d4ca, v138
	v_exp_f32_e32 v141, v0
	v_min_f32_e32 v0, 0x41e6d4ca, v139
	v_exp_f32_e32 v140, v0
	v_pk_add_f32 v[138:139], v[142:143], 1.0 op_sel_hi:[1,0]
	v_pk_add_f32 v[140:141], v[140:141], 1.0 op_sel_hi:[1,0]
	v_mul_f32_e32 v142, v139, v138
	v_mul_f32_e32 v143, v141, v140
	s_nop 0
	v_mul_f32_e32 v0, v142, v143
	v_rcp_f32_e32 v144, v0
	s_nop 0
	v_mul_f32_e32 v0, v143, v144
	v_pk_mul_f32 v[138:139], v[138:139], v[0:1] op_sel_hi:[1,0]
	v_mul_f32_e32 v142, v142, v144
	v_pk_mul_f32 v[134:135], v[134:135], v[138:139]
	v_pk_mul_f32 v[138:139], v[2:3], s[8:9] op_sel_hi:[1,0]
	v_pk_mul_f32 v[140:141], v[140:141], v[142:143] op_sel_hi:[1,0]
	v_min_f32_e32 v0, 0x41e6d4ca, v138
	v_pk_mul_f32 v[140:141], v[136:137], v[140:141]
	v_pk_mul_f32 v[136:137], v[4:5], s[8:9] op_sel_hi:[1,0]
	v_exp_f32_e32 v143, v0
	v_min_f32_e32 v0, 0x41e6d4ca, v139
	v_exp_f32_e32 v142, v0
	v_min_f32_e32 v0, 0x41e6d4ca, v136
	v_exp_f32_e32 v139, v0
	v_min_f32_e32 v0, 0x41e6d4ca, v137
	v_exp_f32_e32 v138, v0
	v_pk_add_f32 v[136:137], v[142:143], 1.0 op_sel_hi:[1,0]
	v_pk_add_f32 v[138:139], v[138:139], 1.0 op_sel_hi:[1,0]
	v_mul_f32_e32 v142, v137, v136
	v_mul_f32_e32 v143, v139, v138
	s_nop 0
	v_mul_f32_e32 v0, v142, v143
	v_rcp_f32_e32 v144, v0
	s_nop 0
	v_mul_f32_e32 v0, v143, v144
	v_mul_f32_e32 v142, v142, v144
	v_pk_mul_f32 v[144:145], v[136:137], v[0:1] op_sel_hi:[1,0]
	v_pk_mul_f32 v[136:137], v[138:139], v[142:143] op_sel_hi:[1,0]
	s_nop 0
	v_pk_mul_f32 v[136:137], v[132:133], v[136:137]
	v_pk_mul_f32 v[132:133], v[130:131], v[144:145]
	v_cvt_pk_bf16_f32 v130, v134, v135
	v_cvt_pk_bf16_f32 v131, v140, v141
	v_cvt_pk_bf16_f32 v132, v132, v133
	s_branch .LBB0_205
.Lsig_m1:
	v_ashrrev_i32_e32 v0, 31, v202
	v_mul_lo_u32 v174, s57, v202
	v_mul_lo_u32 v0, s56, v0
	v_mad_u64_u32 v[176:177], s[10:11], s56, v202, 0
	v_add3_u32 v177, v177, v0, v174
	v_pk_mul_f32 v[174:175], v[128:129], s[8:9] op_sel_hi:[1,0]
	v_pk_mul_f32 v[204:205], v[126:127], s[8:9] op_sel_hi:[1,0]
	v_min_f32_e32 v174, 0x41e6d4ca, v174
	v_min_f32_e32 v203, 0x41e6d4ca, v204
	v_exp_f32_e32 v207, v203
	v_min_f32_e32 v203, 0x41e6d4ca, v205
	v_exp_f32_e32 v205, v174
	v_min_f32_e32 v174, 0x41e6d4ca, v175
	v_exp_f32_e32 v206, v203
	v_exp_f32_e32 v204, v174
	v_pk_add_f32 v[174:175], v[206:207], 1.0 op_sel_hi:[1,0]
	v_pk_add_f32 v[204:205], v[204:205], 1.0 op_sel_hi:[1,0]
	v_mul_f32_e32 v206, v175, v174
	v_mul_f32_e32 v207, v205, v204
	s_nop 0
	v_mul_f32_e32 v203, v206, v207
	v_rcp_f32_e32 v203, v203
	s_nop 0
	v_mul_f32_e32 v208, v207, v203
	v_mul_f32_e32 v206, v206, v203
	v_pk_mul_f32 v[174:175], v[174:175], v[208:209] op_sel_hi:[1,0]
	v_pk_mul_f32 v[204:205], v[204:205], v[206:207] op_sel_hi:[1,0]
	v_pk_mul_f32 v[174:175], v[126:127], v[174:175]
	v_pk_mul_f32 v[206:207], v[122:123], s[8:9] op_sel_hi:[1,0]
	s_nop 0
	v_min_f32_e32 v203, 0x41e6d4ca, v206
	v_pk_mul_f32 v[208:209], v[128:129], v[204:205]
	v_pk_mul_f32 v[204:205], v[124:125], s[8:9] op_sel_hi:[1,0]
	v_exp_f32_e32 v211, v203
	v_min_f32_e32 v203, 0x41e6d4ca, v207
	v_exp_f32_e32 v210, v203
	v_min_f32_e32 v203, 0x41e6d4ca, v204
	v_exp_f32_e32 v207, v203
	v_min_f32_e32 v203, 0x41e6d4ca, v205
	v_exp_f32_e32 v206, v203
	v_pk_add_f32 v[204:205], v[210:211], 1.0 op_sel_hi:[1,0]
	v_pk_add_f32 v[206:207], v[206:207], 1.0 op_sel_hi:[1,0]
	v_mul_f32_e32 v210, v205, v204
	v_mul_f32_e32 v211, v207, v206
	s_nop 0
	v_mul_f32_e32 v203, v210, v211
	v_rcp_f32_e32 v203, v203
	s_nop 0
	v_mul_f32_e32 v212, v211, v203
	v_mul_f32_e32 v210, v210, v203
	v_pk_mul_f32 v[204:205], v[204:205], v[212:213] op_sel_hi:[1,0]
	v_pk_mul_f32 v[206:207], v[206:207], v[210:211] op_sel_hi:[1,0]
	v_pk_mul_f32 v[212:213], v[124:125], v[206:207]
	v_pk_mul_f32 v[206:207], v[122:123], v[204:205]
	v_cvt_pk_bf16_f32 v204, v174, v175
	v_cvt_pk_bf16_f32 v205, v208, v209
	v_lshl_add_u64 v[174:175], v[170:171], 1, s[86:87]
	v_lshlrev_b64 v[208:209], 1, v[176:177]
	v_cvt_pk_bf16_f32 v206, v206, v207
	v_cvt_pk_bf16_f32 v207, v212, v213
	v_lshl_add_u64 v[176:177], v[174:175], 0, v[208:209]
	global_store_dwordx4 v[176:177], v[204:207], off sc1
	v_pk_mul_f32 v[176:177], v[120:121], s[8:9] op_sel_hi:[1,0]
	s_nop 0
	v_pk_mul_f32 v[204:205], v[118:119], s[8:9] op_sel_hi:[1,0]
	v_min_f32_e32 v176, 0x41e6d4ca, v176
	v_min_f32_e32 v203, 0x41e6d4ca, v204
	v_exp_f32_e32 v207, v203
	v_min_f32_e32 v203, 0x41e6d4ca, v205
	v_exp_f32_e32 v205, v176
	v_min_f32_e32 v176, 0x41e6d4ca, v177
	v_exp_f32_e32 v206, v203
	v_exp_f32_e32 v204, v176
	v_pk_add_f32 v[176:177], v[206:207], 1.0 op_sel_hi:[1,0]
	v_pk_add_f32 v[204:205], v[204:205], 1.0 op_sel_hi:[1,0]
	v_mul_f32_e32 v206, v177, v176
	v_mul_f32_e32 v207, v205, v204
	s_nop 0
	v_mul_f32_e32 v203, v206, v207
	v_rcp_f32_e32 v203, v203
	s_nop 0
	v_mul_f32_e32 v210, v207, v203
	v_mul_f32_e32 v206, v206, v203
	v_pk_mul_f32 v[176:177], v[176:177], v[210:211] op_sel_hi:[1,0]
	v_pk_mul_f32 v[204:205], v[204:205], v[206:207] op_sel_hi:[1,0]
	v_pk_mul_f32 v[176:177], v[118:119], v[176:177]
	v_pk_mul_f32 v[206:207], v[114:115], s[8:9] op_sel_hi:[1,0]
	s_nop 0
	v_min_f32_e32 v203, 0x41e6d4ca, v206
	v_pk_mul_f32 v[210:211], v[120:121], v[204:205]
	v_pk_mul_f32 v[204:205], v[116:117], s[8:9] op_sel_hi:[1,0]
	v_exp_f32_e32 v213, v203
	v_min_f32_e32 v203, 0x41e6d4ca, v207
	v_exp_f32_e32 v212, v203
	v_min_f32_e32 v203, 0x41e6d4ca, v204
	v_exp_f32_e32 v207, v203
	v_min_f32_e32 v203, 0x41e6d4ca, v205
	v_exp_f32_e32 v206, v203
	v_pk_add_f32 v[204:205], v[212:213], 1.0 op_sel_hi:[1,0]
	v_pk_add_f32 v[206:207], v[206:207], 1.0 op_sel_hi:[1,0]
	v_mul_f32_e32 v212, v205, v204
	v_mul_f32_e32 v213, v207, v206
	s_nop 0
	v_mul_f32_e32 v203, v212, v213
	v_rcp_f32_e32 v203, v203
	s_nop 0
	v_mul_f32_e32 v216, v213, v203
	v_mul_f32_e32 v212, v212, v203
	v_pk_mul_f32 v[204:205], v[204:205], v[216:217] op_sel_hi:[1,0]
	v_pk_mul_f32 v[206:207], v[206:207], v[212:213] op_sel_hi:[1,0]
	v_pk_mul_f32 v[216:217], v[116:117], v[206:207]
	v_pk_mul_f32 v[206:207], v[114:115], v[204:205]
	v_cvt_pk_bf16_f32 v204, v176, v177
	v_lshl_add_u64 v[176:177], v[172:173], 1, s[86:87]
	v_cvt_pk_bf16_f32 v205, v210, v211
	v_cvt_pk_bf16_f32 v206, v206, v207
	v_cvt_pk_bf16_f32 v207, v216, v217
	v_lshl_add_u64 v[208:209], v[176:177], 0, v[208:209]
	global_store_dwordx4 v[208:209], v[204:207], off sc1
	v_or_b32_e32 v203, 16, v202
	v_mad_u64_u32 v[208:209], s[10:11], s56, v203, 0
	v_pk_mul_f32 v[206:207], v[110:111], s[8:9] op_sel_hi:[1,0]
	v_mul_lo_u32 v204, s57, v203
	v_min_f32_e32 v203, 0x41e6d4ca, v206
	v_add3_u32 v209, v209, v0, v204
	v_pk_mul_f32 v[204:205], v[112:113], s[8:9] op_sel_hi:[1,0]
	v_exp_f32_e32 v211, v203
	v_min_f32_e32 v203, 0x41e6d4ca, v207
	v_exp_f32_e32 v210, v203
	v_min_f32_e32 v203, 0x41e6d4ca, v204
	v_exp_f32_e32 v207, v203
	v_min_f32_e32 v203, 0x41e6d4ca, v205
	v_exp_f32_e32 v206, v203
	v_pk_add_f32 v[204:205], v[210:211], 1.0 op_sel_hi:[1,0]
	v_lshlrev_b64 v[208:209], 1, v[208:209]
	v_pk_add_f32 v[206:207], v[206:207], 1.0 op_sel_hi:[1,0]
	v_mul_f32_e32 v210, v205, v204
	v_mul_f32_e32 v211, v207, v206
	s_nop 0
	v_mul_f32_e32 v203, v210, v211
	v_rcp_f32_e32 v203, v203
	s_nop 0
	v_mul_f32_e32 v212, v211, v203
	v_mul_f32_e32 v210, v210, v203
	v_pk_mul_f32 v[204:205], v[204:205], v[212:213] op_sel_hi:[1,0]
	v_pk_mul_f32 v[206:207], v[206:207], v[210:211] op_sel_hi:[1,0]
	v_pk_mul_f32 v[206:207], v[112:113], v[206:207]
	v_pk_mul_f32 v[212:213], v[106:107], s[8:9] op_sel_hi:[1,0]
	s_nop 0
	v_min_f32_e32 v203, 0x41e6d4ca, v212
	v_pk_mul_f32 v[204:205], v[110:111], v[204:205]
	v_pk_mul_f32 v[210:211], v[108:109], s[8:9] op_sel_hi:[1,0]
	v_exp_f32_e32 v217, v203
	v_min_f32_e32 v203, 0x41e6d4ca, v213
	v_exp_f32_e32 v216, v203
	v_min_f32_e32 v203, 0x41e6d4ca, v210
	v_exp_f32_e32 v213, v203
	v_min_f32_e32 v203, 0x41e6d4ca, v211
	v_exp_f32_e32 v212, v203
	v_pk_add_f32 v[210:211], v[216:217], 1.0 op_sel_hi:[1,0]
	v_cvt_pk_bf16_f32 v204, v204, v205
	v_pk_add_f32 v[212:213], v[212:213], 1.0 op_sel_hi:[1,0]
	v_mul_f32_e32 v216, v211, v210
	v_mul_f32_e32 v217, v213, v212
	v_cvt_pk_bf16_f32 v205, v206, v207
	v_mul_f32_e32 v203, v216, v217
	v_rcp_f32_e32 v203, v203
	s_nop 0
	v_mul_f32_e32 v218, v217, v203
	v_mul_f32_e32 v216, v216, v203
	v_pk_mul_f32 v[210:211], v[210:211], v[218:219] op_sel_hi:[1,0]
	v_pk_mul_f32 v[212:213], v[212:213], v[216:217] op_sel_hi:[1,0]
	v_pk_mul_f32 v[212:213], v[108:109], v[212:213]
	v_pk_mul_f32 v[210:211], v[106:107], v[210:211]
	v_cvt_pk_bf16_f32 v207, v212, v213
	v_cvt_pk_bf16_f32 v206, v210, v211
	v_lshl_add_u64 v[210:211], v[174:175], 0, v[208:209]
	global_store_dwordx4 v[210:211], v[204:207], off sc1
	v_lshl_add_u64 v[208:209], v[176:177], 0, v[208:209]
	s_nop 0
	v_pk_mul_f32 v[206:207], v[102:103], s[8:9] op_sel_hi:[1,0]
	v_pk_mul_f32 v[204:205], v[104:105], s[8:9] op_sel_hi:[1,0]
	v_min_f32_e32 v203, 0x41e6d4ca, v206
	v_exp_f32_e32 v211, v203
	v_min_f32_e32 v203, 0x41e6d4ca, v207
	v_exp_f32_e32 v210, v203
	v_min_f32_e32 v203, 0x41e6d4ca, v204
	v_exp_f32_e32 v207, v203
	v_min_f32_e32 v203, 0x41e6d4ca, v205
	v_exp_f32_e32 v206, v203
	v_pk_add_f32 v[204:205], v[210:211], 1.0 op_sel_hi:[1,0]
	v_pk_add_f32 v[206:207], v[206:207], 1.0 op_sel_hi:[1,0]
	v_mul_f32_e32 v210, v205, v204
	v_mul_f32_e32 v211, v207, v206
	s_nop 0
	v_mul_f32_e32 v203, v210, v211
	v_rcp_f32_e32 v203, v203
	s_nop 0
	v_mul_f32_e32 v212, v211, v203
	v_mul_f32_e32 v210, v210, v203
	v_pk_mul_f32 v[204:205], v[204:205], v[212:213] op_sel_hi:[1,0]
	v_pk_mul_f32 v[206:207], v[206:207], v[210:211] op_sel_hi:[1,0]
	v_pk_mul_f32 v[206:207], v[104:105], v[206:207]
	v_pk_mul_f32 v[212:213], v[98:99], s[8:9] op_sel_hi:[1,0]
	s_nop 0
	v_min_f32_e32 v203, 0x41e6d4ca, v212
	v_pk_mul_f32 v[204:205], v[102:103], v[204:205]
	v_pk_mul_f32 v[210:211], v[100:101], s[8:9] op_sel_hi:[1,0]
	v_exp_f32_e32 v217, v203
	v_min_f32_e32 v203, 0x41e6d4ca, v213
	v_exp_f32_e32 v216, v203
	v_min_f32_e32 v203, 0x41e6d4ca, v210
	v_exp_f32_e32 v213, v203
	v_min_f32_e32 v203, 0x41e6d4ca, v211
	v_exp_f32_e32 v212, v203
	v_pk_add_f32 v[210:211], v[216:217], 1.0 op_sel_hi:[1,0]
	v_cvt_pk_bf16_f32 v204, v204, v205
	v_pk_add_f32 v[212:213], v[212:213], 1.0 op_sel_hi:[1,0]
	v_mul_f32_e32 v216, v211, v210
	v_mul_f32_e32 v217, v213, v212
	v_cvt_pk_bf16_f32 v205, v206, v207
	v_mul_f32_e32 v203, v216, v217
	v_rcp_f32_e32 v203, v203
	s_nop 0
	v_mul_f32_e32 v218, v217, v203
	v_mul_f32_e32 v216, v216, v203
	v_pk_mul_f32 v[210:211], v[210:211], v[218:219] op_sel_hi:[1,0]
	v_pk_mul_f32 v[212:213], v[212:213], v[216:217] op_sel_hi:[1,0]
	v_pk_mul_f32 v[212:213], v[100:101], v[212:213]
	v_pk_mul_f32 v[210:211], v[98:99], v[210:211]
	v_cvt_pk_bf16_f32 v207, v212, v213
	v_cvt_pk_bf16_f32 v206, v210, v211
	global_store_dwordx4 v[208:209], v[204:207], off sc1
	v_or_b32_e32 v203, 32, v202
	v_mad_u64_u32 v[208:209], s[10:11], s56, v203, 0
	v_pk_mul_f32 v[206:207], v[94:95], s[8:9] op_sel_hi:[1,0]
	v_mul_lo_u32 v204, s57, v203
	v_min_f32_e32 v203, 0x41e6d4ca, v206
	v_add3_u32 v209, v209, v0, v204
	v_pk_mul_f32 v[204:205], v[96:97], s[8:9] op_sel_hi:[1,0]
	v_exp_f32_e32 v211, v203
	v_min_f32_e32 v203, 0x41e6d4ca, v207
	v_exp_f32_e32 v210, v203
	v_min_f32_e32 v203, 0x41e6d4ca, v204
	v_exp_f32_e32 v207, v203
	v_min_f32_e32 v203, 0x41e6d4ca, v205
	v_exp_f32_e32 v206, v203
	v_pk_add_f32 v[204:205], v[210:211], 1.0 op_sel_hi:[1,0]
	v_lshlrev_b64 v[208:209], 1, v[208:209]
	v_pk_add_f32 v[206:207], v[206:207], 1.0 op_sel_hi:[1,0]
	v_mul_f32_e32 v210, v205, v204
	v_mul_f32_e32 v211, v207, v206
	s_nop 0
	v_mul_f32_e32 v203, v210, v211
	v_rcp_f32_e32 v203, v203
	s_nop 0
	v_mul_f32_e32 v212, v211, v203
	v_mul_f32_e32 v210, v210, v203
	v_pk_mul_f32 v[204:205], v[204:205], v[212:213] op_sel_hi:[1,0]
	v_pk_mul_f32 v[206:207], v[206:207], v[210:211] op_sel_hi:[1,0]
	v_pk_mul_f32 v[206:207], v[96:97], v[206:207]
	v_pk_mul_f32 v[212:213], v[90:91], s[8:9] op_sel_hi:[1,0]
	s_nop 0
	v_min_f32_e32 v203, 0x41e6d4ca, v212
	v_pk_mul_f32 v[204:205], v[94:95], v[204:205]
	v_pk_mul_f32 v[210:211], v[92:93], s[8:9] op_sel_hi:[1,0]
	v_exp_f32_e32 v217, v203
	v_min_f32_e32 v203, 0x41e6d4ca, v213
	v_exp_f32_e32 v216, v203
	v_min_f32_e32 v203, 0x41e6d4ca, v210
	v_exp_f32_e32 v213, v203
	v_min_f32_e32 v203, 0x41e6d4ca, v211
	v_exp_f32_e32 v212, v203
	v_pk_add_f32 v[210:211], v[216:217], 1.0 op_sel_hi:[1,0]
	v_cvt_pk_bf16_f32 v204, v204, v205
	v_pk_add_f32 v[212:213], v[212:213], 1.0 op_sel_hi:[1,0]
	v_mul_f32_e32 v216, v211, v210
	v_mul_f32_e32 v217, v213, v212
	v_cvt_pk_bf16_f32 v205, v206, v207
	v_mul_f32_e32 v203, v216, v217
	v_rcp_f32_e32 v203, v203
	s_nop 0
	v_mul_f32_e32 v218, v217, v203
	v_mul_f32_e32 v216, v216, v203
	v_pk_mul_f32 v[210:211], v[210:211], v[218:219] op_sel_hi:[1,0]
	v_pk_mul_f32 v[212:213], v[212:213], v[216:217] op_sel_hi:[1,0]
	v_pk_mul_f32 v[212:213], v[92:93], v[212:213]
	v_pk_mul_f32 v[210:211], v[90:91], v[210:211]
	v_cvt_pk_bf16_f32 v207, v212, v213
	v_cvt_pk_bf16_f32 v206, v210, v211
	v_lshl_add_u64 v[210:211], v[174:175], 0, v[208:209]
	global_store_dwordx4 v[210:211], v[204:207], off sc1
	v_lshl_add_u64 v[208:209], v[176:177], 0, v[208:209]
	s_nop 0
	v_pk_mul_f32 v[206:207], v[86:87], s[8:9] op_sel_hi:[1,0]
	v_pk_mul_f32 v[204:205], v[88:89], s[8:9] op_sel_hi:[1,0]
	v_min_f32_e32 v203, 0x41e6d4ca, v206
	v_exp_f32_e32 v211, v203
	v_min_f32_e32 v203, 0x41e6d4ca, v207
	v_exp_f32_e32 v210, v203
	v_min_f32_e32 v203, 0x41e6d4ca, v204
	v_exp_f32_e32 v207, v203
	v_min_f32_e32 v203, 0x41e6d4ca, v205
	v_exp_f32_e32 v206, v203
	v_pk_add_f32 v[204:205], v[210:211], 1.0 op_sel_hi:[1,0]
	v_pk_add_f32 v[206:207], v[206:207], 1.0 op_sel_hi:[1,0]
	v_mul_f32_e32 v210, v205, v204
	v_mul_f32_e32 v211, v207, v206
	s_nop 0
	v_mul_f32_e32 v203, v210, v211
	v_rcp_f32_e32 v203, v203
	s_nop 0
	v_mul_f32_e32 v212, v211, v203
	v_mul_f32_e32 v210, v210, v203
	v_pk_mul_f32 v[204:205], v[204:205], v[212:213] op_sel_hi:[1,0]
	v_pk_mul_f32 v[206:207], v[206:207], v[210:211] op_sel_hi:[1,0]
	v_pk_mul_f32 v[206:207], v[88:89], v[206:207]
	v_pk_mul_f32 v[212:213], v[82:83], s[8:9] op_sel_hi:[1,0]
	s_nop 0
	v_min_f32_e32 v203, 0x41e6d4ca, v212
	v_pk_mul_f32 v[204:205], v[86:87], v[204:205]
	v_pk_mul_f32 v[210:211], v[84:85], s[8:9] op_sel_hi:[1,0]
	v_exp_f32_e32 v217, v203
	v_min_f32_e32 v203, 0x41e6d4ca, v213
	v_exp_f32_e32 v216, v203
	v_min_f32_e32 v203, 0x41e6d4ca, v210
	v_exp_f32_e32 v213, v203
	v_min_f32_e32 v203, 0x41e6d4ca, v211
	v_exp_f32_e32 v212, v203
	v_pk_add_f32 v[210:211], v[216:217], 1.0 op_sel_hi:[1,0]
	v_cvt_pk_bf16_f32 v204, v204, v205
	v_pk_add_f32 v[212:213], v[212:213], 1.0 op_sel_hi:[1,0]
	v_mul_f32_e32 v216, v211, v210
	v_mul_f32_e32 v217, v213, v212
	v_cvt_pk_bf16_f32 v205, v206, v207
	v_mul_f32_e32 v203, v216, v217
	v_rcp_f32_e32 v203, v203
	s_nop 0
	v_mul_f32_e32 v218, v217, v203
	v_mul_f32_e32 v216, v216, v203
	v_pk_mul_f32 v[210:211], v[210:211], v[218:219] op_sel_hi:[1,0]
	v_pk_mul_f32 v[212:213], v[212:213], v[216:217] op_sel_hi:[1,0]
	v_pk_mul_f32 v[212:213], v[84:85], v[212:213]
	v_pk_mul_f32 v[210:211], v[82:83], v[210:211]
	v_cvt_pk_bf16_f32 v207, v212, v213
	v_cvt_pk_bf16_f32 v206, v210, v211
	v_or_b32_e32 v203, 48, v202
	global_store_dwordx4 v[208:209], v[204:207], off sc1
	v_mad_u64_u32 v[208:209], s[10:11], s56, v203, 0
	s_nop 0
	v_mul_lo_u32 v204, s57, v203
	v_pk_mul_f32 v[206:207], v[78:79], s[8:9] op_sel_hi:[1,0]
	v_add3_u32 v209, v209, v0, v204
	v_min_f32_e32 v0, 0x41e6d4ca, v206
	v_pk_mul_f32 v[204:205], v[80:81], s[8:9] op_sel_hi:[1,0]
	v_exp_f32_e32 v211, v0
	v_min_f32_e32 v0, 0x41e6d4ca, v207
	v_exp_f32_e32 v210, v0
	v_min_f32_e32 v0, 0x41e6d4ca, v204
	v_exp_f32_e32 v207, v0
	v_min_f32_e32 v0, 0x41e6d4ca, v205
	v_exp_f32_e32 v206, v0
	v_pk_add_f32 v[204:205], v[210:211], 1.0 op_sel_hi:[1,0]
	v_lshlrev_b64 v[208:209], 1, v[208:209]
	v_pk_add_f32 v[206:207], v[206:207], 1.0 op_sel_hi:[1,0]
	v_mul_f32_e32 v210, v205, v204
	v_mul_f32_e32 v211, v207, v206
	v_mul_f32_e32 v0, v210, v211
	v_rcp_f32_e32 v203, v0
	s_nop 0
	v_mul_f32_e32 v210, v210, v203
	v_pk_mul_f32 v[206:207], v[206:207], v[210:211] op_sel_hi:[1,0]
	v_mul_f32_e32 v0, v211, v203
	v_pk_mul_f32 v[206:207], v[80:81], v[206:207]
	v_pk_mul_f32 v[212:213], v[74:75], s[8:9] op_sel_hi:[1,0]
	v_pk_mul_f32 v[204:205], v[204:205], v[0:1] op_sel_hi:[1,0]
	v_min_f32_e32 v0, 0x41e6d4ca, v212
	v_pk_mul_f32 v[204:205], v[78:79], v[204:205]
	v_pk_mul_f32 v[210:211], v[76:77], s[8:9] op_sel_hi:[1,0]
	v_exp_f32_e32 v217, v0
	v_min_f32_e32 v0, 0x41e6d4ca, v213
	v_exp_f32_e32 v216, v0
	v_min_f32_e32 v0, 0x41e6d4ca, v210
	v_exp_f32_e32 v213, v0
	v_min_f32_e32 v0, 0x41e6d4ca, v211
	v_exp_f32_e32 v212, v0
	v_pk_add_f32 v[210:211], v[216:217], 1.0 op_sel_hi:[1,0]
	v_cvt_pk_bf16_f32 v204, v204, v205
	v_pk_add_f32 v[212:213], v[212:213], 1.0 op_sel_hi:[1,0]
	v_mul_f32_e32 v216, v211, v210
	v_mul_f32_e32 v217, v213, v212
	v_mul_f32_e32 v0, v216, v217
	v_rcp_f32_e32 v203, v0
	v_cvt_pk_bf16_f32 v205, v206, v207
	v_mul_f32_e32 v0, v217, v203
	v_mul_f32_e32 v216, v216, v203
	v_pk_mul_f32 v[210:211], v[210:211], v[0:1] op_sel_hi:[1,0]
	v_pk_mul_f32 v[212:213], v[212:213], v[216:217] op_sel_hi:[1,0]
	v_pk_mul_f32 v[212:213], v[76:77], v[212:213]
	v_pk_mul_f32 v[210:211], v[74:75], v[210:211]
	v_cvt_pk_bf16_f32 v207, v212, v213
	v_cvt_pk_bf16_f32 v206, v210, v211
	v_lshl_add_u64 v[210:211], v[174:175], 0, v[208:209]
	global_store_dwordx4 v[210:211], v[204:207], off sc1
	v_lshl_add_u64 v[208:209], v[176:177], 0, v[208:209]
	s_nop 0
	v_pk_mul_f32 v[206:207], v[70:71], s[8:9] op_sel_hi:[1,0]
	v_pk_mul_f32 v[204:205], v[72:73], s[8:9] op_sel_hi:[1,0]
	v_min_f32_e32 v0, 0x41e6d4ca, v206
	v_exp_f32_e32 v211, v0
	v_min_f32_e32 v0, 0x41e6d4ca, v207
	v_exp_f32_e32 v210, v0
	v_min_f32_e32 v0, 0x41e6d4ca, v204
	v_exp_f32_e32 v207, v0
	v_min_f32_e32 v0, 0x41e6d4ca, v205
	v_exp_f32_e32 v206, v0
	v_pk_add_f32 v[204:205], v[210:211], 1.0 op_sel_hi:[1,0]
	v_pk_add_f32 v[206:207], v[206:207], 1.0 op_sel_hi:[1,0]
	v_mul_f32_e32 v210, v205, v204
	v_mul_f32_e32 v211, v207, v206
	v_mul_f32_e32 v0, v210, v211
	v_rcp_f32_e32 v203, v0
	s_nop 0
	v_mul_f32_e32 v210, v210, v203
	v_pk_mul_f32 v[206:207], v[206:207], v[210:211] op_sel_hi:[1,0]
	v_mul_f32_e32 v0, v211, v203
	v_pk_mul_f32 v[206:207], v[72:73], v[206:207]
	v_pk_mul_f32 v[212:213], v[66:67], s[8:9] op_sel_hi:[1,0]
	v_pk_mul_f32 v[204:205], v[204:205], v[0:1] op_sel_hi:[1,0]
	v_min_f32_e32 v0, 0x41e6d4ca, v212
	v_pk_mul_f32 v[204:205], v[70:71], v[204:205]
	v_pk_mul_f32 v[210:211], v[68:69], s[8:9] op_sel_hi:[1,0]
	v_exp_f32_e32 v217, v0
	v_min_f32_e32 v0, 0x41e6d4ca, v213
	v_exp_f32_e32 v216, v0
	v_min_f32_e32 v0, 0x41e6d4ca, v210
	v_exp_f32_e32 v213, v0
	v_min_f32_e32 v0, 0x41e6d4ca, v211
	v_exp_f32_e32 v212, v0
	v_pk_add_f32 v[210:211], v[216:217], 1.0 op_sel_hi:[1,0]
	v_cvt_pk_bf16_f32 v204, v204, v205
	v_pk_add_f32 v[212:213], v[212:213], 1.0 op_sel_hi:[1,0]
	v_mul_f32_e32 v216, v211, v210
	v_mul_f32_e32 v217, v213, v212
	v_mul_f32_e32 v0, v216, v217
	v_rcp_f32_e32 v203, v0
	v_cvt_pk_bf16_f32 v205, v206, v207
	v_mul_f32_e32 v0, v217, v203
	v_mul_f32_e32 v216, v216, v203
	v_pk_mul_f32 v[210:211], v[210:211], v[0:1] op_sel_hi:[1,0]
	v_pk_mul_f32 v[212:213], v[212:213], v[216:217] op_sel_hi:[1,0]
	v_pk_mul_f32 v[212:213], v[68:69], v[212:213]
	v_pk_mul_f32 v[210:211], v[66:67], v[210:211]
	v_cvt_pk_bf16_f32 v207, v212, v213
	v_cvt_pk_bf16_f32 v206, v210, v211
	v_add_u32_e32 v0, 0x80, v202
	global_store_dwordx4 v[208:209], v[204:207], off sc1
	v_ashrrev_i32_e32 v203, 31, v0
	v_mul_lo_u32 v203, s56, v203
	v_pk_mul_f32 v[206:207], v[62:63], s[8:9] op_sel_hi:[1,0]
	v_mul_lo_u32 v204, s57, v0
	v_mad_u64_u32 v[208:209], s[10:11], s56, v0, 0
	v_min_f32_e32 v0, 0x41e6d4ca, v206
	v_add3_u32 v209, v209, v203, v204
	v_pk_mul_f32 v[204:205], v[64:65], s[8:9] op_sel_hi:[1,0]
	v_exp_f32_e32 v211, v0
	v_min_f32_e32 v0, 0x41e6d4ca, v207
	v_exp_f32_e32 v210, v0
	v_min_f32_e32 v0, 0x41e6d4ca, v204
	v_exp_f32_e32 v207, v0
	v_min_f32_e32 v0, 0x41e6d4ca, v205
	v_exp_f32_e32 v206, v0
	v_pk_add_f32 v[204:205], v[210:211], 1.0 op_sel_hi:[1,0]
	v_lshlrev_b64 v[208:209], 1, v[208:209]
	v_pk_add_f32 v[206:207], v[206:207], 1.0 op_sel_hi:[1,0]
	v_mul_f32_e32 v210, v205, v204
	v_mul_f32_e32 v211, v207, v206
	v_mul_f32_e32 v0, v210, v211
	v_rcp_f32_e32 v203, v0
	s_nop 0
	v_mul_f32_e32 v210, v210, v203
	v_pk_mul_f32 v[206:207], v[206:207], v[210:211] op_sel_hi:[1,0]
	v_mul_f32_e32 v0, v211, v203
	v_pk_mul_f32 v[206:207], v[64:65], v[206:207]
	v_pk_mul_f32 v[212:213], v[58:59], s[8:9] op_sel_hi:[1,0]
	v_pk_mul_f32 v[204:205], v[204:205], v[0:1] op_sel_hi:[1,0]
	v_min_f32_e32 v0, 0x41e6d4ca, v212
	v_pk_mul_f32 v[204:205], v[62:63], v[204:205]
	v_pk_mul_f32 v[210:211], v[60:61], s[8:9] op_sel_hi:[1,0]
	v_exp_f32_e32 v217, v0
	v_min_f32_e32 v0, 0x41e6d4ca, v213
	v_exp_f32_e32 v216, v0
	v_min_f32_e32 v0, 0x41e6d4ca, v210
	v_exp_f32_e32 v213, v0
	v_min_f32_e32 v0, 0x41e6d4ca, v211
	v_exp_f32_e32 v212, v0
	v_pk_add_f32 v[210:211], v[216:217], 1.0 op_sel_hi:[1,0]
	v_cvt_pk_bf16_f32 v204, v204, v205
	v_pk_add_f32 v[212:213], v[212:213], 1.0 op_sel_hi:[1,0]
	v_mul_f32_e32 v216, v211, v210
	v_mul_f32_e32 v217, v213, v212
	v_mul_f32_e32 v0, v216, v217
	v_rcp_f32_e32 v203, v0
	v_cvt_pk_bf16_f32 v205, v206, v207
	v_mul_f32_e32 v0, v217, v203
	v_mul_f32_e32 v216, v216, v203
	v_pk_mul_f32 v[210:211], v[210:211], v[0:1] op_sel_hi:[1,0]
	v_pk_mul_f32 v[212:213], v[212:213], v[216:217] op_sel_hi:[1,0]
	v_pk_mul_f32 v[212:213], v[60:61], v[212:213]
	v_pk_mul_f32 v[210:211], v[58:59], v[210:211]
	v_cvt_pk_bf16_f32 v207, v212, v213
	v_cvt_pk_bf16_f32 v206, v210, v211
	v_lshl_add_u64 v[210:211], v[174:175], 0, v[208:209]
	global_store_dwordx4 v[210:211], v[204:207], off sc1
	v_lshl_add_u64 v[208:209], v[176:177], 0, v[208:209]
	s_nop 0
	v_pk_mul_f32 v[206:207], v[54:55], s[8:9] op_sel_hi:[1,0]
	v_pk_mul_f32 v[204:205], v[56:57], s[8:9] op_sel_hi:[1,0]
	v_min_f32_e32 v0, 0x41e6d4ca, v206
	v_exp_f32_e32 v211, v0
	v_min_f32_e32 v0, 0x41e6d4ca, v207
	v_exp_f32_e32 v210, v0
	v_min_f32_e32 v0, 0x41e6d4ca, v204
	v_exp_f32_e32 v207, v0
	v_min_f32_e32 v0, 0x41e6d4ca, v205
	v_exp_f32_e32 v206, v0
	v_pk_add_f32 v[204:205], v[210:211], 1.0 op_sel_hi:[1,0]
	v_pk_add_f32 v[206:207], v[206:207], 1.0 op_sel_hi:[1,0]
	v_mul_f32_e32 v210, v205, v204
	v_mul_f32_e32 v211, v207, v206
	v_mul_f32_e32 v0, v210, v211
	v_rcp_f32_e32 v203, v0
	s_nop 0
	v_mul_f32_e32 v210, v210, v203
	v_pk_mul_f32 v[206:207], v[206:207], v[210:211] op_sel_hi:[1,0]
	v_mul_f32_e32 v0, v211, v203
	v_pk_mul_f32 v[206:207], v[56:57], v[206:207]
	v_pk_mul_f32 v[212:213], v[50:51], s[8:9] op_sel_hi:[1,0]
	v_pk_mul_f32 v[204:205], v[204:205], v[0:1] op_sel_hi:[1,0]
	v_min_f32_e32 v0, 0x41e6d4ca, v212
	v_pk_mul_f32 v[204:205], v[54:55], v[204:205]
	v_pk_mul_f32 v[210:211], v[52:53], s[8:9] op_sel_hi:[1,0]
	v_exp_f32_e32 v217, v0
	v_min_f32_e32 v0, 0x41e6d4ca, v213
	v_exp_f32_e32 v216, v0
	v_min_f32_e32 v0, 0x41e6d4ca, v210
	v_exp_f32_e32 v213, v0
	v_min_f32_e32 v0, 0x41e6d4ca, v211
	v_exp_f32_e32 v212, v0
	v_pk_add_f32 v[210:211], v[216:217], 1.0 op_sel_hi:[1,0]
	v_cvt_pk_bf16_f32 v204, v204, v205
	v_pk_add_f32 v[212:213], v[212:213], 1.0 op_sel_hi:[1,0]
	v_mul_f32_e32 v216, v211, v210
	v_mul_f32_e32 v217, v213, v212
	v_mul_f32_e32 v0, v216, v217
	v_rcp_f32_e32 v203, v0
	v_cvt_pk_bf16_f32 v205, v206, v207
	v_mul_f32_e32 v0, v217, v203
	v_mul_f32_e32 v216, v216, v203
	v_pk_mul_f32 v[210:211], v[210:211], v[0:1] op_sel_hi:[1,0]
	v_pk_mul_f32 v[212:213], v[212:213], v[216:217] op_sel_hi:[1,0]
	v_pk_mul_f32 v[212:213], v[52:53], v[212:213]
	v_pk_mul_f32 v[210:211], v[50:51], v[210:211]
	v_cvt_pk_bf16_f32 v207, v212, v213
	v_cvt_pk_bf16_f32 v206, v210, v211
	v_add_u32_e32 v0, 0x90, v202
	global_store_dwordx4 v[208:209], v[204:207], off sc1
	v_ashrrev_i32_e32 v203, 31, v0
	v_mul_lo_u32 v203, s56, v203
	v_pk_mul_f32 v[206:207], v[46:47], s[8:9] op_sel_hi:[1,0]
	v_mul_lo_u32 v204, s57, v0
	v_mad_u64_u32 v[208:209], s[10:11], s56, v0, 0
	v_min_f32_e32 v0, 0x41e6d4ca, v206
	v_add3_u32 v209, v209, v203, v204
	v_pk_mul_f32 v[204:205], v[48:49], s[8:9] op_sel_hi:[1,0]
	v_exp_f32_e32 v211, v0
	v_min_f32_e32 v0, 0x41e6d4ca, v207
	v_exp_f32_e32 v210, v0
	v_min_f32_e32 v0, 0x41e6d4ca, v204
	v_exp_f32_e32 v207, v0
	v_min_f32_e32 v0, 0x41e6d4ca, v205
	v_exp_f32_e32 v206, v0
	v_pk_add_f32 v[204:205], v[210:211], 1.0 op_sel_hi:[1,0]
	v_lshlrev_b64 v[208:209], 1, v[208:209]
	v_pk_add_f32 v[206:207], v[206:207], 1.0 op_sel_hi:[1,0]
	v_mul_f32_e32 v210, v205, v204
	v_mul_f32_e32 v211, v207, v206
	v_mul_f32_e32 v0, v210, v211
	v_rcp_f32_e32 v203, v0
	s_nop 0
	v_mul_f32_e32 v210, v210, v203
	v_pk_mul_f32 v[206:207], v[206:207], v[210:211] op_sel_hi:[1,0]
	v_mul_f32_e32 v0, v211, v203
	v_pk_mul_f32 v[206:207], v[48:49], v[206:207]
	v_pk_mul_f32 v[212:213], v[42:43], s[8:9] op_sel_hi:[1,0]
	v_pk_mul_f32 v[204:205], v[204:205], v[0:1] op_sel_hi:[1,0]
	v_min_f32_e32 v0, 0x41e6d4ca, v212
	v_pk_mul_f32 v[204:205], v[46:47], v[204:205]
	v_pk_mul_f32 v[210:211], v[44:45], s[8:9] op_sel_hi:[1,0]
	v_exp_f32_e32 v217, v0
	v_min_f32_e32 v0, 0x41e6d4ca, v213
	v_exp_f32_e32 v216, v0
	v_min_f32_e32 v0, 0x41e6d4ca, v210
	v_exp_f32_e32 v213, v0
	v_min_f32_e32 v0, 0x41e6d4ca, v211
	v_exp_f32_e32 v212, v0
	v_pk_add_f32 v[210:211], v[216:217], 1.0 op_sel_hi:[1,0]
	v_cvt_pk_bf16_f32 v204, v204, v205
	v_pk_add_f32 v[212:213], v[212:213], 1.0 op_sel_hi:[1,0]
	v_mul_f32_e32 v216, v211, v210
	v_mul_f32_e32 v217, v213, v212
	v_mul_f32_e32 v0, v216, v217
	v_rcp_f32_e32 v203, v0
	v_cvt_pk_bf16_f32 v205, v206, v207
	v_mul_f32_e32 v0, v217, v203
	v_mul_f32_e32 v216, v216, v203
	v_pk_mul_f32 v[210:211], v[210:211], v[0:1] op_sel_hi:[1,0]
	v_pk_mul_f32 v[212:213], v[212:213], v[216:217] op_sel_hi:[1,0]
	v_pk_mul_f32 v[212:213], v[44:45], v[212:213]
	v_pk_mul_f32 v[210:211], v[42:43], v[210:211]
	v_cvt_pk_bf16_f32 v207, v212, v213
	v_cvt_pk_bf16_f32 v206, v210, v211
	v_lshl_add_u64 v[210:211], v[174:175], 0, v[208:209]
	global_store_dwordx4 v[210:211], v[204:207], off sc1
	v_lshl_add_u64 v[208:209], v[176:177], 0, v[208:209]
	s_nop 0
	v_pk_mul_f32 v[206:207], v[38:39], s[8:9] op_sel_hi:[1,0]
	v_pk_mul_f32 v[204:205], v[40:41], s[8:9] op_sel_hi:[1,0]
	v_min_f32_e32 v0, 0x41e6d4ca, v206
	v_exp_f32_e32 v211, v0
	v_min_f32_e32 v0, 0x41e6d4ca, v207
	v_exp_f32_e32 v210, v0
	v_min_f32_e32 v0, 0x41e6d4ca, v204
	v_exp_f32_e32 v207, v0
	v_min_f32_e32 v0, 0x41e6d4ca, v205
	v_exp_f32_e32 v206, v0
	v_pk_add_f32 v[204:205], v[210:211], 1.0 op_sel_hi:[1,0]
	v_pk_add_f32 v[206:207], v[206:207], 1.0 op_sel_hi:[1,0]
	v_mul_f32_e32 v210, v205, v204
	v_mul_f32_e32 v211, v207, v206
	v_mul_f32_e32 v0, v210, v211
	v_rcp_f32_e32 v203, v0
	s_nop 0
	v_mul_f32_e32 v210, v210, v203
	v_pk_mul_f32 v[206:207], v[206:207], v[210:211] op_sel_hi:[1,0]
	v_mul_f32_e32 v0, v211, v203
	v_pk_mul_f32 v[206:207], v[40:41], v[206:207]
	v_pk_mul_f32 v[212:213], v[34:35], s[8:9] op_sel_hi:[1,0]
	v_pk_mul_f32 v[204:205], v[204:205], v[0:1] op_sel_hi:[1,0]
	v_min_f32_e32 v0, 0x41e6d4ca, v212
	v_pk_mul_f32 v[204:205], v[38:39], v[204:205]
	v_pk_mul_f32 v[210:211], v[36:37], s[8:9] op_sel_hi:[1,0]
	v_exp_f32_e32 v217, v0
	v_min_f32_e32 v0, 0x41e6d4ca, v213
	v_exp_f32_e32 v216, v0
	v_min_f32_e32 v0, 0x41e6d4ca, v210
	v_exp_f32_e32 v213, v0
	v_min_f32_e32 v0, 0x41e6d4ca, v211
	v_exp_f32_e32 v212, v0
	v_pk_add_f32 v[210:211], v[216:217], 1.0 op_sel_hi:[1,0]
	v_cvt_pk_bf16_f32 v204, v204, v205
	v_pk_add_f32 v[212:213], v[212:213], 1.0 op_sel_hi:[1,0]
	v_mul_f32_e32 v216, v211, v210
	v_mul_f32_e32 v217, v213, v212
	v_mul_f32_e32 v0, v216, v217
	v_rcp_f32_e32 v203, v0
	v_cvt_pk_bf16_f32 v205, v206, v207
	v_mul_f32_e32 v0, v217, v203
	v_mul_f32_e32 v216, v216, v203
	v_pk_mul_f32 v[210:211], v[210:211], v[0:1] op_sel_hi:[1,0]
	v_pk_mul_f32 v[212:213], v[212:213], v[216:217] op_sel_hi:[1,0]
	v_pk_mul_f32 v[212:213], v[36:37], v[212:213]
	v_pk_mul_f32 v[210:211], v[34:35], v[210:211]
	v_cvt_pk_bf16_f32 v207, v212, v213
	v_cvt_pk_bf16_f32 v206, v210, v211
	v_add_u32_e32 v0, 0xa0, v202
	global_store_dwordx4 v[208:209], v[204:207], off sc1
	v_ashrrev_i32_e32 v203, 31, v0
	v_mul_lo_u32 v203, s56, v203
	v_pk_mul_f32 v[206:207], v[30:31], s[8:9] op_sel_hi:[1,0]
	v_mul_lo_u32 v204, s57, v0
	v_mad_u64_u32 v[208:209], s[10:11], s56, v0, 0
	v_min_f32_e32 v0, 0x41e6d4ca, v206
	v_add3_u32 v209, v209, v203, v204
	v_pk_mul_f32 v[204:205], v[32:33], s[8:9] op_sel_hi:[1,0]
	v_exp_f32_e32 v211, v0
	v_min_f32_e32 v0, 0x41e6d4ca, v207
	v_exp_f32_e32 v210, v0
	v_min_f32_e32 v0, 0x41e6d4ca, v204
	v_exp_f32_e32 v207, v0
	v_min_f32_e32 v0, 0x41e6d4ca, v205
	v_exp_f32_e32 v206, v0
	v_pk_add_f32 v[204:205], v[210:211], 1.0 op_sel_hi:[1,0]
	v_lshlrev_b64 v[208:209], 1, v[208:209]
	v_pk_add_f32 v[206:207], v[206:207], 1.0 op_sel_hi:[1,0]
	v_mul_f32_e32 v210, v205, v204
	v_mul_f32_e32 v211, v207, v206
	v_mul_f32_e32 v0, v210, v211
	v_rcp_f32_e32 v203, v0
	v_lshl_add_u64 v[176:177], v[176:177], 0, v[208:209]
	v_mul_f32_e32 v210, v210, v203
	v_pk_mul_f32 v[206:207], v[206:207], v[210:211] op_sel_hi:[1,0]
	v_mul_f32_e32 v0, v211, v203
	v_pk_mul_f32 v[206:207], v[32:33], v[206:207]
	v_pk_mul_f32 v[212:213], v[26:27], s[8:9] op_sel_hi:[1,0]
	v_pk_mul_f32 v[204:205], v[204:205], v[0:1] op_sel_hi:[1,0]
	v_min_f32_e32 v0, 0x41e6d4ca, v212
	v_pk_mul_f32 v[204:205], v[30:31], v[204:205]
	v_pk_mul_f32 v[210:211], v[28:29], s[8:9] op_sel_hi:[1,0]
	v_exp_f32_e32 v217, v0
	v_min_f32_e32 v0, 0x41e6d4ca, v213
	v_exp_f32_e32 v216, v0
	v_min_f32_e32 v0, 0x41e6d4ca, v210
	v_exp_f32_e32 v213, v0
	v_min_f32_e32 v0, 0x41e6d4ca, v211
	v_exp_f32_e32 v212, v0
	v_pk_add_f32 v[210:211], v[216:217], 1.0 op_sel_hi:[1,0]
	v_cvt_pk_bf16_f32 v204, v204, v205
	v_pk_add_f32 v[212:213], v[212:213], 1.0 op_sel_hi:[1,0]
	v_mul_f32_e32 v216, v211, v210
	v_mul_f32_e32 v217, v213, v212
	v_mul_f32_e32 v0, v216, v217
	v_rcp_f32_e32 v203, v0
	v_cvt_pk_bf16_f32 v205, v206, v207
	v_mul_f32_e32 v0, v217, v203
	v_mul_f32_e32 v216, v216, v203
	v_pk_mul_f32 v[210:211], v[210:211], v[0:1] op_sel_hi:[1,0]
	v_pk_mul_f32 v[212:213], v[212:213], v[216:217] op_sel_hi:[1,0]
	v_pk_mul_f32 v[212:213], v[28:29], v[212:213]
	v_pk_mul_f32 v[210:211], v[26:27], v[210:211]
	v_cvt_pk_bf16_f32 v207, v212, v213
	v_cvt_pk_bf16_f32 v206, v210, v211
	v_lshl_add_u64 v[210:211], v[174:175], 0, v[208:209]
	global_store_dwordx4 v[210:211], v[204:207], off sc1
	s_nop 1
	v_pk_mul_f32 v[206:207], v[22:23], s[8:9] op_sel_hi:[1,0]
	v_pk_mul_f32 v[204:205], v[24:25], s[8:9] op_sel_hi:[1,0]
	v_min_f32_e32 v0, 0x41e6d4ca, v206
	v_exp_f32_e32 v211, v0
	v_min_f32_e32 v0, 0x41e6d4ca, v207
	v_exp_f32_e32 v210, v0
	v_min_f32_e32 v0, 0x41e6d4ca, v204
	v_exp_f32_e32 v207, v0
	v_min_f32_e32 v0, 0x41e6d4ca, v205
	v_exp_f32_e32 v206, v0
	v_pk_add_f32 v[204:205], v[210:211], 1.0 op_sel_hi:[1,0]
	v_pk_add_f32 v[206:207], v[206:207], 1.0 op_sel_hi:[1,0]
	v_mul_f32_e32 v210, v205, v204
	v_mul_f32_e32 v211, v207, v206
	v_mul_f32_e32 v0, v210, v211
	v_rcp_f32_e32 v203, v0
	s_nop 0
	v_mul_f32_e32 v210, v210, v203
	v_pk_mul_f32 v[206:207], v[206:207], v[210:211] op_sel_hi:[1,0]
	v_mul_f32_e32 v0, v211, v203
	v_pk_mul_f32 v[206:207], v[24:25], v[206:207]
	v_pk_mul_f32 v[212:213], v[18:19], s[8:9] op_sel_hi:[1,0]
	v_pk_mul_f32 v[204:205], v[204:205], v[0:1] op_sel_hi:[1,0]
	v_min_f32_e32 v0, 0x41e6d4ca, v212
	v_pk_mul_f32 v[204:205], v[22:23], v[204:205]
	v_pk_mul_f32 v[210:211], v[20:21], s[8:9] op_sel_hi:[1,0]
	v_exp_f32_e32 v217, v0
	v_min_f32_e32 v0, 0x41e6d4ca, v213
	v_exp_f32_e32 v216, v0
	v_min_f32_e32 v0, 0x41e6d4ca, v210
	v_exp_f32_e32 v213, v0
	v_min_f32_e32 v0, 0x41e6d4ca, v211
	v_exp_f32_e32 v212, v0
	v_pk_add_f32 v[210:211], v[216:217], 1.0 op_sel_hi:[1,0]
	v_cvt_pk_bf16_f32 v204, v204, v205
	v_pk_add_f32 v[212:213], v[212:213], 1.0 op_sel_hi:[1,0]
	v_mul_f32_e32 v216, v211, v210
	v_mul_f32_e32 v217, v213, v212
	v_mul_f32_e32 v0, v216, v217
	v_rcp_f32_e32 v203, v0
	v_cvt_pk_bf16_f32 v205, v206, v207
	v_mul_f32_e32 v0, v217, v203
	v_mul_f32_e32 v216, v216, v203
	v_pk_mul_f32 v[210:211], v[210:211], v[0:1] op_sel_hi:[1,0]
	v_pk_mul_f32 v[212:213], v[212:213], v[216:217] op_sel_hi:[1,0]
	v_pk_mul_f32 v[212:213], v[20:21], v[212:213]
	v_pk_mul_f32 v[210:211], v[18:19], v[210:211]
	v_cvt_pk_bf16_f32 v207, v212, v213
	v_cvt_pk_bf16_f32 v206, v210, v211
	v_add_u32_e32 v0, 0xb0, v202
	global_store_dwordx4 v[176:177], v[204:207], off sc1
	v_ashrrev_i32_e32 v176, 31, v0
	v_mul_lo_u32 v203, s56, v176
	v_pk_mul_f32 v[206:207], v[14:15], s[8:9] op_sel_hi:[1,0]
	v_mul_lo_u32 v204, s57, v0
	v_mad_u64_u32 v[176:177], s[10:11], s56, v0, 0
	v_min_f32_e32 v0, 0x41e6d4ca, v206
	v_add3_u32 v177, v177, v203, v204
	v_pk_mul_f32 v[204:205], v[16:17], s[8:9] op_sel_hi:[1,0]
	v_exp_f32_e32 v209, v0
	v_min_f32_e32 v0, 0x41e6d4ca, v207
	v_exp_f32_e32 v208, v0
	v_min_f32_e32 v0, 0x41e6d4ca, v204
	v_exp_f32_e32 v207, v0
	v_min_f32_e32 v0, 0x41e6d4ca, v205
	v_exp_f32_e32 v206, v0
	v_pk_add_f32 v[204:205], v[208:209], 1.0 op_sel_hi:[1,0]
	v_pk_add_f32 v[206:207], v[206:207], 1.0 op_sel_hi:[1,0]
	v_mul_f32_e32 v208, v205, v204
	v_mul_f32_e32 v209, v207, v206
	v_mul_f32_e32 v0, v208, v209
	v_rcp_f32_e32 v203, v0
	s_nop 0
	v_mul_f32_e32 v208, v208, v203
	v_pk_mul_f32 v[206:207], v[206:207], v[208:209] op_sel_hi:[1,0]
	v_mul_f32_e32 v0, v209, v203
	v_pk_mul_f32 v[144:145], v[16:17], v[206:207]
	v_pk_mul_f32 v[206:207], v[10:11], s[8:9] op_sel_hi:[1,0]
	v_pk_mul_f32 v[204:205], v[204:205], v[0:1] op_sel_hi:[1,0]
	v_min_f32_e32 v0, 0x41e6d4ca, v206
	v_pk_mul_f32 v[142:143], v[14:15], v[204:205]
	v_pk_mul_f32 v[204:205], v[12:13], s[8:9] op_sel_hi:[1,0]
	v_exp_f32_e32 v209, v0
	v_min_f32_e32 v0, 0x41e6d4ca, v207
	v_exp_f32_e32 v208, v0
	v_min_f32_e32 v0, 0x41e6d4ca, v204
	v_exp_f32_e32 v207, v0
	v_min_f32_e32 v0, 0x41e6d4ca, v205
	v_exp_f32_e32 v206, v0
	v_pk_add_f32 v[204:205], v[208:209], 1.0 op_sel_hi:[1,0]
	v_pk_add_f32 v[206:207], v[206:207], 1.0 op_sel_hi:[1,0]
	v_mul_f32_e32 v208, v205, v204
	s_nop 0
	v_mul_f32_e32 v209, v207, v206
	v_mul_f32_e32 v0, v208, v209
	v_rcp_f32_e32 v203, v0
	s_mov_b64 s[10:11], 0
	v_mul_f32_e32 v0, v209, v203
	v_mul_f32_e32 v208, v208, v203
	v_pk_mul_f32 v[204:205], v[204:205], v[0:1] op_sel_hi:[1,0]
	v_pk_mul_f32 v[206:207], v[206:207], v[208:209] op_sel_hi:[1,0]
	s_nop 0
	v_pk_mul_f32 v[206:207], v[12:13], v[206:207]
	v_pk_mul_f32 v[140:141], v[10:11], v[204:205]
	v_cvt_pk_bf16_f32 v138, v142, v143
	v_cvt_pk_bf16_f32 v139, v144, v145
	v_cvt_pk_bf16_f32 v140, v140, v141
	v_cvt_pk_bf16_f32 v141, v206, v207
	v_lshl_add_u64 v[142:143], v[176:177], 1, v[174:175]
	global_store_dwordx4 v[142:143], v[138:141], off sc1
	s_nop 1
	v_pk_mul_f32 v[140:141], v[6:7], s[8:9] op_sel_hi:[1,0]
	v_pk_mul_f32 v[138:139], v[8:9], s[8:9] op_sel_hi:[1,0]
	v_min_f32_e32 v0, 0x41e6d4ca, v140
	v_exp_f32_e32 v143, v0
	v_min_f32_e32 v0, 0x41e6d4ca, v141
	v_exp_f32_e32 v142, v0
	v_min_f32_e32 v0, 0x41e6d4ca, v138
	v_exp_f32_e32 v141, v0
	v_min_f32_e32 v0, 0x41e6d4ca, v139
	v_exp_f32_e32 v140, v0
	v_pk_add_f32 v[138:139], v[142:143], 1.0 op_sel_hi:[1,0]
	v_pk_add_f32 v[140:141], v[140:141], 1.0 op_sel_hi:[1,0]
	v_mul_f32_e32 v142, v139, v138
	v_mul_f32_e32 v143, v141, v140
	s_nop 0
	v_mul_f32_e32 v0, v142, v143
	v_rcp_f32_e32 v144, v0
	s_nop 0
	v_mul_f32_e32 v0, v143, v144
	v_pk_mul_f32 v[138:139], v[138:139], v[0:1] op_sel_hi:[1,0]
	v_mul_f32_e32 v142, v142, v144
	v_pk_mul_f32 v[134:135], v[6:7], v[138:139]
	v_pk_mul_f32 v[138:139], v[2:3], s[8:9] op_sel_hi:[1,0]
	v_pk_mul_f32 v[140:141], v[140:141], v[142:143] op_sel_hi:[1,0]
	v_min_f32_e32 v0, 0x41e6d4ca, v138
	v_pk_mul_f32 v[140:141], v[8:9], v[140:141]
	v_pk_mul_f32 v[136:137], v[4:5], s[8:9] op_sel_hi:[1,0]
	v_exp_f32_e32 v143, v0
	v_min_f32_e32 v0, 0x41e6d4ca, v139
	v_exp_f32_e32 v142, v0
	v_min_f32_e32 v0, 0x41e6d4ca, v136
	v_exp_f32_e32 v139, v0
	v_min_f32_e32 v0, 0x41e6d4ca, v137
	v_exp_f32_e32 v138, v0
	v_pk_add_f32 v[136:137], v[142:143], 1.0 op_sel_hi:[1,0]
	v_pk_add_f32 v[138:139], v[138:139], 1.0 op_sel_hi:[1,0]
	v_mul_f32_e32 v142, v137, v136
	v_mul_f32_e32 v143, v139, v138
	s_nop 0
	v_mul_f32_e32 v0, v142, v143
	v_rcp_f32_e32 v144, v0
	s_nop 0
	v_mul_f32_e32 v0, v143, v144
	v_mul_f32_e32 v142, v142, v144
	v_pk_mul_f32 v[144:145], v[136:137], v[0:1] op_sel_hi:[1,0]
	v_pk_mul_f32 v[136:137], v[138:139], v[142:143] op_sel_hi:[1,0]
	s_nop 0
	v_pk_mul_f32 v[136:137], v[4:5], v[136:137]
	v_pk_mul_f32 v[132:133], v[2:3], v[144:145]
	v_cvt_pk_bf16_f32 v130, v134, v135
	v_cvt_pk_bf16_f32 v131, v140, v141
	v_cvt_pk_bf16_f32 v132, v132, v133
.LBB0_205:
	s_and_b64 vcc, exec, s[10:11]
	s_cbranch_vccz .LBB0_207
	v_mul_f32_e32 v0, 0xbfb8aa3b, v126
	v_min_f32_e32 v0, 0x41e6d4ca, v0
	v_mul_f32_e32 v131, 0xbfb8aa3b, v127
	v_exp_f32_e32 v0, v0
	v_min_f32_e32 v131, 0x41e6d4ca, v131
	v_mul_f32_e32 v133, 0xbfb8aa3b, v128
	v_exp_f32_e32 v131, v131
	v_min_f32_e32 v133, 0x41e6d4ca, v133
	v_mul_f32_e32 v135, 0xbfb8aa3b, v129
	v_exp_f32_e32 v134, v133
	v_min_f32_e32 v135, 0x41e6d4ca, v135
	v_mul_f32_e32 v137, 0xbfb8aa3b, v122
	v_exp_f32_e32 v135, v135
	v_min_f32_e32 v137, 0x41e6d4ca, v137
	v_mul_f32_e32 v139, 0xbfb8aa3b, v123
	v_add_f32_e32 v0, 1.0, v0
	v_exp_f32_e32 v138, v137
	v_min_f32_e32 v139, 0x41e6d4ca, v139
	v_mul_f32_e32 v141, 0xbfb8aa3b, v124
	v_mul_f32_e32 v130, 0xbfb8aa3b, v118
	v_rcp_f32_e32 v132, v0
	v_add_f32_e32 v0, 1.0, v131
	v_mul_f32_e32 v131, 0xbfb8aa3b, v119
	v_exp_f32_e32 v139, v139
	v_min_f32_e32 v141, 0x41e6d4ca, v141
	v_mul_f32_e32 v143, 0xbfb8aa3b, v125
	v_min_f32_e32 v130, 0x41e6d4ca, v130
	v_min_f32_e32 v131, 0x41e6d4ca, v131
	v_rcp_f32_e32 v133, v0
	v_add_f32_e32 v0, 1.0, v134
	v_exp_f32_e32 v142, v141
	v_min_f32_e32 v143, 0x41e6d4ca, v143
	v_exp_f32_e32 v130, v130
	v_exp_f32_e32 v131, v131
	v_mul_f32_e32 v134, 0xbfb8aa3b, v120
	v_rcp_f32_e32 v136, v0
	v_add_f32_e32 v0, 1.0, v135
	v_mul_f32_e32 v135, 0xbfb8aa3b, v121
	v_exp_f32_e32 v143, v143
	v_min_f32_e32 v134, 0x41e6d4ca, v134
	v_min_f32_e32 v135, 0x41e6d4ca, v135
	v_rcp_f32_e32 v137, v0
	v_add_f32_e32 v0, 1.0, v138
	v_exp_f32_e32 v134, v134
	v_exp_f32_e32 v135, v135
	v_mul_f32_e32 v138, 0xbfb8aa3b, v114
	v_rcp_f32_e32 v140, v0
	v_add_f32_e32 v0, 1.0, v139
	v_mul_f32_e32 v139, 0xbfb8aa3b, v115
	v_min_f32_e32 v138, 0x41e6d4ca, v138
	v_min_f32_e32 v139, 0x41e6d4ca, v139
	v_rcp_f32_e32 v141, v0
	v_add_f32_e32 v0, 1.0, v142
	v_exp_f32_e32 v138, v138
	v_exp_f32_e32 v139, v139
	v_mul_f32_e32 v142, 0xbfb8aa3b, v116
	v_rcp_f32_e32 v144, v0
	v_add_f32_e32 v0, 1.0, v143
	v_mul_f32_e32 v143, 0xbfb8aa3b, v117
	v_pk_add_f32 v[130:131], v[130:131], 1.0 op_sel_hi:[1,0]
	v_min_f32_e32 v142, 0x41e6d4ca, v142
	v_min_f32_e32 v143, 0x41e6d4ca, v143
	v_rcp_f32_e32 v174, v130
	v_rcp_f32_e32 v175, v131
	v_pk_mul_f32 v[130:131], v[132:133], v[130:131]
	v_exp_f32_e32 v142, v142
	v_exp_f32_e32 v143, v143
	v_cvt_pk_bf16_f32 v132, v130, v131
	v_pk_add_f32 v[130:131], v[134:135], 1.0 op_sel_hi:[1,0]
	v_rcp_f32_e32 v145, v0
	v_rcp_f32_e32 v176, v130
	v_rcp_f32_e32 v177, v131
	v_pk_mul_f32 v[130:131], v[136:137], v[130:131]
	v_ashrrev_i32_e32 v0, 31, v202
	v_cvt_pk_bf16_f32 v133, v130, v131
	v_pk_add_f32 v[130:131], v[138:139], 1.0 op_sel_hi:[1,0]
	v_mul_lo_u32 v138, s57, v202
	v_rcp_f32_e32 v203, v130
	v_rcp_f32_e32 v204, v131
	v_pk_mul_f32 v[130:131], v[140:141], v[130:131]
	v_mul_lo_u32 v0, s56, v0
	v_cvt_pk_bf16_f32 v134, v130, v131
	v_pk_add_f32 v[130:131], v[142:143], 1.0 op_sel_hi:[1,0]
	v_mad_u64_u32 v[136:137], s[8:9], s56, v202, 0
	v_rcp_f32_e32 v140, v130
	v_rcp_f32_e32 v141, v131
	v_pk_mul_f32 v[130:131], v[144:145], v[130:131]
	v_add3_u32 v137, v137, v0, v138
	v_cvt_pk_bf16_f32 v135, v130, v131
	v_lshl_add_u64 v[130:131], v[170:171], 1, s[86:87]
	v_lshlrev_b64 v[138:139], 1, v[136:137]
	v_lshl_add_u64 v[136:137], v[130:131], 0, v[138:139]
	global_store_dwordx4 v[136:137], v[132:135], off sc1
	v_cvt_pk_bf16_f32 v137, v140, v141
	v_mul_f32_e32 v140, 0xbfb8aa3b, v110
	v_lshl_add_u64 v[132:133], v[172:173], 1, s[86:87]
	v_min_f32_e32 v140, 0x41e6d4ca, v140
	v_cvt_pk_bf16_f32 v134, v174, v175
	v_cvt_pk_bf16_f32 v135, v176, v177
	v_cvt_pk_bf16_f32 v136, v203, v204
	v_exp_f32_e32 v140, v140
	v_lshl_add_u64 v[138:139], v[132:133], 0, v[138:139]
	global_store_dwordx4 v[138:139], v[134:137], off sc1
	v_mul_f32_e32 v138, 0xbfb8aa3b, v112
	v_min_f32_e32 v138, 0x41e6d4ca, v138
	v_mul_f32_e32 v136, 0xbfb8aa3b, v111
	v_exp_f32_e32 v138, v138
	v_mul_f32_e32 v142, 0xbfb8aa3b, v106
	v_mul_f32_e32 v174, 0xbfb8aa3b, v108
	v_add_f32_e32 v135, 1.0, v140
	v_min_f32_e32 v136, 0x41e6d4ca, v136
	v_mul_f32_e32 v140, 0xbfb8aa3b, v113
	v_min_f32_e32 v142, 0x41e6d4ca, v142
	v_min_f32_e32 v174, 0x41e6d4ca, v174
	v_exp_f32_e32 v137, v136
	v_min_f32_e32 v140, 0x41e6d4ca, v140
	v_exp_f32_e32 v142, v142
	v_exp_f32_e32 v174, v174
	v_exp_f32_e32 v141, v140
	v_mul_f32_e32 v144, 0xbfb8aa3b, v107
	v_mul_f32_e32 v176, 0xbfb8aa3b, v109
	v_mul_f32_e32 v134, 0xbfb8aa3b, v102
	v_rcp_f32_e32 v136, v135
	v_mul_f32_e32 v135, 0xbfb8aa3b, v103
	v_add_f32_e32 v139, 1.0, v138
	v_min_f32_e32 v144, 0x41e6d4ca, v144
	v_min_f32_e32 v176, 0x41e6d4ca, v176
	v_min_f32_e32 v134, 0x41e6d4ca, v134
	v_min_f32_e32 v135, 0x41e6d4ca, v135
	v_mul_f32_e32 v138, 0xbfb8aa3b, v104
	v_rcp_f32_e32 v140, v139
	v_mul_f32_e32 v139, 0xbfb8aa3b, v105
	v_exp_f32_e32 v145, v144
	v_exp_f32_e32 v177, v176
	v_exp_f32_e32 v134, v134
	v_add_f32_e32 v137, 1.0, v137
	v_exp_f32_e32 v135, v135
	v_min_f32_e32 v138, 0x41e6d4ca, v138
	v_min_f32_e32 v139, 0x41e6d4ca, v139
	v_add_f32_e32 v143, 1.0, v142
	v_add_f32_e32 v175, 1.0, v174
	v_rcp_f32_e32 v137, v137
	v_exp_f32_e32 v138, v138
	v_add_f32_e32 v141, 1.0, v141
	v_exp_f32_e32 v139, v139
	v_mul_f32_e32 v142, 0xbfb8aa3b, v98
	v_rcp_f32_e32 v144, v143
	v_mul_f32_e32 v143, 0xbfb8aa3b, v99
	v_mul_f32_e32 v174, 0xbfb8aa3b, v100
	v_rcp_f32_e32 v176, v175
	v_mul_f32_e32 v175, 0xbfb8aa3b, v101
	v_rcp_f32_e32 v141, v141
	v_min_f32_e32 v142, 0x41e6d4ca, v142
	v_min_f32_e32 v143, 0x41e6d4ca, v143
	v_min_f32_e32 v174, 0x41e6d4ca, v174
	v_min_f32_e32 v175, 0x41e6d4ca, v175
	v_exp_f32_e32 v142, v142
	v_add_f32_e32 v145, 1.0, v145
	v_exp_f32_e32 v143, v143
	v_exp_f32_e32 v174, v174
	v_add_f32_e32 v177, 1.0, v177
	v_exp_f32_e32 v175, v175
	v_rcp_f32_e32 v145, v145
	v_rcp_f32_e32 v177, v177
	v_pk_add_f32 v[134:135], v[134:135], 1.0 op_sel_hi:[1,0]
	v_or_b32_e32 v203, 16, v202
	v_rcp_f32_e32 v204, v134
	v_rcp_f32_e32 v205, v135
	v_pk_mul_f32 v[134:135], v[136:137], v[134:135]
	v_pk_add_f32 v[136:137], v[138:139], 1.0 op_sel_hi:[1,0]
	v_cvt_pk_bf16_f32 v134, v134, v135
	v_rcp_f32_e32 v206, v136
	v_rcp_f32_e32 v207, v137
	v_pk_mul_f32 v[136:137], v[140:141], v[136:137]
	v_pk_add_f32 v[138:139], v[174:175], 1.0 op_sel_hi:[1,0]
	v_cvt_pk_bf16_f32 v135, v136, v137
	v_pk_add_f32 v[136:137], v[142:143], 1.0 op_sel_hi:[1,0]
	v_mul_lo_u32 v140, s57, v203
	v_rcp_f32_e32 v142, v136
	v_rcp_f32_e32 v143, v137
	v_pk_mul_f32 v[136:137], v[144:145], v[136:137]
	v_rcp_f32_e32 v144, v138
	v_rcp_f32_e32 v145, v139
	v_pk_mul_f32 v[138:139], v[176:177], v[138:139]
	v_cvt_pk_bf16_f32 v136, v136, v137
	v_cvt_pk_bf16_f32 v137, v138, v139
	v_mad_u64_u32 v[138:139], s[8:9], s56, v203, 0
	v_add3_u32 v139, v139, v0, v140
	v_lshlrev_b64 v[138:139], 1, v[138:139]
	v_lshl_add_u64 v[140:141], v[130:131], 0, v[138:139]
	global_store_dwordx4 v[140:141], v[134:137], off sc1
	v_mul_f32_e32 v140, 0xbfb8aa3b, v94
	v_min_f32_e32 v140, 0x41e6d4ca, v140
	v_cvt_pk_bf16_f32 v134, v204, v205
	v_cvt_pk_bf16_f32 v135, v206, v207
	v_cvt_pk_bf16_f32 v136, v142, v143
	v_cvt_pk_bf16_f32 v137, v144, v145
	v_exp_f32_e32 v140, v140
	v_lshl_add_u64 v[138:139], v[132:133], 0, v[138:139]
	global_store_dwordx4 v[138:139], v[134:137], off sc1
	v_mul_f32_e32 v138, 0xbfb8aa3b, v96
	v_min_f32_e32 v138, 0x41e6d4ca, v138
	v_mul_f32_e32 v136, 0xbfb8aa3b, v95
	v_exp_f32_e32 v138, v138
	v_mul_f32_e32 v142, 0xbfb8aa3b, v90
	v_mul_f32_e32 v174, 0xbfb8aa3b, v92
	v_add_f32_e32 v135, 1.0, v140
	v_min_f32_e32 v136, 0x41e6d4ca, v136
	v_mul_f32_e32 v140, 0xbfb8aa3b, v97
	v_min_f32_e32 v142, 0x41e6d4ca, v142
	v_min_f32_e32 v174, 0x41e6d4ca, v174
	v_exp_f32_e32 v137, v136
	v_min_f32_e32 v140, 0x41e6d4ca, v140
	v_exp_f32_e32 v142, v142
	v_exp_f32_e32 v174, v174
	v_exp_f32_e32 v141, v140
	v_mul_f32_e32 v144, 0xbfb8aa3b, v91
	v_mul_f32_e32 v176, 0xbfb8aa3b, v93
	v_mul_f32_e32 v134, 0xbfb8aa3b, v86
	v_rcp_f32_e32 v136, v135
	v_mul_f32_e32 v135, 0xbfb8aa3b, v87
	v_add_f32_e32 v139, 1.0, v138
	v_min_f32_e32 v144, 0x41e6d4ca, v144
	v_min_f32_e32 v176, 0x41e6d4ca, v176
	v_min_f32_e32 v134, 0x41e6d4ca, v134
	v_min_f32_e32 v135, 0x41e6d4ca, v135
	v_mul_f32_e32 v138, 0xbfb8aa3b, v88
	v_rcp_f32_e32 v140, v139
	v_mul_f32_e32 v139, 0xbfb8aa3b, v89
	v_exp_f32_e32 v145, v144
	v_exp_f32_e32 v177, v176
	v_exp_f32_e32 v134, v134
	v_add_f32_e32 v137, 1.0, v137
	v_exp_f32_e32 v135, v135
	v_min_f32_e32 v138, 0x41e6d4ca, v138
	v_min_f32_e32 v139, 0x41e6d4ca, v139
	v_add_f32_e32 v143, 1.0, v142
	v_add_f32_e32 v175, 1.0, v174
	v_rcp_f32_e32 v137, v137
	v_exp_f32_e32 v138, v138
	v_add_f32_e32 v141, 1.0, v141
	v_exp_f32_e32 v139, v139
	v_mul_f32_e32 v142, 0xbfb8aa3b, v82
	v_rcp_f32_e32 v144, v143
	v_mul_f32_e32 v143, 0xbfb8aa3b, v83
	v_mul_f32_e32 v174, 0xbfb8aa3b, v84
	v_rcp_f32_e32 v176, v175
	v_mul_f32_e32 v175, 0xbfb8aa3b, v85
	v_rcp_f32_e32 v141, v141
	v_min_f32_e32 v142, 0x41e6d4ca, v142
	v_min_f32_e32 v143, 0x41e6d4ca, v143
	v_min_f32_e32 v174, 0x41e6d4ca, v174
	v_min_f32_e32 v175, 0x41e6d4ca, v175
	v_exp_f32_e32 v142, v142
	v_add_f32_e32 v145, 1.0, v145
	v_exp_f32_e32 v143, v143
	v_exp_f32_e32 v174, v174
	v_add_f32_e32 v177, 1.0, v177
	v_exp_f32_e32 v175, v175
	v_rcp_f32_e32 v145, v145
	v_rcp_f32_e32 v177, v177
	v_pk_add_f32 v[134:135], v[134:135], 1.0 op_sel_hi:[1,0]
	v_or_b32_e32 v203, 32, v202
	v_rcp_f32_e32 v204, v134
	v_rcp_f32_e32 v205, v135
	v_pk_mul_f32 v[134:135], v[136:137], v[134:135]
	v_pk_add_f32 v[136:137], v[138:139], 1.0 op_sel_hi:[1,0]
	v_cvt_pk_bf16_f32 v134, v134, v135
	v_rcp_f32_e32 v206, v136
	v_rcp_f32_e32 v207, v137
	v_pk_mul_f32 v[136:137], v[140:141], v[136:137]
	v_pk_add_f32 v[138:139], v[174:175], 1.0 op_sel_hi:[1,0]
	v_cvt_pk_bf16_f32 v135, v136, v137
	v_pk_add_f32 v[136:137], v[142:143], 1.0 op_sel_hi:[1,0]
	v_mul_lo_u32 v140, s57, v203
	v_rcp_f32_e32 v142, v136
	v_rcp_f32_e32 v143, v137
	v_pk_mul_f32 v[136:137], v[144:145], v[136:137]
	v_rcp_f32_e32 v144, v138
	v_rcp_f32_e32 v145, v139
	v_pk_mul_f32 v[138:139], v[176:177], v[138:139]
	v_cvt_pk_bf16_f32 v136, v136, v137
	v_cvt_pk_bf16_f32 v137, v138, v139
	v_mad_u64_u32 v[138:139], s[8:9], s56, v203, 0
	v_add3_u32 v139, v139, v0, v140
	v_lshlrev_b64 v[138:139], 1, v[138:139]
	v_lshl_add_u64 v[140:141], v[130:131], 0, v[138:139]
	global_store_dwordx4 v[140:141], v[134:137], off sc1
	v_mul_f32_e32 v140, 0xbfb8aa3b, v78
	v_min_f32_e32 v140, 0x41e6d4ca, v140
	v_cvt_pk_bf16_f32 v134, v204, v205
	v_cvt_pk_bf16_f32 v135, v206, v207
	v_cvt_pk_bf16_f32 v136, v142, v143
	v_cvt_pk_bf16_f32 v137, v144, v145
	v_exp_f32_e32 v140, v140
	v_lshl_add_u64 v[138:139], v[132:133], 0, v[138:139]
	global_store_dwordx4 v[138:139], v[134:137], off sc1
	v_mul_f32_e32 v138, 0xbfb8aa3b, v80
	v_min_f32_e32 v138, 0x41e6d4ca, v138
	v_mul_f32_e32 v136, 0xbfb8aa3b, v79
	v_exp_f32_e32 v138, v138
	v_mul_f32_e32 v142, 0xbfb8aa3b, v74
	v_mul_f32_e32 v174, 0xbfb8aa3b, v76
	v_add_f32_e32 v135, 1.0, v140
	v_min_f32_e32 v136, 0x41e6d4ca, v136
	v_mul_f32_e32 v140, 0xbfb8aa3b, v81
	v_min_f32_e32 v142, 0x41e6d4ca, v142
	v_min_f32_e32 v174, 0x41e6d4ca, v174
	v_exp_f32_e32 v137, v136
	v_min_f32_e32 v140, 0x41e6d4ca, v140
	v_exp_f32_e32 v142, v142
	v_exp_f32_e32 v174, v174
	v_exp_f32_e32 v141, v140
	v_mul_f32_e32 v144, 0xbfb8aa3b, v75
	v_mul_f32_e32 v176, 0xbfb8aa3b, v77
	v_mul_f32_e32 v134, 0xbfb8aa3b, v70
	v_rcp_f32_e32 v136, v135
	v_mul_f32_e32 v135, 0xbfb8aa3b, v71
	v_add_f32_e32 v139, 1.0, v138
	v_min_f32_e32 v144, 0x41e6d4ca, v144
	v_min_f32_e32 v176, 0x41e6d4ca, v176
	v_min_f32_e32 v134, 0x41e6d4ca, v134
	v_min_f32_e32 v135, 0x41e6d4ca, v135
	v_mul_f32_e32 v138, 0xbfb8aa3b, v72
	v_rcp_f32_e32 v140, v139
	v_mul_f32_e32 v139, 0xbfb8aa3b, v73
	v_exp_f32_e32 v145, v144
	v_exp_f32_e32 v177, v176
	v_exp_f32_e32 v134, v134
	v_add_f32_e32 v137, 1.0, v137
	v_exp_f32_e32 v135, v135
	v_min_f32_e32 v138, 0x41e6d4ca, v138
	v_min_f32_e32 v139, 0x41e6d4ca, v139
	v_add_f32_e32 v143, 1.0, v142
	v_add_f32_e32 v175, 1.0, v174
	v_rcp_f32_e32 v137, v137
	v_exp_f32_e32 v138, v138
	v_add_f32_e32 v141, 1.0, v141
	v_exp_f32_e32 v139, v139
	v_mul_f32_e32 v142, 0xbfb8aa3b, v66
	v_rcp_f32_e32 v144, v143
	v_mul_f32_e32 v143, 0xbfb8aa3b, v67
	v_mul_f32_e32 v174, 0xbfb8aa3b, v68
	v_rcp_f32_e32 v176, v175
	v_mul_f32_e32 v175, 0xbfb8aa3b, v69
	v_rcp_f32_e32 v141, v141
	v_min_f32_e32 v142, 0x41e6d4ca, v142
	v_min_f32_e32 v143, 0x41e6d4ca, v143
	v_min_f32_e32 v174, 0x41e6d4ca, v174
	v_min_f32_e32 v175, 0x41e6d4ca, v175
	v_exp_f32_e32 v142, v142
	v_add_f32_e32 v145, 1.0, v145
	v_exp_f32_e32 v143, v143
	v_exp_f32_e32 v174, v174
	v_add_f32_e32 v177, 1.0, v177
	v_exp_f32_e32 v175, v175
	v_rcp_f32_e32 v145, v145
	v_rcp_f32_e32 v177, v177
	v_pk_add_f32 v[134:135], v[134:135], 1.0 op_sel_hi:[1,0]
	v_or_b32_e32 v203, 48, v202
	v_rcp_f32_e32 v204, v134
	v_rcp_f32_e32 v205, v135
	v_pk_mul_f32 v[134:135], v[136:137], v[134:135]
	v_pk_add_f32 v[136:137], v[138:139], 1.0 op_sel_hi:[1,0]
	v_cvt_pk_bf16_f32 v134, v134, v135
	v_rcp_f32_e32 v206, v136
	v_rcp_f32_e32 v207, v137
	v_pk_mul_f32 v[136:137], v[140:141], v[136:137]
	v_pk_add_f32 v[138:139], v[174:175], 1.0 op_sel_hi:[1,0]
	v_cvt_pk_bf16_f32 v135, v136, v137
	v_pk_add_f32 v[136:137], v[142:143], 1.0 op_sel_hi:[1,0]
	v_mul_lo_u32 v140, s57, v203
	v_rcp_f32_e32 v142, v136
	v_rcp_f32_e32 v143, v137
	v_pk_mul_f32 v[136:137], v[144:145], v[136:137]
	v_rcp_f32_e32 v144, v138
	v_rcp_f32_e32 v145, v139
	v_pk_mul_f32 v[138:139], v[176:177], v[138:139]
	v_cvt_pk_bf16_f32 v136, v136, v137
	v_cvt_pk_bf16_f32 v137, v138, v139
	v_mad_u64_u32 v[138:139], s[8:9], s56, v203, 0
	v_add3_u32 v139, v139, v0, v140
	v_lshlrev_b64 v[138:139], 1, v[138:139]
	v_lshl_add_u64 v[140:141], v[130:131], 0, v[138:139]
	global_store_dwordx4 v[140:141], v[134:137], off sc1
	v_mul_f32_e32 v0, 0xbfb8aa3b, v62
	v_lshl_add_u64 v[138:139], v[132:133], 0, v[138:139]
	v_cvt_pk_bf16_f32 v134, v204, v205
	v_cvt_pk_bf16_f32 v135, v206, v207
	v_cvt_pk_bf16_f32 v136, v142, v143
	v_cvt_pk_bf16_f32 v137, v144, v145
	v_min_f32_e32 v0, 0x41e6d4ca, v0
	global_store_dwordx4 v[138:139], v[134:137], off sc1
	v_exp_f32_e32 v0, v0
	v_mul_f32_e32 v139, 0xbfb8aa3b, v65
	v_mul_f32_e32 v135, 0xbfb8aa3b, v63
	v_min_f32_e32 v135, 0x41e6d4ca, v135
	v_mul_f32_e32 v137, 0xbfb8aa3b, v64
	v_exp_f32_e32 v135, v135
	v_min_f32_e32 v137, 0x41e6d4ca, v137
	v_exp_f32_e32 v138, v137
	v_min_f32_e32 v139, 0x41e6d4ca, v139
	v_mul_f32_e32 v141, 0xbfb8aa3b, v58
	v_exp_f32_e32 v139, v139
	v_min_f32_e32 v141, 0x41e6d4ca, v141
	v_mul_f32_e32 v143, 0xbfb8aa3b, v59
	v_add_f32_e32 v0, 1.0, v0
	v_exp_f32_e32 v142, v141
	v_min_f32_e32 v143, 0x41e6d4ca, v143
	v_mul_f32_e32 v145, 0xbfb8aa3b, v60
	v_rcp_f32_e32 v136, v0
	v_add_f32_e32 v0, 1.0, v135
	v_exp_f32_e32 v143, v143
	v_min_f32_e32 v145, 0x41e6d4ca, v145
	v_mul_f32_e32 v175, 0xbfb8aa3b, v61
	v_rcp_f32_e32 v137, v0
	v_add_f32_e32 v0, 1.0, v138
	v_exp_f32_e32 v174, v145
	v_min_f32_e32 v175, 0x41e6d4ca, v175
	v_rcp_f32_e32 v140, v0
	v_add_f32_e32 v0, 1.0, v139
	v_exp_f32_e32 v175, v175
	v_mul_f32_e32 v134, 0xbfb8aa3b, v54
	v_mul_f32_e32 v135, 0xbfb8aa3b, v55
	v_rcp_f32_e32 v141, v0
	v_add_f32_e32 v0, 1.0, v142
	v_min_f32_e32 v134, 0x41e6d4ca, v134
	v_min_f32_e32 v135, 0x41e6d4ca, v135
	v_mul_f32_e32 v138, 0xbfb8aa3b, v56
	v_mul_f32_e32 v139, 0xbfb8aa3b, v57
	v_rcp_f32_e32 v144, v0
	v_add_f32_e32 v0, 1.0, v143
	v_exp_f32_e32 v134, v134
	v_exp_f32_e32 v135, v135
	v_min_f32_e32 v138, 0x41e6d4ca, v138
	v_min_f32_e32 v139, 0x41e6d4ca, v139
	v_rcp_f32_e32 v145, v0
	v_add_f32_e32 v0, 1.0, v174
	v_exp_f32_e32 v138, v138
	v_exp_f32_e32 v139, v139
	v_mul_f32_e32 v142, 0xbfb8aa3b, v50
	v_mul_f32_e32 v143, 0xbfb8aa3b, v51
	v_mul_f32_e32 v174, 0xbfb8aa3b, v52
	v_rcp_f32_e32 v176, v0
	v_add_f32_e32 v0, 1.0, v175
	v_mul_f32_e32 v175, 0xbfb8aa3b, v53
	v_min_f32_e32 v142, 0x41e6d4ca, v142
	v_min_f32_e32 v143, 0x41e6d4ca, v143
	v_min_f32_e32 v174, 0x41e6d4ca, v174
	v_min_f32_e32 v175, 0x41e6d4ca, v175
	v_exp_f32_e32 v142, v142
	v_exp_f32_e32 v143, v143
	v_exp_f32_e32 v174, v174
	v_exp_f32_e32 v175, v175
	v_rcp_f32_e32 v177, v0
	v_pk_add_f32 v[134:135], v[134:135], 1.0 op_sel_hi:[1,0]
	v_add_u32_e32 v203, 0x80, v202
	v_rcp_f32_e32 v204, v134
	v_rcp_f32_e32 v205, v135
	v_pk_mul_f32 v[134:135], v[136:137], v[134:135]
	v_pk_add_f32 v[136:137], v[138:139], 1.0 op_sel_hi:[1,0]
	v_cvt_pk_bf16_f32 v134, v134, v135
	v_rcp_f32_e32 v206, v136
	v_rcp_f32_e32 v207, v137
	v_pk_mul_f32 v[136:137], v[140:141], v[136:137]
	v_pk_add_f32 v[138:139], v[174:175], 1.0 op_sel_hi:[1,0]
	v_cvt_pk_bf16_f32 v135, v136, v137
	v_pk_add_f32 v[136:137], v[142:143], 1.0 op_sel_hi:[1,0]
	v_ashrrev_i32_e32 v0, 31, v203
	v_rcp_f32_e32 v142, v136
	v_rcp_f32_e32 v143, v137
	v_pk_mul_f32 v[136:137], v[144:145], v[136:137]
	v_rcp_f32_e32 v144, v138
	v_rcp_f32_e32 v145, v139
	v_pk_mul_f32 v[138:139], v[176:177], v[138:139]
	v_cvt_pk_bf16_f32 v136, v136, v137
	v_cvt_pk_bf16_f32 v137, v138, v139
	v_mul_lo_u32 v0, s56, v0
	v_mul_lo_u32 v140, s57, v203
	v_mad_u64_u32 v[138:139], s[8:9], s56, v203, 0
	v_add3_u32 v139, v139, v0, v140
	v_lshlrev_b64 v[138:139], 1, v[138:139]
	v_lshl_add_u64 v[140:141], v[130:131], 0, v[138:139]
	global_store_dwordx4 v[140:141], v[134:137], off sc1
	v_mul_f32_e32 v0, 0xbfb8aa3b, v46
	v_lshl_add_u64 v[138:139], v[132:133], 0, v[138:139]
	v_cvt_pk_bf16_f32 v134, v204, v205
	v_cvt_pk_bf16_f32 v135, v206, v207
	v_cvt_pk_bf16_f32 v136, v142, v143
	v_cvt_pk_bf16_f32 v137, v144, v145
	v_min_f32_e32 v0, 0x41e6d4ca, v0
	global_store_dwordx4 v[138:139], v[134:137], off sc1
	v_exp_f32_e32 v0, v0
	v_mul_f32_e32 v139, 0xbfb8aa3b, v49
	v_mul_f32_e32 v135, 0xbfb8aa3b, v47
	v_min_f32_e32 v135, 0x41e6d4ca, v135
	v_mul_f32_e32 v137, 0xbfb8aa3b, v48
	v_exp_f32_e32 v135, v135
	v_min_f32_e32 v137, 0x41e6d4ca, v137
	v_exp_f32_e32 v138, v137
	v_min_f32_e32 v139, 0x41e6d4ca, v139
	v_mul_f32_e32 v141, 0xbfb8aa3b, v42
	v_exp_f32_e32 v139, v139
	v_min_f32_e32 v141, 0x41e6d4ca, v141
	v_mul_f32_e32 v143, 0xbfb8aa3b, v43
	v_add_f32_e32 v0, 1.0, v0
	v_exp_f32_e32 v142, v141
	v_min_f32_e32 v143, 0x41e6d4ca, v143
	v_mul_f32_e32 v145, 0xbfb8aa3b, v44
	v_rcp_f32_e32 v136, v0
	v_add_f32_e32 v0, 1.0, v135
	v_exp_f32_e32 v143, v143
	v_min_f32_e32 v145, 0x41e6d4ca, v145
	v_mul_f32_e32 v175, 0xbfb8aa3b, v45
	v_rcp_f32_e32 v137, v0
	v_add_f32_e32 v0, 1.0, v138
	v_exp_f32_e32 v174, v145
	v_min_f32_e32 v175, 0x41e6d4ca, v175
	v_rcp_f32_e32 v140, v0
	v_add_f32_e32 v0, 1.0, v139
	v_exp_f32_e32 v175, v175
	v_mul_f32_e32 v134, 0xbfb8aa3b, v38
	v_mul_f32_e32 v135, 0xbfb8aa3b, v39
	v_rcp_f32_e32 v141, v0
	v_add_f32_e32 v0, 1.0, v142
	v_min_f32_e32 v134, 0x41e6d4ca, v134
	v_min_f32_e32 v135, 0x41e6d4ca, v135
	v_mul_f32_e32 v138, 0xbfb8aa3b, v40
	v_mul_f32_e32 v139, 0xbfb8aa3b, v41
	v_rcp_f32_e32 v144, v0
	v_add_f32_e32 v0, 1.0, v143
	v_exp_f32_e32 v134, v134
	v_exp_f32_e32 v135, v135
	v_min_f32_e32 v138, 0x41e6d4ca, v138
	v_min_f32_e32 v139, 0x41e6d4ca, v139
	v_rcp_f32_e32 v145, v0
	v_add_f32_e32 v0, 1.0, v174
	v_exp_f32_e32 v138, v138
	v_exp_f32_e32 v139, v139
	v_mul_f32_e32 v142, 0xbfb8aa3b, v34
	v_mul_f32_e32 v143, 0xbfb8aa3b, v35
	v_mul_f32_e32 v174, 0xbfb8aa3b, v36
	v_rcp_f32_e32 v176, v0
	v_add_f32_e32 v0, 1.0, v175
	v_mul_f32_e32 v175, 0xbfb8aa3b, v37
	v_min_f32_e32 v142, 0x41e6d4ca, v142
	v_min_f32_e32 v143, 0x41e6d4ca, v143
	v_min_f32_e32 v174, 0x41e6d4ca, v174
	v_min_f32_e32 v175, 0x41e6d4ca, v175
	v_exp_f32_e32 v142, v142
	v_exp_f32_e32 v143, v143
	v_exp_f32_e32 v174, v174
	v_exp_f32_e32 v175, v175
	v_rcp_f32_e32 v177, v0
	v_pk_add_f32 v[134:135], v[134:135], 1.0 op_sel_hi:[1,0]
	v_add_u32_e32 v203, 0x90, v202
	v_rcp_f32_e32 v204, v134
	v_rcp_f32_e32 v205, v135
	v_pk_mul_f32 v[134:135], v[136:137], v[134:135]
	v_pk_add_f32 v[136:137], v[138:139], 1.0 op_sel_hi:[1,0]
	v_cvt_pk_bf16_f32 v134, v134, v135
	v_rcp_f32_e32 v206, v136
	v_rcp_f32_e32 v207, v137
	v_pk_mul_f32 v[136:137], v[140:141], v[136:137]
	v_pk_add_f32 v[138:139], v[174:175], 1.0 op_sel_hi:[1,0]
	v_cvt_pk_bf16_f32 v135, v136, v137
	v_pk_add_f32 v[136:137], v[142:143], 1.0 op_sel_hi:[1,0]
	v_ashrrev_i32_e32 v0, 31, v203
	v_rcp_f32_e32 v142, v136
	v_rcp_f32_e32 v143, v137
	v_pk_mul_f32 v[136:137], v[144:145], v[136:137]
	v_rcp_f32_e32 v144, v138
	v_rcp_f32_e32 v145, v139
	v_pk_mul_f32 v[138:139], v[176:177], v[138:139]
	v_cvt_pk_bf16_f32 v136, v136, v137
	v_cvt_pk_bf16_f32 v137, v138, v139
	v_mul_lo_u32 v0, s56, v0
	v_mul_lo_u32 v140, s57, v203
	v_mad_u64_u32 v[138:139], s[8:9], s56, v203, 0
	v_add3_u32 v139, v139, v0, v140
	v_lshlrev_b64 v[138:139], 1, v[138:139]
	v_lshl_add_u64 v[140:141], v[130:131], 0, v[138:139]
	global_store_dwordx4 v[140:141], v[134:137], off sc1
	v_mul_f32_e32 v0, 0xbfb8aa3b, v30
	v_lshl_add_u64 v[138:139], v[132:133], 0, v[138:139]
	v_cvt_pk_bf16_f32 v134, v204, v205
	v_cvt_pk_bf16_f32 v135, v206, v207
	v_cvt_pk_bf16_f32 v136, v142, v143
	v_cvt_pk_bf16_f32 v137, v144, v145
	v_min_f32_e32 v0, 0x41e6d4ca, v0
	global_store_dwordx4 v[138:139], v[134:137], off sc1
	v_exp_f32_e32 v0, v0
	v_mul_f32_e32 v139, 0xbfb8aa3b, v33
	v_mul_f32_e32 v135, 0xbfb8aa3b, v31
	v_min_f32_e32 v135, 0x41e6d4ca, v135
	v_mul_f32_e32 v137, 0xbfb8aa3b, v32
	v_exp_f32_e32 v135, v135
	v_min_f32_e32 v137, 0x41e6d4ca, v137
	v_exp_f32_e32 v138, v137
	v_min_f32_e32 v139, 0x41e6d4ca, v139
	v_mul_f32_e32 v141, 0xbfb8aa3b, v26
	v_exp_f32_e32 v139, v139
	v_min_f32_e32 v141, 0x41e6d4ca, v141
	v_mul_f32_e32 v143, 0xbfb8aa3b, v27
	v_add_f32_e32 v0, 1.0, v0
	v_exp_f32_e32 v142, v141
	v_min_f32_e32 v143, 0x41e6d4ca, v143
	v_mul_f32_e32 v145, 0xbfb8aa3b, v28
	v_rcp_f32_e32 v136, v0
	v_add_f32_e32 v0, 1.0, v135
	v_exp_f32_e32 v143, v143
	v_min_f32_e32 v145, 0x41e6d4ca, v145
	v_mul_f32_e32 v175, 0xbfb8aa3b, v29
	v_rcp_f32_e32 v137, v0
	v_add_f32_e32 v0, 1.0, v138
	v_exp_f32_e32 v174, v145
	v_min_f32_e32 v175, 0x41e6d4ca, v175
	v_rcp_f32_e32 v140, v0
	v_add_f32_e32 v0, 1.0, v139
	v_exp_f32_e32 v175, v175
	v_mul_f32_e32 v134, 0xbfb8aa3b, v22
	v_mul_f32_e32 v135, 0xbfb8aa3b, v23
	v_rcp_f32_e32 v141, v0
	v_add_f32_e32 v0, 1.0, v142
	v_min_f32_e32 v134, 0x41e6d4ca, v134
	v_min_f32_e32 v135, 0x41e6d4ca, v135
	v_mul_f32_e32 v138, 0xbfb8aa3b, v24
	v_mul_f32_e32 v139, 0xbfb8aa3b, v25
	v_rcp_f32_e32 v144, v0
	v_add_f32_e32 v0, 1.0, v143
	v_exp_f32_e32 v134, v134
	v_exp_f32_e32 v135, v135
	v_min_f32_e32 v138, 0x41e6d4ca, v138
	v_min_f32_e32 v139, 0x41e6d4ca, v139
	v_rcp_f32_e32 v145, v0
	v_add_f32_e32 v0, 1.0, v174
	v_exp_f32_e32 v138, v138
	v_exp_f32_e32 v139, v139
	v_mul_f32_e32 v142, 0xbfb8aa3b, v18
	v_mul_f32_e32 v143, 0xbfb8aa3b, v19
	v_mul_f32_e32 v174, 0xbfb8aa3b, v20
	v_rcp_f32_e32 v176, v0
	v_add_f32_e32 v0, 1.0, v175
	v_mul_f32_e32 v175, 0xbfb8aa3b, v21
	v_min_f32_e32 v142, 0x41e6d4ca, v142
	v_min_f32_e32 v143, 0x41e6d4ca, v143
	v_min_f32_e32 v174, 0x41e6d4ca, v174
	v_min_f32_e32 v175, 0x41e6d4ca, v175
	v_exp_f32_e32 v142, v142
	v_exp_f32_e32 v143, v143
	v_exp_f32_e32 v174, v174
	v_exp_f32_e32 v175, v175
	v_rcp_f32_e32 v177, v0
	v_pk_add_f32 v[134:135], v[134:135], 1.0 op_sel_hi:[1,0]
	v_add_u32_e32 v203, 0xa0, v202
	v_rcp_f32_e32 v204, v134
	v_rcp_f32_e32 v205, v135
	v_pk_mul_f32 v[134:135], v[136:137], v[134:135]
	v_pk_add_f32 v[136:137], v[138:139], 1.0 op_sel_hi:[1,0]
	v_cvt_pk_bf16_f32 v134, v134, v135
	v_rcp_f32_e32 v206, v136
	v_rcp_f32_e32 v207, v137
	v_pk_mul_f32 v[136:137], v[140:141], v[136:137]
	v_pk_add_f32 v[138:139], v[174:175], 1.0 op_sel_hi:[1,0]
	v_cvt_pk_bf16_f32 v135, v136, v137
	v_pk_add_f32 v[136:137], v[142:143], 1.0 op_sel_hi:[1,0]
	v_ashrrev_i32_e32 v0, 31, v203
	v_rcp_f32_e32 v142, v136
	v_rcp_f32_e32 v143, v137
	v_pk_mul_f32 v[136:137], v[144:145], v[136:137]
	v_rcp_f32_e32 v144, v138
	v_rcp_f32_e32 v145, v139
	v_pk_mul_f32 v[138:139], v[176:177], v[138:139]
	v_cvt_pk_bf16_f32 v136, v136, v137
	v_cvt_pk_bf16_f32 v137, v138, v139
	v_mul_lo_u32 v0, s56, v0
	v_mul_lo_u32 v140, s57, v203
	v_mad_u64_u32 v[138:139], s[8:9], s56, v203, 0
	v_add3_u32 v139, v139, v0, v140
	v_lshlrev_b64 v[138:139], 1, v[138:139]
	v_lshl_add_u64 v[140:141], v[130:131], 0, v[138:139]
	global_store_dwordx4 v[140:141], v[134:137], off sc1
	v_mul_f32_e32 v0, 0xbfb8aa3b, v14
	v_lshl_add_u64 v[132:133], v[132:133], 0, v[138:139]
	v_cvt_pk_bf16_f32 v134, v204, v205
	v_cvt_pk_bf16_f32 v135, v206, v207
	v_cvt_pk_bf16_f32 v136, v142, v143
	v_cvt_pk_bf16_f32 v137, v144, v145
	v_min_f32_e32 v0, 0x41e6d4ca, v0
	global_store_dwordx4 v[132:133], v[134:137], off sc1
	v_mul_f32_e32 v133, 0xbfb8aa3b, v15
	v_exp_f32_e32 v0, v0
	v_min_f32_e32 v133, 0x41e6d4ca, v133
	v_mul_f32_e32 v135, 0xbfb8aa3b, v16
	v_exp_f32_e32 v133, v133
	v_min_f32_e32 v135, 0x41e6d4ca, v135
	v_mul_f32_e32 v137, 0xbfb8aa3b, v17
	v_exp_f32_e32 v136, v135
	v_min_f32_e32 v137, 0x41e6d4ca, v137
	v_mul_f32_e32 v139, 0xbfb8aa3b, v10
	v_exp_f32_e32 v137, v137
	v_min_f32_e32 v139, 0x41e6d4ca, v139
	v_mul_f32_e32 v141, 0xbfb8aa3b, v11
	v_add_f32_e32 v0, 1.0, v0
	v_exp_f32_e32 v140, v139
	v_min_f32_e32 v141, 0x41e6d4ca, v141
	v_mul_f32_e32 v143, 0xbfb8aa3b, v12
	v_rcp_f32_e32 v134, v0
	v_add_f32_e32 v0, 1.0, v133
	v_exp_f32_e32 v141, v141
	v_min_f32_e32 v143, 0x41e6d4ca, v143
	v_mul_f32_e32 v145, 0xbfb8aa3b, v13
	v_rcp_f32_e32 v135, v0
	v_add_f32_e32 v0, 1.0, v136
	v_exp_f32_e32 v144, v143
	v_min_f32_e32 v145, 0x41e6d4ca, v145
	v_rcp_f32_e32 v138, v0
	v_add_f32_e32 v0, 1.0, v137
	v_exp_f32_e32 v145, v145
	v_mul_f32_e32 v132, 0xbfb8aa3b, v6
	v_mul_f32_e32 v133, 0xbfb8aa3b, v7
	v_rcp_f32_e32 v139, v0
	v_add_f32_e32 v0, 1.0, v140
	v_min_f32_e32 v132, 0x41e6d4ca, v132
	v_min_f32_e32 v133, 0x41e6d4ca, v133
	v_mul_f32_e32 v136, 0xbfb8aa3b, v8
	v_mul_f32_e32 v137, 0xbfb8aa3b, v9
	v_rcp_f32_e32 v142, v0
	v_add_f32_e32 v0, 1.0, v141
	v_exp_f32_e32 v132, v132
	v_exp_f32_e32 v133, v133
	v_min_f32_e32 v136, 0x41e6d4ca, v136
	v_min_f32_e32 v137, 0x41e6d4ca, v137
	v_rcp_f32_e32 v143, v0
	v_add_f32_e32 v0, 1.0, v144
	v_exp_f32_e32 v136, v136
	v_exp_f32_e32 v137, v137
	v_mul_f32_e32 v140, 0xbfb8aa3b, v2
	v_mul_f32_e32 v141, 0xbfb8aa3b, v3
	v_mul_f32_e32 v144, 0xbfb8aa3b, v4
	v_rcp_f32_e32 v174, v0
	v_add_f32_e32 v0, 1.0, v145
	v_mul_f32_e32 v145, 0xbfb8aa3b, v5
	v_min_f32_e32 v140, 0x41e6d4ca, v140
	v_min_f32_e32 v141, 0x41e6d4ca, v141
	v_min_f32_e32 v144, 0x41e6d4ca, v144
	v_min_f32_e32 v145, 0x41e6d4ca, v145
	v_exp_f32_e32 v140, v140
	v_exp_f32_e32 v141, v141
	v_exp_f32_e32 v144, v144
	v_exp_f32_e32 v145, v145
	v_rcp_f32_e32 v175, v0
	v_pk_add_f32 v[132:133], v[132:133], 1.0 op_sel_hi:[1,0]
	v_add_u32_e32 v176, 0xb0, v202
	v_rcp_f32_e32 v203, v132
	v_rcp_f32_e32 v204, v133
	v_pk_mul_f32 v[132:133], v[134:135], v[132:133]
	v_pk_add_f32 v[134:135], v[136:137], 1.0 op_sel_hi:[1,0]
	v_cvt_pk_bf16_f32 v132, v132, v133
	v_rcp_f32_e32 v205, v134
	v_rcp_f32_e32 v206, v135
	v_pk_mul_f32 v[134:135], v[138:139], v[134:135]
	v_pk_add_f32 v[138:139], v[144:145], 1.0 op_sel_hi:[1,0]
	v_cvt_pk_bf16_f32 v133, v134, v135
	v_pk_add_f32 v[134:135], v[140:141], 1.0 op_sel_hi:[1,0]
	v_ashrrev_i32_e32 v0, 31, v176
	v_rcp_f32_e32 v140, v134
	v_rcp_f32_e32 v141, v135
	v_pk_mul_f32 v[134:135], v[142:143], v[134:135]
	v_rcp_f32_e32 v136, v138
	v_rcp_f32_e32 v137, v139
	v_pk_mul_f32 v[138:139], v[174:175], v[138:139]
	v_cvt_pk_bf16_f32 v134, v134, v135
	v_cvt_pk_bf16_f32 v135, v138, v139
	v_mul_lo_u32 v0, s56, v0
	v_mul_lo_u32 v138, s57, v176
	v_mad_u64_u32 v[176:177], s[8:9], s56, v176, 0
	v_add3_u32 v177, v177, v0, v138
	v_lshl_add_u64 v[130:131], v[176:177], 1, v[130:131]
	global_store_dwordx4 v[130:131], v[132:135], off sc1
	v_cvt_pk_bf16_f32 v130, v203, v204
	v_cvt_pk_bf16_f32 v131, v205, v206
	v_cvt_pk_bf16_f32 v132, v140, v141
.LBB0_207:
	s_and_b64 vcc, exec, s[2:3]
	s_cbranch_vccz .LBB0_209
	v_ashrrev_i32_e32 v0, 31, v202
	v_mul_lo_u32 v130, s57, v202
	v_mul_lo_u32 v0, s56, v0
	v_mad_u64_u32 v[134:135], s[2:3], s56, v202, 0
	v_add3_u32 v135, v135, v0, v130
	v_lshl_add_u64 v[136:137], v[170:171], 1, s[86:87]
	v_lshlrev_b64 v[134:135], 1, v[134:135]
	v_cvt_pk_bf16_f32 v130, v126, v127
	v_cvt_pk_bf16_f32 v131, v128, v129
	v_cvt_pk_bf16_f32 v132, v122, v123
	v_cvt_pk_bf16_f32 v133, v124, v125
	v_lshl_add_u64 v[138:139], v[136:137], 0, v[134:135]
	global_store_dwordx4 v[138:139], v[130:133], off sc1
	v_lshl_add_u64 v[138:139], v[172:173], 1, s[86:87]
	v_lshl_add_u64 v[134:135], v[138:139], 0, v[134:135]
	v_cvt_pk_bf16_f32 v130, v118, v119
	v_cvt_pk_bf16_f32 v131, v120, v121
	v_cvt_pk_bf16_f32 v132, v114, v115
	v_cvt_pk_bf16_f32 v133, v116, v117
	global_store_dwordx4 v[134:135], v[130:133], off sc1
	s_nop 1
	v_or_b32_e32 v130, 16, v202
	v_mul_lo_u32 v131, s57, v130
	v_mad_u64_u32 v[134:135], s[2:3], s56, v130, 0
	v_add3_u32 v135, v135, v0, v131
	v_lshlrev_b64 v[134:135], 1, v[134:135]
	v_cvt_pk_bf16_f32 v130, v110, v111
	v_cvt_pk_bf16_f32 v131, v112, v113
	v_cvt_pk_bf16_f32 v132, v106, v107
	v_cvt_pk_bf16_f32 v133, v108, v109
	v_lshl_add_u64 v[140:141], v[136:137], 0, v[134:135]
	global_store_dwordx4 v[140:141], v[130:133], off sc1
	v_lshl_add_u64 v[134:135], v[138:139], 0, v[134:135]
	s_nop 0
	v_cvt_pk_bf16_f32 v130, v102, v103
	v_cvt_pk_bf16_f32 v131, v104, v105
	v_cvt_pk_bf16_f32 v132, v98, v99
	v_cvt_pk_bf16_f32 v133, v100, v101
	global_store_dwordx4 v[134:135], v[130:133], off sc1
	s_nop 1
	v_or_b32_e32 v130, 32, v202
	v_mul_lo_u32 v131, s57, v130
	v_mad_u64_u32 v[134:135], s[2:3], s56, v130, 0
	v_add3_u32 v135, v135, v0, v131
	v_lshlrev_b64 v[134:135], 1, v[134:135]
	v_cvt_pk_bf16_f32 v130, v94, v95
	v_cvt_pk_bf16_f32 v131, v96, v97
	v_cvt_pk_bf16_f32 v132, v90, v91
	v_cvt_pk_bf16_f32 v133, v92, v93
	v_lshl_add_u64 v[140:141], v[136:137], 0, v[134:135]
	global_store_dwordx4 v[140:141], v[130:133], off sc1
	v_lshl_add_u64 v[134:135], v[138:139], 0, v[134:135]
	s_nop 0
	v_cvt_pk_bf16_f32 v130, v86, v87
	v_cvt_pk_bf16_f32 v131, v88, v89
	v_cvt_pk_bf16_f32 v132, v82, v83
	v_cvt_pk_bf16_f32 v133, v84, v85
	global_store_dwordx4 v[134:135], v[130:133], off sc1
	s_nop 1
	v_or_b32_e32 v130, 48, v202
	v_mul_lo_u32 v131, s57, v130
	v_mad_u64_u32 v[134:135], s[2:3], s56, v130, 0
	v_add3_u32 v135, v135, v0, v131
	v_lshlrev_b64 v[134:135], 1, v[134:135]
	v_cvt_pk_bf16_f32 v130, v78, v79
	v_cvt_pk_bf16_f32 v131, v80, v81
	v_cvt_pk_bf16_f32 v132, v74, v75
	v_cvt_pk_bf16_f32 v133, v76, v77
	v_lshl_add_u64 v[140:141], v[136:137], 0, v[134:135]
	global_store_dwordx4 v[140:141], v[130:133], off sc1
	v_lshl_add_u64 v[134:135], v[138:139], 0, v[134:135]
	v_add_u32_e32 v0, 0x80, v202
	v_cvt_pk_bf16_f32 v130, v70, v71
	v_cvt_pk_bf16_f32 v131, v72, v73
	v_cvt_pk_bf16_f32 v132, v66, v67
	v_cvt_pk_bf16_f32 v133, v68, v69
	global_store_dwordx4 v[134:135], v[130:133], off sc1
	v_mad_u64_u32 v[134:135], s[2:3], s56, v0, 0
	s_nop 0
	v_ashrrev_i32_e32 v130, 31, v0
	v_mul_lo_u32 v130, s56, v130
	v_mul_lo_u32 v131, s57, v0
	v_add3_u32 v135, v135, v130, v131
	v_lshlrev_b64 v[134:135], 1, v[134:135]
	v_cvt_pk_bf16_f32 v130, v62, v63
	v_cvt_pk_bf16_f32 v131, v64, v65
	v_cvt_pk_bf16_f32 v132, v58, v59
	v_cvt_pk_bf16_f32 v133, v60, v61
	v_lshl_add_u64 v[140:141], v[136:137], 0, v[134:135]
	global_store_dwordx4 v[140:141], v[130:133], off sc1
	v_lshl_add_u64 v[134:135], v[138:139], 0, v[134:135]
	v_add_u32_e32 v0, 0x90, v202
	v_cvt_pk_bf16_f32 v130, v54, v55
	v_cvt_pk_bf16_f32 v131, v56, v57
	v_cvt_pk_bf16_f32 v132, v50, v51
	v_cvt_pk_bf16_f32 v133, v52, v53
	global_store_dwordx4 v[134:135], v[130:133], off sc1
	v_mad_u64_u32 v[134:135], s[2:3], s56, v0, 0
	s_nop 0
	v_ashrrev_i32_e32 v130, 31, v0
	v_mul_lo_u32 v130, s56, v130
	v_mul_lo_u32 v131, s57, v0
	v_add3_u32 v135, v135, v130, v131
	v_lshlrev_b64 v[134:135], 1, v[134:135]
	v_cvt_pk_bf16_f32 v130, v46, v47
	v_cvt_pk_bf16_f32 v131, v48, v49
	v_cvt_pk_bf16_f32 v132, v42, v43
	v_cvt_pk_bf16_f32 v133, v44, v45
	v_lshl_add_u64 v[140:141], v[136:137], 0, v[134:135]
	global_store_dwordx4 v[140:141], v[130:133], off sc1
	v_lshl_add_u64 v[134:135], v[138:139], 0, v[134:135]
	v_add_u32_e32 v0, 0xa0, v202
	v_cvt_pk_bf16_f32 v130, v38, v39
	v_cvt_pk_bf16_f32 v131, v40, v41
	v_cvt_pk_bf16_f32 v132, v34, v35
	v_cvt_pk_bf16_f32 v133, v36, v37
	global_store_dwordx4 v[134:135], v[130:133], off sc1
	v_mad_u64_u32 v[134:135], s[2:3], s56, v0, 0
	s_nop 0
	v_ashrrev_i32_e32 v130, 31, v0
	v_mul_lo_u32 v130, s56, v130
	v_mul_lo_u32 v131, s57, v0
	v_add3_u32 v135, v135, v130, v131
	v_lshlrev_b64 v[134:135], 1, v[134:135]
	v_cvt_pk_bf16_f32 v130, v30, v31
	v_cvt_pk_bf16_f32 v131, v32, v33
	v_cvt_pk_bf16_f32 v132, v26, v27
	v_cvt_pk_bf16_f32 v133, v28, v29
	v_lshl_add_u64 v[140:141], v[136:137], 0, v[134:135]
	global_store_dwordx4 v[140:141], v[130:133], off sc1
	v_lshl_add_u64 v[134:135], v[138:139], 0, v[134:135]
	v_add_u32_e32 v0, 0xb0, v202
	v_cvt_pk_bf16_f32 v130, v22, v23
	v_cvt_pk_bf16_f32 v131, v24, v25
	v_cvt_pk_bf16_f32 v132, v18, v19
	v_cvt_pk_bf16_f32 v133, v20, v21
	global_store_dwordx4 v[134:135], v[130:133], off sc1
	v_mad_u64_u32 v[176:177], s[2:3], s56, v0, 0
	s_nop 0
	v_ashrrev_i32_e32 v130, 31, v0
	v_mul_lo_u32 v130, s56, v130
	v_mul_lo_u32 v131, s57, v0
	v_add3_u32 v177, v177, v130, v131
	v_cvt_pk_bf16_f32 v130, v14, v15
	v_cvt_pk_bf16_f32 v131, v16, v17
	v_cvt_pk_bf16_f32 v132, v10, v11
	v_cvt_pk_bf16_f32 v133, v12, v13
	v_lshl_add_u64 v[134:135], v[176:177], 1, v[136:137]
	global_store_dwordx4 v[134:135], v[130:133], off sc1
	v_mov_b32_e32 v137, v5
	v_mov_b32_e32 v136, v4
	v_cvt_pk_bf16_f32 v130, v6, v7
	v_cvt_pk_bf16_f32 v131, v8, v9
	v_cvt_pk_bf16_f32 v132, v2, v3

.LBB0_273:
	s_or_b64 exec, exec, s[42:43]
	ds_read_b64_tr_b16 v[28:29], v114 offset:1088
	ds_read_b64_tr_b16 v[26:27], v114
	ds_read_b64_tr_b16 v[30:31], v114 offset:32
	ds_read_b64_tr_b16 v[32:33], v114 offset:1120
	ds_read_b64_tr_b16 v[36:37], v115 offset:35904
	ds_read_b64_tr_b16 v[34:35], v115 offset:34816
	ds_read_b64_tr_b16 v[38:39], v115 offset:34848
	ds_read_b64_tr_b16 v[40:41], v115 offset:35936
	ds_read_b64_tr_b16 v[50:51], v115 offset:34880
	ds_read_b64_tr_b16 v[52:53], v115 offset:35968
	ds_read_b64_tr_b16 v[132:133], v115 offset:34912
	ds_read_b64_tr_b16 v[134:135], v115 offset:36000
	ds_read_b64_tr_b16 v[140:141], v115 offset:34944
	ds_read_b64_tr_b16 v[142:143], v115 offset:36032
	ds_read_b64_tr_b16 v[156:157], v115 offset:34976
	ds_read_b64_tr_b16 v[158:159], v115 offset:36064
	ds_read_b64_tr_b16 v[166:167], v115 offset:35008
	ds_read_b64_tr_b16 v[168:169], v115 offset:36096
	ds_read_b64_tr_b16 v[174:175], v115 offset:35040
	ds_read_b64_tr_b16 v[176:177], v115 offset:36128
	s_waitcnt lgkmcnt(14)
	v_mfma_f32_16x16x32_bf16 v[42:45], v[26:29], v[34:37], 0
	v_add_u32_e32 v131, v112, v113
	s_add_u32 s12, s12, s2
	s_addc_u32 s13, s13, s3
	s_waitcnt lgkmcnt(12)
	v_mfma_f32_16x16x32_bf16 v[46:49], v[26:29], v[38:41], 0
	v_lshl_add_u64 v[84:85], v[84:85], 0, s[10:11]
	s_cmpk_gt_i32 s12, 0x7ff
	s_waitcnt lgkmcnt(10)
	v_mfma_f32_16x16x32_bf16 v[54:57], v[26:29], v[50:53], 0
	s_waitcnt lgkmcnt(8)
	v_mfma_f32_16x16x32_bf16 v[136:139], v[26:29], v[132:135], 0
	s_waitcnt lgkmcnt(6)
	v_mfma_f32_16x16x32_bf16 v[152:155], v[26:29], v[140:143], 0
	s_waitcnt lgkmcnt(4)
	v_mfma_f32_16x16x32_bf16 v[162:165], v[26:29], v[156:159], 0
	s_waitcnt lgkmcnt(2)
	v_mfma_f32_16x16x32_bf16 v[170:173], v[26:29], v[166:169], 0
	s_waitcnt lgkmcnt(0)
	v_mfma_f32_16x16x32_bf16 v[198:201], v[26:29], v[174:177], 0
	ds_read_b64_tr_b16 v[202:203], v114 offset:8704
	ds_read_b64_tr_b16 v[204:205], v114 offset:9792
	ds_read_b64_tr_b16 v[206:207], v114 offset:8736
	ds_read_b64_tr_b16 v[208:209], v114 offset:9824
	ds_read_b64_tr_b16 v[26:27], v115 offset:43520
	ds_read_b64_tr_b16 v[28:29], v115 offset:44608
	v_mfma_f32_16x16x32_bf16 v[34:37], v[30:33], v[34:37], 0
	v_mfma_f32_16x16x32_bf16 v[38:41], v[30:33], v[38:41], 0
	v_mfma_f32_16x16x32_bf16 v[50:53], v[30:33], v[50:53], 0
	v_mfma_f32_16x16x32_bf16 v[132:135], v[30:33], v[132:135], 0
	v_mfma_f32_16x16x32_bf16 v[140:143], v[30:33], v[140:143], 0
	v_mfma_f32_16x16x32_bf16 v[156:159], v[30:33], v[156:159], 0
	v_mfma_f32_16x16x32_bf16 v[166:169], v[30:33], v[166:169], 0
	v_mfma_f32_16x16x32_bf16 v[174:177], v[30:33], v[174:177], 0
	ds_read_b64_tr_b16 v[30:31], v115 offset:43552
	ds_read_b64_tr_b16 v[32:33], v115 offset:44640
	s_waitcnt lgkmcnt(2)
	v_mfma_f32_16x16x32_bf16 v[210:213], v[202:205], v[26:29], v[42:45]
	v_mfma_f32_16x16x32_bf16 v[26:29], v[206:209], v[26:29], v[34:37]
	s_nop 2
	ds_read_b64_tr_b16 v[34:35], v115 offset:43584
	ds_read_b64_tr_b16 v[36:37], v115 offset:44672
	s_waitcnt lgkmcnt(2)
	v_mfma_f32_16x16x32_bf16 v[216:219], v[202:205], v[30:33], v[46:49]
	v_mfma_f32_16x16x32_bf16 v[30:33], v[206:209], v[30:33], v[38:41]
	s_nop 2
	ds_read_b64_tr_b16 v[38:39], v115 offset:43616
	ds_read_b64_tr_b16 v[40:41], v115 offset:44704
	ds_read_b64_tr_b16 v[42:43], v115 offset:43648
	ds_read_b64_tr_b16 v[44:45], v115 offset:44736
	ds_read_b64_tr_b16 v[46:47], v115 offset:43680
	ds_read_b64_tr_b16 v[48:49], v115 offset:44768
	s_waitcnt lgkmcnt(6)
	v_mfma_f32_16x16x32_bf16 v[220:223], v[202:205], v[34:37], v[54:57]
	v_mfma_f32_16x16x32_bf16 v[34:37], v[206:209], v[34:37], v[50:53]
	s_nop 2
	ds_read_b64_tr_b16 v[50:51], v115 offset:43712
	ds_read_b64_tr_b16 v[52:53], v115 offset:44800
	ds_read_b64_tr_b16 v[54:55], v115 offset:43744
	ds_read_b64_tr_b16 v[56:57], v115 offset:44832
	s_waitcnt lgkmcnt(8)
	v_mfma_f32_16x16x32_bf16 v[136:139], v[202:205], v[38:41], v[136:139]
	v_mfma_f32_16x16x32_bf16 v[38:41], v[206:209], v[38:41], v[132:135]
	s_waitcnt lgkmcnt(6)
	v_mfma_f32_16x16x32_bf16 v[132:135], v[202:205], v[42:45], v[152:155]
	v_mfma_f32_16x16x32_bf16 v[42:45], v[206:209], v[42:45], v[140:143]
	s_waitcnt lgkmcnt(4)
	v_mfma_f32_16x16x32_bf16 v[140:143], v[202:205], v[46:49], v[162:165]
	v_mfma_f32_16x16x32_bf16 v[46:49], v[206:209], v[46:49], v[156:159]
	s_waitcnt lgkmcnt(2)
	v_mfma_f32_16x16x32_bf16 v[152:155], v[202:205], v[50:53], v[170:173]
	v_mfma_f32_16x16x32_bf16 v[50:53], v[206:209], v[50:53], v[166:169]
	s_waitcnt lgkmcnt(0)
	v_mfma_f32_16x16x32_bf16 v[156:159], v[202:205], v[54:57], v[198:201]
	v_mfma_f32_16x16x32_bf16 v[54:57], v[206:209], v[54:57], v[174:177]
	ds_read_b128 v[162:165], v111 offset:52224
	ds_read_b128 v[166:169], v111 offset:52736
	ds_read_b128 v[170:173], v111 offset:53248
	ds_read_b128 v[174:177], v111 offset:53760
	s_waitcnt lgkmcnt(2)
	v_pk_mul_f32 v[144:145], v[162:163], v[166:167]
	v_pk_mul_f32 v[162:163], v[164:165], v[168:169]
	s_waitcnt lgkmcnt(0)
	v_pk_mul_f32 v[164:165], v[170:171], v[174:175]
	v_pk_mul_f32 v[166:167], v[172:173], v[176:177]
	v_pk_mul_f32 v[144:145], v[144:145], v[164:165]
	v_pk_mul_f32 v[162:163], v[162:163], v[166:167]
	v_pk_mul_f32 v[132:133], v[132:133], v[144:145]
	v_pk_mul_f32 v[134:135], v[134:135], v[162:163]
	v_cvt_pk_bf16_f32 v132, v132, v133
	v_cvt_pk_bf16_f32 v133, v134, v135
	v_pk_mul_f32 v[164:165], v[212:213], v[162:163]
	v_pk_mul_f32 v[166:167], v[210:211], v[144:145]
	ds_write_b64 v118, v[132:133] offset:57344
	v_pk_mul_f32 v[132:133], v[142:143], v[162:163]
	v_pk_mul_f32 v[134:135], v[140:141], v[144:145]
	v_cvt_pk_bf16_f32 v166, v166, v167
	v_cvt_pk_bf16_f32 v167, v164, v165
	v_cvt_pk_bf16_f32 v134, v134, v135
	v_cvt_pk_bf16_f32 v135, v132, v133
	ds_write_b64 v131, v[166:167] offset:57344
	v_pk_mul_f32 v[164:165], v[218:219], v[162:163]
	v_pk_mul_f32 v[166:167], v[216:217], v[144:145]
	ds_write_b64 v119, v[134:135] offset:57344
	v_pk_mul_f32 v[132:133], v[154:155], v[162:163]
	v_pk_mul_f32 v[134:135], v[152:153], v[144:145]
	v_cvt_pk_bf16_f32 v166, v166, v167
	v_cvt_pk_bf16_f32 v167, v164, v165
	v_cvt_pk_bf16_f32 v134, v134, v135
	v_cvt_pk_bf16_f32 v135, v132, v133
	ds_write_b64 v131, v[166:167] offset:61696
	v_pk_mul_f32 v[164:165], v[222:223], v[162:163]
	v_pk_mul_f32 v[166:167], v[220:221], v[144:145]
	v_pk_mul_f32 v[138:139], v[138:139], v[162:163]
	v_pk_mul_f32 v[136:137], v[136:137], v[144:145]
	ds_write_b64 v120, v[134:135] offset:57344
	v_pk_mul_f32 v[132:133], v[158:159], v[162:163]
	v_pk_mul_f32 v[134:135], v[156:157], v[144:145]
	v_cvt_pk_bf16_f32 v166, v166, v167
	v_cvt_pk_bf16_f32 v167, v164, v165
	v_cvt_pk_bf16_f32 v136, v136, v137
	v_cvt_pk_bf16_f32 v137, v138, v139
	v_cvt_pk_bf16_f32 v134, v134, v135
	v_cvt_pk_bf16_f32 v135, v132, v133
	ds_write_b64 v116, v[166:167] offset:57344
	ds_write_b64 v117, v[136:137] offset:57344
	ds_write_b64 v121, v[134:135] offset:57344
	ds_read_b128 v[132:135], v111 offset:52288
	ds_read_b128 v[136:139], v111 offset:52800
	ds_read_b128 v[140:143], v111 offset:53312
	ds_read_b128 v[152:155], v111 offset:53824
	s_waitcnt lgkmcnt(2)
	v_pk_mul_f32 v[132:133], v[132:133], v[136:137]
	v_pk_mul_f32 v[134:135], v[134:135], v[138:139]
	s_waitcnt lgkmcnt(0)
	v_pk_mul_f32 v[136:137], v[140:141], v[152:153]
	v_pk_mul_f32 v[138:139], v[142:143], v[154:155]
	v_pk_mul_f32 v[132:133], v[132:133], v[136:137]
	v_pk_mul_f32 v[134:135], v[134:135], v[138:139]
	v_pk_mul_f32 v[26:27], v[26:27], v[132:133]
	v_pk_mul_f32 v[28:29], v[28:29], v[134:135]
	v_cvt_pk_bf16_f32 v26, v26, v27
	v_cvt_pk_bf16_f32 v27, v28, v29
	ds_write_b64 v131, v[26:27] offset:57376
	v_pk_mul_f32 v[26:27], v[32:33], v[134:135]
	v_pk_mul_f32 v[28:29], v[30:31], v[132:133]
	s_nop 0
	v_cvt_pk_bf16_f32 v28, v28, v29
	v_cvt_pk_bf16_f32 v29, v26, v27
	ds_write_b64 v131, v[28:29] offset:61728
	v_pk_mul_f32 v[26:27], v[36:37], v[134:135]
	v_pk_mul_f32 v[28:29], v[34:35], v[132:133]
	s_nop 0
	v_cvt_pk_bf16_f32 v28, v28, v29
	v_cvt_pk_bf16_f32 v29, v26, v27
	ds_write_b64 v116, v[28:29] offset:57376
	v_pk_mul_f32 v[26:27], v[40:41], v[134:135]
	v_pk_mul_f32 v[28:29], v[38:39], v[132:133]
	s_nop 0
	v_cvt_pk_bf16_f32 v28, v28, v29
	v_cvt_pk_bf16_f32 v29, v26, v27
	ds_write_b64 v117, v[28:29] offset:57376
	v_pk_mul_f32 v[26:27], v[44:45], v[134:135]
	v_pk_mul_f32 v[28:29], v[42:43], v[132:133]
	s_nop 0
	v_cvt_pk_bf16_f32 v28, v28, v29
	v_cvt_pk_bf16_f32 v29, v26, v27
	ds_write_b64 v118, v[28:29] offset:57376
	v_pk_mul_f32 v[26:27], v[48:49], v[134:135]
	v_pk_mul_f32 v[28:29], v[46:47], v[132:133]
	s_nop 0
	v_cvt_pk_bf16_f32 v28, v28, v29
	v_cvt_pk_bf16_f32 v29, v26, v27
	ds_write_b64 v119, v[28:29] offset:57376
	v_pk_mul_f32 v[26:27], v[52:53], v[134:135]
	v_pk_mul_f32 v[28:29], v[50:51], v[132:133]
	s_nop 0
	v_cvt_pk_bf16_f32 v28, v28, v29
	v_cvt_pk_bf16_f32 v29, v26, v27
	ds_write_b64 v120, v[28:29] offset:57376
	v_pk_mul_f32 v[26:27], v[56:57], v[134:135]
	v_pk_mul_f32 v[28:29], v[54:55], v[132:133]
	s_nop 0
	v_cvt_pk_bf16_f32 v28, v28, v29
	v_cvt_pk_bf16_f32 v29, v26, v27
	v_lshlrev_b64 v[26:27], 16, v[86:87]
	ds_write_b64 v121, v[28:29] offset:57376
	s_waitcnt lgkmcnt(0)
	s_barrier
	v_lshl_add_u64 v[30:31], v[66:67], 0, v[26:27]
	ds_read_b128 v[26:29], v122 offset:57344
	ds_read_b128 v[224:227], v123 offset:57344
	ds_read_b128 v[228:231], v124 offset:57344
	ds_read_b128 v[232:235], v125 offset:57344
	v_lshl_add_u64 v[32:33], v[30:31], 0, v[68:69]
	s_waitcnt lgkmcnt(3)
	global_store_dwordx4 v[32:33], v[26:29], off sc1
	v_lshl_add_u64 v[252:253], v[30:31], 0, v[70:71]
	ds_read_b128 v[26:29], v126 offset:57344
	s_waitcnt lgkmcnt(3)
	global_store_dwordx4 v[252:253], v[224:227], off sc1
	v_lshl_add_u64 v[32:33], v[30:31], 0, v[72:73]
	ds_read_b128 v[224:227], v127 offset:57344
	s_waitcnt lgkmcnt(3)
	global_store_dwordx4 v[32:33], v[228:231], off sc1
	v_lshl_add_u64 v[252:253], v[30:31], 0, v[74:75]
	ds_read_b128 v[228:231], v128 offset:57344
	s_waitcnt lgkmcnt(3)
	global_store_dwordx4 v[252:253], v[232:235], off sc1
	v_lshl_add_u64 v[32:33], v[30:31], 0, v[76:77]
	ds_read_b128 v[232:235], v129 offset:57344
	s_waitcnt lgkmcnt(3)
	global_store_dwordx4 v[32:33], v[26:29], off sc1
	v_lshl_add_u64 v[252:253], v[30:31], 0, v[78:79]
	s_waitcnt lgkmcnt(2)
	global_store_dwordx4 v[252:253], v[224:227], off sc1
	v_lshl_add_u64 v[32:33], v[30:31], 0, v[80:81]
	s_waitcnt lgkmcnt(1)
	global_store_dwordx4 v[32:33], v[228:231], off sc1
	v_lshl_add_u64 v[30:31], v[30:31], 0, v[82:83]
	s_waitcnt lgkmcnt(0)
	global_store_dwordx4 v[30:31], v[232:235], off sc1
	s_barrier
	s_cbranch_scc1 .LBB0_286

.LBB0_363:
	v_mov_b32_e32 v0, s24
	v_mov_b32_e32 v2, s17
	s_xor_b32 s25, s17, -2
	v_cndmask_b32_e32 v0, v0, v2, vcc
	s_add_i32 s25, s25, s13
	s_add_i32 s26, s17, 1
	v_add_u32_e32 v108, v0, v124
	v_mov_b32_e32 v0, s25
	v_mov_b32_e32 v10, s26
	s_xor_b32 s25, s17, -3
	v_cndmask_b32_e32 v0, v0, v10, vcc
	s_add_i32 s25, s25, s13
	s_add_i32 s26, s17, 2
	v_add_u32_e32 v110, v0, v124
	v_mov_b32_e32 v0, s25
	v_mov_b32_e32 v26, s26
	s_xor_b32 s25, s17, -4
	v_ashrrev_i32_e32 v109, 31, v108
	v_cndmask_b32_e32 v0, v0, v26, vcc
	s_add_i32 s25, s25, s13
	s_add_i32 s26, s17, 3
	v_lshlrev_b64 v[2:3], 10, v[108:109]
	v_ashrrev_i32_e32 v111, 31, v110
	v_add_u32_e32 v112, v0, v124
	v_mov_b32_e32 v0, s25
	v_mov_b32_e32 v38, s26
	s_xor_b32 s25, s17, -5
	v_or_b32_e32 v2, v2, v96
	v_lshlrev_b64 v[10:11], 10, v[110:111]
	v_cndmask_b32_e32 v0, v0, v38, vcc
	s_add_i32 s25, s25, s13
	s_add_i32 s26, s17, 4
	v_or_b32_e32 v4, v2, v90
	v_mov_b32_e32 v5, v3
	v_or_b32_e32 v10, v10, v96
	v_ashrrev_i32_e32 v113, 31, v112
	v_add_u32_e32 v114, v0, v124
	v_mov_b32_e32 v0, s25
	v_mov_b32_e32 v50, s26
	s_xor_b32 s25, s17, -6
	v_lshlrev_b64 v[4:5], 8, v[4:5]
	v_or_b32_e32 v12, v10, v90
	v_mov_b32_e32 v13, v11
	v_lshlrev_b64 v[26:27], 10, v[112:113]
	v_cndmask_b32_e32 v0, v0, v50, vcc
	s_add_i32 s25, s25, s13
	s_add_i32 s26, s17, 5
	v_lshl_add_u64 v[4:5], v[92:93], 0, v[4:5]
	v_lshlrev_b64 v[12:13], 8, v[12:13]
	v_or_b32_e32 v26, v26, v96
	v_ashrrev_i32_e32 v115, 31, v114
	v_add_u32_e32 v116, v0, v124
	v_mov_b32_e32 v0, s25
	v_mov_b32_e32 v62, s26
	s_xor_b32 s25, s17, -7
	global_load_dwordx4 v[22:25], v[4:5], off nt
	v_lshl_add_u64 v[6:7], v[2:3], 2, v[94:95]
	v_lshl_add_u64 v[12:13], v[92:93], 0, v[12:13]
	v_or_b32_e32 v28, v26, v90
	v_mov_b32_e32 v29, v27
	v_lshlrev_b64 v[38:39], 10, v[114:115]
	v_cndmask_b32_e32 v0, v0, v62, vcc
	s_add_i32 s25, s25, s13
	s_add_i32 s26, s17, 6
	global_load_dwordx4 v[2:5], v[6:7], off offset:16 nt
	s_nop 0
	global_load_dwordx4 v[6:9], v[6:7], off nt
	v_lshl_add_u64 v[14:15], v[10:11], 2, v[94:95]
	global_load_dwordx4 v[18:21], v[12:13], off nt
	v_lshlrev_b64 v[28:29], 8, v[28:29]
	v_or_b32_e32 v38, v38, v96
	v_ashrrev_i32_e32 v117, 31, v116
	v_add_u32_e32 v118, v0, v124
	v_mov_b32_e32 v0, s25
	v_mov_b32_e32 v74, s26
	s_xor_b32 s25, s17, -8
	global_load_dwordx4 v[10:13], v[14:15], off offset:16 nt
	s_nop 0
	global_load_dwordx4 v[14:17], v[14:15], off nt
	v_lshl_add_u64 v[28:29], v[92:93], 0, v[28:29]
	v_or_b32_e32 v40, v38, v90
	v_mov_b32_e32 v41, v39
	v_lshlrev_b64 v[50:51], 10, v[116:117]
	v_cndmask_b32_e32 v0, v0, v74, vcc
	s_add_i32 s25, s25, s13
	s_add_i32 s26, s17, 7
	global_load_dwordx4 v[34:37], v[28:29], off nt
	v_lshl_add_u64 v[30:31], v[26:27], 2, v[94:95]
	v_lshlrev_b64 v[40:41], 8, v[40:41]
	v_or_b32_e32 v50, v50, v96
	v_ashrrev_i32_e32 v119, 31, v118
	v_add_u32_e32 v120, v0, v124
	v_mov_b32_e32 v0, s25
	v_mov_b32_e32 v86, s26
	global_load_dwordx4 v[26:29], v[30:31], off offset:16 nt
	s_nop 0
	global_load_dwordx4 v[30:33], v[30:31], off nt
	v_lshl_add_u64 v[40:41], v[92:93], 0, v[40:41]
	v_or_b32_e32 v52, v50, v90
	v_mov_b32_e32 v53, v51
	v_lshlrev_b64 v[62:63], 10, v[118:119]
	v_cndmask_b32_e32 v0, v0, v86, vcc
	global_load_dwordx4 v[46:49], v[40:41], off nt
	v_lshl_add_u64 v[42:43], v[38:39], 2, v[94:95]
	v_lshlrev_b64 v[52:53], 8, v[52:53]
	v_or_b32_e32 v62, v62, v96
	v_ashrrev_i32_e32 v121, 31, v120
	v_add_u32_e32 v122, v0, v124
	global_load_dwordx4 v[38:41], v[42:43], off offset:16 nt
	s_nop 0
	global_load_dwordx4 v[42:45], v[42:43], off nt
	v_lshl_add_u64 v[52:53], v[92:93], 0, v[52:53]
	v_or_b32_e32 v64, v62, v90
	v_mov_b32_e32 v65, v63
	v_lshlrev_b64 v[74:75], 10, v[120:121]
	v_ashrrev_i32_e32 v123, 31, v122
	global_load_dwordx4 v[58:61], v[52:53], off nt
	v_lshl_add_u64 v[54:55], v[50:51], 2, v[94:95]
	v_lshlrev_b64 v[64:65], 8, v[64:65]
	v_or_b32_e32 v74, v74, v96
	v_lshlrev_b64 v[86:87], 10, v[122:123]
	global_load_dwordx4 v[50:53], v[54:55], off offset:16 nt
	s_nop 0
	global_load_dwordx4 v[54:57], v[54:55], off nt
	v_lshl_add_u64 v[64:65], v[92:93], 0, v[64:65]
	v_or_b32_e32 v76, v74, v90
	v_mov_b32_e32 v77, v75
	v_or_b32_e32 v86, v86, v96
	global_load_dwordx4 v[70:73], v[64:65], off nt
	v_lshl_add_u64 v[66:67], v[62:63], 2, v[94:95]
	v_lshlrev_b64 v[76:77], 8, v[76:77]
	v_or_b32_e32 v88, v86, v90
	v_mov_b32_e32 v89, v87
	global_load_dwordx4 v[62:65], v[66:67], off offset:16 nt
	s_nop 0
	global_load_dwordx4 v[66:69], v[66:67], off nt
	v_lshl_add_u64 v[76:77], v[92:93], 0, v[76:77]
	v_lshlrev_b64 v[88:89], 8, v[88:89]
	global_load_dwordx4 v[82:85], v[76:77], off nt
	v_lshl_add_u64 v[78:79], v[74:75], 2, v[94:95]
	v_lshl_add_u64 v[88:89], v[92:93], 0, v[88:89]
	global_load_dwordx4 v[74:77], v[78:79], off offset:16 nt
	s_nop 0
	global_load_dwordx4 v[78:81], v[78:79], off nt
	v_lshl_add_u64 v[130:131], v[86:87], 2, v[94:95]
	global_load_dwordx4 v[126:129], v[88:89], off nt
	s_nop 0
	global_load_dwordx4 v[86:89], v[130:131], off offset:16 nt
	s_nop 0
	global_load_dwordx4 v[130:133], v[130:131], off nt
	v_lshlrev_b64 v[108:109], 18, v[108:109]
	v_lshl_add_u64 v[108:109], v[98:99], 0, v[108:109]
	s_waitcnt vmcnt(23)
	v_lshlrev_b32_e32 v134, 16, v22
	v_and_b32_e32 v135, 0xffff0000, v22
	v_lshlrev_b32_e32 v136, 16, v23
	v_and_b32_e32 v137, 0xffff0000, v23
	v_lshlrev_b32_e32 v138, 16, v24
	v_and_b32_e32 v139, 0xffff0000, v24
	v_lshlrev_b32_e32 v140, 16, v25
	v_and_b32_e32 v141, 0xffff0000, v25
	v_cvt_pk_bf16_f32 v22, v100, v101
	v_cvt_pk_bf16_f32 v23, v102, v103
	v_cvt_pk_bf16_f32 v24, v104, v105
	v_cvt_pk_bf16_f32 v25, v106, v107
	global_store_dwordx4 v[108:109], v[22:25], off sc1
	s_waitcnt vmcnt(22)
	v_pk_fma_f32 v[8:9], v[102:103], v[8:9], v[136:137]
	v_pk_fma_f32 v[6:7], v[100:101], v[6:7], v[134:135]
	v_pk_fma_f32 v[22:23], v[106:107], v[4:5], v[140:141]
	v_pk_fma_f32 v[24:25], v[104:105], v[2:3], v[138:139]
	s_waitcnt vmcnt(21)
	v_lshlrev_b32_e32 v100, 16, v18
	v_and_b32_e32 v101, 0xffff0000, v18
	v_lshlrev_b32_e32 v18, 16, v19
	v_and_b32_e32 v19, 0xffff0000, v19
	v_lshlrev_b32_e32 v102, 16, v20
	v_and_b32_e32 v103, 0xffff0000, v20
	v_lshlrev_b32_e32 v20, 16, v21
	v_and_b32_e32 v21, 0xffff0000, v21
	v_lshlrev_b64 v[104:105], 18, v[110:111]
	v_cvt_pk_bf16_f32 v2, v6, v7
	v_cvt_pk_bf16_f32 v3, v8, v9
	v_cvt_pk_bf16_f32 v4, v24, v25
	v_cvt_pk_bf16_f32 v5, v22, v23
	v_lshl_add_u64 v[104:105], v[98:99], 0, v[104:105]
	s_waitcnt vmcnt(19)
	v_pk_fma_f32 v[8:9], v[16:17], v[8:9], v[18:19]
	v_pk_fma_f32 v[6:7], v[14:15], v[6:7], v[100:101]
	v_pk_fma_f32 v[12:13], v[12:13], v[22:23], v[20:21]
	v_pk_fma_f32 v[10:11], v[10:11], v[24:25], v[102:103]
	v_lshlrev_b64 v[22:23], 18, v[112:113]
	global_store_dwordx4 v[104:105], v[2:5], off sc1
	s_waitcnt vmcnt(19)
	v_lshlrev_b32_e32 v14, 16, v34
	v_and_b32_e32 v15, 0xffff0000, v34
	v_lshlrev_b32_e32 v16, 16, v35
	v_and_b32_e32 v17, 0xffff0000, v35
	v_lshlrev_b32_e32 v18, 16, v36
	v_and_b32_e32 v19, 0xffff0000, v36
	v_lshlrev_b32_e32 v20, 16, v37
	v_and_b32_e32 v21, 0xffff0000, v37
	v_cvt_pk_bf16_f32 v2, v6, v7
	v_cvt_pk_bf16_f32 v3, v8, v9
	v_cvt_pk_bf16_f32 v4, v10, v11
	v_cvt_pk_bf16_f32 v5, v12, v13
	v_lshl_add_u64 v[22:23], v[98:99], 0, v[22:23]
	global_store_dwordx4 v[22:23], v[2:5], off sc1
	s_waitcnt vmcnt(18)
	v_pk_fma_f32 v[8:9], v[32:33], v[8:9], v[16:17]
	v_pk_fma_f32 v[6:7], v[30:31], v[6:7], v[14:15]
	v_pk_fma_f32 v[12:13], v[28:29], v[12:13], v[20:21]
	v_pk_fma_f32 v[10:11], v[26:27], v[10:11], v[18:19]
	v_lshlrev_b64 v[22:23], 18, v[114:115]
	s_waitcnt vmcnt(17)
	v_lshlrev_b32_e32 v14, 16, v46
	v_and_b32_e32 v15, 0xffff0000, v46
	v_lshlrev_b32_e32 v16, 16, v47
	v_and_b32_e32 v17, 0xffff0000, v47
	v_lshlrev_b32_e32 v18, 16, v48
	v_and_b32_e32 v19, 0xffff0000, v48
	v_lshlrev_b32_e32 v20, 16, v49
	v_and_b32_e32 v21, 0xffff0000, v49
	v_cvt_pk_bf16_f32 v2, v6, v7
	v_cvt_pk_bf16_f32 v3, v8, v9
	v_cvt_pk_bf16_f32 v4, v10, v11
	v_cvt_pk_bf16_f32 v5, v12, v13
	v_lshl_add_u64 v[22:23], v[98:99], 0, v[22:23]
	global_store_dwordx4 v[22:23], v[2:5], off sc1
	s_waitcnt vmcnt(16)
	v_pk_fma_f32 v[8:9], v[44:45], v[8:9], v[16:17]
	v_pk_fma_f32 v[6:7], v[42:43], v[6:7], v[14:15]
	v_pk_fma_f32 v[12:13], v[40:41], v[12:13], v[20:21]
	v_pk_fma_f32 v[10:11], v[38:39], v[10:11], v[18:19]
	v_lshlrev_b64 v[22:23], 18, v[116:117]
	s_waitcnt vmcnt(15)
	v_lshlrev_b32_e32 v14, 16, v58
	v_and_b32_e32 v15, 0xffff0000, v58
	v_lshlrev_b32_e32 v16, 16, v59
	v_and_b32_e32 v17, 0xffff0000, v59
	v_lshlrev_b32_e32 v18, 16, v60
	v_and_b32_e32 v19, 0xffff0000, v60
	v_lshlrev_b32_e32 v20, 16, v61
	v_and_b32_e32 v21, 0xffff0000, v61
	v_cvt_pk_bf16_f32 v2, v6, v7
	v_cvt_pk_bf16_f32 v3, v8, v9
	v_cvt_pk_bf16_f32 v4, v10, v11
	v_cvt_pk_bf16_f32 v5, v12, v13
	v_lshl_add_u64 v[22:23], v[98:99], 0, v[22:23]
	global_store_dwordx4 v[22:23], v[2:5], off sc1
	s_waitcnt vmcnt(14)
	v_pk_fma_f32 v[8:9], v[56:57], v[8:9], v[16:17]
	v_pk_fma_f32 v[6:7], v[54:55], v[6:7], v[14:15]
	v_pk_fma_f32 v[12:13], v[52:53], v[12:13], v[20:21]
	v_pk_fma_f32 v[10:11], v[50:51], v[10:11], v[18:19]
	v_lshlrev_b64 v[22:23], 18, v[118:119]
	s_waitcnt vmcnt(13)
	v_lshlrev_b32_e32 v14, 16, v70
	v_and_b32_e32 v15, 0xffff0000, v70
	v_lshlrev_b32_e32 v16, 16, v71
	v_and_b32_e32 v17, 0xffff0000, v71
	v_lshlrev_b32_e32 v18, 16, v72
	v_and_b32_e32 v19, 0xffff0000, v72
	v_lshlrev_b32_e32 v20, 16, v73
	v_and_b32_e32 v21, 0xffff0000, v73
	v_cvt_pk_bf16_f32 v2, v6, v7
	v_cvt_pk_bf16_f32 v3, v8, v9
	v_cvt_pk_bf16_f32 v4, v10, v11
	v_cvt_pk_bf16_f32 v5, v12, v13
	v_lshl_add_u64 v[22:23], v[98:99], 0, v[22:23]
	global_store_dwordx4 v[22:23], v[2:5], off sc1
	s_waitcnt vmcnt(12)
	v_pk_fma_f32 v[8:9], v[68:69], v[8:9], v[16:17]
	v_pk_fma_f32 v[6:7], v[66:67], v[6:7], v[14:15]
	v_pk_fma_f32 v[12:13], v[64:65], v[12:13], v[20:21]
	v_pk_fma_f32 v[10:11], v[62:63], v[10:11], v[18:19]
	v_lshlrev_b64 v[22:23], 18, v[120:121]
	s_waitcnt vmcnt(11)
	v_lshlrev_b32_e32 v14, 16, v82
	v_and_b32_e32 v15, 0xffff0000, v82
	v_lshlrev_b32_e32 v16, 16, v83
	v_and_b32_e32 v17, 0xffff0000, v83
	v_lshlrev_b32_e32 v18, 16, v84
	v_and_b32_e32 v19, 0xffff0000, v84
	v_lshlrev_b32_e32 v20, 16, v85
	v_and_b32_e32 v21, 0xffff0000, v85
	v_cvt_pk_bf16_f32 v2, v6, v7
	v_cvt_pk_bf16_f32 v3, v8, v9
	v_cvt_pk_bf16_f32 v4, v10, v11
	v_cvt_pk_bf16_f32 v5, v12, v13
	v_lshl_add_u64 v[22:23], v[98:99], 0, v[22:23]
	global_store_dwordx4 v[22:23], v[2:5], off sc1
	s_waitcnt vmcnt(10)
	v_pk_fma_f32 v[8:9], v[80:81], v[8:9], v[16:17]
	v_pk_fma_f32 v[6:7], v[78:79], v[6:7], v[14:15]
	v_pk_fma_f32 v[12:13], v[76:77], v[12:13], v[20:21]
	v_pk_fma_f32 v[10:11], v[74:75], v[10:11], v[18:19]
	s_waitcnt vmcnt(9)
	v_lshlrev_b32_e32 v14, 16, v126
	v_and_b32_e32 v15, 0xffff0000, v126
	v_lshlrev_b32_e32 v16, 16, v127
	v_and_b32_e32 v17, 0xffff0000, v127
	v_lshlrev_b32_e32 v18, 16, v128
	v_and_b32_e32 v19, 0xffff0000, v128
	v_lshlrev_b32_e32 v20, 16, v129
	v_and_b32_e32 v21, 0xffff0000, v129
	v_lshlrev_b64 v[22:23], 18, v[122:123]
	s_add_i32 s24, s24, -8
	s_add_i32 s17, s17, 8
	v_cvt_pk_bf16_f32 v2, v6, v7
	v_cvt_pk_bf16_f32 v3, v8, v9
	v_cvt_pk_bf16_f32 v4, v10, v11
	v_cvt_pk_bf16_f32 v5, v12, v13
	v_lshl_add_u64 v[22:23], v[98:99], 0, v[22:23]
	s_waitcnt vmcnt(7)
	v_pk_fma_f32 v[102:103], v[132:133], v[8:9], v[16:17]
	v_pk_fma_f32 v[100:101], v[130:131], v[6:7], v[14:15]
	v_pk_fma_f32 v[106:107], v[88:89], v[12:13], v[20:21]
	v_pk_fma_f32 v[104:105], v[86:87], v[10:11], v[18:19]
	s_cmp_ge_u32 s17, s13
	global_store_dwordx4 v[22:23], v[2:5], off sc1
	s_cbranch_scc0 .LBB0_363
	v_add_u32_e32 v97, s10, v97
	v_cmp_le_i32_e32 vcc, s12, v97
	s_or_b64 s[8:9], vcc, s[8:9]
	s_andn2_b64 exec, exec, s[8:9]
	s_cbranch_execnz .LBB0_362

.LBB0_368:
	v_mov_b32_e32 v0, s16
	v_mov_b32_e32 v2, s15
	v_cndmask_b32_e32 v0, v0, v2, vcc
	v_add_u32_e32 v2, v0, v54
	v_ashrrev_i32_e32 v3, 31, v2
	v_lshlrev_b64 v[42:43], 17, v[2:3]
	s_xor_b32 s17, s15, -2
	v_lshl_add_u64 v[2:3], v[30:31], 0, v[42:43]
	s_add_i32 s17, s17, s12
	s_add_i32 s24, s15, 1
	global_load_dwordx4 v[10:13], v[2:3], off nt
	v_mov_b32_e32 v0, s17
	v_mov_b32_e32 v2, s24
	s_xor_b32 s17, s15, -3
	v_cndmask_b32_e32 v0, v0, v2, vcc
	s_add_i32 s17, s17, s12
	s_add_i32 s24, s15, 2
	v_add_u32_e32 v2, v0, v54
	v_mov_b32_e32 v0, s17
	v_mov_b32_e32 v6, s24
	s_xor_b32 s17, s15, -4
	v_cndmask_b32_e32 v0, v0, v6, vcc
	s_add_i32 s17, s17, s12
	s_add_i32 s24, s15, 3
	v_add_u32_e32 v6, v0, v54
	v_mov_b32_e32 v0, s17
	v_mov_b32_e32 v14, s24
	s_xor_b32 s17, s15, -5
	v_cndmask_b32_e32 v0, v0, v14, vcc
	s_add_i32 s17, s17, s12
	s_add_i32 s24, s15, 4
	v_add_u32_e32 v14, v0, v54
	v_mov_b32_e32 v0, s17
	v_mov_b32_e32 v18, s24
	s_xor_b32 s17, s15, -6
	v_cndmask_b32_e32 v0, v0, v18, vcc
	s_add_i32 s17, s17, s12
	s_add_i32 s24, s15, 5
	v_add_u32_e32 v18, v0, v54
	v_mov_b32_e32 v0, s17
	v_mov_b32_e32 v22, s24
	s_xor_b32 s17, s15, -7
	v_ashrrev_i32_e32 v3, 31, v2
	v_cndmask_b32_e32 v0, v0, v22, vcc
	s_add_i32 s17, s17, s12
	s_add_i32 s24, s15, 6
	v_lshlrev_b64 v[44:45], 17, v[2:3]
	v_ashrrev_i32_e32 v7, 31, v6
	v_add_u32_e32 v22, v0, v54
	v_mov_b32_e32 v0, s17
	v_mov_b32_e32 v55, s24
	s_xor_b32 s17, s15, -8
	v_lshl_add_u64 v[2:3], v[30:31], 0, v[44:45]
	v_lshlrev_b64 v[46:47], 17, v[6:7]
	v_ashrrev_i32_e32 v15, 31, v14
	v_cndmask_b32_e32 v0, v0, v55, vcc
	s_add_i32 s17, s17, s12
	s_add_i32 s24, s15, 7
	global_load_dwordx4 v[2:5], v[2:3], off nt
	v_lshl_add_u64 v[6:7], v[30:31], 0, v[46:47]
	v_lshlrev_b64 v[48:49], 17, v[14:15]
	v_ashrrev_i32_e32 v19, 31, v18
	v_add_u32_e32 v56, v0, v54
	v_mov_b32_e32 v0, s17
	v_mov_b32_e32 v55, s24
	global_load_dwordx4 v[6:9], v[6:7], off nt
	v_lshl_add_u64 v[14:15], v[30:31], 0, v[48:49]
	v_lshlrev_b64 v[50:51], 17, v[18:19]
	v_ashrrev_i32_e32 v23, 31, v22
	v_cndmask_b32_e32 v0, v0, v55, vcc
	global_load_dwordx4 v[14:17], v[14:15], off nt
	v_lshl_add_u64 v[18:19], v[30:31], 0, v[50:51]
	v_lshlrev_b64 v[52:53], 17, v[22:23]
	v_ashrrev_i32_e32 v57, 31, v56
	v_add_u32_e32 v60, v0, v54
	global_load_dwordx4 v[18:21], v[18:19], off nt
	v_lshl_add_u64 v[22:23], v[30:31], 0, v[52:53]
	v_lshlrev_b64 v[64:65], 17, v[56:57]
	v_ashrrev_i32_e32 v61, 31, v60
	global_load_dwordx4 v[22:25], v[22:23], off nt
	v_lshl_add_u64 v[56:57], v[30:31], 0, v[64:65]
	v_lshlrev_b64 v[66:67], 17, v[60:61]
	global_load_dwordx4 v[56:59], v[56:57], off nt
	v_lshl_add_u64 v[60:61], v[30:31], 0, v[66:67]
	global_load_dwordx4 v[60:63], v[60:61], off nt
	v_lshl_add_u64 v[42:43], v[32:33], 0, v[42:43]
	v_lshl_add_u64 v[44:45], v[32:33], 0, v[44:45]
	s_add_i32 s16, s16, -8
	s_add_i32 s15, s15, 8
	s_cmp_ge_u32 s15, s12
	s_waitcnt vmcnt(7)
	v_lshlrev_b32_e32 v68, 16, v10
	v_and_b32_e32 v69, 0xffff0000, v10
	v_lshlrev_b32_e32 v70, 16, v11
	v_and_b32_e32 v71, 0xffff0000, v11
	v_lshlrev_b32_e32 v72, 16, v12
	v_and_b32_e32 v73, 0xffff0000, v12
	v_lshlrev_b32_e32 v74, 16, v13
	v_and_b32_e32 v75, 0xffff0000, v13
	v_cvt_pk_bf16_f32 v10, v38, v39
	v_cvt_pk_bf16_f32 v11, v40, v41
	v_cvt_pk_bf16_f32 v12, v34, v35
	v_cvt_pk_bf16_f32 v13, v36, v37
	global_store_dwordx4 v[42:43], v[10:13], off sc1
	v_pk_fma_f32 v[36:37], v[28:29], v[36:37], v[74:75]
	v_pk_fma_f32 v[34:35], v[26:27], v[34:35], v[72:73]
	v_pk_fma_f32 v[10:11], v[28:29], v[40:41], v[70:71]
	v_pk_fma_f32 v[12:13], v[26:27], v[38:39], v[68:69]
	s_waitcnt vmcnt(7)
	v_lshlrev_b32_e32 v38, 16, v2
	v_and_b32_e32 v39, 0xffff0000, v2
	v_lshlrev_b32_e32 v40, 16, v3
	v_and_b32_e32 v41, 0xffff0000, v3
	v_lshlrev_b32_e32 v42, 16, v4
	v_and_b32_e32 v43, 0xffff0000, v4
	v_lshlrev_b32_e32 v68, 16, v5
	v_and_b32_e32 v69, 0xffff0000, v5
	v_cvt_pk_bf16_f32 v2, v12, v13
	v_cvt_pk_bf16_f32 v3, v10, v11
	v_cvt_pk_bf16_f32 v4, v34, v35
	v_cvt_pk_bf16_f32 v5, v36, v37
	v_pk_fma_f32 v[10:11], v[28:29], v[10:11], v[40:41]
	v_pk_fma_f32 v[12:13], v[26:27], v[12:13], v[38:39]
	v_pk_fma_f32 v[36:37], v[28:29], v[36:37], v[68:69]
	v_pk_fma_f32 v[34:35], v[26:27], v[34:35], v[42:43]
	s_waitcnt vmcnt(6)
	v_lshlrev_b32_e32 v38, 16, v6
	v_and_b32_e32 v39, 0xffff0000, v6
	v_lshlrev_b32_e32 v6, 16, v7
	v_and_b32_e32 v7, 0xffff0000, v7
	v_lshlrev_b32_e32 v40, 16, v8
	v_and_b32_e32 v41, 0xffff0000, v8
	v_lshlrev_b32_e32 v8, 16, v9
	v_and_b32_e32 v9, 0xffff0000, v9
	global_store_dwordx4 v[44:45], v[2:5], off sc1
	v_lshl_add_u64 v[42:43], v[32:33], 0, v[46:47]
	v_pk_fma_f32 v[6:7], v[28:29], v[10:11], v[6:7]
	v_cvt_pk_bf16_f32 v2, v12, v13
	v_cvt_pk_bf16_f32 v3, v10, v11
	v_cvt_pk_bf16_f32 v4, v34, v35
	v_cvt_pk_bf16_f32 v5, v36, v37
	v_pk_fma_f32 v[10:11], v[26:27], v[12:13], v[38:39]
	v_pk_fma_f32 v[8:9], v[28:29], v[36:37], v[8:9]
	v_pk_fma_f32 v[12:13], v[26:27], v[34:35], v[40:41]
	s_waitcnt vmcnt(6)
	v_lshlrev_b32_e32 v34, 16, v14
	v_and_b32_e32 v35, 0xffff0000, v14
	v_lshlrev_b32_e32 v14, 16, v15
	v_and_b32_e32 v15, 0xffff0000, v15
	v_lshlrev_b32_e32 v36, 16, v16
	v_and_b32_e32 v37, 0xffff0000, v16
	v_lshlrev_b32_e32 v16, 16, v17
	v_and_b32_e32 v17, 0xffff0000, v17
	global_store_dwordx4 v[42:43], v[2:5], off sc1
	v_lshl_add_u64 v[38:39], v[32:33], 0, v[48:49]
	s_nop 0
	v_cvt_pk_bf16_f32 v2, v10, v11
	v_cvt_pk_bf16_f32 v3, v6, v7
	v_cvt_pk_bf16_f32 v4, v12, v13
	v_cvt_pk_bf16_f32 v5, v8, v9
	v_pk_fma_f32 v[6:7], v[28:29], v[6:7], v[14:15]
	v_pk_fma_f32 v[10:11], v[26:27], v[10:11], v[34:35]
	v_pk_fma_f32 v[8:9], v[28:29], v[8:9], v[16:17]
	v_pk_fma_f32 v[12:13], v[26:27], v[12:13], v[36:37]
	s_waitcnt vmcnt(6)
	v_lshlrev_b32_e32 v14, 16, v18
	v_and_b32_e32 v15, 0xffff0000, v18
	v_lshlrev_b32_e32 v16, 16, v19
	v_and_b32_e32 v17, 0xffff0000, v19
	v_lshlrev_b32_e32 v18, 16, v20
	v_and_b32_e32 v19, 0xffff0000, v20
	v_lshlrev_b32_e32 v20, 16, v21
	v_and_b32_e32 v21, 0xffff0000, v21
	global_store_dwordx4 v[38:39], v[2:5], off sc1
	v_lshl_add_u64 v[34:35], v[32:33], 0, v[50:51]
	s_nop 0
	v_cvt_pk_bf16_f32 v2, v10, v11
	v_cvt_pk_bf16_f32 v3, v6, v7
	v_cvt_pk_bf16_f32 v4, v12, v13
	v_cvt_pk_bf16_f32 v5, v8, v9
	v_pk_fma_f32 v[6:7], v[28:29], v[6:7], v[16:17]
	v_pk_fma_f32 v[10:11], v[26:27], v[10:11], v[14:15]
	v_pk_fma_f32 v[8:9], v[28:29], v[8:9], v[20:21]
	v_pk_fma_f32 v[12:13], v[26:27], v[12:13], v[18:19]
	s_waitcnt vmcnt(6)
	v_lshlrev_b32_e32 v14, 16, v22
	v_and_b32_e32 v15, 0xffff0000, v22
	v_lshlrev_b32_e32 v16, 16, v23
	v_and_b32_e32 v17, 0xffff0000, v23
	v_lshlrev_b32_e32 v18, 16, v24
	v_and_b32_e32 v19, 0xffff0000, v24
	v_lshlrev_b32_e32 v20, 16, v25
	v_and_b32_e32 v21, 0xffff0000, v25
	global_store_dwordx4 v[34:35], v[2:5], off sc1
	v_lshl_add_u64 v[22:23], v[32:33], 0, v[52:53]
	s_nop 0
	v_cvt_pk_bf16_f32 v2, v10, v11
	v_cvt_pk_bf16_f32 v3, v6, v7
	v_cvt_pk_bf16_f32 v4, v12, v13
	v_cvt_pk_bf16_f32 v5, v8, v9
	v_pk_fma_f32 v[6:7], v[28:29], v[6:7], v[16:17]
	v_pk_fma_f32 v[10:11], v[26:27], v[10:11], v[14:15]
	v_pk_fma_f32 v[8:9], v[28:29], v[8:9], v[20:21]
	v_pk_fma_f32 v[12:13], v[26:27], v[12:13], v[18:19]
	s_waitcnt vmcnt(6)
	v_lshlrev_b32_e32 v14, 16, v56
	v_and_b32_e32 v15, 0xffff0000, v56
	v_lshlrev_b32_e32 v16, 16, v57
	v_and_b32_e32 v17, 0xffff0000, v57
	v_lshlrev_b32_e32 v18, 16, v58
	v_and_b32_e32 v19, 0xffff0000, v58
	v_lshlrev_b32_e32 v20, 16, v59
	v_and_b32_e32 v21, 0xffff0000, v59
	global_store_dwordx4 v[22:23], v[2:5], off sc1
	v_lshl_add_u64 v[22:23], v[32:33], 0, v[64:65]
	s_nop 0
	v_cvt_pk_bf16_f32 v2, v10, v11
	v_cvt_pk_bf16_f32 v3, v6, v7
	v_cvt_pk_bf16_f32 v4, v12, v13
	v_cvt_pk_bf16_f32 v5, v8, v9
	v_pk_fma_f32 v[6:7], v[28:29], v[6:7], v[16:17]
	v_pk_fma_f32 v[10:11], v[26:27], v[10:11], v[14:15]
	v_pk_fma_f32 v[8:9], v[28:29], v[8:9], v[20:21]
	v_pk_fma_f32 v[12:13], v[26:27], v[12:13], v[18:19]
	s_waitcnt vmcnt(6)
	v_lshlrev_b32_e32 v14, 16, v60
	v_and_b32_e32 v15, 0xffff0000, v60
	v_lshlrev_b32_e32 v16, 16, v61
	v_and_b32_e32 v17, 0xffff0000, v61
	v_lshlrev_b32_e32 v18, 16, v62
	v_and_b32_e32 v19, 0xffff0000, v62
	v_lshlrev_b32_e32 v20, 16, v63
	v_and_b32_e32 v21, 0xffff0000, v63
	global_store_dwordx4 v[22:23], v[2:5], off sc1
	v_lshl_add_u64 v[22:23], v[32:33], 0, v[66:67]
	v_pk_fma_f32 v[40:41], v[28:29], v[6:7], v[16:17]
	v_cvt_pk_bf16_f32 v2, v10, v11
	v_cvt_pk_bf16_f32 v3, v6, v7
	v_cvt_pk_bf16_f32 v4, v12, v13
	v_cvt_pk_bf16_f32 v5, v8, v9
	v_pk_fma_f32 v[38:39], v[26:27], v[10:11], v[14:15]
	v_pk_fma_f32 v[36:37], v[28:29], v[8:9], v[20:21]
	v_pk_fma_f32 v[34:35], v[26:27], v[12:13], v[18:19]
	global_store_dwordx4 v[22:23], v[2:5], off sc1
	s_cbranch_scc0 .LBB0_368
	v_add_u32_e32 v91, s10, v91
	v_cmp_le_i32_e32 vcc, s11, v91
	s_or_b64 s[8:9], vcc, s[8:9]
	s_andn2_b64 exec, exec, s[8:9]
	s_cbranch_execnz .LBB0_367

.LBB0_444:
	s_or_b64 exec, exec, s[14:15]
	v_mul_u32_u24_e32 v147, 0x44, v173
	v_lshl_add_u32 v147, v147, 2, v113
	ds_read_b32 v175, v147
	v_mad_u32_u24 v173, v173, s20, v102
	v_lshl_add_u32 v173, v173, 2, v135
	ds_read_b32 v177, v173
	s_ashr_i32 s14, s29, 2
	s_waitcnt lgkmcnt(1)
	v_lshlrev_b32_e32 v174, 16, v175
	v_and_b32_e32 v175, 0xffff0000, v175
	v_pk_add_f32 v[198:199], v[174:175], 1.0 op_sel_hi:[1,0] neg_lo:[1,0] neg_hi:[1,0]
	s_waitcnt lgkmcnt(0)
	v_lshlrev_b32_e32 v176, 16, v177
	v_pk_mul_f32 v[84:85], v[84:85], v[198:199]
	v_and_b32_e32 v177, 0xffff0000, v177
	v_max_f32_e32 v197, 0xda24260, v84
	v_rcp_f32_e32 v198, v197
	v_max_f32_e32 v197, 0xda24260, v85
	v_rcp_f32_e32 v199, v197
	s_ashr_i32 s15, s14, 31
	s_lshl_b64 vcc, s[14:15], 6
	s_and_b32 s14, s29, 3
	v_pk_mul_f32 v[174:175], v[198:199], v[174:175]
	s_lshl_b32 s15, s14, 23
	v_cvt_pk_bf16_f32 v174, v174, v175
	ds_write_b32 v147, v174
	v_pk_mul_f32 v[174:175], v[84:85], v[176:177]
	s_add_u32 s16, s86, s15
	v_cvt_pk_bf16_f32 v147, v174, v175
	ds_write_b32 v173, v147
	global_load_dwordx4 v[50:53], v[34:35], off nt
	v_mul_u32_u24_e32 v147, 0x44, v172
	v_lshl_add_u32 v147, v147, 2, v113
	ds_read_b32 v173, v147
	v_mad_u32_u24 v174, v172, s20, v102
	v_lshl_add_u32 v197, v174, 2, v135
	ds_read_b32 v175, v197
	s_addc_u32 s17, s87, 0
	s_waitcnt lgkmcnt(1)
	v_lshlrev_b32_e32 v172, 16, v173
	v_and_b32_e32 v173, 0xffff0000, v173
	v_pk_add_f32 v[176:177], v[172:173], 1.0 op_sel_hi:[1,0] neg_lo:[1,0] neg_hi:[1,0]
	s_waitcnt lgkmcnt(0)
	v_lshlrev_b32_e32 v174, 16, v175
	v_pk_mul_f32 v[84:85], v[84:85], v[176:177]
	v_and_b32_e32 v175, 0xffff0000, v175
	v_max_f32_e32 v176, 0xda24260, v84
	v_max_f32_e32 v177, 0xda24260, v85
	v_rcp_f32_e32 v176, v176
	v_rcp_f32_e32 v177, v177
	s_brev_b32 s15, 8
	s_lshl_b32 s80, s14, 9
	v_pk_mul_f32 v[172:173], v[176:177], v[172:173]
	s_mov_b32 s29, s28
	v_cvt_pk_bf16_f32 v172, v172, v173
	ds_write_b32 v147, v172
	v_pk_mul_f32 v[172:173], v[84:85], v[174:175]
	s_nop 0
	v_cvt_pk_bf16_f32 v147, v172, v173
	ds_write_b32 v197, v147
	global_load_dwordx4 v[46:49], v[82:83], off offset:-192 nt
	v_mul_u32_u24_e32 v147, 0x44, v171
	v_lshl_add_u32 v147, v147, 2, v113
	ds_read_b32 v173, v147
	v_mad_u32_u24 v171, v171, s20, v102
	v_lshl_add_u32 v171, v171, 2, v135
	ds_read_b32 v175, v171
	s_waitcnt lgkmcnt(1)
	v_lshlrev_b32_e32 v172, 16, v173
	v_and_b32_e32 v173, 0xffff0000, v173
	v_pk_add_f32 v[176:177], v[172:173], 1.0 op_sel_hi:[1,0] neg_lo:[1,0] neg_hi:[1,0]
	s_waitcnt lgkmcnt(0)
	v_lshlrev_b32_e32 v174, 16, v175
	v_pk_mul_f32 v[84:85], v[84:85], v[176:177]
	v_and_b32_e32 v175, 0xffff0000, v175
	v_max_f32_e32 v176, 0xda24260, v84
	v_max_f32_e32 v177, 0xda24260, v85
	v_rcp_f32_e32 v176, v176
	v_rcp_f32_e32 v177, v177
	s_nop 0
	v_pk_mul_f32 v[172:173], v[176:177], v[172:173]
	s_nop 0
	v_cvt_pk_bf16_f32 v172, v172, v173
	ds_write_b32 v147, v172
	v_pk_mul_f32 v[172:173], v[84:85], v[174:175]
	s_nop 0
	v_cvt_pk_bf16_f32 v147, v172, v173
	ds_write_b32 v171, v147
	global_load_dwordx4 v[42:45], v[82:83], off offset:-128 nt
	v_mul_u32_u24_e32 v147, 0x44, v170
	v_lshl_add_u32 v147, v147, 2, v113
	ds_read_b32 v171, v147
	v_mad_u32_u24 v172, v170, s20, v102
	v_lshl_add_u32 v176, v172, 2, v135
	ds_read_b32 v173, v176
	s_waitcnt lgkmcnt(1)
	v_lshlrev_b32_e32 v170, 16, v171
	v_and_b32_e32 v171, 0xffff0000, v171
	v_pk_add_f32 v[174:175], v[170:171], 1.0 op_sel_hi:[1,0] neg_lo:[1,0] neg_hi:[1,0]
	s_waitcnt lgkmcnt(0)
	v_lshlrev_b32_e32 v172, 16, v173
	v_pk_mul_f32 v[84:85], v[84:85], v[174:175]
	v_and_b32_e32 v173, 0xffff0000, v173
	v_max_f32_e32 v174, 0xda24260, v84
	v_max_f32_e32 v175, 0xda24260, v85
	v_rcp_f32_e32 v174, v174
	v_rcp_f32_e32 v175, v175
	s_nop 0
	v_pk_mul_f32 v[170:171], v[174:175], v[170:171]
	s_nop 0
	v_cvt_pk_bf16_f32 v170, v170, v171
	ds_write_b32 v147, v170
	v_pk_mul_f32 v[170:171], v[84:85], v[172:173]
	s_nop 0
	v_cvt_pk_bf16_f32 v147, v170, v171
	ds_write_b32 v176, v147
	global_load_dwordx4 v[38:41], v[82:83], off offset:-64 nt
	v_mul_u32_u24_e32 v147, 0x44, v169
	v_lshl_add_u32 v147, v147, 2, v113
	ds_read_b32 v171, v147
	v_mad_u32_u24 v169, v169, s20, v102
	v_lshl_add_u32 v169, v169, 2, v135
	ds_read_b32 v173, v169
	v_add_u32_e32 v176, v137, v73
	s_waitcnt lgkmcnt(1)
	v_lshlrev_b32_e32 v170, 16, v171
	v_and_b32_e32 v171, 0xffff0000, v171
	v_pk_add_f32 v[174:175], v[170:171], 1.0 op_sel_hi:[1,0] neg_lo:[1,0] neg_hi:[1,0]
	s_waitcnt lgkmcnt(0)
	v_lshlrev_b32_e32 v172, 16, v173
	v_pk_mul_f32 v[84:85], v[84:85], v[174:175]
	v_and_b32_e32 v173, 0xffff0000, v173
	v_max_f32_e32 v174, 0xda24260, v84
	v_max_f32_e32 v175, 0xda24260, v85
	v_rcp_f32_e32 v174, v174
	v_rcp_f32_e32 v175, v175
	s_nop 0
	v_pk_mul_f32 v[170:171], v[174:175], v[170:171]
	s_nop 0
	v_cvt_pk_bf16_f32 v170, v170, v171
	ds_write_b32 v147, v170
	v_pk_mul_f32 v[170:171], v[84:85], v[172:173]
	s_nop 0
	v_cvt_pk_bf16_f32 v147, v170, v171
	ds_write_b32 v169, v147
	global_load_dwordx4 v[34:37], v[82:83], off nt
	v_lshl_add_u64 v[82:83], v[82:83], 0, s[10:11]
	v_mul_u32_u24_e32 v147, 0x44, v168
	v_lshl_add_u32 v147, v147, 2, v113
	ds_read_b32 v169, v147
	v_mad_u32_u24 v170, v168, s20, v102
	v_lshl_add_u32 v174, v170, 2, v135
	ds_read_b32 v171, v174
	s_waitcnt lgkmcnt(1)
	v_lshlrev_b32_e32 v168, 16, v169
	v_and_b32_e32 v169, 0xffff0000, v169
	v_pk_add_f32 v[172:173], v[168:169], 1.0 op_sel_hi:[1,0] neg_lo:[1,0] neg_hi:[1,0]
	s_waitcnt lgkmcnt(0)
	v_lshlrev_b32_e32 v170, 16, v171
	v_pk_mul_f32 v[84:85], v[84:85], v[172:173]
	v_and_b32_e32 v171, 0xffff0000, v171
	v_max_f32_e32 v172, 0xda24260, v84
	v_max_f32_e32 v173, 0xda24260, v85
	v_rcp_f32_e32 v172, v172
	v_rcp_f32_e32 v173, v173
	s_nop 0
	v_pk_mul_f32 v[168:169], v[172:173], v[168:169]
	s_nop 0
	v_cvt_pk_bf16_f32 v168, v168, v169
	ds_write_b32 v147, v168
	v_pk_mul_f32 v[168:169], v[84:85], v[170:171]
	s_nop 0
	v_cvt_pk_bf16_f32 v147, v168, v169
	ds_write_b32 v174, v147
	global_load_dwordx4 v[2:5], v236, s[100:101] nt
	v_mul_u32_u24_e32 v147, 0x44, v95
	v_lshl_add_u32 v147, v147, 2, v113
	ds_read_b32 v169, v147
	v_mad_u32_u24 v95, v95, s20, v102
	v_lshl_add_u32 v95, v95, 2, v135
	ds_read_b32 v171, v95
	s_waitcnt lgkmcnt(1)
	v_lshlrev_b32_e32 v168, 16, v169
	v_and_b32_e32 v169, 0xffff0000, v169
	v_pk_add_f32 v[172:173], v[168:169], 1.0 op_sel_hi:[1,0] neg_lo:[1,0] neg_hi:[1,0]
	s_waitcnt lgkmcnt(0)
	v_lshlrev_b32_e32 v170, 16, v171
	v_pk_mul_f32 v[84:85], v[84:85], v[172:173]
	v_and_b32_e32 v171, 0xffff0000, v171
	v_max_f32_e32 v172, 0xda24260, v84
	v_max_f32_e32 v173, 0xda24260, v85
	v_rcp_f32_e32 v172, v172
	v_rcp_f32_e32 v173, v173
	s_nop 0
	v_pk_mul_f32 v[168:169], v[172:173], v[168:169]
	s_nop 0
	v_cvt_pk_bf16_f32 v168, v168, v169
	ds_write_b32 v147, v168
	v_pk_mul_f32 v[168:169], v[84:85], v[170:171]
	s_nop 0
	v_cvt_pk_bf16_f32 v147, v168, v169
	ds_write_b32 v95, v147
	v_mul_u32_u24_e32 v95, 0x44, v94
	v_lshl_add_u32 v172, v95, 2, v113
	ds_read_b32 v95, v172
	v_mad_u32_u24 v147, v94, s20, v102
	v_lshl_add_u32 v147, v147, 2, v135
	ds_read_b32 v169, v147
	s_waitcnt lgkmcnt(1)
	v_lshlrev_b32_e32 v94, 16, v95
	v_and_b32_e32 v95, 0xffff0000, v95
	v_pk_add_f32 v[170:171], v[94:95], 1.0 op_sel_hi:[1,0] neg_lo:[1,0] neg_hi:[1,0]
	s_waitcnt lgkmcnt(0)
	v_lshlrev_b32_e32 v168, 16, v169
	v_pk_mul_f32 v[84:85], v[84:85], v[170:171]
	v_and_b32_e32 v169, 0xffff0000, v169
	v_max_f32_e32 v170, 0xda24260, v84
	v_max_f32_e32 v171, 0xda24260, v85
	v_rcp_f32_e32 v170, v170
	v_rcp_f32_e32 v171, v171
	s_nop 0
	v_pk_mul_f32 v[94:95], v[170:171], v[94:95]
	s_nop 0
	v_cvt_pk_bf16_f32 v94, v94, v95
	ds_write_b32 v172, v94
	v_pk_mul_f32 v[94:95], v[84:85], v[168:169]
	s_nop 0
	v_cvt_pk_bf16_f32 v94, v94, v95
	ds_write_b32 v147, v94
	global_load_dwordx4 v[6:9], v237, s[100:101] nt
	v_mul_u32_u24_e32 v94, 0x44, v93
	v_lshl_add_u32 v147, v94, 2, v113
	ds_read_b32 v95, v147
	v_mad_u32_u24 v93, v93, s20, v102
	v_lshl_add_u32 v93, v93, 2, v135
	ds_read_b32 v169, v93
	s_waitcnt lgkmcnt(1)
	v_lshlrev_b32_e32 v94, 16, v95
	v_and_b32_e32 v95, 0xffff0000, v95
	v_pk_add_f32 v[170:171], v[94:95], 1.0 op_sel_hi:[1,0] neg_lo:[1,0] neg_hi:[1,0]
	s_waitcnt lgkmcnt(0)
	v_lshlrev_b32_e32 v168, 16, v169
	v_pk_mul_f32 v[84:85], v[84:85], v[170:171]
	v_and_b32_e32 v169, 0xffff0000, v169
	v_max_f32_e32 v170, 0xda24260, v84
	v_max_f32_e32 v171, 0xda24260, v85
	v_rcp_f32_e32 v170, v170
	v_rcp_f32_e32 v171, v171
	s_nop 0
	v_pk_mul_f32 v[94:95], v[170:171], v[94:95]
	s_nop 0
	v_cvt_pk_bf16_f32 v94, v94, v95
	ds_write_b32 v147, v94
	v_pk_mul_f32 v[94:95], v[84:85], v[168:169]
	s_nop 0
	v_cvt_pk_bf16_f32 v94, v94, v95
	ds_write_b32 v93, v94
	v_mul_u32_u24_e32 v93, 0x44, v92
	v_lshl_add_u32 v147, v93, 2, v113
	ds_read_b32 v93, v147
	v_mad_u32_u24 v94, v92, s20, v102
	v_lshl_add_u32 v170, v94, 2, v135
	ds_read_b32 v95, v170
	s_waitcnt lgkmcnt(1)
	v_lshlrev_b32_e32 v92, 16, v93
	v_and_b32_e32 v93, 0xffff0000, v93
	v_pk_add_f32 v[168:169], v[92:93], 1.0 op_sel_hi:[1,0] neg_lo:[1,0] neg_hi:[1,0]
	s_waitcnt lgkmcnt(0)
	v_lshlrev_b32_e32 v94, 16, v95
	v_pk_mul_f32 v[84:85], v[84:85], v[168:169]
	v_and_b32_e32 v95, 0xffff0000, v95
	v_max_f32_e32 v168, 0xda24260, v84
	v_max_f32_e32 v169, 0xda24260, v85
	v_rcp_f32_e32 v168, v168
	v_rcp_f32_e32 v169, v169
	s_nop 0
	v_pk_mul_f32 v[92:93], v[168:169], v[92:93]
	s_nop 0
	v_cvt_pk_bf16_f32 v92, v92, v93
	ds_write_b32 v147, v92
	v_pk_mul_f32 v[92:93], v[84:85], v[94:95]
	s_nop 0
	v_cvt_pk_bf16_f32 v92, v92, v93
	ds_write_b32 v170, v92
	global_load_dwordx4 v[18:21], v238, s[100:101] nt
	v_mul_u32_u24_e32 v92, 0x44, v91
	v_lshl_add_u32 v147, v92, 2, v113
	ds_read_b32 v93, v147
	v_mad_u32_u24 v91, v91, s20, v102
	v_lshl_add_u32 v91, v91, 2, v135
	ds_read_b32 v95, v91
	s_waitcnt lgkmcnt(1)
	v_lshlrev_b32_e32 v92, 16, v93
	v_and_b32_e32 v93, 0xffff0000, v93
	v_pk_add_f32 v[168:169], v[92:93], 1.0 op_sel_hi:[1,0] neg_lo:[1,0] neg_hi:[1,0]
	s_waitcnt lgkmcnt(0)
	v_lshlrev_b32_e32 v94, 16, v95
	v_pk_mul_f32 v[84:85], v[84:85], v[168:169]
	v_and_b32_e32 v95, 0xffff0000, v95
	v_max_f32_e32 v168, 0xda24260, v84
	v_max_f32_e32 v169, 0xda24260, v85
	v_rcp_f32_e32 v168, v168
	v_rcp_f32_e32 v169, v169
	s_nop 0
	v_pk_mul_f32 v[92:93], v[168:169], v[92:93]
	s_nop 0
	v_cvt_pk_bf16_f32 v92, v92, v93
	ds_write_b32 v147, v92
	v_pk_mul_f32 v[92:93], v[84:85], v[94:95]
	s_nop 0
	v_cvt_pk_bf16_f32 v92, v92, v93
	ds_write_b32 v91, v92
	v_mul_u32_u24_e32 v91, 0x44, v90
	v_lshl_add_u32 v147, v91, 2, v113
	ds_read_b32 v91, v147
	v_mad_u32_u24 v92, v90, s20, v102
	v_lshl_add_u32 v168, v92, 2, v135
	ds_read_b32 v93, v168
	s_waitcnt lgkmcnt(1)
	v_lshlrev_b32_e32 v90, 16, v91
	v_and_b32_e32 v91, 0xffff0000, v91
	v_pk_add_f32 v[94:95], v[90:91], 1.0 op_sel_hi:[1,0] neg_lo:[1,0] neg_hi:[1,0]
	s_waitcnt lgkmcnt(0)
	v_lshlrev_b32_e32 v92, 16, v93
	v_pk_mul_f32 v[84:85], v[84:85], v[94:95]
	v_and_b32_e32 v93, 0xffff0000, v93
	v_max_f32_e32 v94, 0xda24260, v84
	v_max_f32_e32 v95, 0xda24260, v85
	v_rcp_f32_e32 v94, v94
	v_rcp_f32_e32 v95, v95
	s_nop 0
	v_pk_mul_f32 v[90:91], v[94:95], v[90:91]
	s_nop 0
	v_cvt_pk_bf16_f32 v90, v90, v91
	ds_write_b32 v147, v90
	v_pk_mul_f32 v[90:91], v[84:85], v[92:93]
	s_nop 0
	v_cvt_pk_bf16_f32 v90, v90, v91
	ds_write_b32 v168, v90
	global_load_dwordx4 v[22:25], v239, s[100:101] nt
	v_mul_u32_u24_e32 v90, 0x44, v89
	v_lshl_add_u32 v147, v90, 2, v113
	ds_read_b32 v91, v147
	v_mad_u32_u24 v89, v89, s20, v102
	v_lshl_add_u32 v89, v89, 2, v135
	ds_read_b32 v93, v89
	s_waitcnt lgkmcnt(1)
	v_lshlrev_b32_e32 v90, 16, v91
	v_and_b32_e32 v91, 0xffff0000, v91
	v_pk_add_f32 v[94:95], v[90:91], 1.0 op_sel_hi:[1,0] neg_lo:[1,0] neg_hi:[1,0]
	s_waitcnt lgkmcnt(0)
	v_lshlrev_b32_e32 v92, 16, v93
	v_pk_mul_f32 v[84:85], v[84:85], v[94:95]
	v_and_b32_e32 v93, 0xffff0000, v93
	v_max_f32_e32 v94, 0xda24260, v84
	v_max_f32_e32 v95, 0xda24260, v85
	v_rcp_f32_e32 v94, v94
	v_rcp_f32_e32 v95, v95
	s_nop 0
	v_pk_mul_f32 v[90:91], v[94:95], v[90:91]
	s_nop 0
	v_cvt_pk_bf16_f32 v90, v90, v91
	ds_write_b32 v147, v90
	v_pk_mul_f32 v[90:91], v[84:85], v[92:93]
	v_add_u32_e32 v147, v137, v71
	v_cvt_pk_bf16_f32 v90, v90, v91
	ds_write_b32 v89, v90
	v_mul_u32_u24_e32 v89, 0x44, v88
	v_lshl_add_u32 v94, v89, 2, v113
	ds_read_b32 v89, v94
	v_mad_u32_u24 v90, v88, s20, v102
	v_lshl_add_u32 v95, v90, 2, v135
	ds_read_b32 v91, v95
	s_waitcnt lgkmcnt(1)
	v_lshlrev_b32_e32 v88, 16, v89
	v_and_b32_e32 v89, 0xffff0000, v89
	v_pk_add_f32 v[92:93], v[88:89], 1.0 op_sel_hi:[1,0] neg_lo:[1,0] neg_hi:[1,0]
	s_waitcnt lgkmcnt(0)
	v_lshlrev_b32_e32 v90, 16, v91
	v_pk_mul_f32 v[84:85], v[84:85], v[92:93]
	v_and_b32_e32 v91, 0xffff0000, v91
	v_max_f32_e32 v92, 0xda24260, v84
	v_max_f32_e32 v93, 0xda24260, v85
	v_rcp_f32_e32 v92, v92
	v_rcp_f32_e32 v93, v93
	s_nop 0
	v_pk_mul_f32 v[88:89], v[92:93], v[88:89]
	s_nop 0
	v_cvt_pk_bf16_f32 v88, v88, v89
	ds_write_b32 v94, v88
	v_pk_mul_f32 v[88:89], v[84:85], v[90:91]
	s_nop 0
	v_cvt_pk_bf16_f32 v88, v88, v89
	ds_write_b32 v95, v88
	global_load_dwordx4 v[10:13], v240, s[100:101] nt
	v_mul_u32_u24_e32 v88, 0x44, v87
	v_lshl_add_u32 v94, v88, 2, v113
	ds_read_b32 v89, v94
	v_mad_u32_u24 v87, v87, s20, v102
	v_lshl_add_u32 v87, v87, 2, v135
	ds_read_b32 v91, v87
	s_waitcnt lgkmcnt(1)
	v_lshlrev_b32_e32 v88, 16, v89
	v_and_b32_e32 v89, 0xffff0000, v89
	v_pk_add_f32 v[92:93], v[88:89], 1.0 op_sel_hi:[1,0] neg_lo:[1,0] neg_hi:[1,0]
	s_waitcnt lgkmcnt(0)
	v_lshlrev_b32_e32 v90, 16, v91
	v_pk_mul_f32 v[84:85], v[84:85], v[92:93]
	v_and_b32_e32 v91, 0xffff0000, v91
	v_max_f32_e32 v92, 0xda24260, v84
	v_max_f32_e32 v93, 0xda24260, v85
	v_rcp_f32_e32 v92, v92
	v_rcp_f32_e32 v93, v93
	s_nop 0
	v_pk_mul_f32 v[88:89], v[92:93], v[88:89]
	s_nop 0
	v_cvt_pk_bf16_f32 v88, v88, v89
	ds_write_b32 v94, v88
	v_pk_mul_f32 v[88:89], v[84:85], v[90:91]
	s_nop 0
	v_cvt_pk_bf16_f32 v88, v88, v89
	ds_write_b32 v87, v88
	v_mul_u32_u24_e32 v87, 0x44, v86
	v_lshl_add_u32 v92, v87, 2, v113
	ds_read_b32 v87, v92
	v_mad_u32_u24 v88, v86, s20, v102
	v_lshl_add_u32 v93, v88, 2, v135
	ds_read_b32 v89, v93
	s_waitcnt lgkmcnt(1)
	v_lshlrev_b32_e32 v86, 16, v87
	v_and_b32_e32 v87, 0xffff0000, v87
	v_pk_add_f32 v[90:91], v[86:87], 1.0 op_sel_hi:[1,0] neg_lo:[1,0] neg_hi:[1,0]
	s_waitcnt lgkmcnt(0)
	v_lshlrev_b32_e32 v88, 16, v89
	v_pk_mul_f32 v[84:85], v[84:85], v[90:91]
	v_and_b32_e32 v89, 0xffff0000, v89
	v_max_f32_e32 v90, 0xda24260, v84
	v_max_f32_e32 v91, 0xda24260, v85
	v_rcp_f32_e32 v90, v90
	v_rcp_f32_e32 v91, v91
	v_pk_mul_f32 v[84:85], v[84:85], v[88:89]
	v_pk_mul_f32 v[86:87], v[90:91], v[86:87]
	s_nop 0
	v_cvt_pk_bf16_f32 v86, v86, v87
	v_cvt_pk_bf16_f32 v84, v84, v85
	ds_write_b32 v92, v86
	ds_write_b32 v93, v84
	global_load_dwordx4 v[14:17], v241, s[100:101] nt
	s_waitcnt lgkmcnt(0)
	s_barrier
	ds_read_b128 v[246:249], v136
	ds_read_b128 v[172:175], v147
	ds_read_b128 v[198:201], v147 offset:4352
	ds_read_b128 v[202:205], v147 offset:8704
	s_waitcnt lgkmcnt(2)
	v_mfma_f32_16x16x32_bf16 v[88:91], v[246:249], v[172:175], 0
	ds_read_b128 v[172:175], v176
	s_waitcnt lgkmcnt(2)
	v_mfma_f32_16x16x32_bf16 v[92:95], v[246:249], v[198:201], 0
	ds_read_b128 v[250:253], v136 offset:64
	ds_read_b128 v[198:201], v147 offset:64
	s_waitcnt lgkmcnt(3)
	v_mfma_f32_16x16x32_bf16 v[168:171], v[246:249], v[202:205], 0
	ds_read_b128 v[202:205], v147 offset:4416
	s_waitcnt lgkmcnt(3)
	v_mfma_f32_16x16x32_bf16 v[84:87], v[246:249], v[172:175], 0
	ds_read_b128 v[172:175], v147 offset:8768
	s_waitcnt lgkmcnt(2)
	v_mfma_f32_16x16x32_bf16 v[88:91], v[250:253], v[198:201], v[88:91]
	ds_read_b128 v[198:201], v176 offset:64
	global_load_dwordx4 v[26:29], v242, s[100:101] nt
	s_waitcnt lgkmcnt(2)
	v_mfma_f32_16x16x32_bf16 v[92:95], v[250:253], v[202:205], v[92:95]
	ds_read_b128 v[246:249], v136 offset:128
	ds_read_b128 v[202:205], v147 offset:128
	s_waitcnt lgkmcnt(3)
	v_mfma_f32_16x16x32_bf16 v[168:171], v[250:253], v[172:175], v[168:171]
	ds_read_b128 v[172:175], v147 offset:4480
	s_waitcnt lgkmcnt(3)
	v_mfma_f32_16x16x32_bf16 v[84:87], v[250:253], v[198:201], v[84:87]
	ds_read_b128 v[198:201], v147 offset:8832
	s_waitcnt lgkmcnt(2)
	v_mfma_f32_16x16x32_bf16 v[88:91], v[246:249], v[202:205], v[88:91]
	ds_read_b128 v[202:205], v176 offset:128
	s_waitcnt lgkmcnt(2)
	v_mfma_f32_16x16x32_bf16 v[92:95], v[246:249], v[172:175], v[92:95]
	ds_read_b128 v[250:253], v136 offset:192
	ds_read_b128 v[172:175], v147 offset:192
	s_waitcnt lgkmcnt(3)
	v_mfma_f32_16x16x32_bf16 v[168:171], v[246:249], v[198:201], v[168:171]
	ds_read_b128 v[198:201], v147 offset:4544
	s_waitcnt lgkmcnt(3)
	v_mfma_f32_16x16x32_bf16 v[84:87], v[246:249], v[202:205], v[84:87]
	ds_read_b128 v[202:205], v147 offset:8896
	s_waitcnt lgkmcnt(2)
	v_mfma_f32_16x16x32_bf16 v[88:91], v[250:253], v[172:175], v[88:91]
	ds_read_b128 v[172:175], v176 offset:192
	s_waitcnt lgkmcnt(2)
	v_mfma_f32_16x16x32_bf16 v[92:95], v[250:253], v[198:201], v[92:95]
	s_waitcnt lgkmcnt(1)
	v_mfma_f32_16x16x32_bf16 v[168:171], v[250:253], v[202:205], v[168:171]
	s_waitcnt lgkmcnt(0)
	v_mfma_f32_16x16x32_bf16 v[84:87], v[250:253], v[172:175], v[84:87]
	s_nop 7
	v_cvt_pk_bf16_f32 v88, v88, s0
	v_cvt_pk_bf16_f32 v89, v89, s0
	v_cvt_pk_bf16_f32 v90, v90, s0
	v_cvt_pk_bf16_f32 v91, v91, s0
	v_cndmask_b32_e64 v88, 0, v88, s[42:43]
	v_cndmask_b32_e64 v89, 0, v89, s[44:45]
	v_cndmask_b32_e64 v90, 0, v90, s[46:47]
	v_cndmask_b32_e64 v91, 0, v91, s[48:49]
	v_perm_b32 v88, v89, v88, s21
	v_perm_b32 v89, v91, v90, s21
	v_add_u32_e32 v90, v138, v75
	global_load_dwordx4 v[30:33], v243, s[100:101] nt
	ds_write_b64 v90, v[88:89]
	v_cvt_pk_bf16_f32 v88, v92, s0
	v_cvt_pk_bf16_f32 v89, v93, s0
	v_cvt_pk_bf16_f32 v91, v94, s0
	v_cvt_pk_bf16_f32 v92, v95, s0
	v_cndmask_b32_e64 v88, 0, v88, s[50:51]
	v_cndmask_b32_e64 v89, 0, v89, s[52:53]
	v_cndmask_b32_e64 v91, 0, v91, s[54:55]
	v_cndmask_b32_e64 v92, 0, v92, s[56:57]
	v_perm_b32 v88, v89, v88, s21
	v_perm_b32 v89, v92, v91, s21
	ds_write_b64 v90, v[88:89] offset:2304
	v_cvt_pk_bf16_f32 v88, v168, s0
	v_cvt_pk_bf16_f32 v89, v169, s0
	v_cvt_pk_bf16_f32 v91, v170, s0
	v_cvt_pk_bf16_f32 v92, v171, s0
	v_cvt_pk_bf16_f32 v84, v84, s0
	v_cvt_pk_bf16_f32 v85, v85, s0
	v_cvt_pk_bf16_f32 v86, v86, s0
	v_cvt_pk_bf16_f32 v87, v87, s0
	v_cndmask_b32_e64 v88, 0, v88, s[58:59]
	v_cndmask_b32_e64 v89, 0, v89, s[60:61]
	v_cndmask_b32_e64 v91, 0, v91, s[62:63]
	v_cndmask_b32_e64 v92, 0, v92, s[64:65]
	v_cndmask_b32_e64 v84, 0, v84, s[66:67]
	v_cndmask_b32_e64 v85, 0, v85, s[68:69]
	v_cndmask_b32_e64 v86, 0, v86, s[70:71]
	v_cndmask_b32_e64 v87, 0, v87, s[72:73]
	v_perm_b32 v88, v89, v88, s21
	v_perm_b32 v89, v92, v91, s21
	v_perm_b32 v84, v85, v84, s21
	v_perm_b32 v85, v87, v86, s21
	v_add_u32_e32 v86, v138, v96
	ds_write_b64 v90, v[88:89] offset:4608
	ds_write_b64 v86, v[84:85]
	s_waitcnt lgkmcnt(0)
	s_barrier
	ds_read_b64_tr_b16 v[84:85], v164
	ds_read_b64_tr_b16 v[86:87], v164 offset:1088
	ds_read_b128 v[88:91], v139
	ds_read_b128 v[92:95], v140
	s_waitcnt lgkmcnt(1)
	v_mfma_f32_16x16x32_bf16 v[88:91], v[88:91], v[84:87], 0
	v_add_u32_e32 v147, v106, v71
	v_add_u32_e32 v176, v106, v73
	s_waitcnt lgkmcnt(0)
	v_mfma_f32_16x16x32_bf16 v[88:91], v[92:95], v[84:87], v[88:91]
	ds_read_b128 v[92:95], v141
	ds_read_b128 v[168:171], v142
	s_waitcnt lgkmcnt(1)
	v_mfma_f32_16x16x32_bf16 v[92:95], v[92:95], v[84:87], 0
	s_waitcnt lgkmcnt(0)
	v_mfma_f32_16x16x32_bf16 v[92:95], v[168:171], v[84:87], v[92:95]
	ds_read_b128 v[168:171], v143
	ds_read_b128 v[172:175], v144
	s_waitcnt lgkmcnt(1)
	v_mfma_f32_16x16x32_bf16 v[168:171], v[168:171], v[84:87], 0
	s_waitcnt lgkmcnt(0)
	v_mfma_f32_16x16x32_bf16 v[168:171], v[172:175], v[84:87], v[168:171]
	ds_read_b128 v[172:175], v145
	ds_read_b128 v[198:201], v152
	s_waitcnt lgkmcnt(1)
	v_mfma_f32_16x16x32_bf16 v[172:175], v[172:175], v[84:87], 0
	s_waitcnt lgkmcnt(0)
	v_mfma_f32_16x16x32_bf16 v[84:87], v[198:201], v[84:87], v[172:175]
	s_nop 5
	ds_read_b64_tr_b16 v[172:173], v165
	ds_read_b64_tr_b16 v[174:175], v165 offset:1088
	ds_read_b128 v[198:201], v153
	ds_read_b128 v[202:205], v154
	s_waitcnt lgkmcnt(1)
	v_mfma_f32_16x16x32_bf16 v[88:91], v[198:201], v[172:175], v[88:91]
	s_waitcnt lgkmcnt(0)
	v_mfma_f32_16x16x32_bf16 v[88:91], v[202:205], v[172:175], v[88:91]
	ds_read_b128 v[198:201], v155
	ds_read_b128 v[202:205], v156
	s_waitcnt lgkmcnt(1)
	v_mfma_f32_16x16x32_bf16 v[92:95], v[198:201], v[172:175], v[92:95]
	s_waitcnt lgkmcnt(0)
	v_mfma_f32_16x16x32_bf16 v[92:95], v[202:205], v[172:175], v[92:95]
	ds_read_b128 v[198:201], v157
	ds_read_b128 v[202:205], v158
	s_waitcnt lgkmcnt(1)
	v_mfma_f32_16x16x32_bf16 v[168:171], v[198:201], v[172:175], v[168:171]
	s_waitcnt lgkmcnt(0)
	v_mfma_f32_16x16x32_bf16 v[168:171], v[202:205], v[172:175], v[168:171]
	ds_read_b128 v[198:201], v159
	ds_read_b128 v[202:205], v160
	s_waitcnt lgkmcnt(1)
	v_mfma_f32_16x16x32_bf16 v[84:87], v[198:201], v[172:175], v[84:87]
	s_waitcnt lgkmcnt(0)
	v_mfma_f32_16x16x32_bf16 v[84:87], v[202:205], v[172:175], v[84:87]
	ds_read_b128 v[172:175], v147
	ds_read_b128 v[198:201], v147 offset:4352
	ds_read_b128 v[202:205], v147 offset:8704
	ds_read_b128 v[246:249], v176
	s_lshl_b32 s80, s14, 8
	ds_read_b128 v[250:253], v147 offset:64
	s_waitcnt vmcnt(15) lgkmcnt(4)
	v_mfma_f32_16x16x32_bf16 v[88:91], v[172:175], v[62:65], v[88:91]
	ds_read_b128 v[172:175], v147 offset:4416
	s_waitcnt lgkmcnt(4)
	v_mfma_f32_16x16x32_bf16 v[92:95], v[198:201], v[62:65], v[92:95]
	ds_read_b128 v[198:201], v147 offset:8768
	s_waitcnt lgkmcnt(4)
	v_mfma_f32_16x16x32_bf16 v[168:171], v[202:205], v[62:65], v[168:171]
	ds_read_b128 v[202:205], v176 offset:64
	s_waitcnt lgkmcnt(4)
	v_mfma_f32_16x16x32_bf16 v[84:87], v[246:249], v[62:65], v[84:87]
	ds_read_b128 v[246:249], v147 offset:128
	s_waitcnt vmcnt(14) lgkmcnt(4)
	v_mfma_f32_16x16x32_bf16 v[88:91], v[250:253], v[58:61], v[88:91]
	ds_read_b128 v[250:253], v147 offset:4480
	s_waitcnt lgkmcnt(4)
	v_mfma_f32_16x16x32_bf16 v[92:95], v[172:175], v[58:61], v[92:95]
	ds_read_b128 v[172:175], v147 offset:8832
	s_waitcnt lgkmcnt(4)
	v_mfma_f32_16x16x32_bf16 v[168:171], v[198:201], v[58:61], v[168:171]
	ds_read_b128 v[198:201], v176 offset:128
	s_waitcnt lgkmcnt(4)
	v_mfma_f32_16x16x32_bf16 v[84:87], v[202:205], v[58:61], v[84:87]
	ds_read_b128 v[202:205], v147 offset:192
	s_waitcnt vmcnt(13) lgkmcnt(4)
	v_mfma_f32_16x16x32_bf16 v[88:91], v[246:249], v[54:57], v[88:91]
	ds_read_b128 v[246:249], v147 offset:4544
	s_waitcnt lgkmcnt(4)
	v_mfma_f32_16x16x32_bf16 v[92:95], v[250:253], v[54:57], v[92:95]
	ds_read_b128 v[250:253], v147 offset:8896
	s_waitcnt lgkmcnt(4)
	v_mfma_f32_16x16x32_bf16 v[168:171], v[172:175], v[54:57], v[168:171]
	ds_read_b128 v[172:175], v176 offset:192
	s_waitcnt lgkmcnt(4)
	v_mfma_f32_16x16x32_bf16 v[84:87], v[198:201], v[54:57], v[84:87]
	ds_read_b128 v[198:201], v147 offset:17408
	s_waitcnt vmcnt(12) lgkmcnt(4)
	v_mfma_f32_16x16x32_bf16 v[88:91], v[202:205], v[50:53], v[88:91]
	ds_read_b128 v[202:205], v147 offset:21760
	s_waitcnt lgkmcnt(4)
	v_mfma_f32_16x16x32_bf16 v[92:95], v[246:249], v[50:53], v[92:95]
	ds_read_b128 v[246:249], v147 offset:26112
	s_waitcnt lgkmcnt(4)
	v_mfma_f32_16x16x32_bf16 v[168:171], v[250:253], v[50:53], v[168:171]
	ds_read_b128 v[250:253], v176 offset:17408
	s_waitcnt lgkmcnt(4)
	v_mfma_f32_16x16x32_bf16 v[84:87], v[172:175], v[50:53], v[84:87]
	ds_read_b128 v[172:175], v147 offset:17472
	s_waitcnt vmcnt(11) lgkmcnt(4)
	v_mfma_f32_16x16x32_bf16 v[88:91], v[198:201], v[46:49], v[88:91]
	ds_read_b128 v[198:201], v147 offset:21824
	s_waitcnt lgkmcnt(4)
	v_mfma_f32_16x16x32_bf16 v[92:95], v[202:205], v[46:49], v[92:95]
	ds_read_b128 v[202:205], v147 offset:26176
	s_waitcnt lgkmcnt(4)
	v_mfma_f32_16x16x32_bf16 v[168:171], v[246:249], v[46:49], v[168:171]
	ds_read_b128 v[246:249], v176 offset:17472
	s_waitcnt lgkmcnt(4)
	v_mfma_f32_16x16x32_bf16 v[84:87], v[250:253], v[46:49], v[84:87]
	ds_read_b128 v[250:253], v147 offset:17536
	s_waitcnt vmcnt(10) lgkmcnt(4)
	v_mfma_f32_16x16x32_bf16 v[88:91], v[172:175], v[42:45], v[88:91]
	ds_read_b128 v[172:175], v147 offset:21888
	s_waitcnt lgkmcnt(4)
	v_mfma_f32_16x16x32_bf16 v[92:95], v[198:201], v[42:45], v[92:95]
	ds_read_b128 v[198:201], v147 offset:26240
	s_waitcnt lgkmcnt(4)
	v_mfma_f32_16x16x32_bf16 v[168:171], v[202:205], v[42:45], v[168:171]
	ds_read_b128 v[202:205], v176 offset:17536
	s_waitcnt lgkmcnt(4)
	v_mfma_f32_16x16x32_bf16 v[84:87], v[246:249], v[42:45], v[84:87]
	ds_read_b128 v[246:249], v147 offset:17600
	s_waitcnt vmcnt(9) lgkmcnt(4)
	v_mfma_f32_16x16x32_bf16 v[88:91], v[250:253], v[38:41], v[88:91]
	ds_read_b128 v[250:253], v147 offset:21952
	s_waitcnt lgkmcnt(4)
	v_mfma_f32_16x16x32_bf16 v[92:95], v[172:175], v[38:41], v[92:95]
	ds_read_b128 v[172:175], v147 offset:26304
	s_waitcnt lgkmcnt(4)
	v_mfma_f32_16x16x32_bf16 v[168:171], v[198:201], v[38:41], v[168:171]
	ds_read_b128 v[198:201], v176 offset:17600
	s_waitcnt lgkmcnt(4)
	v_mfma_f32_16x16x32_bf16 v[84:87], v[202:205], v[38:41], v[84:87]
	v_lshl_add_u64 v[58:59], vcc, 0, v[76:77]
	s_waitcnt vmcnt(8) lgkmcnt(3)
	v_mfma_f32_16x16x32_bf16 v[42:45], v[246:249], v[34:37], v[88:91]
	s_waitcnt lgkmcnt(2)
	v_mfma_f32_16x16x32_bf16 v[46:49], v[250:253], v[34:37], v[92:95]
	s_waitcnt lgkmcnt(1)
	v_mfma_f32_16x16x32_bf16 v[50:53], v[172:175], v[34:37], v[168:171]
	s_waitcnt lgkmcnt(0)
	v_mfma_f32_16x16x32_bf16 v[38:41], v[198:201], v[34:37], v[84:87]
	v_lshlrev_b64 v[34:35], 8, v[58:59]
	v_lshl_add_u64 v[34:35], s[16:17], 0, v[34:35]
	v_lshl_add_u64 v[34:35], v[34:35], 0, v[0:1]
	s_mov_b64 s[16:17], 0x10000000
	v_lshl_add_u64 v[36:37], v[34:35], 0, s[16:17]
	v_add_co_u32_e32 v34, vcc, s15, v34
	v_lshlrev_b64 v[58:59], 11, v[58:59]
	s_nop 0
	v_addc_co_u32_e32 v35, vcc, 0, v35, vcc
	global_load_dwordx4 v[54:57], v[34:35], off nt
	s_nop 0
	global_load_dwordx4 v[34:37], v[36:37], off offset:16 nt
	s_barrier
	ds_write2_b32 v166, v42, v43 offset1:132
	v_add_u32_e32 v42, 0x400, v166
	ds_write2_b32 v42, v44, v45 offset0:8 offset1:140
	v_add_u32_e32 v42, 0x2000, v166
	ds_write2_b32 v42, v46, v47 offset0:64 offset1:196
	v_add_u32_e32 v42, 0x2400, v166
	ds_write2_b32 v42, v48, v49 offset0:72 offset1:204
	v_add_u32_e32 v42, 0x4200, v166
	ds_write2_b32 v42, v50, v51 offset1:132
	v_add_u32_e32 v42, 0x4600, v166
	ds_write2_b32 v42, v52, v53 offset0:8 offset1:140
	v_add_u32_e32 v42, 0x6200, v166
	ds_write2_b32 v42, v38, v39 offset0:64 offset1:196
	v_add_u32_e32 v38, 0x6600, v166
	ds_write2_b32 v38, v40, v41 offset0:72 offset1:204
	s_waitcnt lgkmcnt(0)
	s_barrier
	ds_read_b128 v[50:53], v162
	ds_read_b128 v[46:49], v162 offset:16
	ds_read_b128 v[42:45], v162 offset:32
	ds_read_b128 v[38:41], v162 offset:48
	v_lshl_add_u64 v[58:59], s[74:75], 0, v[58:59]
	s_waitcnt lgkmcnt(3)
	v_pk_mul_f32 v[60:61], v[52:53], v[52:53]
	v_pk_mul_f32 v[62:63], v[50:51], v[50:51]
	v_lshl_add_u64 v[58:59], v[58:59], 0, s[80:81]
	v_pk_mov_b32 v[64:65], v[62:63], v[60:61] op_sel:[1,0]
	v_mov_b32_e32 v63, v61
	v_pk_add_f32 v[60:61], v[64:65], v[62:63]
	s_waitcnt lgkmcnt(2)
	v_pk_mul_f32 v[62:63], v[48:49], v[48:49]
	v_pk_mul_f32 v[64:65], v[46:47], v[46:47]
	v_pk_add_f32 v[60:61], v[60:61], v[60:61] op_sel:[0,1] op_sel_hi:[1,0]
	v_pk_mov_b32 v[84:85], v[64:65], v[62:63] op_sel:[1,0]
	v_mov_b32_e32 v65, v63
	v_pk_add_f32 v[62:63], v[84:85], v[64:65]
	s_waitcnt lgkmcnt(0)
	v_mul_f32_e32 v64, v38, v38
	v_mul_f32_e32 v65, v39, v39
	v_pk_add_f32 v[62:63], v[62:63], v[62:63] op_sel:[0,1] op_sel_hi:[1,0]
	v_mov_b32_e32 v61, v64
	v_mov_b32_e32 v63, v65
	v_pk_add_f32 v[60:61], v[60:61], v[62:63]
	v_mul_f32_e32 v62, v43, v43
	v_mul_f32_e32 v64, v45, v45
	v_mul_f32_e32 v84, v40, v40
	v_mul_f32_e32 v85, v41, v41
	v_pk_fma_f32 v[62:63], v[42:43], v[42:43], v[62:63] op_sel_hi:[1,1,0]
	v_pk_fma_f32 v[64:65], v[44:45], v[44:45], v[64:65] op_sel_hi:[1,1,0]
	v_mov_b32_e32 v63, v84
	v_mov_b32_e32 v65, v85
	v_pk_add_f32 v[62:63], v[62:63], v[64:65]
	v_lshl_add_u64 v[86:87], v[58:59], 0, v[0:1]
	v_pk_add_f32 v[60:61], v[60:61], v[62:63]
	s_waitcnt vmcnt(1)
	v_lshlrev_b32_e32 v92, 16, v54
	v_add_f32_e32 v60, v60, v61
	ds_bpermute_b32 v61, v97, v60
	v_and_b32_e32 v93, 0xffff0000, v54
	v_lshlrev_b32_e32 v94, 16, v55
	v_and_b32_e32 v95, 0xffff0000, v55
	v_lshlrev_b32_e32 v88, 16, v56
	s_waitcnt lgkmcnt(0)
	v_add_f32_e32 v60, v60, v61
	ds_bpermute_b32 v61, v98, v60
	v_and_b32_e32 v89, 0xffff0000, v56
	v_lshlrev_b32_e32 v90, 16, v57
	v_and_b32_e32 v91, 0xffff0000, v57
	s_waitcnt lgkmcnt(0)
	v_add_f32_e32 v60, v60, v61
	ds_bpermute_b32 v61, v163, v60
	s_waitcnt lgkmcnt(0)
	v_add_f32_e32 v60, v60, v61
	v_fmamk_f32 v60, v60, 0x3c000000, v178
	v_cmp_gt_f32_e32 vcc, s22, v60
	v_mul_f32_e32 v61, 0x4b800000, v60
	s_nop 0
	v_cndmask_b32_e32 v60, v60, v61, vcc
	v_rsq_f32_e32 v60, v60
	s_nop 0
	v_mul_f32_e32 v61, 0x45800000, v60
	v_cndmask_b32_e32 v84, v60, v61, vcc
	v_pk_mul_f32 v[52:53], v[52:53], v[84:85] op_sel_hi:[1,0]
	v_pk_mul_f32 v[50:51], v[50:51], v[84:85] op_sel_hi:[1,0]
	v_pk_mul_f32 v[48:49], v[48:49], v[84:85] op_sel_hi:[1,0]
	v_pk_mul_f32 v[46:47], v[46:47], v[84:85] op_sel_hi:[1,0]
	v_pk_mul_f32 v[44:45], v[44:45], v[84:85] op_sel_hi:[1,0]
	v_pk_mul_f32 v[42:43], v[42:43], v[84:85] op_sel_hi:[1,0]
	v_pk_mul_f32 v[40:41], v[40:41], v[84:85] op_sel_hi:[1,0]
	v_pk_mul_f32 v[38:39], v[38:39], v[84:85] op_sel_hi:[1,0]
	s_and_b64 vcc, exec, s[12:13]
	v_pk_mul_f32 v[38:39], v[232:233], v[38:39]
	v_pk_mul_f32 v[42:43], v[228:229], v[42:43]
	v_pk_mul_f32 v[46:47], v[224:225], v[46:47]
	v_pk_mul_f32 v[50:51], v[220:221], v[50:51]
	v_pk_mul_f32 v[52:53], v[222:223], v[52:53]
	v_pk_mul_f32 v[48:49], v[226:227], v[48:49]
	v_pk_mul_f32 v[52:53], v[52:53], v[94:95]
	v_pk_mul_f32 v[50:51], v[50:51], v[92:93]
	v_pk_mul_f32 v[62:63], v[48:49], v[90:91]
	v_pk_mul_f32 v[48:49], v[46:47], v[88:89]
	v_cvt_pk_bf16_f32 v46, v50, v51
	v_cvt_pk_bf16_f32 v47, v52, v53
	v_cvt_pk_bf16_f32 v48, v48, v49
	v_cvt_pk_bf16_f32 v49, v62, v63
	global_store_dwordx4 v[86:87], v[46:49], off offset:1024 sc1
	v_pk_mul_f32 v[44:45], v[230:231], v[44:45]
	v_pk_mul_f32 v[40:41], v[234:235], v[40:41]
	s_waitcnt vmcnt(1)
	v_lshlrev_b32_e32 v46, 16, v34
	v_and_b32_e32 v47, 0xffff0000, v34
	v_lshlrev_b32_e32 v34, 16, v35
	v_and_b32_e32 v35, 0xffff0000, v35
	v_lshlrev_b32_e32 v48, 16, v36
	v_and_b32_e32 v49, 0xffff0000, v36
	v_lshlrev_b32_e32 v36, 16, v37
	v_and_b32_e32 v37, 0xffff0000, v37
	v_pk_mul_f32 v[44:45], v[44:45], v[34:35]
	v_pk_mul_f32 v[34:35], v[42:43], v[46:47]
	v_pk_mul_f32 v[40:41], v[40:41], v[36:37]
	v_pk_mul_f32 v[36:37], v[38:39], v[48:49]
	v_cvt_pk_bf16_f32 v34, v34, v35
	v_cvt_pk_bf16_f32 v35, v44, v45
	v_cvt_pk_bf16_f32 v36, v36, v37
	v_cvt_pk_bf16_f32 v37, v40, v41
	global_store_dwordx4 v[86:87], v[34:37], off offset:1040 sc1
	s_barrier
	s_cbranch_vccnz .LBB0_455

.LBB0_456:
	ds_read_b128 v[26:29], v44 offset:55296
	v_add_u32_e32 v144, v42, v75
	ds_read_b128 v[30:33], v144
	ds_read_b128 v[124:127], v44 offset:55360
	ds_read_b128 v[34:37], v144 offset:64
	ds_read_b128 v[38:41], v144 offset:2304
	ds_read_b128 v[128:131], v144 offset:2368
	v_add_u32_e32 v145, v42, v96
	v_mul_f32_e32 v160, v123, v65
	v_exp_f32_e32 v160, v160
	s_ashr_i32 s14, s8, 3
	s_ashr_i32 s15, s14, 31
	s_waitcnt lgkmcnt(1)
	v_mfma_f32_16x16x32_bf16 v[132:135], v[26:29], v[38:41], 0
	ds_read_b128 v[38:41], v144 offset:4608
	ds_read_b128 v[136:139], v144 offset:4672
	s_lshl_b64 s[14:15], s[14:15], 7
	s_lshl_b32 s8, s9, 22
	s_waitcnt lgkmcnt(1)
	v_mfma_f32_16x16x32_bf16 v[140:143], v[26:29], v[38:41], 0
	ds_read_b128 v[38:41], v145
	ds_read_b128 v[152:155], v145 offset:64
	s_add_u32 s16, s86, s8
	s_addc_u32 s17, s87, 0
	s_waitcnt lgkmcnt(1)
	v_mfma_f32_16x16x32_bf16 v[156:159], v[26:29], v[38:41], 0
	ds_read_b128 v[38:41], v144 offset:9216
	ds_read_b128 v[162:165], v144 offset:9280
	s_mov_b32 s8, 0x6000000
	s_lshl_b32 s80, s9, 8
	s_waitcnt lgkmcnt(1)
	v_mfma_f32_16x16x32_bf16 v[166:169], v[26:29], v[38:41], 0
	ds_read_b128 v[38:41], v144 offset:11520
	ds_read_b128 v[170:173], v144 offset:11584
	s_waitcnt lgkmcnt(1)
	v_mfma_f32_16x16x32_bf16 v[174:177], v[26:29], v[38:41], 0
	ds_read_b128 v[38:41], v144 offset:13824
	ds_read_b128 v[198:201], v72
	ds_read_b128 v[202:205], v144 offset:13888
	v_add_co_u32_e32 v144, vcc, 0xffffe000, v50
	v_mfma_f32_16x16x32_bf16 v[30:33], v[26:29], v[30:33], 0
	s_nop 0
	v_addc_co_u32_e32 v145, vcc, -1, v51, vcc
	ds_read_b128 v[210:213], v72 offset:64
	v_mfma_f32_16x16x32_bf16 v[128:131], v[124:127], v[128:131], v[132:135]
	v_mfma_f32_16x16x32_bf16 v[132:135], v[124:127], v[136:139], v[140:143]
	v_mul_f32_e32 v136, v123, v60
	s_nop 5
	v_mul_f32_e32 v130, v160, v130
	v_mul_f32_e32 v140, v123, v61
	s_waitcnt lgkmcnt(3)
	v_mfma_f32_16x16x32_bf16 v[206:209], v[26:29], v[38:41], 0
	v_exp_f32_e32 v147, v140
	v_mul_f32_e32 v140, v123, v62
	s_waitcnt lgkmcnt(2)
	v_mfma_f32_16x16x32_bf16 v[198:201], v[26:29], v[198:201], 0
	v_mul_f32_e32 v26, v123, v59
	v_mfma_f32_16x16x32_bf16 v[216:219], v[124:127], v[34:37], v[30:33]
	global_load_dwordx4 v[38:41], v[144:145], off offset:-64 nt
	global_load_dwordx4 v[34:37], v[144:145], off nt
	v_exp_f32_e32 v144, v26
	v_exp_f32_e32 v145, v136
	v_mfma_f32_16x16x32_bf16 v[136:139], v[124:127], v[152:155], v[156:159]
	v_exp_f32_e32 v152, v140
	s_nop 1
	v_mul_f32_e32 v144, v144, v216
	v_mul_f32_e32 v145, v145, v217
	v_mul_f32_e32 v147, v147, v218
	v_mul_f32_e32 v156, v152, v219
	v_cvt_pk_bf16_f32 v144, v144, v145
	v_cvt_pk_bf16_f32 v145, v147, v156
	v_add_u32_e32 v147, v45, v71
	global_load_dwordx4 v[30:33], v[50:51], off offset:-64 nt
	global_load_dwordx4 v[26:29], v[50:51], off nt
	v_mfma_f32_16x16x32_bf16 v[140:143], v[124:127], v[162:165], v[166:169]
	ds_write_b64 v147, v[144:145]
	v_mul_f32_e32 v144, v123, v63
	v_mul_f32_e32 v145, v123, v64
	v_mul_f32_e32 v162, v123, v74
	v_exp_f32_e32 v144, v144
	v_exp_f32_e32 v145, v145
	v_exp_f32_e32 v162, v162
	v_mfma_f32_16x16x32_bf16 v[152:155], v[124:127], v[170:173], v[174:177]
	v_mul_f32_e32 v128, v144, v128
	v_mul_f32_e32 v129, v145, v129
	v_mul_f32_e32 v131, v162, v131
	v_cvt_pk_bf16_f32 v128, v128, v129
	v_cvt_pk_bf16_f32 v129, v130, v131
	ds_write_b64 v147, v[128:129] offset:4352
	v_mul_f32_e32 v128, v123, v76
	v_mul_f32_e32 v129, v123, v77
	v_mul_f32_e32 v130, v123, v78
	v_mul_f32_e32 v131, v123, v79
	v_exp_f32_e32 v128, v128
	v_exp_f32_e32 v129, v129
	v_exp_f32_e32 v130, v130
	v_exp_f32_e32 v131, v131
	v_mul_f32_e32 v128, v128, v132
	v_mul_f32_e32 v129, v129, v133
	v_mul_f32_e32 v130, v130, v134
	v_mul_f32_e32 v131, v131, v135
	v_cvt_pk_bf16_f32 v128, v128, v129
	v_cvt_pk_bf16_f32 v129, v130, v131
	ds_write_b64 v147, v[128:129] offset:8704
	v_mul_f32_e32 v128, v123, v80
	v_mul_f32_e32 v129, v123, v81
	v_mul_f32_e32 v130, v123, v82
	v_mul_f32_e32 v131, v123, v83
	v_exp_f32_e32 v128, v128
	v_exp_f32_e32 v129, v129
	v_exp_f32_e32 v130, v130
	v_exp_f32_e32 v131, v131
	v_mul_f32_e32 v128, v128, v136
	v_mul_f32_e32 v129, v129, v137
	v_mul_f32_e32 v130, v130, v138
	v_mul_f32_e32 v131, v131, v139
	v_cvt_pk_bf16_f32 v128, v128, v129
	v_cvt_pk_bf16_f32 v129, v130, v131
	v_add_u32_e32 v130, v45, v73
	ds_write_b64 v130, v[128:129]
	v_mul_f32_e32 v128, v123, v84
	v_mul_f32_e32 v129, v123, v85
	v_mul_f32_e32 v130, v123, v86
	v_mul_f32_e32 v131, v123, v87
	v_exp_f32_e32 v128, v128
	v_exp_f32_e32 v129, v129
	v_exp_f32_e32 v130, v130
	v_exp_f32_e32 v131, v131
	v_mul_f32_e32 v128, v128, v140
	v_mul_f32_e32 v129, v129, v141
	v_mul_f32_e32 v130, v130, v142
	v_mul_f32_e32 v131, v131, v143
	v_cvt_pk_bf16_f32 v128, v128, v129
	v_cvt_pk_bf16_f32 v129, v130, v131
	ds_write_b64 v147, v[128:129] offset:17408
	v_mul_f32_e32 v128, v123, v88
	v_mul_f32_e32 v129, v123, v89
	v_mul_f32_e32 v130, v123, v90
	v_mul_f32_e32 v131, v123, v91
	v_exp_f32_e32 v128, v128
	v_exp_f32_e32 v129, v129
	v_exp_f32_e32 v130, v130
	v_exp_f32_e32 v131, v131
	v_mul_f32_e32 v128, v128, v152
	v_mul_f32_e32 v129, v129, v153
	v_mul_f32_e32 v130, v130, v154
	v_mul_f32_e32 v131, v131, v155
	v_cvt_pk_bf16_f32 v128, v128, v129
	v_cvt_pk_bf16_f32 v129, v130, v131
	ds_write_b64 v147, v[128:129] offset:21760
	v_mul_f32_e32 v128, v123, v92
	v_mul_f32_e32 v129, v123, v93
	v_mul_f32_e32 v130, v123, v94
	v_mul_f32_e32 v131, v123, v95
	s_waitcnt lgkmcnt(7)
	v_mfma_f32_16x16x32_bf16 v[156:159], v[124:127], v[202:205], v[206:209]
	v_exp_f32_e32 v128, v128
	v_exp_f32_e32 v129, v129
	v_exp_f32_e32 v130, v130
	v_exp_f32_e32 v131, v131
	s_waitcnt lgkmcnt(6)
	v_mfma_f32_16x16x32_bf16 v[124:127], v[124:127], v[210:213], v[198:201]
	s_nop 1
	v_mul_f32_e32 v128, v128, v156
	v_mul_f32_e32 v129, v129, v157
	v_mul_f32_e32 v130, v130, v158
	v_mul_f32_e32 v131, v131, v159
	v_cvt_pk_bf16_f32 v128, v128, v129
	v_cvt_pk_bf16_f32 v129, v130, v131
	ds_write_b64 v147, v[128:129] offset:26112
	v_mul_f32_e32 v128, v123, v102
	v_mul_f32_e32 v129, v123, v103
	v_mul_f32_e32 v130, v123, v104
	v_mul_f32_e32 v123, v123, v105
	v_exp_f32_e32 v128, v128
	v_exp_f32_e32 v129, v129
	v_exp_f32_e32 v130, v130
	v_exp_f32_e32 v123, v123
	v_mul_f32_e32 v124, v128, v124
	v_mul_f32_e32 v125, v129, v125
	v_mul_f32_e32 v126, v130, v126
	v_mul_f32_e32 v123, v123, v127
	v_cvt_pk_bf16_f32 v124, v124, v125
	v_cvt_pk_bf16_f32 v125, v126, v123
	ds_write_b64 v99, v[124:125]
	s_waitcnt lgkmcnt(0)
	s_barrier
	ds_read_b128 v[124:127], v117
	ds_read_b64_tr_b16 v[128:129], v101
	ds_read_b64_tr_b16 v[130:131], v101 offset:576
	ds_read_b128 v[132:135], v117 offset:4352
	ds_read_b128 v[136:139], v117 offset:8704
	ds_read_b128 v[152:155], v107
	ds_read_b128 v[140:143], v117 offset:13056
	s_waitcnt lgkmcnt(4)
	v_mfma_f32_16x16x32_bf16 v[124:127], v[124:127], v[128:131], 0
	v_lshl_add_u64 v[144:145], s[14:15], 0, v[46:47]
	s_mov_b64 s[14:15], 0x6000000
	v_lshl_add_u64 v[50:51], v[50:51], 0, s[10:11]
	s_waitcnt lgkmcnt(3)
	v_mfma_f32_16x16x32_bf16 v[132:135], v[132:135], v[128:131], 0
	s_waitcnt lgkmcnt(2)
	v_mfma_f32_16x16x32_bf16 v[136:139], v[136:139], v[128:131], 0
	s_waitcnt lgkmcnt(0)
	v_mfma_f32_16x16x32_bf16 v[128:131], v[140:143], v[128:131], 0
	ds_read_b128 v[140:143], v109
	ds_read_b64_tr_b16 v[156:157], v119
	ds_read_b64_tr_b16 v[158:159], v119 offset:576
	ds_read_b64_tr_b16 v[162:163], v120
	ds_read_b64_tr_b16 v[164:165], v120 offset:576
	s_waitcnt lgkmcnt(2)
	v_mfma_f32_16x16x32_bf16 v[124:127], v[152:155], v[156:159], v[124:127]
	ds_read_b128 v[152:155], v110
	s_waitcnt lgkmcnt(0)
	v_mfma_f32_16x16x32_bf16 v[136:139], v[152:155], v[156:159], v[136:139]
	ds_read_b128 v[152:155], v112
	v_mfma_f32_16x16x32_bf16 v[132:135], v[140:143], v[156:159], v[132:135]
	ds_read_b128 v[140:143], v111
	s_waitcnt lgkmcnt(1)
	v_mfma_f32_16x16x32_bf16 v[124:127], v[152:155], v[162:165], v[124:127]
	ds_read_b128 v[152:155], v114
	s_waitcnt lgkmcnt(0)
	v_mfma_f32_16x16x32_bf16 v[136:139], v[152:155], v[162:165], v[136:139]
	ds_read_b128 v[152:155], v100
	v_mfma_f32_16x16x32_bf16 v[128:131], v[140:143], v[156:159], v[128:131]
	ds_read_b128 v[140:143], v113
	s_waitcnt lgkmcnt(0)
	v_mfma_f32_16x16x32_bf16 v[132:135], v[140:143], v[162:165], v[132:135]
	ds_read_b128 v[140:143], v115
	s_waitcnt lgkmcnt(0)
	v_mfma_f32_16x16x32_bf16 v[128:131], v[140:143], v[162:165], v[128:131]
	ds_read_b64_tr_b16 v[140:141], v121
	ds_read_b64_tr_b16 v[142:143], v121 offset:576
	ds_read_b128 v[156:159], v108
	s_waitcnt lgkmcnt(1)
	v_mfma_f32_16x16x32_bf16 v[124:127], v[152:155], v[140:143], v[124:127]
	ds_read_b128 v[152:155], v116
	s_waitcnt lgkmcnt(1)
	v_mfma_f32_16x16x32_bf16 v[132:135], v[156:159], v[140:143], v[132:135]
	ds_read_b128 v[156:159], v118
	s_waitcnt lgkmcnt(1)
	v_mfma_f32_16x16x32_bf16 v[136:139], v[152:155], v[140:143], v[136:139]
	s_waitcnt lgkmcnt(0)
	v_mfma_f32_16x16x32_bf16 v[128:131], v[156:159], v[140:143], v[128:131]
	ds_read_b128 v[140:143], v106 offset:18432
	ds_read_b128 v[152:155], v106 offset:18496
	s_waitcnt vmcnt(3) lgkmcnt(1)
	v_mfma_f32_16x16x32_bf16 v[124:127], v[140:143], v[38:41], v[124:127]
	ds_read_b128 v[140:143], v106 offset:20736
	ds_read_b128 v[156:159], v106 offset:20800
	s_waitcnt lgkmcnt(1)
	v_mfma_f32_16x16x32_bf16 v[132:135], v[140:143], v[38:41], v[132:135]
	ds_read_b128 v[140:143], v106 offset:23040
	ds_read_b128 v[162:165], v106 offset:23104
	s_waitcnt lgkmcnt(1)
	v_mfma_f32_16x16x32_bf16 v[136:139], v[140:143], v[38:41], v[136:139]
	ds_read_b128 v[140:143], v106 offset:25344
	ds_read_b128 v[166:169], v106 offset:25408
	s_waitcnt lgkmcnt(1)
	v_mfma_f32_16x16x32_bf16 v[38:41], v[140:143], v[38:41], v[128:131]
	s_waitcnt vmcnt(2)
	v_mfma_f32_16x16x32_bf16 v[124:127], v[152:155], v[34:37], v[124:127]
	v_mfma_f32_16x16x32_bf16 v[128:131], v[156:159], v[34:37], v[132:135]
	v_mfma_f32_16x16x32_bf16 v[132:135], v[162:165], v[34:37], v[136:139]
	s_waitcnt lgkmcnt(0)
	v_mfma_f32_16x16x32_bf16 v[34:37], v[166:169], v[34:37], v[38:41]
	s_nop 2
	ds_read_b128 v[38:41], v106 offset:36864
	ds_read_b128 v[136:139], v106 offset:36928
	s_waitcnt vmcnt(1) lgkmcnt(1)
	v_mfma_f32_16x16x32_bf16 v[38:41], v[38:41], v[30:33], v[124:127]
	s_nop 2
	ds_read_b128 v[124:127], v106 offset:39168
	ds_read_b128 v[140:143], v106 offset:39232
	s_waitcnt lgkmcnt(1)
	v_mfma_f32_16x16x32_bf16 v[124:127], v[124:127], v[30:33], v[128:131]
	s_nop 2
	ds_read_b128 v[128:131], v106 offset:41472
	ds_read_b128 v[152:155], v106 offset:41536
	s_waitcnt lgkmcnt(1)
	v_mfma_f32_16x16x32_bf16 v[128:131], v[128:131], v[30:33], v[132:135]
	s_nop 2
	ds_read_b128 v[132:135], v106 offset:43776
	ds_read_b128 v[156:159], v106 offset:43840
	s_waitcnt lgkmcnt(1)
	v_mfma_f32_16x16x32_bf16 v[30:33], v[132:135], v[30:33], v[34:37]
	s_waitcnt vmcnt(0)
	v_mfma_f32_16x16x32_bf16 v[34:37], v[136:139], v[26:29], v[38:41]
	v_mfma_f32_16x16x32_bf16 v[38:41], v[140:143], v[26:29], v[124:127]
	v_mfma_f32_16x16x32_bf16 v[124:127], v[152:155], v[26:29], v[128:131]
	v_lshl_add_u64 v[152:153], v[48:49], 0, s[80:81]
	s_lshl_b32 s80, s9, 7
	s_waitcnt lgkmcnt(0)
	v_mfma_f32_16x16x32_bf16 v[26:29], v[156:159], v[26:29], v[30:33]
	s_nop 2
	global_load_dwordx4 v[2:5], v236, s[100:101] nt
	global_load_dwordx4 v[6:9], v237, s[100:101] nt
	global_load_dwordx4 v[22:25], v238, s[100:101] nt
	v_lshlrev_b64 v[30:31], 7, v[144:145]
	v_lshl_add_u64 v[30:31], s[16:17], 0, v[30:31]
	v_lshl_add_u64 v[30:31], v[30:31], 0, v[0:1]
	v_lshl_add_u64 v[128:129], v[30:31], 0, s[14:15]
	v_add_co_u32_e32 v30, vcc, s8, v30
	v_lshlrev_b64 v[144:145], 11, v[144:145]
	s_nop 0
	v_addc_co_u32_e32 v31, vcc, 0, v31, vcc
	global_load_dwordx4 v[30:33], v[30:31], off nt
	s_nop 0
	global_load_dwordx4 v[128:131], v[128:129], off offset:16 nt
	s_barrier
	global_load_dwordx4 v[18:21], v239, s[100:101] nt
	global_load_dwordx4 v[10:13], v240, s[100:101] nt
	global_load_dwordx4 v[14:17], v241, s[100:101] nt
	ds_write2_b32 v122, v34, v35 offset1:68
	ds_write2_b32 v122, v36, v37 offset0:136 offset1:204
	v_add_u32_e32 v34, 0x1000, v122
	ds_write2_b32 v34, v38, v39 offset0:64 offset1:132
	v_add_u32_e32 v34, 0x1200, v122
	ds_write2_b32 v34, v40, v41 offset0:72 offset1:140
	v_add_u32_e32 v34, 0x2000, v122
	ds_write2_b32 v34, v124, v125 offset0:128 offset1:196
	v_add_u32_e32 v34, 0x2400, v122
	ds_write2_b32 v34, v126, v127 offset0:8 offset1:76
	v_add_u32_e32 v34, 0x3200, v122
	ds_write2_b32 v34, v26, v27 offset0:64 offset1:132
	v_add_u32_e32 v26, 0x3400, v122
	ds_write2_b32 v26, v28, v29 offset0:72 offset1:140
	s_waitcnt lgkmcnt(0)
	s_barrier
	ds_read_b128 v[38:41], v70
	ds_read_b128 v[124:127], v70 offset:16
	ds_read_b128 v[132:135], v70 offset:32
	ds_read_b128 v[136:139], v70 offset:48
	v_lshl_add_u64 v[144:145], s[74:75], 0, v[144:145]
	s_waitcnt lgkmcnt(3)
	v_pk_mul_f32 v[140:141], v[40:41], v[40:41]
	v_pk_mul_f32 v[142:143], v[38:39], v[38:39]
	v_lshl_add_u64 v[144:145], v[144:145], 0, s[80:81]
	v_pk_mov_b32 v[154:155], v[142:143], v[140:141] op_sel:[1,0]
	v_mov_b32_e32 v143, v141
	v_pk_add_f32 v[156:157], v[154:155], v[142:143]
	s_waitcnt lgkmcnt(2)
	v_pk_mul_f32 v[140:141], v[126:127], v[126:127]
	v_pk_mul_f32 v[142:143], v[124:125], v[124:125]
	s_waitcnt lgkmcnt(0)
	v_mul_f32_e32 v123, v136, v136
	v_pk_mov_b32 v[154:155], v[142:143], v[140:141] op_sel:[1,0]
	v_mov_b32_e32 v143, v141
	v_pk_add_f32 v[158:159], v[154:155], v[142:143]
	v_mul_f32_e32 v147, v137, v137
	v_pk_add_f32 v[156:157], v[156:157], v[156:157] op_sel:[0,1] op_sel_hi:[1,0]
	v_pk_add_f32 v[158:159], v[158:159], v[158:159] op_sel:[0,1] op_sel_hi:[1,0]
	v_mov_b32_e32 v157, v123
	v_mov_b32_e32 v159, v147
	v_pk_add_f32 v[156:157], v[156:157], v[158:159]
	v_mul_f32_e32 v158, v133, v133
	v_mul_f32_e32 v160, v138, v138
	v_pk_fma_f32 v[158:159], v[132:133], v[132:133], v[158:159] op_sel_hi:[1,1,0]
	v_mul_f32_e32 v164, v139, v139
	v_mov_b32_e32 v159, v160
	v_mul_f32_e32 v160, v135, v135
	v_pk_fma_f32 v[162:163], v[134:135], v[134:135], v[160:161] op_sel_hi:[1,1,0]
	v_lshl_add_u64 v[144:145], v[144:145], 0, v[0:1]
	v_mov_b32_e32 v163, v164
	v_pk_add_f32 v[158:159], v[158:159], v[162:163]
	s_mov_b32 s8, s3
	v_pk_add_f32 v[156:157], v[156:157], v[158:159]
	s_waitcnt vmcnt(4)
	v_lshlrev_b32_e32 v158, 16, v30
	v_add_f32_e32 v123, v156, v157
	ds_bpermute_b32 v147, v97, v123
	v_and_b32_e32 v159, 0xffff0000, v30
	v_lshlrev_b32_e32 v30, 16, v31
	v_and_b32_e32 v31, 0xffff0000, v31
	v_lshlrev_b32_e32 v162, 16, v32
	s_waitcnt lgkmcnt(0)
	v_add_f32_e32 v123, v123, v147
	ds_bpermute_b32 v147, v98, v123
	v_and_b32_e32 v163, 0xffff0000, v32
	v_lshlrev_b32_e32 v32, 16, v33
	v_and_b32_e32 v33, 0xffff0000, v33
	s_waitcnt lgkmcnt(0)
	v_add_f32_e32 v123, v123, v147
	v_fmamk_f32 v123, v123, 0x3c800000, v178
	v_mul_f32_e32 v147, 0x4b800000, v123
	v_cmp_gt_f32_e32 vcc, s22, v123
	s_nop 1
	v_cndmask_b32_e32 v123, v123, v147, vcc
	v_rsq_f32_e32 v123, v123
	s_nop 0
	v_mul_f32_e32 v147, 0x45800000, v123
	v_cndmask_b32_e32 v156, v123, v147, vcc
	v_pk_mul_f32 v[40:41], v[40:41], v[156:157] op_sel_hi:[1,0]
	v_pk_mul_f32 v[38:39], v[38:39], v[156:157] op_sel_hi:[1,0]
	v_pk_mul_f32 v[28:29], v[222:223], v[40:41]
	v_pk_mul_f32 v[26:27], v[220:221], v[38:39]
	v_pk_mul_f32 v[28:29], v[28:29], v[30:31]
	v_pk_mul_f32 v[30:31], v[126:127], v[156:157] op_sel_hi:[1,0]
	v_pk_mul_f32 v[38:39], v[124:125], v[156:157] op_sel_hi:[1,0]
	v_pk_mul_f32 v[30:31], v[226:227], v[30:31]
	v_pk_mul_f32 v[34:35], v[224:225], v[38:39]
	v_pk_mul_f32 v[26:27], v[26:27], v[158:159]
	v_pk_mul_f32 v[30:31], v[30:31], v[32:33]
	v_pk_mul_f32 v[32:33], v[34:35], v[162:163]
	v_cvt_pk_bf16_f32 v26, v26, v27
	v_cvt_pk_bf16_f32 v27, v28, v29
	v_cvt_pk_bf16_f32 v28, v32, v33
	v_cvt_pk_bf16_f32 v29, v30, v31
	v_pk_mul_f32 v[34:35], v[134:135], v[156:157] op_sel_hi:[1,0]
	v_pk_mul_f32 v[36:37], v[132:133], v[156:157] op_sel_hi:[1,0]
	global_store_dwordx4 v[144:145], v[26:29], off sc1
	s_waitcnt vmcnt(4)
	v_pk_mul_f32 v[36:37], v[228:229], v[36:37]
	v_pk_mul_f32 v[34:35], v[230:231], v[34:35]
	v_lshlrev_b32_e32 v26, 16, v128
	v_and_b32_e32 v27, 0xffff0000, v128
	v_lshlrev_b32_e32 v28, 16, v129
	v_and_b32_e32 v29, 0xffff0000, v129
	v_pk_mul_f32 v[28:29], v[34:35], v[28:29]
	v_pk_mul_f32 v[26:27], v[36:37], v[26:27]
	v_pk_mul_f32 v[34:35], v[138:139], v[156:157] op_sel_hi:[1,0]
	v_pk_mul_f32 v[36:37], v[136:137], v[156:157] op_sel_hi:[1,0]
	v_lshlrev_b32_e32 v30, 16, v130
	v_and_b32_e32 v31, 0xffff0000, v130
	v_lshlrev_b32_e32 v32, 16, v131
	v_and_b32_e32 v33, 0xffff0000, v131
	v_pk_mul_f32 v[36:37], v[232:233], v[36:37]
	v_pk_mul_f32 v[34:35], v[234:235], v[34:35]
	v_pk_mul_f32 v[30:31], v[36:37], v[30:31]
	v_pk_mul_f32 v[32:33], v[34:35], v[32:33]
	v_cvt_pk_bf16_f32 v26, v26, v27
	v_cvt_pk_bf16_f32 v27, v28, v29
	v_cvt_pk_bf16_f32 v28, v30, v31
	v_cvt_pk_bf16_f32 v29, v32, v33
	s_and_b64 vcc, exec, s[12:13]
	global_store_dwordx4 v[144:145], v[26:29], off offset:16 sc1
	s_barrier
	s_cbranch_vccnz .LBB0_459

.LBB0_768:
	v_pk_mul_f32 v[210:211], v[148:149], v[208:209] op_sel_hi:[1,0]
	s_waitcnt lgkmcnt(0)
	v_mov_b32_dpp v172, v164 row_shr:1 row_mask:0xf bank_mask:0xf
	v_mov_b32_dpp v173, v165 row_shr:1 row_mask:0xf bank_mask:0xf
	v_mov_b32_dpp v148, v210 row_ror:15 row_mask:0xf bank_mask:0xf
	v_mov_b32_dpp v149, v211 row_ror:15 row_mask:0xf bank_mask:0xf
	s_waitcnt vmcnt(0)
	v_pk_fma_f32 v[172:173], v[80:81], v[172:173], v[84:85]
	v_pk_mul_f32 v[206:207], v[150:151], v[208:209] op_sel_hi:[1,0]
	v_mov_b32_dpp v174, v166 row_shr:1 row_mask:0xf bank_mask:0xf
	v_mov_b32_dpp v175, v167 row_shr:1 row_mask:0xf bank_mask:0xf
	v_mov_b32_dpp v148, v164 row_shl:1 row_mask:0xf bank_mask:0xf
	v_mov_b32_dpp v149, v165 row_shl:1 row_mask:0xf bank_mask:0xf
	v_pk_fma_f32 v[172:173], v[164:165], v[76:77], v[172:173]
	v_mov_b32_dpp v150, v206 row_ror:15 row_mask:0xf bank_mask:0xf
	v_mov_b32_dpp v151, v207 row_ror:15 row_mask:0xf bank_mask:0xf
	v_pk_fma_f32 v[174:175], v[82:83], v[174:175], v[86:87]
	v_pk_fma_f32 v[148:149], v[72:73], v[148:149], v[172:173]
	v_mov_b32_dpp v150, v166 row_shl:1 row_mask:0xf bank_mask:0xf
	v_mov_b32_dpp v151, v167 row_shl:1 row_mask:0xf bank_mask:0xf
	v_pk_fma_f32 v[174:175], v[166:167], v[78:79], v[174:175]
	v_pk_mul_f32 v[172:173], v[148:149], v[148:149]
	v_pk_fma_f32 v[150:151], v[74:75], v[150:151], v[174:175]
	v_pk_mul_f32 v[172:173], v[148:149], v[172:173]
	v_pk_mul_f32 v[174:175], v[150:151], v[150:151]
	v_pk_fma_f32 v[172:173], v[172:173], s[70:71], v[148:149] op_sel_hi:[1,0,1]
	v_pk_mul_f32 v[174:175], v[150:151], v[174:175]
	v_pk_mul_f32 v[172:173], v[172:173], s[72:73] op_sel_hi:[1,0]
	v_pk_fma_f32 v[174:175], v[174:175], s[70:71], v[150:151] op_sel_hi:[1,0,1]
	v_min_f32_e32 v172, 0x41e6d4ca, v172
	v_pk_mul_f32 v[174:175], v[174:175], s[72:73] op_sel_hi:[1,0]
	v_exp_f32_e32 v233, v172
	v_min_f32_e32 v172, 0x41e6d4ca, v173
	v_exp_f32_e32 v232, v172
	v_min_f32_e32 v172, 0x41e6d4ca, v174
	v_exp_f32_e32 v173, v172
	v_min_f32_e32 v172, 0x41e6d4ca, v175
	v_exp_f32_e32 v172, v172
	v_pk_mul_f32 v[146:147], v[146:147], v[212:213] op_sel_hi:[1,0]
	v_pk_mul_f32 v[144:145], v[144:145], v[212:213]
	v_pk_mul_f32 v[138:139], v[138:139], v[212:213] op_sel_hi:[1,0]
	v_pk_mul_f32 v[136:137], v[136:137], v[212:213]
	v_pk_add_f32 v[212:213], v[232:233], 1.0 op_sel_hi:[1,0]
	v_pk_add_f32 v[230:231], v[172:173], 1.0 op_sel_hi:[1,0]
	v_mul_f32_e32 v232, v213, v212
	v_mul_f32_e32 v233, v231, v230
	v_pk_mul_f32 v[174:175], v[140:141], v[208:209] op_sel_hi:[1,0]
	v_mul_f32_e32 v172, v232, v233
	v_rcp_f32_e32 v199, v172
	v_mov_b32_dpp v168, v160 row_shr:1 row_mask:0xf bank_mask:0xf
	v_mov_b32_dpp v169, v161 row_shr:1 row_mask:0xf bank_mask:0xf
	v_pk_fma_f32 v[168:169], v[64:65], v[168:169], v[68:69]
	v_mul_f32_e32 v140, v232, v199
	v_pk_mul_f32 v[230:231], v[230:231], v[140:141] op_sel_hi:[1,0]
	v_pk_mul_f32 v[172:173], v[142:143], v[208:209] op_sel_hi:[1,0]
	v_mov_b32_dpp v140, v174 row_ror:15 row_mask:0xf bank_mask:0xf
	v_mov_b32_dpp v141, v175 row_ror:15 row_mask:0xf bank_mask:0xf
	v_mov_b32_dpp v170, v162 row_shr:1 row_mask:0xf bank_mask:0xf
	v_mov_b32_dpp v171, v163 row_shr:1 row_mask:0xf bank_mask:0xf
	v_mov_b32_dpp v140, v160 row_shl:1 row_mask:0xf bank_mask:0xf
	v_mov_b32_dpp v141, v161 row_shl:1 row_mask:0xf bank_mask:0xf
	v_pk_fma_f32 v[168:169], v[160:161], v[60:61], v[168:169]
	v_mov_b32_dpp v142, v172 row_ror:15 row_mask:0xf bank_mask:0xf
	v_mov_b32_dpp v143, v173 row_ror:15 row_mask:0xf bank_mask:0xf
	v_pk_fma_f32 v[170:171], v[66:67], v[170:171], v[70:71]
	v_pk_fma_f32 v[140:141], v[56:57], v[140:141], v[168:169]
	v_mov_b32_dpp v142, v162 row_shl:1 row_mask:0xf bank_mask:0xf
	v_mov_b32_dpp v143, v163 row_shl:1 row_mask:0xf bank_mask:0xf
	v_pk_fma_f32 v[170:171], v[162:163], v[62:63], v[170:171]
	v_pk_mul_f32 v[168:169], v[140:141], v[140:141]
	v_pk_fma_f32 v[142:143], v[58:59], v[142:143], v[170:171]
	v_pk_mul_f32 v[168:169], v[140:141], v[168:169]
	v_pk_mul_f32 v[170:171], v[142:143], v[142:143]
	v_pk_fma_f32 v[168:169], v[168:169], s[70:71], v[140:141] op_sel_hi:[1,0,1]
	v_pk_mul_f32 v[170:171], v[142:143], v[170:171]
	v_pk_mul_f32 v[168:169], v[168:169], s[72:73] op_sel_hi:[1,0]
	v_pk_fma_f32 v[170:171], v[170:171], s[70:71], v[142:143] op_sel_hi:[1,0,1]
	v_min_f32_e32 v168, 0x41e6d4ca, v168
	v_mul_f32_e32 v234, v233, v199
	v_pk_mul_f32 v[170:171], v[170:171], s[72:73] op_sel_hi:[1,0]
	v_exp_f32_e32 v233, v168
	v_min_f32_e32 v168, 0x41e6d4ca, v169
	v_exp_f32_e32 v232, v168
	v_min_f32_e32 v168, 0x41e6d4ca, v170
	v_exp_f32_e32 v169, v168
	v_min_f32_e32 v168, 0x41e6d4ca, v171
	v_exp_f32_e32 v168, v168
	v_pk_mul_f32 v[170:171], v[212:213], v[234:235] op_sel_hi:[1,0]
	v_pk_add_f32 v[212:213], v[232:233], 1.0 op_sel_hi:[1,0]
	v_pk_mul_f32 v[170:171], v[148:149], v[170:171]
	v_pk_add_f32 v[168:169], v[168:169], 1.0 op_sel_hi:[1,0]
	v_mul_f32_e32 v232, v213, v212
	s_nop 0
	v_mul_f32_e32 v233, v169, v168
	v_pk_mul_f32 v[170:171], v[144:145], v[170:171]
	v_mul_f32_e32 v199, v232, v233
	v_rcp_f32_e32 v199, v199
	v_add_u32_e32 v197, s11, v217
	v_pk_mul_f32 v[230:231], v[150:151], v[230:231]
	s_lshl_b32 s12, s10, 1
	v_mul_f32_e32 v234, v233, v199
	v_mul_f32_e32 v232, v232, v199
	v_pk_mul_f32 v[212:213], v[212:213], v[234:235] op_sel_hi:[1,0]
	v_pk_mul_f32 v[168:169], v[168:169], v[232:233] op_sel_hi:[1,0]
	v_pk_mul_f32 v[212:213], v[140:141], v[212:213]
	v_pk_mul_f32 v[168:169], v[142:143], v[168:169]
	v_pk_mul_f32 v[212:213], v[136:137], v[212:213]
	v_pk_mul_f32 v[232:233], v[138:139], v[168:169]
	v_cvt_pk_bf16_f32 v168, v170, v171
	v_cvt_pk_bf16_f32 v170, v212, v213
	v_mov_b64_e32 v[212:213], s[86:87]
	s_mul_i32 s15, s10, 0x10800
	v_pk_mul_f32 v[230:231], v[146:147], v[230:231]
	v_mad_i64_i32 v[212:213], s[10:11], v197, s90, v[212:213]
	s_mul_hi_i32 s16, s12, 0x8400
	v_cvt_pk_bf16_f32 v169, v230, v231
	v_cvt_pk_bf16_f32 v171, v232, v233
	v_lshl_add_u64 v[212:213], v[192:193], 1, v[212:213]
	global_store_dwordx4 v[212:213], v[168:171], off sc1
	s_and_saveexec_b64 s[10:11], s[40:41]
	s_cbranch_execz .LBB0_770
	s_add_u32 s24, s4, s15
	s_addc_u32 s25, s5, s16
	v_lshl_add_u64 v[168:169], v[192:193], 2, s[24:25]
	global_store_dwordx4 v[168:169], v[148:151], off sc1
	s_nop 1
	v_add_co_u32_e32 v148, vcc, 0x2000, v168
	s_nop 1
	v_addc_co_u32_e32 v149, vcc, 0, v169, vcc
	v_add_co_u32_e32 v150, vcc, 0x5000, v168
	global_store_dwordx4 v[148:149], v[164:167], off offset:3072 sc1
	s_nop 0
	v_addc_co_u32_e32 v151, vcc, 0, v169, vcc
	global_store_dwordx4 v[150:151], v[144:147], off offset:2048 sc1
	global_store_dwordx4 v[168:169], v[140:143], off offset:16 sc1
	global_store_dwordx4 v[148:149], v[160:163], off offset:3088 sc1
	global_store_dwordx4 v[150:151], v[136:139], off offset:2064 sc1
.LBB0_770:
	s_or_b64 exec, exec, s[10:11]
	v_pk_mul_f32 v[140:141], v[116:117], v[208:209] op_sel_hi:[1,0]
	v_pk_mul_f32 v[116:117], v[120:121], v[202:203] op_sel_hi:[1,0]
	v_pk_mul_f32 v[102:103], v[102:103], v[204:205] op_sel_hi:[1,0]
	v_pk_mul_f32 v[98:99], v[98:99], v[204:205] op_sel_hi:[1,0]
	v_mov_b32_dpp v120, v164 row_ror:1 row_mask:0xf bank_mask:0xf
	v_mov_b32_dpp v121, v165 row_ror:1 row_mask:0xf bank_mask:0xf
	v_pk_mul_f32 v[138:139], v[118:119], v[208:209] op_sel_hi:[1,0]
	v_pk_mul_f32 v[136:137], v[114:115], v[208:209] op_sel_hi:[1,0]
	v_pk_mul_f32 v[118:119], v[126:127], v[202:203] op_sel_hi:[1,0]
	v_pk_mul_f32 v[124:125], v[124:125], v[202:203] op_sel_hi:[1,0]
	v_pk_mul_f32 v[114:115], v[122:123], v[202:203] op_sel_hi:[1,0]
	v_mov_b32_dpp v120, v210 row_shr:1 row_mask:0xf bank_mask:0xf
	v_mov_b32_dpp v121, v211 row_shr:1 row_mask:0xf bank_mask:0xf
	v_mov_b32_dpp v122, v166 row_ror:1 row_mask:0xf bank_mask:0xf
	v_mov_b32_dpp v123, v167 row_ror:1 row_mask:0xf bank_mask:0xf
	v_mov_b32_dpp v126, v124 row_ror:15 row_mask:0xf bank_mask:0xf
	v_mov_b32_dpp v127, v125 row_ror:15 row_mask:0xf bank_mask:0xf
	v_pk_fma_f32 v[120:121], v[80:81], v[120:121], v[84:85]
	v_mov_b32_dpp v122, v206 row_shr:1 row_mask:0xf bank_mask:0xf
	v_mov_b32_dpp v123, v207 row_shr:1 row_mask:0xf bank_mask:0xf
	v_mov_b32_dpp v126, v210 row_shl:1 row_mask:0xf bank_mask:0xf
	v_mov_b32_dpp v127, v211 row_shl:1 row_mask:0xf bank_mask:0xf
	v_pk_fma_f32 v[120:121], v[210:211], v[76:77], v[120:121]
	v_mov_b32_dpp v142, v118 row_ror:15 row_mask:0xf bank_mask:0xf
	v_mov_b32_dpp v143, v119 row_ror:15 row_mask:0xf bank_mask:0xf
	v_pk_fma_f32 v[122:123], v[82:83], v[122:123], v[86:87]
	v_pk_fma_f32 v[120:121], v[72:73], v[126:127], v[120:121]
	v_mov_b32_dpp v142, v206 row_shl:1 row_mask:0xf bank_mask:0xf
	v_mov_b32_dpp v143, v207 row_shl:1 row_mask:0xf bank_mask:0xf
	v_pk_fma_f32 v[122:123], v[206:207], v[78:79], v[122:123]
	v_pk_mul_f32 v[126:127], v[120:121], v[120:121]
	v_pk_fma_f32 v[122:123], v[74:75], v[142:143], v[122:123]
	v_pk_mul_f32 v[126:127], v[120:121], v[126:127]
	v_pk_mul_f32 v[142:143], v[122:123], v[122:123]
	v_pk_fma_f32 v[126:127], v[126:127], s[70:71], v[120:121] op_sel_hi:[1,0,1]
	v_pk_mul_f32 v[142:143], v[122:123], v[142:143]
	v_pk_mul_f32 v[126:127], v[126:127], s[72:73] op_sel_hi:[1,0]
	v_pk_fma_f32 v[142:143], v[142:143], s[70:71], v[122:123] op_sel_hi:[1,0,1]
	v_min_f32_e32 v126, 0x41e6d4ca, v126
	v_pk_mul_f32 v[142:143], v[142:143], s[72:73] op_sel_hi:[1,0]
	v_exp_f32_e32 v145, v126
	v_min_f32_e32 v126, 0x41e6d4ca, v127
	v_exp_f32_e32 v144, v126
	v_min_f32_e32 v126, 0x41e6d4ca, v142
	v_exp_f32_e32 v127, v126
	v_min_f32_e32 v126, 0x41e6d4ca, v143
	v_exp_f32_e32 v126, v126
	v_pk_add_f32 v[142:143], v[144:145], 1.0 op_sel_hi:[1,0]
	v_pk_mul_f32 v[112:113], v[112:113], v[208:209] op_sel_hi:[1,0]
	v_pk_add_f32 v[126:127], v[126:127], 1.0 op_sel_hi:[1,0]
	v_mul_f32_e32 v144, v143, v142
	v_mul_f32_e32 v145, v127, v126
	v_or_b32_e32 v148, 16, v197
	v_mul_f32_e32 v146, v144, v145
	v_rcp_f32_e32 v147, v146
	v_pk_mul_f32 v[108:109], v[108:109], v[202:203] op_sel_hi:[1,0]
	v_pk_mul_f32 v[110:111], v[110:111], v[202:203] op_sel_hi:[1,0]
	v_pk_mul_f32 v[106:107], v[106:107], v[202:203] op_sel_hi:[1,0]
	v_mul_f32_e32 v144, v144, v147
	v_mul_f32_e32 v146, v145, v147
	v_pk_mul_f32 v[126:127], v[126:127], v[144:145] op_sel_hi:[1,0]
	v_pk_mul_f32 v[142:143], v[142:143], v[146:147] op_sel_hi:[1,0]
	v_pk_mul_f32 v[122:123], v[122:123], v[126:127]
	v_pk_mul_f32 v[120:121], v[120:121], v[142:143]
	v_mov_b32_dpp v126, v160 row_ror:1 row_mask:0xf bank_mask:0xf
	v_mov_b32_dpp v127, v161 row_ror:1 row_mask:0xf bank_mask:0xf
	v_pk_mul_f32 v[122:123], v[138:139], v[122:123]
	v_pk_mul_f32 v[120:121], v[140:141], v[120:121]
	v_mov_b32_dpp v126, v174 row_shr:1 row_mask:0xf bank_mask:0xf
	v_mov_b32_dpp v127, v175 row_shr:1 row_mask:0xf bank_mask:0xf
	v_mov_b32_dpp v138, v162 row_ror:1 row_mask:0xf bank_mask:0xf
	v_mov_b32_dpp v139, v163 row_ror:1 row_mask:0xf bank_mask:0xf
	v_mov_b32_dpp v140, v116 row_ror:15 row_mask:0xf bank_mask:0xf
	v_mov_b32_dpp v141, v117 row_ror:15 row_mask:0xf bank_mask:0xf
	v_pk_fma_f32 v[126:127], v[64:65], v[126:127], v[68:69]
	v_mov_b32_dpp v138, v172 row_shr:1 row_mask:0xf bank_mask:0xf
	v_mov_b32_dpp v139, v173 row_shr:1 row_mask:0xf bank_mask:0xf
	v_mov_b32_dpp v140, v174 row_shl:1 row_mask:0xf bank_mask:0xf
	v_mov_b32_dpp v141, v175 row_shl:1 row_mask:0xf bank_mask:0xf
	v_pk_fma_f32 v[126:127], v[174:175], v[60:61], v[126:127]
	v_mov_b32_dpp v142, v114 row_ror:15 row_mask:0xf bank_mask:0xf
	v_mov_b32_dpp v143, v115 row_ror:15 row_mask:0xf bank_mask:0xf
	v_pk_fma_f32 v[138:139], v[66:67], v[138:139], v[70:71]
	v_pk_fma_f32 v[126:127], v[56:57], v[140:141], v[126:127]
	v_mov_b32_dpp v142, v172 row_shl:1 row_mask:0xf bank_mask:0xf
	v_mov_b32_dpp v143, v173 row_shl:1 row_mask:0xf bank_mask:0xf
	v_pk_fma_f32 v[138:139], v[172:173], v[62:63], v[138:139]
	v_pk_mul_f32 v[140:141], v[126:127], v[126:127]
	v_pk_fma_f32 v[138:139], v[58:59], v[142:143], v[138:139]
	v_pk_mul_f32 v[140:141], v[126:127], v[140:141]
	v_pk_mul_f32 v[142:143], v[138:139], v[138:139]
	v_pk_fma_f32 v[140:141], v[140:141], s[70:71], v[126:127] op_sel_hi:[1,0,1]
	v_pk_mul_f32 v[142:143], v[138:139], v[142:143]
	v_pk_mul_f32 v[140:141], v[140:141], s[72:73] op_sel_hi:[1,0]
	v_pk_fma_f32 v[142:143], v[142:143], s[70:71], v[138:139] op_sel_hi:[1,0,1]
	v_min_f32_e32 v140, 0x41e6d4ca, v140
	v_pk_mul_f32 v[142:143], v[142:143], s[72:73] op_sel_hi:[1,0]
	v_exp_f32_e32 v145, v140
	v_min_f32_e32 v140, 0x41e6d4ca, v141
	v_exp_f32_e32 v144, v140
	v_min_f32_e32 v140, 0x41e6d4ca, v142
	v_exp_f32_e32 v141, v140
	v_min_f32_e32 v140, 0x41e6d4ca, v143
	v_exp_f32_e32 v140, v140
	v_pk_add_f32 v[142:143], v[144:145], 1.0 op_sel_hi:[1,0]
	v_pk_mul_f32 v[104:105], v[104:105], v[202:203] op_sel_hi:[1,0]
	v_pk_add_f32 v[140:141], v[140:141], 1.0 op_sel_hi:[1,0]
	v_mul_f32_e32 v144, v143, v142
	v_mul_f32_e32 v145, v141, v140
	v_mov_b32_dpp v156, v132 row_shl:1 row_mask:0xf bank_mask:0xf
	v_mul_f32_e32 v146, v144, v145
	v_rcp_f32_e32 v147, v146
	v_mov_b32_dpp v157, v133 row_shl:1 row_mask:0xf bank_mask:0xf
	v_mov_b32_dpp v158, v134 row_shl:1 row_mask:0xf bank_mask:0xf
	v_mov_b32_dpp v159, v135 row_shl:1 row_mask:0xf bank_mask:0xf
	v_mul_f32_e32 v146, v145, v147
	v_mul_f32_e32 v144, v144, v147
	v_pk_mul_f32 v[140:141], v[140:141], v[144:145] op_sel_hi:[1,0]
	v_pk_mul_f32 v[142:143], v[142:143], v[146:147] op_sel_hi:[1,0]
	v_pk_mul_f32 v[138:139], v[138:139], v[140:141]
	v_pk_mul_f32 v[126:127], v[126:127], v[142:143]
	v_pk_mul_f32 v[140:141], v[136:137], v[138:139]
	v_pk_mul_f32 v[112:113], v[112:113], v[126:127]
	v_cvt_pk_bf16_f32 v136, v120, v121
	v_mov_b64_e32 v[120:121], s[86:87]
	v_cvt_pk_bf16_f32 v137, v122, v123
	v_cvt_pk_bf16_f32 v138, v112, v113
	v_mad_i64_i32 v[122:123], s[10:11], v148, s90, v[120:121]
	v_lshlrev_b64 v[112:113], 1, v[192:193]
	v_cvt_pk_bf16_f32 v139, v140, v141
	v_lshl_add_u64 v[122:123], v[122:123], 0, v[112:113]
	global_store_dwordx4 v[122:123], v[136:139], off sc1
	s_nop 0
	v_mov_b32_dpp v122, v210 row_ror:1 row_mask:0xf bank_mask:0xf
	v_mov_b32_dpp v123, v211 row_ror:1 row_mask:0xf bank_mask:0xf
	s_nop 0
	v_mov_b32_dpp v122, v124 row_shr:1 row_mask:0xf bank_mask:0xf
	v_mov_b32_dpp v123, v125 row_shr:1 row_mask:0xf bank_mask:0xf
	v_mov_b32_dpp v126, v206 row_ror:1 row_mask:0xf bank_mask:0xf
	v_mov_b32_dpp v127, v207 row_ror:1 row_mask:0xf bank_mask:0xf
	v_mov_b32_dpp v136, v132 row_ror:15 row_mask:0xf bank_mask:0xf
	v_mov_b32_dpp v137, v133 row_ror:15 row_mask:0xf bank_mask:0xf
	v_pk_fma_f32 v[122:123], v[80:81], v[122:123], v[84:85]
	v_mov_b32_dpp v126, v118 row_shr:1 row_mask:0xf bank_mask:0xf
	v_mov_b32_dpp v127, v119 row_shr:1 row_mask:0xf bank_mask:0xf
	v_mov_b32_dpp v136, v124 row_shl:1 row_mask:0xf bank_mask:0xf
	v_mov_b32_dpp v137, v125 row_shl:1 row_mask:0xf bank_mask:0xf
	v_pk_fma_f32 v[122:123], v[124:125], v[76:77], v[122:123]
	v_mov_b32_dpp v138, v134 row_ror:15 row_mask:0xf bank_mask:0xf
	v_mov_b32_dpp v139, v135 row_ror:15 row_mask:0xf bank_mask:0xf
	v_pk_fma_f32 v[126:127], v[82:83], v[126:127], v[86:87]
	v_pk_fma_f32 v[122:123], v[72:73], v[136:137], v[122:123]
	v_mov_b32_dpp v138, v118 row_shl:1 row_mask:0xf bank_mask:0xf
	v_mov_b32_dpp v139, v119 row_shl:1 row_mask:0xf bank_mask:0xf
	v_pk_fma_f32 v[126:127], v[118:119], v[78:79], v[126:127]
	v_pk_mul_f32 v[136:137], v[122:123], v[122:123]
	v_pk_fma_f32 v[126:127], v[74:75], v[138:139], v[126:127]
	v_pk_mul_f32 v[136:137], v[122:123], v[136:137]
	v_pk_mul_f32 v[138:139], v[126:127], v[126:127]
	v_pk_fma_f32 v[136:137], v[136:137], s[70:71], v[122:123] op_sel_hi:[1,0,1]
	v_pk_mul_f32 v[138:139], v[126:127], v[138:139]
	v_pk_mul_f32 v[136:137], v[136:137], s[72:73] op_sel_hi:[1,0]
	v_pk_fma_f32 v[138:139], v[138:139], s[70:71], v[126:127] op_sel_hi:[1,0,1]
	v_min_f32_e32 v136, 0x41e6d4ca, v136
	v_pk_mul_f32 v[138:139], v[138:139], s[72:73] op_sel_hi:[1,0]
	v_exp_f32_e32 v141, v136
	v_min_f32_e32 v136, 0x41e6d4ca, v137
	v_exp_f32_e32 v140, v136
	v_min_f32_e32 v136, 0x41e6d4ca, v138
	v_exp_f32_e32 v137, v136
	v_min_f32_e32 v136, 0x41e6d4ca, v139
	v_exp_f32_e32 v136, v136
	v_pk_add_f32 v[138:139], v[140:141], 1.0 op_sel_hi:[1,0]
	v_or_b32_e32 v144, 32, v197
	v_pk_add_f32 v[136:137], v[136:137], 1.0 op_sel_hi:[1,0]
	v_mul_f32_e32 v140, v139, v138
	v_mul_f32_e32 v141, v137, v136
	v_pk_mul_f32 v[100:101], v[100:101], v[204:205]
	v_mul_f32_e32 v142, v140, v141
	v_rcp_f32_e32 v143, v142
	v_mov_b32_dpp v152, v128 row_shl:1 row_mask:0xf bank_mask:0xf
	v_mov_b32_dpp v153, v129 row_shl:1 row_mask:0xf bank_mask:0xf
	v_mov_b32_dpp v154, v130 row_shl:1 row_mask:0xf bank_mask:0xf
	v_mul_f32_e32 v142, v141, v143
	v_pk_mul_f32 v[138:139], v[138:139], v[142:143] op_sel_hi:[1,0]
	v_mul_f32_e32 v140, v140, v143
	v_pk_mul_f32 v[122:123], v[122:123], v[138:139]
	v_pk_mul_f32 v[136:137], v[136:137], v[140:141] op_sel_hi:[1,0]
	v_pk_mul_f32 v[108:109], v[108:109], v[122:123]
	v_pk_mul_f32 v[126:127], v[126:127], v[136:137]
	v_mov_b32_dpp v122, v174 row_ror:1 row_mask:0xf bank_mask:0xf
	v_mov_b32_dpp v123, v175 row_ror:1 row_mask:0xf bank_mask:0xf
	v_pk_mul_f32 v[110:111], v[110:111], v[126:127]
	v_mov_b32_dpp v122, v116 row_shr:1 row_mask:0xf bank_mask:0xf
	v_mov_b32_dpp v123, v117 row_shr:1 row_mask:0xf bank_mask:0xf
	v_mov_b32_dpp v126, v172 row_ror:1 row_mask:0xf bank_mask:0xf
	v_mov_b32_dpp v127, v173 row_ror:1 row_mask:0xf bank_mask:0xf
	v_mov_b32_dpp v136, v128 row_ror:15 row_mask:0xf bank_mask:0xf
	v_mov_b32_dpp v137, v129 row_ror:15 row_mask:0xf bank_mask:0xf
	v_pk_fma_f32 v[122:123], v[64:65], v[122:123], v[68:69]
	v_mov_b32_dpp v126, v114 row_shr:1 row_mask:0xf bank_mask:0xf
	v_mov_b32_dpp v127, v115 row_shr:1 row_mask:0xf bank_mask:0xf
	v_mov_b32_dpp v136, v116 row_shl:1 row_mask:0xf bank_mask:0xf
	v_mov_b32_dpp v137, v117 row_shl:1 row_mask:0xf bank_mask:0xf
	v_pk_fma_f32 v[122:123], v[116:117], v[60:61], v[122:123]
	v_mov_b32_dpp v138, v130 row_ror:15 row_mask:0xf bank_mask:0xf
	v_mov_b32_dpp v139, v131 row_ror:15 row_mask:0xf bank_mask:0xf
	v_pk_fma_f32 v[126:127], v[66:67], v[126:127], v[70:71]
	v_pk_fma_f32 v[122:123], v[56:57], v[136:137], v[122:123]
	v_mov_b32_dpp v138, v114 row_shl:1 row_mask:0xf bank_mask:0xf
	v_mov_b32_dpp v139, v115 row_shl:1 row_mask:0xf bank_mask:0xf
	v_pk_fma_f32 v[126:127], v[114:115], v[62:63], v[126:127]
	v_pk_mul_f32 v[136:137], v[122:123], v[122:123]
	v_pk_fma_f32 v[126:127], v[58:59], v[138:139], v[126:127]
	v_pk_mul_f32 v[136:137], v[122:123], v[136:137]
	v_pk_mul_f32 v[138:139], v[126:127], v[126:127]
	v_pk_fma_f32 v[136:137], v[136:137], s[70:71], v[122:123] op_sel_hi:[1,0,1]
	v_pk_mul_f32 v[138:139], v[126:127], v[138:139]
	v_pk_mul_f32 v[136:137], v[136:137], s[72:73] op_sel_hi:[1,0]
	v_pk_fma_f32 v[138:139], v[138:139], s[70:71], v[126:127] op_sel_hi:[1,0,1]
	v_min_f32_e32 v136, 0x41e6d4ca, v136
	v_pk_mul_f32 v[138:139], v[138:139], s[72:73] op_sel_hi:[1,0]
	v_exp_f32_e32 v141, v136
	v_min_f32_e32 v136, 0x41e6d4ca, v137
	v_exp_f32_e32 v140, v136
	v_min_f32_e32 v136, 0x41e6d4ca, v138
	v_exp_f32_e32 v137, v136
	v_min_f32_e32 v136, 0x41e6d4ca, v139
	v_exp_f32_e32 v136, v136
	v_pk_add_f32 v[138:139], v[140:141], 1.0 op_sel_hi:[1,0]
	v_mov_b32_dpp v155, v131 row_shl:1 row_mask:0xf bank_mask:0xf
	v_pk_add_f32 v[136:137], v[136:137], 1.0 op_sel_hi:[1,0]
	v_mul_f32_e32 v140, v139, v138
	v_mul_f32_e32 v141, v137, v136
	v_pk_mul_f32 v[96:97], v[96:97], v[204:205]
	v_mul_f32_e32 v142, v140, v141
	v_rcp_f32_e32 v143, v142
	s_or_b32 s14, s12, 1
	s_mul_hi_i32 s12, s14, 0x8400
	s_mul_i32 s14, s14, 0x8400
	v_mul_f32_e32 v142, v141, v143
	v_mul_f32_e32 v140, v140, v143
	v_pk_mul_f32 v[136:137], v[136:137], v[140:141] op_sel_hi:[1,0]
	v_pk_mul_f32 v[138:139], v[138:139], v[142:143] op_sel_hi:[1,0]
	v_pk_mul_f32 v[126:127], v[126:127], v[136:137]
	v_pk_mul_f32 v[122:123], v[122:123], v[138:139]
	v_pk_mul_f32 v[126:127], v[106:107], v[126:127]
	v_pk_mul_f32 v[106:107], v[104:105], v[122:123]
	v_cvt_pk_bf16_f32 v104, v108, v109
	v_mad_i64_i32 v[108:109], s[10:11], v144, s90, v[120:121]
	v_cvt_pk_bf16_f32 v105, v110, v111
	v_cvt_pk_bf16_f32 v106, v106, v107
	v_cvt_pk_bf16_f32 v107, v126, v127
	v_lshl_add_u64 v[108:109], v[108:109], 0, v[112:113]
	global_store_dwordx4 v[108:109], v[104:107], off sc1
	v_or_b32_e32 v136, 48, v197
	s_nop 0
	v_mov_b32_dpp v104, v124 row_ror:1 row_mask:0xf bank_mask:0xf
	v_mov_b32_dpp v105, v125 row_ror:1 row_mask:0xf bank_mask:0xf
	s_nop 0
	v_mov_b32_dpp v104, v132 row_shr:1 row_mask:0xf bank_mask:0xf
	v_mov_b32_dpp v105, v133 row_shr:1 row_mask:0xf bank_mask:0xf
	v_mov_b32_dpp v106, v118 row_ror:1 row_mask:0xf bank_mask:0xf
	v_mov_b32_dpp v107, v119 row_ror:1 row_mask:0xf bank_mask:0xf
	v_pk_fma_f32 v[104:105], v[80:81], v[104:105], v[84:85]
	v_mov_b32_dpp v106, v134 row_shr:1 row_mask:0xf bank_mask:0xf
	v_mov_b32_dpp v107, v135 row_shr:1 row_mask:0xf bank_mask:0xf
	v_pk_fma_f32 v[104:105], v[132:133], v[76:77], v[104:105]
	v_pk_fma_f32 v[106:107], v[82:83], v[106:107], v[86:87]
	v_pk_fma_f32 v[104:105], v[72:73], v[156:157], v[104:105]
	v_pk_fma_f32 v[106:107], v[134:135], v[78:79], v[106:107]
	v_pk_mul_f32 v[108:109], v[104:105], v[104:105]
	v_pk_fma_f32 v[106:107], v[74:75], v[158:159], v[106:107]
	v_pk_mul_f32 v[108:109], v[104:105], v[108:109]
	v_pk_mul_f32 v[110:111], v[106:107], v[106:107]
	v_pk_fma_f32 v[108:109], v[108:109], s[70:71], v[104:105] op_sel_hi:[1,0,1]
	v_pk_mul_f32 v[110:111], v[106:107], v[110:111]
	v_pk_mul_f32 v[108:109], v[108:109], s[72:73] op_sel_hi:[1,0]
	v_pk_fma_f32 v[110:111], v[110:111], s[70:71], v[106:107] op_sel_hi:[1,0,1]
	v_min_f32_e32 v108, 0x41e6d4ca, v108
	v_pk_mul_f32 v[110:111], v[110:111], s[72:73] op_sel_hi:[1,0]
	v_exp_f32_e32 v119, v108
	v_min_f32_e32 v108, 0x41e6d4ca, v109
	v_exp_f32_e32 v118, v108
	v_min_f32_e32 v108, 0x41e6d4ca, v110
	v_exp_f32_e32 v109, v108
	v_min_f32_e32 v108, 0x41e6d4ca, v111
	v_exp_f32_e32 v108, v108
	v_pk_add_f32 v[110:111], v[118:119], 1.0 op_sel_hi:[1,0]
	v_pk_add_f32 v[108:109], v[108:109], 1.0 op_sel_hi:[1,0]
	v_mul_f32_e32 v118, v111, v110
	v_mul_f32_e32 v119, v109, v108
	s_nop 0
	v_mul_f32_e32 v122, v118, v119
	v_rcp_f32_e32 v123, v122
	s_nop 0
	v_mul_f32_e32 v118, v118, v123
	v_pk_mul_f32 v[108:109], v[108:109], v[118:119] op_sel_hi:[1,0]
	v_mul_f32_e32 v122, v119, v123
	v_pk_mul_f32 v[108:109], v[106:107], v[108:109]
	v_pk_mul_f32 v[110:111], v[110:111], v[122:123] op_sel_hi:[1,0]
	v_pk_mul_f32 v[118:119], v[102:103], v[108:109]
	v_pk_mul_f32 v[110:111], v[104:105], v[110:111]
	v_mov_b32_dpp v108, v116 row_ror:1 row_mask:0xf bank_mask:0xf
	v_mov_b32_dpp v109, v117 row_ror:1 row_mask:0xf bank_mask:0xf
	v_pk_mul_f32 v[122:123], v[100:101], v[110:111]
	v_mov_b32_dpp v108, v128 row_shr:1 row_mask:0xf bank_mask:0xf
	v_mov_b32_dpp v109, v129 row_shr:1 row_mask:0xf bank_mask:0xf
	v_mov_b32_dpp v110, v114 row_ror:1 row_mask:0xf bank_mask:0xf
	v_mov_b32_dpp v111, v115 row_ror:1 row_mask:0xf bank_mask:0xf
	v_pk_fma_f32 v[108:109], v[64:65], v[108:109], v[68:69]
	v_mov_b32_dpp v110, v130 row_shr:1 row_mask:0xf bank_mask:0xf
	v_mov_b32_dpp v111, v131 row_shr:1 row_mask:0xf bank_mask:0xf
	v_pk_fma_f32 v[108:109], v[128:129], v[60:61], v[108:109]
	v_pk_fma_f32 v[110:111], v[66:67], v[110:111], v[70:71]
	v_pk_fma_f32 v[108:109], v[56:57], v[152:153], v[108:109]
	v_pk_fma_f32 v[110:111], v[130:131], v[62:63], v[110:111]
	v_pk_mul_f32 v[114:115], v[108:109], v[108:109]
	v_pk_fma_f32 v[110:111], v[58:59], v[154:155], v[110:111]
	v_pk_mul_f32 v[114:115], v[108:109], v[114:115]
	v_pk_mul_f32 v[116:117], v[110:111], v[110:111]
	v_pk_fma_f32 v[114:115], v[114:115], s[70:71], v[108:109] op_sel_hi:[1,0,1]
	v_pk_mul_f32 v[116:117], v[110:111], v[116:117]
	v_pk_mul_f32 v[114:115], v[114:115], s[72:73] op_sel_hi:[1,0]
	v_pk_fma_f32 v[116:117], v[116:117], s[70:71], v[110:111] op_sel_hi:[1,0,1]
	v_min_f32_e32 v114, 0x41e6d4ca, v114
	v_pk_mul_f32 v[116:117], v[116:117], s[72:73] op_sel_hi:[1,0]
	v_exp_f32_e32 v125, v114
	v_min_f32_e32 v114, 0x41e6d4ca, v115
	v_exp_f32_e32 v124, v114
	v_min_f32_e32 v114, 0x41e6d4ca, v116
	v_exp_f32_e32 v115, v114
	v_min_f32_e32 v114, 0x41e6d4ca, v117
	v_exp_f32_e32 v114, v114
	v_pk_add_f32 v[116:117], v[124:125], 1.0 op_sel_hi:[1,0]
	v_pk_add_f32 v[114:115], v[114:115], 1.0 op_sel_hi:[1,0]
	v_mul_f32_e32 v124, v117, v116
	v_mul_f32_e32 v125, v115, v114
	s_nop 0
	v_mul_f32_e32 v126, v124, v125
	v_rcp_f32_e32 v127, v126
	s_nop 0
	v_mul_f32_e32 v126, v125, v127
	v_mul_f32_e32 v124, v124, v127
	v_pk_mul_f32 v[114:115], v[114:115], v[124:125] op_sel_hi:[1,0]
	v_pk_mul_f32 v[116:117], v[116:117], v[126:127] op_sel_hi:[1,0]
	v_pk_mul_f32 v[114:115], v[110:111], v[114:115]
	v_pk_mul_f32 v[116:117], v[108:109], v[116:117]
	v_pk_mul_f32 v[124:125], v[98:99], v[114:115]
	v_pk_mul_f32 v[116:117], v[96:97], v[116:117]
	v_cvt_pk_bf16_f32 v115, v118, v119
	v_mad_i64_i32 v[118:119], s[10:11], v136, s90, v[120:121]
	v_cvt_pk_bf16_f32 v114, v122, v123
	v_cvt_pk_bf16_f32 v116, v116, v117
	v_cvt_pk_bf16_f32 v117, v124, v125
	v_lshl_add_u64 v[118:119], v[118:119], 0, v[112:113]
	global_store_dwordx4 v[118:119], v[114:117], off sc1
	s_and_saveexec_b64 s[10:11], s[58:59]
	s_cbranch_execz .LBB0_772
	s_add_u32 s24, s4, s14
	s_addc_u32 s25, s5, s12
	v_lshl_add_u64 v[114:115], v[192:193], 2, s[24:25]
	global_store_dwordx4 v[114:115], v[104:107], off sc1
	s_nop 1
	v_add_co_u32_e32 v104, vcc, 0x2000, v114
	s_nop 1
	v_addc_co_u32_e32 v105, vcc, 0, v115, vcc
	v_add_co_u32_e32 v106, vcc, 0x5000, v114
	global_store_dwordx4 v[104:105], v[132:135], off offset:3072 sc1
	s_nop 0
	v_addc_co_u32_e32 v107, vcc, 0, v115, vcc
	global_store_dwordx4 v[106:107], v[100:103], off offset:2048 sc1
	global_store_dwordx4 v[114:115], v[108:111], off offset:16 sc1
	global_store_dwordx4 v[104:105], v[128:131], off offset:3088 sc1
	global_store_dwordx4 v[106:107], v[96:99], off offset:2064 sc1

.LBB0_780:
	v_pk_mul_f32 v[116:117], v[52:53], v[198:199] op_sel_hi:[1,0]
	s_waitcnt lgkmcnt(0)
	v_mov_b32_dpp v108, v92 row_shr:1 row_mask:0xf bank_mask:0xf
	v_mov_b32_dpp v109, v93 row_shr:1 row_mask:0xf bank_mask:0xf
	v_mov_b32_dpp v52, v116 row_ror:15 row_mask:0xf bank_mask:0xf
	v_mov_b32_dpp v53, v117 row_ror:15 row_mask:0xf bank_mask:0xf
	v_pk_fma_f32 v[108:109], v[80:81], v[108:109], v[84:85]
	v_pk_mul_f32 v[114:115], v[54:55], v[198:199] op_sel_hi:[1,0]
	v_mov_b32_dpp v110, v94 row_shr:1 row_mask:0xf bank_mask:0xf
	v_mov_b32_dpp v111, v95 row_shr:1 row_mask:0xf bank_mask:0xf
	v_mov_b32_dpp v52, v92 row_shl:1 row_mask:0xf bank_mask:0xf
	v_mov_b32_dpp v53, v93 row_shl:1 row_mask:0xf bank_mask:0xf
	v_pk_fma_f32 v[108:109], v[92:93], v[76:77], v[108:109]
	v_mov_b32_dpp v54, v114 row_ror:15 row_mask:0xf bank_mask:0xf
	v_mov_b32_dpp v55, v115 row_ror:15 row_mask:0xf bank_mask:0xf
	v_pk_fma_f32 v[110:111], v[82:83], v[110:111], v[86:87]
	v_pk_fma_f32 v[52:53], v[72:73], v[52:53], v[108:109]
	v_mov_b32_dpp v54, v94 row_shl:1 row_mask:0xf bank_mask:0xf
	v_mov_b32_dpp v55, v95 row_shl:1 row_mask:0xf bank_mask:0xf
	v_pk_fma_f32 v[110:111], v[94:95], v[78:79], v[110:111]
	v_pk_mul_f32 v[108:109], v[52:53], v[52:53]
	v_pk_fma_f32 v[54:55], v[74:75], v[54:55], v[110:111]
	v_pk_mul_f32 v[108:109], v[52:53], v[108:109]
	v_pk_mul_f32 v[110:111], v[54:55], v[54:55]
	v_pk_fma_f32 v[108:109], v[108:109], s[70:71], v[52:53] op_sel_hi:[1,0,1]
	v_pk_mul_f32 v[110:111], v[54:55], v[110:111]
	v_pk_mul_f32 v[108:109], v[108:109], s[72:73] op_sel_hi:[1,0]
	v_pk_fma_f32 v[110:111], v[110:111], s[70:71], v[54:55] op_sel_hi:[1,0,1]
	v_min_f32_e32 v108, 0x41e6d4ca, v108
	v_pk_mul_f32 v[110:111], v[110:111], s[72:73] op_sel_hi:[1,0]
	v_exp_f32_e32 v121, v108
	v_min_f32_e32 v108, 0x41e6d4ca, v109
	v_exp_f32_e32 v120, v108
	v_min_f32_e32 v108, 0x41e6d4ca, v110
	v_exp_f32_e32 v109, v108
	v_min_f32_e32 v108, 0x41e6d4ca, v111
	v_exp_f32_e32 v108, v108
	v_pk_mul_f32 v[50:51], v[50:51], v[200:201] op_sel_hi:[1,0]
	v_pk_mul_f32 v[42:43], v[42:43], v[200:201] op_sel_hi:[1,0]
	v_pk_add_f32 v[118:119], v[120:121], 1.0 op_sel_hi:[1,0]
	v_pk_add_f32 v[120:121], v[108:109], 1.0 op_sel_hi:[1,0]
	v_mul_f32_e32 v122, v119, v118
	v_mul_f32_e32 v123, v121, v120
	v_pk_mul_f32 v[110:111], v[44:45], v[198:199] op_sel_hi:[1,0]
	v_mul_f32_e32 v108, v122, v123
	v_rcp_f32_e32 v125, v108
	v_mov_b32_dpp v104, v88 row_shr:1 row_mask:0xf bank_mask:0xf
	v_mov_b32_dpp v105, v89 row_shr:1 row_mask:0xf bank_mask:0xf
	v_pk_fma_f32 v[104:105], v[64:65], v[104:105], v[68:69]
	v_mul_f32_e32 v44, v122, v125
	v_pk_mul_f32 v[120:121], v[120:121], v[44:45] op_sel_hi:[1,0]
	v_pk_mul_f32 v[108:109], v[46:47], v[198:199] op_sel_hi:[1,0]
	v_mov_b32_dpp v44, v110 row_ror:15 row_mask:0xf bank_mask:0xf
	v_mov_b32_dpp v45, v111 row_ror:15 row_mask:0xf bank_mask:0xf
	v_mov_b32_dpp v106, v90 row_shr:1 row_mask:0xf bank_mask:0xf
	v_mov_b32_dpp v107, v91 row_shr:1 row_mask:0xf bank_mask:0xf
	v_mov_b32_dpp v44, v88 row_shl:1 row_mask:0xf bank_mask:0xf
	v_mov_b32_dpp v45, v89 row_shl:1 row_mask:0xf bank_mask:0xf
	v_pk_fma_f32 v[104:105], v[88:89], v[60:61], v[104:105]
	v_mov_b32_dpp v46, v108 row_ror:15 row_mask:0xf bank_mask:0xf
	v_mov_b32_dpp v47, v109 row_ror:15 row_mask:0xf bank_mask:0xf
	v_pk_fma_f32 v[106:107], v[66:67], v[106:107], v[70:71]
	v_pk_fma_f32 v[44:45], v[56:57], v[44:45], v[104:105]
	v_mov_b32_dpp v46, v90 row_shl:1 row_mask:0xf bank_mask:0xf
	v_mov_b32_dpp v47, v91 row_shl:1 row_mask:0xf bank_mask:0xf
	v_pk_fma_f32 v[106:107], v[90:91], v[62:63], v[106:107]
	v_pk_mul_f32 v[104:105], v[44:45], v[44:45]
	v_pk_fma_f32 v[46:47], v[58:59], v[46:47], v[106:107]
	v_pk_mul_f32 v[104:105], v[44:45], v[104:105]
	v_pk_mul_f32 v[106:107], v[46:47], v[46:47]
	v_pk_fma_f32 v[104:105], v[104:105], s[70:71], v[44:45] op_sel_hi:[1,0,1]
	v_pk_mul_f32 v[106:107], v[46:47], v[106:107]
	v_pk_mul_f32 v[104:105], v[104:105], s[72:73] op_sel_hi:[1,0]
	v_pk_fma_f32 v[106:107], v[106:107], s[70:71], v[46:47] op_sel_hi:[1,0,1]
	v_min_f32_e32 v104, 0x41e6d4ca, v104
	v_mul_f32_e32 v124, v123, v125
	v_pk_mul_f32 v[106:107], v[106:107], s[72:73] op_sel_hi:[1,0]
	v_exp_f32_e32 v123, v104
	v_min_f32_e32 v104, 0x41e6d4ca, v105
	v_exp_f32_e32 v122, v104
	v_min_f32_e32 v104, 0x41e6d4ca, v106
	v_exp_f32_e32 v105, v104
	v_min_f32_e32 v104, 0x41e6d4ca, v107
	v_exp_f32_e32 v104, v104
	v_pk_mul_f32 v[106:107], v[118:119], v[124:125] op_sel_hi:[1,0]
	v_pk_add_f32 v[118:119], v[122:123], 1.0 op_sel_hi:[1,0]
	v_pk_mul_f32 v[48:49], v[48:49], v[200:201]
	v_pk_add_f32 v[104:105], v[104:105], 1.0 op_sel_hi:[1,0]
	v_mul_f32_e32 v122, v119, v118
	v_mul_f32_e32 v123, v105, v104
	v_pk_mul_f32 v[40:41], v[40:41], v[200:201]
	v_mul_f32_e32 v124, v122, v123
	v_rcp_f32_e32 v125, v124
	v_pk_mul_f32 v[106:107], v[52:53], v[106:107]
	v_add_u32_e32 v126, 0x80, v197
	v_pk_mul_f32 v[106:107], v[48:49], v[106:107]
	v_mul_f32_e32 v124, v123, v125
	v_mul_f32_e32 v122, v122, v125
	v_pk_mul_f32 v[118:119], v[118:119], v[124:125] op_sel_hi:[1,0]
	v_pk_mul_f32 v[104:105], v[104:105], v[122:123] op_sel_hi:[1,0]
	v_pk_mul_f32 v[118:119], v[44:45], v[118:119]
	v_pk_mul_f32 v[104:105], v[46:47], v[104:105]
	v_pk_mul_f32 v[118:119], v[40:41], v[118:119]
	v_pk_mul_f32 v[120:121], v[54:55], v[120:121]
	v_pk_mul_f32 v[122:123], v[42:43], v[104:105]
	v_cvt_pk_bf16_f32 v104, v106, v107
	v_cvt_pk_bf16_f32 v106, v118, v119
	v_mov_b64_e32 v[118:119], s[86:87]
	v_pk_mul_f32 v[120:121], v[50:51], v[120:121]
	v_mad_i64_i32 v[118:119], s[10:11], v126, s90, v[118:119]
	v_cvt_pk_bf16_f32 v105, v120, v121
	v_cvt_pk_bf16_f32 v107, v122, v123
	v_lshl_add_u64 v[118:119], v[192:193], 1, v[118:119]
	global_store_dwordx4 v[118:119], v[104:107], off sc1
	s_and_saveexec_b64 s[10:11], s[42:43]
	s_cbranch_execz .LBB0_782
	s_add_u32 s24, s4, s15
	s_addc_u32 s25, s5, s16
	v_lshl_add_u64 v[104:105], v[192:193], 2, s[24:25]
	global_store_dwordx4 v[104:105], v[52:55], off sc1
	s_nop 1
	v_add_co_u32_e32 v52, vcc, 0x2000, v104
	s_nop 1
	v_addc_co_u32_e32 v53, vcc, 0, v105, vcc
	v_add_co_u32_e32 v54, vcc, 0x5000, v104
	global_store_dwordx4 v[52:53], v[92:95], off offset:3072 sc1
	s_nop 0
	v_addc_co_u32_e32 v55, vcc, 0, v105, vcc
	global_store_dwordx4 v[54:55], v[48:51], off offset:2048 sc1
	global_store_dwordx4 v[104:105], v[44:47], off offset:16 sc1
	global_store_dwordx4 v[52:53], v[88:91], off offset:3088 sc1
	global_store_dwordx4 v[54:55], v[40:43], off offset:2064 sc1
.LBB0_782:
	s_or_b64 exec, exec, s[10:11]
	s_nop 0
	v_pk_mul_f32 v[44:45], v[22:23], v[198:199] op_sel_hi:[1,0]
	v_pk_mul_f32 v[40:41], v[18:19], v[198:199] op_sel_hi:[1,0]
	v_pk_mul_f32 v[18:19], v[24:25], v[196:197] op_sel_hi:[1,0]
	v_pk_mul_f32 v[6:7], v[6:7], v[194:195] op_sel_hi:[1,0]
	v_pk_mul_f32 v[2:3], v[2:3], v[194:195] op_sel_hi:[1,0]
	v_mov_b32_dpp v24, v92 row_ror:1 row_mask:0xf bank_mask:0xf
	v_mov_b32_dpp v25, v93 row_ror:1 row_mask:0xf bank_mask:0xf
	v_pk_mul_f32 v[42:43], v[16:17], v[198:199] op_sel_hi:[1,0]
	v_pk_mul_f32 v[22:23], v[28:29], v[196:197] op_sel_hi:[1,0]
	v_pk_mul_f32 v[16:17], v[26:27], v[196:197] op_sel_hi:[1,0]
	v_mov_b32_dpp v24, v116 row_shr:1 row_mask:0xf bank_mask:0xf
	v_mov_b32_dpp v25, v117 row_shr:1 row_mask:0xf bank_mask:0xf
	v_mov_b32_dpp v26, v94 row_ror:1 row_mask:0xf bank_mask:0xf
	v_mov_b32_dpp v27, v95 row_ror:1 row_mask:0xf bank_mask:0xf
	v_mov_b32_dpp v28, v22 row_ror:15 row_mask:0xf bank_mask:0xf
	v_mov_b32_dpp v29, v23 row_ror:15 row_mask:0xf bank_mask:0xf
	v_pk_fma_f32 v[24:25], v[80:81], v[24:25], v[84:85]
	v_pk_mul_f32 v[46:47], v[20:21], v[198:199] op_sel_hi:[1,0]
	v_pk_mul_f32 v[20:21], v[30:31], v[196:197] op_sel_hi:[1,0]
	v_mov_b32_dpp v26, v114 row_shr:1 row_mask:0xf bank_mask:0xf
	v_mov_b32_dpp v27, v115 row_shr:1 row_mask:0xf bank_mask:0xf
	v_mov_b32_dpp v28, v116 row_shl:1 row_mask:0xf bank_mask:0xf
	v_mov_b32_dpp v29, v117 row_shl:1 row_mask:0xf bank_mask:0xf
	v_pk_fma_f32 v[24:25], v[116:117], v[76:77], v[24:25]
	v_mov_b32_dpp v30, v20 row_ror:15 row_mask:0xf bank_mask:0xf
	v_mov_b32_dpp v31, v21 row_ror:15 row_mask:0xf bank_mask:0xf
	v_pk_fma_f32 v[26:27], v[82:83], v[26:27], v[86:87]
	v_pk_fma_f32 v[24:25], v[72:73], v[28:29], v[24:25]
	v_mov_b32_dpp v30, v114 row_shl:1 row_mask:0xf bank_mask:0xf
	v_mov_b32_dpp v31, v115 row_shl:1 row_mask:0xf bank_mask:0xf
	v_pk_fma_f32 v[26:27], v[114:115], v[78:79], v[26:27]
	v_pk_mul_f32 v[28:29], v[24:25], v[24:25]
	v_pk_fma_f32 v[26:27], v[74:75], v[30:31], v[26:27]
	v_pk_mul_f32 v[28:29], v[24:25], v[28:29]
	v_pk_mul_f32 v[30:31], v[26:27], v[26:27]
	v_pk_fma_f32 v[28:29], v[28:29], s[70:71], v[24:25] op_sel_hi:[1,0,1]
	v_pk_mul_f32 v[30:31], v[26:27], v[30:31]
	v_pk_mul_f32 v[28:29], v[28:29], s[72:73] op_sel_hi:[1,0]
	v_pk_fma_f32 v[30:31], v[30:31], s[70:71], v[26:27] op_sel_hi:[1,0,1]
	v_min_f32_e32 v28, 0x41e6d4ca, v28
	v_pk_mul_f32 v[30:31], v[30:31], s[72:73] op_sel_hi:[1,0]
	v_exp_f32_e32 v49, v28
	v_min_f32_e32 v28, 0x41e6d4ca, v29
	v_exp_f32_e32 v48, v28
	v_min_f32_e32 v28, 0x41e6d4ca, v30
	v_exp_f32_e32 v29, v28
	v_min_f32_e32 v28, 0x41e6d4ca, v31
	v_exp_f32_e32 v28, v28
	v_pk_add_f32 v[30:31], v[48:49], 1.0 op_sel_hi:[1,0]
	v_add_u32_e32 v52, 0x90, v197
	v_pk_add_f32 v[28:29], v[28:29], 1.0 op_sel_hi:[1,0]
	v_mul_f32_e32 v48, v31, v30
	v_mul_f32_e32 v49, v29, v28
	v_pk_mul_f32 v[12:13], v[12:13], v[196:197] op_sel_hi:[1,0]
	v_mul_f32_e32 v50, v48, v49
	v_rcp_f32_e32 v51, v50
	v_pk_mul_f32 v[14:15], v[14:15], v[196:197] op_sel_hi:[1,0]
	v_pk_mul_f32 v[10:11], v[10:11], v[196:197] op_sel_hi:[1,0]
	v_pk_mul_f32 v[8:9], v[8:9], v[196:197] op_sel_hi:[1,0]
	v_mul_f32_e32 v48, v48, v51
	v_pk_mul_f32 v[28:29], v[28:29], v[48:49] op_sel_hi:[1,0]
	v_mul_f32_e32 v50, v49, v51
	v_pk_mul_f32 v[26:27], v[26:27], v[28:29]
	v_pk_mul_f32 v[30:31], v[30:31], v[50:51] op_sel_hi:[1,0]
	v_pk_mul_f32 v[28:29], v[44:45], v[26:27]
	v_pk_mul_f32 v[24:25], v[24:25], v[30:31]
	v_mov_b32_dpp v26, v88 row_ror:1 row_mask:0xf bank_mask:0xf
	v_mov_b32_dpp v27, v89 row_ror:1 row_mask:0xf bank_mask:0xf
	s_nop 0
	v_mov_b32_dpp v26, v110 row_shr:1 row_mask:0xf bank_mask:0xf
	v_mov_b32_dpp v27, v111 row_shr:1 row_mask:0xf bank_mask:0xf
	v_mov_b32_dpp v30, v90 row_ror:1 row_mask:0xf bank_mask:0xf
	v_mov_b32_dpp v31, v91 row_ror:1 row_mask:0xf bank_mask:0xf
	v_mov_b32_dpp v44, v18 row_ror:15 row_mask:0xf bank_mask:0xf
	v_mov_b32_dpp v45, v19 row_ror:15 row_mask:0xf bank_mask:0xf
	v_pk_fma_f32 v[26:27], v[64:65], v[26:27], v[68:69]
	v_pk_mul_f32 v[24:25], v[46:47], v[24:25]
	v_mov_b32_dpp v30, v108 row_shr:1 row_mask:0xf bank_mask:0xf
	v_mov_b32_dpp v31, v109 row_shr:1 row_mask:0xf bank_mask:0xf
	v_mov_b32_dpp v44, v110 row_shl:1 row_mask:0xf bank_mask:0xf
	v_mov_b32_dpp v45, v111 row_shl:1 row_mask:0xf bank_mask:0xf
	v_pk_fma_f32 v[26:27], v[110:111], v[60:61], v[26:27]
	v_mov_b32_dpp v46, v16 row_ror:15 row_mask:0xf bank_mask:0xf
	v_mov_b32_dpp v47, v17 row_ror:15 row_mask:0xf bank_mask:0xf
	v_pk_fma_f32 v[30:31], v[66:67], v[30:31], v[70:71]
	v_pk_fma_f32 v[26:27], v[56:57], v[44:45], v[26:27]
	v_mov_b32_dpp v46, v108 row_shl:1 row_mask:0xf bank_mask:0xf
	v_mov_b32_dpp v47, v109 row_shl:1 row_mask:0xf bank_mask:0xf
	v_pk_fma_f32 v[30:31], v[108:109], v[62:63], v[30:31]
	v_pk_mul_f32 v[44:45], v[26:27], v[26:27]
	v_pk_fma_f32 v[30:31], v[58:59], v[46:47], v[30:31]
	v_pk_mul_f32 v[44:45], v[26:27], v[44:45]
	v_pk_mul_f32 v[46:47], v[30:31], v[30:31]
	v_pk_fma_f32 v[44:45], v[44:45], s[70:71], v[26:27] op_sel_hi:[1,0,1]
	v_pk_mul_f32 v[46:47], v[30:31], v[46:47]
	v_pk_mul_f32 v[44:45], v[44:45], s[72:73] op_sel_hi:[1,0]
	v_pk_fma_f32 v[46:47], v[46:47], s[70:71], v[30:31] op_sel_hi:[1,0,1]
	v_min_f32_e32 v44, 0x41e6d4ca, v44
	v_pk_mul_f32 v[46:47], v[46:47], s[72:73] op_sel_hi:[1,0]
	v_exp_f32_e32 v49, v44
	v_min_f32_e32 v44, 0x41e6d4ca, v45
	v_exp_f32_e32 v48, v44
	v_min_f32_e32 v44, 0x41e6d4ca, v46
	v_exp_f32_e32 v45, v44
	v_min_f32_e32 v44, 0x41e6d4ca, v47
	v_exp_f32_e32 v44, v44
	v_pk_add_f32 v[46:47], v[48:49], 1.0 op_sel_hi:[1,0]
	v_mov_b32_dpp v100, v36 row_shl:1 row_mask:0xf bank_mask:0xf
	v_pk_add_f32 v[44:45], v[44:45], 1.0 op_sel_hi:[1,0]
	v_mul_f32_e32 v48, v47, v46
	v_mul_f32_e32 v49, v45, v44
	v_mov_b32_dpp v101, v37 row_shl:1 row_mask:0xf bank_mask:0xf
	v_mul_f32_e32 v50, v48, v49
	v_rcp_f32_e32 v51, v50
	v_mov_b32_dpp v102, v38 row_shl:1 row_mask:0xf bank_mask:0xf
	v_mov_b32_dpp v103, v39 row_shl:1 row_mask:0xf bank_mask:0xf
	v_pk_mul_f32 v[4:5], v[4:5], v[194:195]
	v_mul_f32_e32 v50, v49, v51
	v_mul_f32_e32 v48, v48, v51
	v_pk_mul_f32 v[44:45], v[44:45], v[48:49] op_sel_hi:[1,0]
	v_pk_mul_f32 v[46:47], v[46:47], v[50:51] op_sel_hi:[1,0]
	v_pk_mul_f32 v[30:31], v[30:31], v[44:45]
	v_pk_mul_f32 v[26:27], v[26:27], v[46:47]
	v_pk_mul_f32 v[30:31], v[40:41], v[30:31]
	v_pk_mul_f32 v[40:41], v[42:43], v[26:27]
	v_cvt_pk_bf16_f32 v26, v24, v25
	v_mov_b64_e32 v[24:25], s[86:87]
	v_cvt_pk_bf16_f32 v27, v28, v29
	v_cvt_pk_bf16_f32 v29, v30, v31
	v_mad_i64_i32 v[30:31], s[10:11], v52, s90, v[24:25]
	v_cvt_pk_bf16_f32 v28, v40, v41
	v_lshl_add_u64 v[30:31], v[30:31], 0, v[112:113]
	global_store_dwordx4 v[30:31], v[26:29], off sc1
	s_nop 0
	s_nop 0
	v_mov_b32_dpp v26, v116 row_ror:1 row_mask:0xf bank_mask:0xf
	v_mov_b32_dpp v27, v117 row_ror:1 row_mask:0xf bank_mask:0xf
	s_nop 0
	v_mov_b32_dpp v26, v22 row_shr:1 row_mask:0xf bank_mask:0xf
	v_mov_b32_dpp v27, v23 row_shr:1 row_mask:0xf bank_mask:0xf
	v_mov_b32_dpp v28, v114 row_ror:1 row_mask:0xf bank_mask:0xf
	v_mov_b32_dpp v29, v115 row_ror:1 row_mask:0xf bank_mask:0xf
	v_mov_b32_dpp v30, v36 row_ror:15 row_mask:0xf bank_mask:0xf
	v_mov_b32_dpp v31, v37 row_ror:15 row_mask:0xf bank_mask:0xf
	v_pk_fma_f32 v[26:27], v[80:81], v[26:27], v[84:85]
	v_mov_b32_dpp v28, v20 row_shr:1 row_mask:0xf bank_mask:0xf
	v_mov_b32_dpp v29, v21 row_shr:1 row_mask:0xf bank_mask:0xf
	v_mov_b32_dpp v30, v22 row_shl:1 row_mask:0xf bank_mask:0xf
	v_mov_b32_dpp v31, v23 row_shl:1 row_mask:0xf bank_mask:0xf
	v_pk_fma_f32 v[26:27], v[22:23], v[76:77], v[26:27]
	v_mov_b32_dpp v40, v38 row_ror:15 row_mask:0xf bank_mask:0xf
	v_mov_b32_dpp v41, v39 row_ror:15 row_mask:0xf bank_mask:0xf
	v_pk_fma_f32 v[28:29], v[82:83], v[28:29], v[86:87]
	v_pk_fma_f32 v[26:27], v[72:73], v[30:31], v[26:27]
	v_mov_b32_dpp v40, v20 row_shl:1 row_mask:0xf bank_mask:0xf
	v_mov_b32_dpp v41, v21 row_shl:1 row_mask:0xf bank_mask:0xf
	v_pk_fma_f32 v[28:29], v[20:21], v[78:79], v[28:29]
	v_pk_mul_f32 v[30:31], v[26:27], v[26:27]
	v_pk_fma_f32 v[28:29], v[74:75], v[40:41], v[28:29]
	v_pk_mul_f32 v[30:31], v[26:27], v[30:31]
	v_pk_mul_f32 v[40:41], v[28:29], v[28:29]
	v_pk_fma_f32 v[30:31], v[30:31], s[70:71], v[26:27] op_sel_hi:[1,0,1]
	v_pk_mul_f32 v[40:41], v[28:29], v[40:41]
	v_pk_mul_f32 v[30:31], v[30:31], s[72:73] op_sel_hi:[1,0]
	v_pk_fma_f32 v[40:41], v[40:41], s[70:71], v[28:29] op_sel_hi:[1,0,1]
	v_min_f32_e32 v30, 0x41e6d4ca, v30
	v_pk_mul_f32 v[40:41], v[40:41], s[72:73] op_sel_hi:[1,0]
	v_exp_f32_e32 v43, v30
	v_min_f32_e32 v30, 0x41e6d4ca, v31
	v_exp_f32_e32 v42, v30
	v_min_f32_e32 v30, 0x41e6d4ca, v40
	v_exp_f32_e32 v31, v30
	v_min_f32_e32 v30, 0x41e6d4ca, v41
	v_exp_f32_e32 v30, v30
	v_pk_add_f32 v[40:41], v[42:43], 1.0 op_sel_hi:[1,0]
	v_add_u32_e32 v46, 0xa0, v197
	v_pk_add_f32 v[30:31], v[30:31], 1.0 op_sel_hi:[1,0]
	v_mul_f32_e32 v42, v41, v40
	v_mul_f32_e32 v43, v31, v30
	v_mov_b32_dpp v96, v32 row_shl:1 row_mask:0xf bank_mask:0xf
	v_mul_f32_e32 v44, v42, v43
	v_rcp_f32_e32 v45, v44
	v_mov_b32_dpp v97, v33 row_shl:1 row_mask:0xf bank_mask:0xf
	v_mov_b32_dpp v98, v34 row_shl:1 row_mask:0xf bank_mask:0xf
	v_mov_b32_dpp v99, v35 row_shl:1 row_mask:0xf bank_mask:0xf
	v_mul_f32_e32 v44, v43, v45
	v_pk_mul_f32 v[40:41], v[40:41], v[44:45] op_sel_hi:[1,0]
	v_mul_f32_e32 v42, v42, v45
	v_pk_mul_f32 v[26:27], v[26:27], v[40:41]
	v_pk_mul_f32 v[30:31], v[30:31], v[42:43] op_sel_hi:[1,0]
	v_pk_mul_f32 v[12:13], v[12:13], v[26:27]
	v_pk_mul_f32 v[28:29], v[28:29], v[30:31]
	v_mov_b32_dpp v26, v110 row_ror:1 row_mask:0xf bank_mask:0xf
	v_mov_b32_dpp v27, v111 row_ror:1 row_mask:0xf bank_mask:0xf
	v_pk_mul_f32 v[14:15], v[14:15], v[28:29]
	v_mov_b32_dpp v26, v18 row_shr:1 row_mask:0xf bank_mask:0xf
	v_mov_b32_dpp v27, v19 row_shr:1 row_mask:0xf bank_mask:0xf
	v_mov_b32_dpp v28, v108 row_ror:1 row_mask:0xf bank_mask:0xf
	v_mov_b32_dpp v29, v109 row_ror:1 row_mask:0xf bank_mask:0xf
	v_mov_b32_dpp v30, v32 row_ror:15 row_mask:0xf bank_mask:0xf
	v_mov_b32_dpp v31, v33 row_ror:15 row_mask:0xf bank_mask:0xf
	v_pk_fma_f32 v[26:27], v[64:65], v[26:27], v[68:69]
	v_mov_b32_dpp v28, v16 row_shr:1 row_mask:0xf bank_mask:0xf
	v_mov_b32_dpp v29, v17 row_shr:1 row_mask:0xf bank_mask:0xf
	v_mov_b32_dpp v30, v18 row_shl:1 row_mask:0xf bank_mask:0xf
	v_mov_b32_dpp v31, v19 row_shl:1 row_mask:0xf bank_mask:0xf
	v_pk_fma_f32 v[26:27], v[18:19], v[60:61], v[26:27]
	v_mov_b32_dpp v40, v34 row_ror:15 row_mask:0xf bank_mask:0xf
	v_mov_b32_dpp v41, v35 row_ror:15 row_mask:0xf bank_mask:0xf
	v_pk_fma_f32 v[28:29], v[66:67], v[28:29], v[70:71]
	v_pk_fma_f32 v[26:27], v[56:57], v[30:31], v[26:27]
	v_mov_b32_dpp v40, v16 row_shl:1 row_mask:0xf bank_mask:0xf
	v_mov_b32_dpp v41, v17 row_shl:1 row_mask:0xf bank_mask:0xf
	v_pk_fma_f32 v[28:29], v[16:17], v[62:63], v[28:29]
	v_pk_mul_f32 v[30:31], v[26:27], v[26:27]
	v_pk_fma_f32 v[28:29], v[58:59], v[40:41], v[28:29]
	v_pk_mul_f32 v[30:31], v[26:27], v[30:31]
	v_pk_mul_f32 v[40:41], v[28:29], v[28:29]
	v_pk_fma_f32 v[30:31], v[30:31], s[70:71], v[26:27] op_sel_hi:[1,0,1]
	v_pk_mul_f32 v[40:41], v[28:29], v[40:41]
	v_pk_mul_f32 v[30:31], v[30:31], s[72:73] op_sel_hi:[1,0]
	v_pk_fma_f32 v[40:41], v[40:41], s[70:71], v[28:29] op_sel_hi:[1,0,1]
	v_min_f32_e32 v30, 0x41e6d4ca, v30
	v_pk_mul_f32 v[40:41], v[40:41], s[72:73] op_sel_hi:[1,0]
	v_exp_f32_e32 v43, v30
	v_min_f32_e32 v30, 0x41e6d4ca, v31
	v_exp_f32_e32 v42, v30
	v_min_f32_e32 v30, 0x41e6d4ca, v40
	v_exp_f32_e32 v31, v30
	v_min_f32_e32 v30, 0x41e6d4ca, v41
	v_exp_f32_e32 v30, v30
	v_pk_add_f32 v[40:41], v[42:43], 1.0 op_sel_hi:[1,0]
	v_pk_mul_f32 v[0:1], v[0:1], v[194:195]
	v_pk_add_f32 v[30:31], v[30:31], 1.0 op_sel_hi:[1,0]
	v_mul_f32_e32 v42, v41, v40
	v_mul_f32_e32 v43, v31, v30
	s_nop 0
	v_mul_f32_e32 v44, v42, v43
	v_rcp_f32_e32 v45, v44
	s_nop 0
	v_mul_f32_e32 v44, v43, v45
	v_mul_f32_e32 v42, v42, v45
	v_pk_mul_f32 v[30:31], v[30:31], v[42:43] op_sel_hi:[1,0]
	v_pk_mul_f32 v[40:41], v[40:41], v[44:45] op_sel_hi:[1,0]
	v_pk_mul_f32 v[28:29], v[28:29], v[30:31]
	v_pk_mul_f32 v[26:27], v[26:27], v[40:41]
	v_pk_mul_f32 v[28:29], v[10:11], v[28:29]
	v_pk_mul_f32 v[10:11], v[8:9], v[26:27]
	v_cvt_pk_bf16_f32 v8, v12, v13
	v_mad_i64_i32 v[12:13], s[10:11], v46, s90, v[24:25]
	v_cvt_pk_bf16_f32 v9, v14, v15
	v_cvt_pk_bf16_f32 v10, v10, v11
	v_cvt_pk_bf16_f32 v11, v28, v29
	v_lshl_add_u64 v[12:13], v[12:13], 0, v[112:113]
	global_store_dwordx4 v[12:13], v[8:11], off sc1
	v_add_u32_e32 v30, 0xb0, v197
	s_nop 0
	v_mov_b32_dpp v8, v22 row_ror:1 row_mask:0xf bank_mask:0xf
	v_mov_b32_dpp v9, v23 row_ror:1 row_mask:0xf bank_mask:0xf
	s_nop 0
	v_mov_b32_dpp v8, v36 row_shr:1 row_mask:0xf bank_mask:0xf
	v_mov_b32_dpp v9, v37 row_shr:1 row_mask:0xf bank_mask:0xf
	v_mov_b32_dpp v10, v20 row_ror:1 row_mask:0xf bank_mask:0xf
	v_mov_b32_dpp v11, v21 row_ror:1 row_mask:0xf bank_mask:0xf
	v_pk_fma_f32 v[8:9], v[80:81], v[8:9], v[84:85]
	v_mov_b32_dpp v10, v38 row_shr:1 row_mask:0xf bank_mask:0xf
	v_mov_b32_dpp v11, v39 row_shr:1 row_mask:0xf bank_mask:0xf
	v_pk_fma_f32 v[8:9], v[36:37], v[76:77], v[8:9]
	v_pk_fma_f32 v[10:11], v[82:83], v[10:11], v[86:87]
	v_pk_fma_f32 v[8:9], v[72:73], v[100:101], v[8:9]
	v_pk_fma_f32 v[10:11], v[38:39], v[78:79], v[10:11]
	v_pk_mul_f32 v[12:13], v[8:9], v[8:9]
	v_pk_fma_f32 v[10:11], v[74:75], v[102:103], v[10:11]
	v_pk_mul_f32 v[12:13], v[8:9], v[12:13]
	v_pk_mul_f32 v[14:15], v[10:11], v[10:11]
	v_pk_fma_f32 v[12:13], v[12:13], s[70:71], v[8:9] op_sel_hi:[1,0,1]
	v_pk_mul_f32 v[14:15], v[10:11], v[14:15]
	v_pk_mul_f32 v[12:13], v[12:13], s[72:73] op_sel_hi:[1,0]
	v_pk_fma_f32 v[14:15], v[14:15], s[70:71], v[10:11] op_sel_hi:[1,0,1]
	v_min_f32_e32 v12, 0x41e6d4ca, v12
	v_pk_mul_f32 v[14:15], v[14:15], s[72:73] op_sel_hi:[1,0]
	v_exp_f32_e32 v21, v12
	v_min_f32_e32 v12, 0x41e6d4ca, v13
	v_exp_f32_e32 v20, v12
	v_min_f32_e32 v12, 0x41e6d4ca, v14
	v_exp_f32_e32 v13, v12
	v_min_f32_e32 v12, 0x41e6d4ca, v15
	v_exp_f32_e32 v12, v12
	v_pk_add_f32 v[14:15], v[20:21], 1.0 op_sel_hi:[1,0]
	v_pk_add_f32 v[12:13], v[12:13], 1.0 op_sel_hi:[1,0]
	v_mul_f32_e32 v20, v15, v14
	v_mul_f32_e32 v21, v13, v12
	s_nop 0
	v_mul_f32_e32 v22, v20, v21
	v_rcp_f32_e32 v23, v22
	s_nop 0
	v_mul_f32_e32 v20, v20, v23
	v_pk_mul_f32 v[12:13], v[12:13], v[20:21] op_sel_hi:[1,0]
	v_mul_f32_e32 v22, v21, v23
	v_pk_mul_f32 v[12:13], v[10:11], v[12:13]
	v_pk_mul_f32 v[14:15], v[14:15], v[22:23] op_sel_hi:[1,0]
	v_pk_mul_f32 v[20:21], v[6:7], v[12:13]
	v_pk_mul_f32 v[14:15], v[8:9], v[14:15]
	v_mov_b32_dpp v12, v18 row_ror:1 row_mask:0xf bank_mask:0xf
	v_mov_b32_dpp v13, v19 row_ror:1 row_mask:0xf bank_mask:0xf
	v_pk_mul_f32 v[22:23], v[4:5], v[14:15]
	v_mov_b32_dpp v12, v32 row_shr:1 row_mask:0xf bank_mask:0xf
	v_mov_b32_dpp v13, v33 row_shr:1 row_mask:0xf bank_mask:0xf
	v_mov_b32_dpp v14, v16 row_ror:1 row_mask:0xf bank_mask:0xf
	v_mov_b32_dpp v15, v17 row_ror:1 row_mask:0xf bank_mask:0xf
	v_pk_fma_f32 v[12:13], v[64:65], v[12:13], v[68:69]
	v_mov_b32_dpp v14, v34 row_shr:1 row_mask:0xf bank_mask:0xf
	v_mov_b32_dpp v15, v35 row_shr:1 row_mask:0xf bank_mask:0xf
	v_pk_fma_f32 v[12:13], v[32:33], v[60:61], v[12:13]
	v_pk_fma_f32 v[14:15], v[66:67], v[14:15], v[70:71]
	v_pk_fma_f32 v[12:13], v[56:57], v[96:97], v[12:13]
	v_pk_fma_f32 v[14:15], v[34:35], v[62:63], v[14:15]
	v_pk_mul_f32 v[16:17], v[12:13], v[12:13]
	v_pk_fma_f32 v[14:15], v[58:59], v[98:99], v[14:15]
	v_pk_mul_f32 v[16:17], v[12:13], v[16:17]
	v_pk_mul_f32 v[18:19], v[14:15], v[14:15]
	v_pk_fma_f32 v[16:17], v[16:17], s[70:71], v[12:13] op_sel_hi:[1,0,1]
	v_pk_mul_f32 v[18:19], v[14:15], v[18:19]
	v_pk_mul_f32 v[16:17], v[16:17], s[72:73] op_sel_hi:[1,0]
	v_pk_fma_f32 v[18:19], v[18:19], s[70:71], v[14:15] op_sel_hi:[1,0,1]
	v_min_f32_e32 v16, 0x41e6d4ca, v16
	v_pk_mul_f32 v[18:19], v[18:19], s[72:73] op_sel_hi:[1,0]
	v_exp_f32_e32 v27, v16
	v_min_f32_e32 v16, 0x41e6d4ca, v17
	v_exp_f32_e32 v26, v16
	v_min_f32_e32 v16, 0x41e6d4ca, v18
	v_exp_f32_e32 v17, v16
	v_min_f32_e32 v16, 0x41e6d4ca, v19
	v_exp_f32_e32 v16, v16
	v_pk_add_f32 v[18:19], v[26:27], 1.0 op_sel_hi:[1,0]
	v_pk_add_f32 v[16:17], v[16:17], 1.0 op_sel_hi:[1,0]
	v_mul_f32_e32 v26, v19, v18
	v_mul_f32_e32 v27, v17, v16
	s_nop 0
	v_mul_f32_e32 v28, v26, v27
	v_rcp_f32_e32 v29, v28
	s_nop 0
	v_mul_f32_e32 v28, v27, v29
	v_mul_f32_e32 v26, v26, v29
	v_pk_mul_f32 v[16:17], v[16:17], v[26:27] op_sel_hi:[1,0]
	v_pk_mul_f32 v[18:19], v[18:19], v[28:29] op_sel_hi:[1,0]
	v_pk_mul_f32 v[16:17], v[14:15], v[16:17]
	v_pk_mul_f32 v[18:19], v[12:13], v[18:19]
	v_pk_mul_f32 v[26:27], v[2:3], v[16:17]
	v_pk_mul_f32 v[18:19], v[0:1], v[18:19]
	v_cvt_pk_bf16_f32 v17, v20, v21
	v_mad_i64_i32 v[20:21], s[10:11], v30, s90, v[24:25]
	v_cvt_pk_bf16_f32 v16, v22, v23
	v_cvt_pk_bf16_f32 v18, v18, v19
	v_cvt_pk_bf16_f32 v19, v26, v27
	v_lshl_add_u64 v[20:21], v[20:21], 0, v[112:113]
	global_store_dwordx4 v[20:21], v[16:19], off sc1
	s_and_saveexec_b64 s[10:11], s[64:65]
	s_cbranch_execz .LBB0_784
	s_add_u32 s14, s4, s14
	s_addc_u32 s15, s5, s12
	v_lshl_add_u64 v[16:17], v[192:193], 2, s[14:15]
	global_store_dwordx4 v[16:17], v[8:11], off sc1
	s_nop 1
	v_add_co_u32_e32 v8, vcc, 0x2000, v16
	s_nop 1
	v_addc_co_u32_e32 v9, vcc, 0, v17, vcc
	v_add_co_u32_e32 v10, vcc, 0x5000, v16
	global_store_dwordx4 v[8:9], v[36:39], off offset:3072 sc1
	s_nop 0
	v_addc_co_u32_e32 v11, vcc, 0, v17, vcc
	global_store_dwordx4 v[10:11], v[4:7], off offset:2048 sc1
	global_store_dwordx4 v[16:17], v[12:15], off offset:16 sc1
	global_store_dwordx4 v[8:9], v[32:35], off offset:3088 sc1
	global_store_dwordx4 v[10:11], v[0:3], off offset:2064 sc1
